# v sweep's first three batches ride on the u ring's read-ahead past its end (u descriptor spans both tables): no drain between the sweeps
# baseline (speedup 1.0000x reference)
; __device__ __forceinline__ unsigned f2key(float f) { const unsigned u = __float_as_uint(f); return (u & 0x80000000u) ? ~u : (u | 0x80000000u); }
; __device__ __forceinline__ void peer_tile(const Args& A, LAS unsigned char* lds, int tile) {
;     ...
;         const int tg = w & 3, hg = w >> 2, tl = 16 * tg + l15;
;         const size_t m = (size_t)tile * 64 + tl;
;         unsigned LA[4][2][16];
; #pragma unroll
;         for (int hh = 0; hh < 4; ++hh) {
;             const int h = 4 * hg + hh;
; #pragma unroll
;             for (int p = 0; p < 2; ++p) {
;                 const int hp = 2 * h + p;
;                 unsigned k0[16], k1[16];
;                 { const bf16_t* sp = QRY + m * 2048 + hp * 128 + 32 * g;
;                   const u32x4 s0 = *(const u32x4*)sp, s1 = *(const u32x4*)(sp + 8), s2 = *(const u32x4*)(sp + 16), s3 = *(const u32x4*)(sp + 24);
;                   const unsigned sw[16] = {s0.x, s0.y, s0.z, s0.w, s1.x, s1.y, s1.z, s1.w, s2.x, s2.y, s2.z, s2.w, s3.x, s3.y, s3.z, s3.w};
; #pragma unroll
;                   for (int i = 0; i < 16; ++i) {
;                       const float lo = (float)__builtin_bit_cast(_Float16, (unsigned short)(sw[i] & 0xffffu)), hi = (float)__builtin_bit_cast(_Float16, (unsigned short)(sw[i] >> 16));
;                       const unsigned klo = (f2key(lo) & ~127u) | (unsigned)(127 - (32 * g + 2 * i)), khi = (f2key(hi) & ~127u) | (unsigned)(127 - (32 * g + 2 * i + 1));
;                       if (i < 8) { k0[2 * i] = klo; k0[2 * i + 1] = khi; } else { k1[2 * (i - 8)] = klo; k1[2 * (i - 8) + 1] = khi; } } }
.LBB0_699:
	s_mov_b64 exec, -1
	s_mov_b32 s33, 0x80000000
	s_mov_b32 s40, 0x7fffff80
	s_mov_b32 s41, 0x7fffffff
	v_and_b32_e32 v68, 63, v214
	v_lshrrev_b32_e32 v66, 6, v214
	s_nop 0
	v_readfirstlane_b32 s36, v66
	s_lshl_b32 s0, s2, 18
	s_lshl_b32 s1, s36, 9
	s_add_u32 s34, s54, s0
	s_addc_u32 s35, s55, 0
	s_add_u32 s34, s34, s1
	s_addc_u32 s35, s35, 0
	v_lshrrev_b32_e32 v66, 3, v68
	v_and_b32_e32 v64, 7, v68
	v_lshlrev_b32_e32 v64, 4, v64
	v_mul_u32_u24_e32 v65, 0x90, v66
	v_lshl_add_u32 v66, v66, 12, v64
	s_mul_i32 s0, s36, 0x2400
	s_cmp_eq_u32 s36, 7
	s_cselect_b32 s0, 0x21000, s0
	v_add3_u32 v64, v64, v65, s0
	v_mul_u32_u24_e32 v65, 0x90, v68
	v_add_u32_e32 v65, s0, v65
	v_mul_u32_u24_e32 v67, 0x84, v68
	v_lshlrev_b32_e32 v68, 10, v68
	s_lshl_b32 s1, s36, 7
	s_add_i32 s1, s1, 0x11000
	v_add_u32_e32 v67, s0, v67
	v_add_u32_e32 v68, s1, v68
	s_mov_b64 s[38:39], s[34:35]
	global_load_dwordx4 v[0:3], v66, s[38:39] offset:0
	s_add_u32 s38, s38, 0x8000
	s_addc_u32 s39, s39, 0
	global_load_dwordx4 v[4:7], v66, s[38:39] offset:0
	s_add_u32 s38, s38, 0x8000
	s_addc_u32 s39, s39, 0
	global_load_dwordx4 v[8:11], v66, s[38:39] offset:0
	s_add_u32 s38, s38, 0x8000
	s_addc_u32 s39, s39, 0
	global_load_dwordx4 v[12:15], v66, s[38:39] offset:0
	s_add_u32 s38, s38, 0x8000
	s_addc_u32 s39, s39, 0
	global_load_dwordx4 v[16:19], v66, s[38:39] offset:0
	s_add_u32 s38, s38, 0x8000
	s_addc_u32 s39, s39, 0
	global_load_dwordx4 v[20:23], v66, s[38:39] offset:0
	s_add_u32 s38, s38, 0x8000
	s_addc_u32 s39, s39, 0
	global_load_dwordx4 v[24:27], v66, s[38:39] offset:0
	s_add_u32 s38, s38, 0x8000
	s_addc_u32 s39, s39, 0
	global_load_dwordx4 v[28:31], v66, s[38:39] offset:0
	s_mov_b64 s[38:39], s[34:35]
	global_load_dwordx4 v[32:35], v66, s[38:39] offset:128
	s_add_u32 s38, s38, 0x8000
	s_addc_u32 s39, s39, 0
	global_load_dwordx4 v[36:39], v66, s[38:39] offset:128
	s_add_u32 s38, s38, 0x8000
	s_addc_u32 s39, s39, 0
	global_load_dwordx4 v[40:43], v66, s[38:39] offset:128
	s_add_u32 s38, s38, 0x8000
	s_addc_u32 s39, s39, 0
	global_load_dwordx4 v[44:47], v66, s[38:39] offset:128
	s_add_u32 s38, s38, 0x8000
	s_addc_u32 s39, s39, 0
	global_load_dwordx4 v[48:51], v66, s[38:39] offset:128
	s_add_u32 s38, s38, 0x8000
	s_addc_u32 s39, s39, 0
	global_load_dwordx4 v[52:55], v66, s[38:39] offset:128
	s_add_u32 s38, s38, 0x8000
	s_addc_u32 s39, s39, 0
	global_load_dwordx4 v[56:59], v66, s[38:39] offset:128
	s_add_u32 s38, s38, 0x8000
	s_addc_u32 s39, s39, 0
	global_load_dwordx4 v[60:63], v66, s[38:39] offset:128
	s_waitcnt vmcnt(8)
	ds_write_b128 v64, v[0:3] offset:0
	ds_write_b128 v64, v[4:7] offset:1152
	ds_write_b128 v64, v[8:11] offset:2304
	ds_write_b128 v64, v[12:15] offset:3456
	ds_write_b128 v64, v[16:19] offset:4608
	ds_write_b128 v64, v[20:23] offset:5760
	ds_write_b128 v64, v[24:27] offset:6912
	ds_write_b128 v64, v[28:31] offset:8064
	s_waitcnt lgkmcnt(0)
	ds_read_b128 v[0:3], v65 offset:0
	ds_read_b128 v[4:7], v65 offset:16
	ds_read_b128 v[8:11], v65 offset:32
	ds_read_b128 v[12:15], v65 offset:48
	ds_read_b128 v[16:19], v65 offset:64
	ds_read_b128 v[20:23], v65 offset:80
	ds_read_b128 v[24:27], v65 offset:96
	ds_read_b128 v[28:31], v65 offset:112
	s_waitcnt lgkmcnt(0)
	v_cvt_f32_f16_e32 v70, v0
	v_cvt_f32_f16_sdwa v71, v0 dst_sel:DWORD dst_unused:UNUSED_PAD src0_sel:WORD_1
	v_ashrrev_i32_e32 v72, 31, v70
	v_bitop3_b32 v70, v70, v72, s40 bitop3:0x78
	v_xor_b32_e32 v70, 0x8000007f, v70
	v_ashrrev_i32_e32 v72, 31, v71
	v_bitop3_b32 v71, v71, v72, s40 bitop3:0x78
	v_xor_b32_e32 v71, 0x8000007e, v71
	v_cvt_f32_f16_e32 v72, v1
	v_cvt_f32_f16_sdwa v73, v1 dst_sel:DWORD dst_unused:UNUSED_PAD src0_sel:WORD_1
	v_ashrrev_i32_e32 v74, 31, v72
	v_bitop3_b32 v72, v72, v74, s40 bitop3:0x78
	v_xor_b32_e32 v72, 0x8000007d, v72
	v_ashrrev_i32_e32 v74, 31, v73
	v_bitop3_b32 v73, v73, v74, s40 bitop3:0x78
	v_xor_b32_e32 v73, 0x8000007c, v73
	v_cvt_f32_f16_e32 v74, v2
	v_cvt_f32_f16_sdwa v75, v2 dst_sel:DWORD dst_unused:UNUSED_PAD src0_sel:WORD_1
	v_ashrrev_i32_e32 v76, 31, v74
	v_bitop3_b32 v74, v74, v76, s40 bitop3:0x78
	v_xor_b32_e32 v74, 0x8000007b, v74
	v_ashrrev_i32_e32 v76, 31, v75
	v_bitop3_b32 v75, v75, v76, s40 bitop3:0x78
	v_xor_b32_e32 v75, 0x8000007a, v75
	v_cvt_f32_f16_e32 v76, v3
	v_cvt_f32_f16_sdwa v77, v3 dst_sel:DWORD dst_unused:UNUSED_PAD src0_sel:WORD_1
	v_ashrrev_i32_e32 v78, 31, v76
	v_bitop3_b32 v76, v76, v78, s40 bitop3:0x78
	v_xor_b32_e32 v76, 0x80000079, v76
	v_ashrrev_i32_e32 v78, 31, v77
	v_bitop3_b32 v77, v77, v78, s40 bitop3:0x78
	v_xor_b32_e32 v77, 0x80000078, v77
	v_cvt_f32_f16_e32 v78, v4
	v_cvt_f32_f16_sdwa v79, v4 dst_sel:DWORD dst_unused:UNUSED_PAD src0_sel:WORD_1
	v_ashrrev_i32_e32 v80, 31, v78
	v_bitop3_b32 v78, v78, v80, s40 bitop3:0x78
	v_xor_b32_e32 v78, 0x80000077, v78
	v_ashrrev_i32_e32 v80, 31, v79
	v_bitop3_b32 v79, v79, v80, s40 bitop3:0x78
	v_xor_b32_e32 v79, 0x80000076, v79
	v_cvt_f32_f16_e32 v80, v5
	v_cvt_f32_f16_sdwa v81, v5 dst_sel:DWORD dst_unused:UNUSED_PAD src0_sel:WORD_1
	v_ashrrev_i32_e32 v82, 31, v80
	v_bitop3_b32 v80, v80, v82, s40 bitop3:0x78
	v_xor_b32_e32 v80, 0x80000075, v80
	v_ashrrev_i32_e32 v82, 31, v81
	v_bitop3_b32 v81, v81, v82, s40 bitop3:0x78
	v_xor_b32_e32 v81, 0x80000074, v81
	v_cvt_f32_f16_e32 v82, v6
	v_cvt_f32_f16_sdwa v83, v6 dst_sel:DWORD dst_unused:UNUSED_PAD src0_sel:WORD_1
	v_ashrrev_i32_e32 v84, 31, v82
	v_bitop3_b32 v82, v82, v84, s40 bitop3:0x78
	v_xor_b32_e32 v82, 0x80000073, v82
	v_ashrrev_i32_e32 v84, 31, v83
	v_bitop3_b32 v83, v83, v84, s40 bitop3:0x78
	v_xor_b32_e32 v83, 0x80000072, v83
	v_cvt_f32_f16_e32 v84, v7
	v_cvt_f32_f16_sdwa v85, v7 dst_sel:DWORD dst_unused:UNUSED_PAD src0_sel:WORD_1
; __device__ __forceinline__ unsigned f2key(float f) { const unsigned u = __float_as_uint(f); return (u & 0x80000000u) ? ~u : (u | 0x80000000u); }
; #define CE_DESC(a, b) do { const unsigned _mx = (a) > (b) ? (a) : (b), _mn = (a) > (b) ? (b) : (a); (a) = _mx; (b) = _mn; } while (0)
; __device__ __forceinline__ void sort16_desc(unsigned (&k)[16]) {
; #pragma unroll
;     for (int size = 2; size <= 16; size <<= 1)
; #pragma unroll
;         for (int stride = size >> 1; stride > 0; stride >>= 1)
; #pragma unroll
;             for (int i = 0; i < 16; ++i) { const int j = i ^ stride;
;                 if (j > i) { if ((i & size) == 0) CE_DESC(k[i], k[j]); else CE_DESC(k[j], k[i]); } }
; }
; __device__ __forceinline__ void merge16(unsigned (&a)[16], const unsigned (&b)[16]) {
; #pragma unroll
;     for (int i = 0; i < 16; ++i) a[i] = a[i] > b[15 - i] ? a[i] : b[15 - i];
; #pragma unroll
;     for (int stride = 8; stride > 0; stride >>= 1)
; #pragma unroll
;         for (int i = 0; i < 16; ++i) { const int j = i ^ stride; if (j > i) CE_DESC(a[i], a[j]); }
; }
; __device__ __forceinline__ void peer_tile(const Args& A, LAS unsigned char* lds, int tile) {
;     ...
;                   for (int i = 0; i < 16; ++i) {
;                       const float lo = (float)__builtin_bit_cast(_Float16, (unsigned short)(sw[i] & 0xffffu)), hi = (float)__builtin_bit_cast(_Float16, (unsigned short)(sw[i] >> 16));
;                       const unsigned klo = (f2key(lo) & ~127u) | (unsigned)(127 - (32 * g + 2 * i)), khi = (f2key(hi) & ~127u) | (unsigned)(127 - (32 * g + 2 * i + 1));
;                       if (i < 8) { k0[2 * i] = klo; k0[2 * i + 1] = khi; } else { k1[2 * (i - 8)] = klo; k1[2 * (i - 8) + 1] = khi; } } }
	v_ashrrev_i32_e32 v86, 31, v84
	v_bitop3_b32 v84, v84, v86, s40 bitop3:0x78
	v_xor_b32_e32 v84, 0x80000071, v84
	v_ashrrev_i32_e32 v86, 31, v85
	v_bitop3_b32 v85, v85, v86, s40 bitop3:0x78
	v_xor_b32_e32 v85, 0x80000070, v85
	v_max_u32_e32 v86, v70, v83
	v_min_u32_e32 v83, v70, v83
	v_max_u32_e32 v70, v71, v82
	v_min_u32_e32 v82, v71, v82
	v_max_u32_e32 v71, v72, v85
	v_min_u32_e32 v85, v72, v85
	v_max_u32_e32 v72, v73, v84
	v_min_u32_e32 v84, v73, v84
	v_max_u32_e32 v73, v74, v78
	v_min_u32_e32 v78, v74, v78
	v_max_u32_e32 v74, v75, v76
	v_min_u32_e32 v76, v75, v76
	v_max_u32_e32 v75, v77, v81
	v_min_u32_e32 v81, v77, v81
	v_max_u32_e32 v77, v79, v80
	v_min_u32_e32 v80, v79, v80
	v_max_u32_e32 v79, v86, v74
	v_min_u32_e32 v74, v86, v74
	v_max_u32_e32 v86, v70, v75
	v_min_u32_e32 v75, v70, v75
	v_max_u32_e32 v70, v71, v77
	v_min_u32_e32 v77, v71, v77
	v_max_u32_e32 v71, v72, v73
	v_min_u32_e32 v73, v72, v73
	v_max_u32_e32 v72, v76, v83
	v_min_u32_e32 v83, v76, v83
	v_max_u32_e32 v76, v78, v84
	v_min_u32_e32 v84, v78, v84
	v_max_u32_e32 v78, v80, v85
	v_min_u32_e32 v85, v80, v85
	v_max_u32_e32 v80, v81, v82
	v_min_u32_e32 v82, v81, v82
	v_max_u32_e32 v81, v79, v86
	v_min_u32_e32 v86, v79, v86
	v_max_u32_e32 v79, v70, v71
	v_min_u32_e32 v71, v70, v71
	v_max_u32_e32 v70, v73, v74
	v_min_u32_e32 v74, v73, v74
	v_max_u32_e32 v73, v72, v76
	v_min_u32_e32 v76, v72, v76
	v_max_u32_e32 v72, v75, v77
	v_min_u32_e32 v77, v75, v77
	v_max_u32_e32 v75, v78, v80
	v_min_u32_e32 v80, v78, v80
	v_max_u32_e32 v78, v82, v83
	v_min_u32_e32 v83, v82, v83
	v_max_u32_e32 v82, v84, v85
	v_min_u32_e32 v85, v84, v85
	v_max_u32_e32 v84, v81, v79
	v_min_u32_e32 v79, v81, v79
	v_max_u32_e32 v81, v86, v71
	v_min_u32_e32 v71, v86, v71
	v_max_u32_e32 v86, v70, v75
	v_min_u32_e32 v75, v70, v75
	v_max_u32_e32 v70, v74, v80
	v_min_u32_e32 v80, v74, v80
	v_max_u32_e32 v74, v73, v72
	v_min_u32_e32 v72, v73, v72
	v_max_u32_e32 v73, v76, v77
	v_min_u32_e32 v77, v76, v77
	v_max_u32_e32 v76, v78, v82
	v_min_u32_e32 v82, v78, v82
	v_max_u32_e32 v78, v83, v85
	v_min_u32_e32 v85, v83, v85
	v_max_u32_e32 v83, v81, v79
	v_min_u32_e32 v79, v81, v79
	v_max_u32_e32 v81, v71, v76
	v_min_u32_e32 v76, v71, v76
	v_max_u32_e32 v71, v86, v74
	v_min_u32_e32 v74, v86, v74
	v_max_u32_e32 v86, v70, v72
	v_min_u32_e32 v72, v70, v72
	v_max_u32_e32 v70, v73, v75
	v_min_u32_e32 v75, v73, v75
	v_max_u32_e32 v73, v77, v80
	v_min_u32_e32 v80, v77, v80
	v_max_u32_e32 v77, v78, v82
	v_min_u32_e32 v82, v78, v82
	v_max_u32_e32 v78, v83, v71
	v_min_u32_e32 v71, v83, v71
	v_max_u32_e32 v83, v79, v74
	v_min_u32_e32 v74, v79, v74
	v_max_u32_e32 v79, v86, v70
	v_min_u32_e32 v70, v86, v70
	v_max_u32_e32 v86, v72, v75
	v_min_u32_e32 v75, v72, v75
	v_max_u32_e32 v72, v73, v77
	v_min_u32_e32 v77, v73, v77
	v_max_u32_e32 v73, v80, v82
	v_min_u32_e32 v82, v80, v82
	v_max_u32_e32 v80, v83, v71
	v_min_u32_e32 v71, v83, v71
	v_max_u32_e32 v83, v81, v74
	v_min_u32_e32 v74, v81, v74
	v_max_u32_e32 v81, v72, v76
	v_min_u32_e32 v76, v72, v76
	v_max_u32_e32 v72, v73, v77
	v_min_u32_e32 v77, v73, v77
	v_max_u32_e32 v73, v83, v79
	v_min_u32_e32 v79, v83, v79
	v_max_u32_e32 v83, v74, v70
	v_min_u32_e32 v70, v74, v70
	v_max_u32_e32 v74, v86, v81
	v_min_u32_e32 v81, v86, v81
	v_max_u32_e32 v86, v75, v76
	v_min_u32_e32 v76, v75, v76
	v_max_u32_e32 v75, v73, v71
	v_min_u32_e32 v71, v73, v71
	v_max_u32_e32 v73, v79, v83
	v_min_u32_e32 v83, v79, v83
	v_max_u32_e32 v79, v74, v70
	v_min_u32_e32 v70, v74, v70
	v_max_u32_e32 v74, v81, v86
	v_min_u32_e32 v86, v81, v86
	v_max_u32_e32 v81, v72, v76
	v_min_u32_e32 v76, v72, v76
	v_max_u32_e32 v72, v83, v79
	v_min_u32_e32 v79, v83, v79
	v_max_u32_e32 v83, v70, v74
	v_min_u32_e32 v74, v70, v74
	v_cvt_f32_f16_e32 v70, v8
	v_cvt_f32_f16_sdwa v87, v8 dst_sel:DWORD dst_unused:UNUSED_PAD src0_sel:WORD_1
	v_ashrrev_i32_e32 v88, 31, v70
	v_bitop3_b32 v70, v70, v88, s40 bitop3:0x78
	v_xor_b32_e32 v70, 0x8000006f, v70
	v_ashrrev_i32_e32 v88, 31, v87
	v_bitop3_b32 v87, v87, v88, s40 bitop3:0x78
	v_xor_b32_e32 v87, 0x8000006e, v87
	v_cvt_f32_f16_e32 v88, v9
	v_cvt_f32_f16_sdwa v89, v9 dst_sel:DWORD dst_unused:UNUSED_PAD src0_sel:WORD_1
	v_ashrrev_i32_e32 v90, 31, v88
	v_bitop3_b32 v88, v88, v90, s40 bitop3:0x78
	v_xor_b32_e32 v88, 0x8000006d, v88
	v_ashrrev_i32_e32 v90, 31, v89
	v_bitop3_b32 v89, v89, v90, s40 bitop3:0x78
	v_xor_b32_e32 v89, 0x8000006c, v89
	v_cvt_f32_f16_e32 v90, v10
	v_cvt_f32_f16_sdwa v91, v10 dst_sel:DWORD dst_unused:UNUSED_PAD src0_sel:WORD_1
	v_ashrrev_i32_e32 v92, 31, v90
	v_bitop3_b32 v90, v90, v92, s40 bitop3:0x78
	v_xor_b32_e32 v90, 0x8000006b, v90
	v_ashrrev_i32_e32 v92, 31, v91
	v_bitop3_b32 v91, v91, v92, s40 bitop3:0x78
	v_xor_b32_e32 v91, 0x8000006a, v91
	v_cvt_f32_f16_e32 v92, v11
	v_cvt_f32_f16_sdwa v93, v11 dst_sel:DWORD dst_unused:UNUSED_PAD src0_sel:WORD_1
	v_ashrrev_i32_e32 v94, 31, v92
	v_bitop3_b32 v92, v92, v94, s40 bitop3:0x78
	v_xor_b32_e32 v92, 0x80000069, v92
	v_ashrrev_i32_e32 v94, 31, v93
	v_bitop3_b32 v93, v93, v94, s40 bitop3:0x78
	v_xor_b32_e32 v93, 0x80000068, v93
	v_cvt_f32_f16_e32 v94, v12
	v_cvt_f32_f16_sdwa v95, v12 dst_sel:DWORD dst_unused:UNUSED_PAD src0_sel:WORD_1
	v_ashrrev_i32_e32 v96, 31, v94
	v_bitop3_b32 v94, v94, v96, s40 bitop3:0x78
	v_xor_b32_e32 v94, 0x80000067, v94
	v_ashrrev_i32_e32 v96, 31, v95
	v_bitop3_b32 v95, v95, v96, s40 bitop3:0x78
	v_xor_b32_e32 v95, 0x80000066, v95
	v_cvt_f32_f16_e32 v96, v13
	v_cvt_f32_f16_sdwa v97, v13 dst_sel:DWORD dst_unused:UNUSED_PAD src0_sel:WORD_1
	v_ashrrev_i32_e32 v98, 31, v96
	v_bitop3_b32 v96, v96, v98, s40 bitop3:0x78
	v_xor_b32_e32 v96, 0x80000065, v96
	v_ashrrev_i32_e32 v98, 31, v97
; __device__ __forceinline__ unsigned f2key(float f) { const unsigned u = __float_as_uint(f); return (u & 0x80000000u) ? ~u : (u | 0x80000000u); }
; #define CE_DESC(a, b) do { const unsigned _mx = (a) > (b) ? (a) : (b), _mn = (a) > (b) ? (b) : (a); (a) = _mx; (b) = _mn; } while (0)
; __device__ __forceinline__ void sort16_desc(unsigned (&k)[16]) {
; #pragma unroll
;     for (int size = 2; size <= 16; size <<= 1)
; #pragma unroll
;         for (int stride = size >> 1; stride > 0; stride >>= 1)
; #pragma unroll
;             for (int i = 0; i < 16; ++i) { const int j = i ^ stride;
;                 if (j > i) { if ((i & size) == 0) CE_DESC(k[i], k[j]); else CE_DESC(k[j], k[i]); } }
; }
; __device__ __forceinline__ void merge16(unsigned (&a)[16], const unsigned (&b)[16]) {
; #pragma unroll
;     for (int i = 0; i < 16; ++i) a[i] = a[i] > b[15 - i] ? a[i] : b[15 - i];
; #pragma unroll
;     for (int stride = 8; stride > 0; stride >>= 1)
; #pragma unroll
;         for (int i = 0; i < 16; ++i) { const int j = i ^ stride; if (j > i) CE_DESC(a[i], a[j]); }
; }
; __device__ __forceinline__ void peer_tile(const Args& A, LAS unsigned char* lds, int tile) {
;     ...
;                   for (int i = 0; i < 16; ++i) {
;                       const float lo = (float)__builtin_bit_cast(_Float16, (unsigned short)(sw[i] & 0xffffu)), hi = (float)__builtin_bit_cast(_Float16, (unsigned short)(sw[i] >> 16));
;                       const unsigned klo = (f2key(lo) & ~127u) | (unsigned)(127 - (32 * g + 2 * i)), khi = (f2key(hi) & ~127u) | (unsigned)(127 - (32 * g + 2 * i + 1));
;                       if (i < 8) { k0[2 * i] = klo; k0[2 * i + 1] = khi; } else { k1[2 * (i - 8)] = klo; k1[2 * (i - 8) + 1] = khi; } } }
;                 sort16_desc(k0); sort16_desc(k1); merge16(k0, k1);
	v_bitop3_b32 v97, v97, v98, s40 bitop3:0x78
	v_xor_b32_e32 v97, 0x80000064, v97
	v_cvt_f32_f16_e32 v98, v14
	v_cvt_f32_f16_sdwa v99, v14 dst_sel:DWORD dst_unused:UNUSED_PAD src0_sel:WORD_1
	v_ashrrev_i32_e32 v100, 31, v98
	v_bitop3_b32 v98, v98, v100, s40 bitop3:0x78
	v_xor_b32_e32 v98, 0x80000063, v98
	v_ashrrev_i32_e32 v100, 31, v99
	v_bitop3_b32 v99, v99, v100, s40 bitop3:0x78
	v_xor_b32_e32 v99, 0x80000062, v99
	v_cvt_f32_f16_e32 v100, v15
	v_cvt_f32_f16_sdwa v101, v15 dst_sel:DWORD dst_unused:UNUSED_PAD src0_sel:WORD_1
	v_ashrrev_i32_e32 v102, 31, v100
	v_bitop3_b32 v100, v100, v102, s40 bitop3:0x78
	v_xor_b32_e32 v100, 0x80000061, v100
	v_ashrrev_i32_e32 v102, 31, v101
	v_bitop3_b32 v101, v101, v102, s40 bitop3:0x78
	v_xor_b32_e32 v101, 0x80000060, v101
	v_max_u32_e32 v102, v70, v99
	v_min_u32_e32 v99, v70, v99
	v_max_u32_e32 v70, v87, v98
	v_min_u32_e32 v98, v87, v98
	v_max_u32_e32 v87, v88, v101
	v_min_u32_e32 v101, v88, v101
	v_max_u32_e32 v88, v89, v100
	v_min_u32_e32 v100, v89, v100
	v_max_u32_e32 v89, v90, v94
	v_min_u32_e32 v94, v90, v94
	v_max_u32_e32 v90, v91, v92
	v_min_u32_e32 v92, v91, v92
	v_max_u32_e32 v91, v93, v97
	v_min_u32_e32 v97, v93, v97
	v_max_u32_e32 v93, v95, v96
	v_min_u32_e32 v96, v95, v96
	v_max_u32_e32 v95, v102, v90
	v_min_u32_e32 v90, v102, v90
	v_max_u32_e32 v102, v70, v91
	v_min_u32_e32 v91, v70, v91
	v_max_u32_e32 v70, v87, v93
	v_min_u32_e32 v93, v87, v93
	v_max_u32_e32 v87, v88, v89
	v_min_u32_e32 v89, v88, v89
	v_max_u32_e32 v88, v92, v99
	v_min_u32_e32 v99, v92, v99
	v_max_u32_e32 v92, v94, v100
	v_min_u32_e32 v100, v94, v100
	v_max_u32_e32 v94, v96, v101
	v_min_u32_e32 v101, v96, v101
	v_max_u32_e32 v96, v97, v98
	v_min_u32_e32 v98, v97, v98
	v_max_u32_e32 v97, v95, v102
	v_min_u32_e32 v102, v95, v102
	v_max_u32_e32 v95, v70, v87
	v_min_u32_e32 v87, v70, v87
	v_max_u32_e32 v70, v89, v90
	v_min_u32_e32 v90, v89, v90
	v_max_u32_e32 v89, v88, v92
	v_min_u32_e32 v92, v88, v92
	v_max_u32_e32 v88, v91, v93
	v_min_u32_e32 v93, v91, v93
	v_max_u32_e32 v91, v94, v96
	v_min_u32_e32 v96, v94, v96
	v_max_u32_e32 v94, v98, v99
	v_min_u32_e32 v99, v98, v99
	v_max_u32_e32 v98, v100, v101
	v_min_u32_e32 v101, v100, v101
	v_max_u32_e32 v100, v97, v95
	v_min_u32_e32 v95, v97, v95
	v_max_u32_e32 v97, v102, v87
	v_min_u32_e32 v87, v102, v87
	v_max_u32_e32 v102, v70, v91
	v_min_u32_e32 v91, v70, v91
	v_max_u32_e32 v70, v90, v96
	v_min_u32_e32 v96, v90, v96
	v_max_u32_e32 v90, v89, v88
	v_min_u32_e32 v88, v89, v88
	v_max_u32_e32 v89, v92, v93
	v_min_u32_e32 v93, v92, v93
	v_max_u32_e32 v92, v94, v98
	v_min_u32_e32 v98, v94, v98
	v_max_u32_e32 v94, v99, v101
	v_min_u32_e32 v101, v99, v101
	v_max_u32_e32 v99, v97, v95
	v_min_u32_e32 v95, v97, v95
	v_max_u32_e32 v97, v87, v92
	v_min_u32_e32 v92, v87, v92
	v_max_u32_e32 v87, v102, v90
	v_min_u32_e32 v90, v102, v90
	v_max_u32_e32 v102, v70, v88
	v_min_u32_e32 v88, v70, v88
	v_max_u32_e32 v70, v89, v91
	v_min_u32_e32 v91, v89, v91
	v_max_u32_e32 v89, v93, v96
	v_min_u32_e32 v96, v93, v96
	v_max_u32_e32 v93, v94, v98
	v_min_u32_e32 v98, v94, v98
	v_max_u32_e32 v94, v99, v87
	v_min_u32_e32 v87, v99, v87
	v_max_u32_e32 v99, v95, v90
	v_min_u32_e32 v90, v95, v90
	v_max_u32_e32 v95, v102, v70
	v_min_u32_e32 v70, v102, v70
	v_max_u32_e32 v102, v88, v91
	v_min_u32_e32 v91, v88, v91
	v_max_u32_e32 v88, v89, v93
	v_min_u32_e32 v93, v89, v93
	v_max_u32_e32 v89, v96, v98
	v_min_u32_e32 v98, v96, v98
	v_max_u32_e32 v96, v99, v87
	v_min_u32_e32 v87, v99, v87
	v_max_u32_e32 v99, v97, v90
	v_min_u32_e32 v90, v97, v90
	v_max_u32_e32 v97, v88, v92
	v_min_u32_e32 v92, v88, v92
	v_max_u32_e32 v88, v89, v93
	v_min_u32_e32 v93, v89, v93
	v_max_u32_e32 v89, v99, v95
	v_min_u32_e32 v95, v99, v95
	v_max_u32_e32 v99, v90, v70
	v_min_u32_e32 v70, v90, v70
	v_max_u32_e32 v90, v102, v97
	v_min_u32_e32 v97, v102, v97
	v_max_u32_e32 v102, v91, v92
	v_min_u32_e32 v92, v91, v92
	v_max_u32_e32 v91, v89, v87
	v_min_u32_e32 v87, v89, v87
	v_max_u32_e32 v89, v95, v99
	v_min_u32_e32 v99, v95, v99
	v_max_u32_e32 v95, v90, v70
	v_min_u32_e32 v70, v90, v70
	v_max_u32_e32 v90, v97, v102
	v_min_u32_e32 v102, v97, v102
	v_max_u32_e32 v97, v88, v92
	v_min_u32_e32 v92, v88, v92
	v_max_u32_e32 v88, v99, v95
	v_min_u32_e32 v95, v99, v95
	v_max_u32_e32 v99, v70, v90
	v_min_u32_e32 v90, v70, v90
	v_max_u32_e32 v84, v84, v101
	v_max_u32_e32 v78, v78, v98
	v_max_u32_e32 v80, v80, v93
	v_max_u32_e32 v75, v75, v92
	v_max_u32_e32 v71, v71, v97
	v_max_u32_e32 v73, v73, v102
	v_max_u32_e32 v72, v72, v90
	v_max_u32_e32 v79, v79, v99
	v_max_u32_e32 v83, v83, v95
	v_max_u32_e32 v74, v74, v88
	v_max_u32_e32 v86, v86, v89
	v_max_u32_e32 v81, v81, v87
	v_max_u32_e32 v76, v76, v91
	v_max_u32_e32 v77, v77, v96
	v_max_u32_e32 v82, v82, v94
	v_max_u32_e32 v85, v85, v100
	v_max_u32_e32 v101, v84, v83
	v_min_u32_e32 v83, v84, v83
	v_max_u32_e32 v84, v78, v74
	v_min_u32_e32 v74, v78, v74
	v_max_u32_e32 v78, v80, v86
	v_min_u32_e32 v86, v80, v86
	v_max_u32_e32 v80, v75, v81
	v_min_u32_e32 v81, v75, v81
	v_max_u32_e32 v75, v71, v76
	v_min_u32_e32 v76, v71, v76
	v_max_u32_e32 v71, v73, v77
	v_min_u32_e32 v77, v73, v77
	v_max_u32_e32 v73, v72, v82
	v_min_u32_e32 v82, v72, v82
	v_max_u32_e32 v72, v79, v85
	v_min_u32_e32 v85, v79, v85
	v_max_u32_e32 v79, v101, v75
	v_min_u32_e32 v75, v101, v75
	v_max_u32_e32 v101, v84, v71
	v_min_u32_e32 v71, v84, v71
	v_max_u32_e32 v84, v78, v73
	v_min_u32_e32 v73, v78, v73
	v_max_u32_e32 v78, v80, v72
	v_min_u32_e32 v72, v80, v72
	v_max_u32_e32 v80, v83, v76
	v_min_u32_e32 v76, v83, v76
	v_max_u32_e32 v83, v74, v77
	v_min_u32_e32 v77, v74, v77
	v_max_u32_e32 v74, v86, v82
	v_min_u32_e32 v82, v86, v82
; __device__ __forceinline__ unsigned f2key(float f) { const unsigned u = __float_as_uint(f); return (u & 0x80000000u) ? ~u : (u | 0x80000000u); }
; #define CE_DESC(a, b) do { const unsigned _mx = (a) > (b) ? (a) : (b), _mn = (a) > (b) ? (b) : (a); (a) = _mx; (b) = _mn; } while (0)
; __device__ __forceinline__ void sort16_desc(unsigned (&k)[16]) {
; #pragma unroll
;     for (int size = 2; size <= 16; size <<= 1)
; #pragma unroll
;         for (int stride = size >> 1; stride > 0; stride >>= 1)
; #pragma unroll
;             for (int i = 0; i < 16; ++i) { const int j = i ^ stride;
;                 if (j > i) { if ((i & size) == 0) CE_DESC(k[i], k[j]); else CE_DESC(k[j], k[i]); } }
; }
; __device__ __forceinline__ void merge16(unsigned (&a)[16], const unsigned (&b)[16]) {
; #pragma unroll
;     for (int i = 0; i < 16; ++i) a[i] = a[i] > b[15 - i] ? a[i] : b[15 - i];
; #pragma unroll
;     for (int stride = 8; stride > 0; stride >>= 1)
; #pragma unroll
;         for (int i = 0; i < 16; ++i) { const int j = i ^ stride; if (j > i) CE_DESC(a[i], a[j]); }
; }
; __device__ __forceinline__ void peer_tile(const Args& A, LAS unsigned char* lds, int tile) {
;     ...
;                   for (int i = 0; i < 16; ++i) {
;                       const float lo = (float)__builtin_bit_cast(_Float16, (unsigned short)(sw[i] & 0xffffu)), hi = (float)__builtin_bit_cast(_Float16, (unsigned short)(sw[i] >> 16));
;                       const unsigned klo = (f2key(lo) & ~127u) | (unsigned)(127 - (32 * g + 2 * i)), khi = (f2key(hi) & ~127u) | (unsigned)(127 - (32 * g + 2 * i + 1));
;                       if (i < 8) { k0[2 * i] = klo; k0[2 * i + 1] = khi; } else { k1[2 * (i - 8)] = klo; k1[2 * (i - 8) + 1] = khi; } } }
	v_max_u32_e32 v86, v81, v85
	v_min_u32_e32 v85, v81, v85
	v_max_u32_e32 v81, v79, v84
	v_min_u32_e32 v84, v79, v84
	v_max_u32_e32 v79, v101, v78
	v_min_u32_e32 v78, v101, v78
	v_max_u32_e32 v101, v75, v73
	v_min_u32_e32 v73, v75, v73
	v_max_u32_e32 v75, v71, v72
	v_min_u32_e32 v72, v71, v72
	v_max_u32_e32 v71, v80, v74
	v_min_u32_e32 v74, v80, v74
	v_max_u32_e32 v80, v83, v86
	v_min_u32_e32 v86, v83, v86
	v_max_u32_e32 v83, v76, v82
	v_min_u32_e32 v82, v76, v82
	v_max_u32_e32 v76, v77, v85
	v_min_u32_e32 v85, v77, v85
	v_max_u32_e32 v77, v81, v79
	v_min_u32_e32 v79, v81, v79
	v_max_u32_e32 v81, v84, v78
	v_min_u32_e32 v78, v84, v78
	v_max_u32_e32 v84, v101, v75
	v_min_u32_e32 v75, v101, v75
	v_max_u32_e32 v101, v73, v72
	v_min_u32_e32 v72, v73, v72
	v_max_u32_e32 v73, v71, v80
	v_min_u32_e32 v80, v71, v80
	v_max_u32_e32 v71, v74, v86
	v_min_u32_e32 v86, v74, v86
	v_max_u32_e32 v74, v83, v76
	v_min_u32_e32 v76, v83, v76
	v_max_u32_e32 v83, v82, v85
	v_min_u32_e32 v85, v82, v85
	v_cvt_f32_f16_e32 v82, v16
	v_cvt_f32_f16_sdwa v98, v16 dst_sel:DWORD dst_unused:UNUSED_PAD src0_sel:WORD_1
	v_ashrrev_i32_e32 v93, 31, v82
	v_bitop3_b32 v82, v82, v93, s40 bitop3:0x78
	v_xor_b32_e32 v82, 0x8000005f, v82
	v_ashrrev_i32_e32 v93, 31, v98
	v_bitop3_b32 v98, v98, v93, s40 bitop3:0x78
	v_xor_b32_e32 v98, 0x8000005e, v98
	v_cvt_f32_f16_e32 v93, v17
	v_cvt_f32_f16_sdwa v92, v17 dst_sel:DWORD dst_unused:UNUSED_PAD src0_sel:WORD_1
	v_ashrrev_i32_e32 v97, 31, v93
	v_bitop3_b32 v93, v93, v97, s40 bitop3:0x78
	v_xor_b32_e32 v93, 0x8000005d, v93
	v_ashrrev_i32_e32 v97, 31, v92
	v_bitop3_b32 v92, v92, v97, s40 bitop3:0x78
	v_xor_b32_e32 v92, 0x8000005c, v92
	v_cvt_f32_f16_e32 v97, v18
	v_cvt_f32_f16_sdwa v102, v18 dst_sel:DWORD dst_unused:UNUSED_PAD src0_sel:WORD_1
	v_ashrrev_i32_e32 v90, 31, v97
	v_bitop3_b32 v97, v97, v90, s40 bitop3:0x78
	v_xor_b32_e32 v97, 0x8000005b, v97
	v_ashrrev_i32_e32 v90, 31, v102
	v_bitop3_b32 v102, v102, v90, s40 bitop3:0x78
	v_xor_b32_e32 v102, 0x8000005a, v102
	v_cvt_f32_f16_e32 v90, v19
	v_cvt_f32_f16_sdwa v99, v19 dst_sel:DWORD dst_unused:UNUSED_PAD src0_sel:WORD_1
	v_ashrrev_i32_e32 v95, 31, v90
	v_bitop3_b32 v90, v90, v95, s40 bitop3:0x78
	v_xor_b32_e32 v90, 0x80000059, v90
	v_ashrrev_i32_e32 v95, 31, v99
	v_bitop3_b32 v99, v99, v95, s40 bitop3:0x78
	v_xor_b32_e32 v99, 0x80000058, v99
	v_cvt_f32_f16_e32 v95, v20
	v_cvt_f32_f16_sdwa v88, v20 dst_sel:DWORD dst_unused:UNUSED_PAD src0_sel:WORD_1
	v_ashrrev_i32_e32 v89, 31, v95
	v_bitop3_b32 v95, v95, v89, s40 bitop3:0x78
	v_xor_b32_e32 v95, 0x80000057, v95
	v_ashrrev_i32_e32 v89, 31, v88
	v_bitop3_b32 v88, v88, v89, s40 bitop3:0x78
	v_xor_b32_e32 v88, 0x80000056, v88
	v_cvt_f32_f16_e32 v89, v21
	v_cvt_f32_f16_sdwa v87, v21 dst_sel:DWORD dst_unused:UNUSED_PAD src0_sel:WORD_1
	v_ashrrev_i32_e32 v91, 31, v89
	v_bitop3_b32 v89, v89, v91, s40 bitop3:0x78
	v_xor_b32_e32 v89, 0x80000055, v89
	v_ashrrev_i32_e32 v91, 31, v87
	v_bitop3_b32 v87, v87, v91, s40 bitop3:0x78
	v_xor_b32_e32 v87, 0x80000054, v87
	v_cvt_f32_f16_e32 v91, v22
	v_cvt_f32_f16_sdwa v96, v22 dst_sel:DWORD dst_unused:UNUSED_PAD src0_sel:WORD_1
	v_ashrrev_i32_e32 v94, 31, v91
	v_bitop3_b32 v91, v91, v94, s40 bitop3:0x78
	v_xor_b32_e32 v91, 0x80000053, v91
	v_ashrrev_i32_e32 v94, 31, v96
	v_bitop3_b32 v96, v96, v94, s40 bitop3:0x78
	v_xor_b32_e32 v96, 0x80000052, v96
	v_cvt_f32_f16_e32 v94, v23
	v_cvt_f32_f16_sdwa v100, v23 dst_sel:DWORD dst_unused:UNUSED_PAD src0_sel:WORD_1
	v_ashrrev_i32_e32 v70, 31, v94
	v_bitop3_b32 v94, v94, v70, s40 bitop3:0x78
	v_xor_b32_e32 v94, 0x80000051, v94
	v_ashrrev_i32_e32 v70, 31, v100
	v_bitop3_b32 v100, v100, v70, s40 bitop3:0x78
	v_xor_b32_e32 v100, 0x80000050, v100
	v_max_u32_e32 v70, v82, v96
	v_min_u32_e32 v96, v82, v96
	v_max_u32_e32 v82, v98, v91
	v_min_u32_e32 v91, v98, v91
	v_max_u32_e32 v98, v93, v100
	v_min_u32_e32 v100, v93, v100
	v_max_u32_e32 v93, v92, v94
	v_min_u32_e32 v94, v92, v94
	v_max_u32_e32 v92, v97, v95
	v_min_u32_e32 v95, v97, v95
	v_max_u32_e32 v97, v102, v90
	v_min_u32_e32 v90, v102, v90
	v_max_u32_e32 v102, v99, v87
	v_min_u32_e32 v87, v99, v87
	v_max_u32_e32 v99, v88, v89
	v_min_u32_e32 v89, v88, v89
	v_max_u32_e32 v88, v70, v97
	v_min_u32_e32 v97, v70, v97
	v_max_u32_e32 v70, v82, v102
	v_min_u32_e32 v102, v82, v102
	v_max_u32_e32 v82, v98, v99
	v_min_u32_e32 v99, v98, v99
	v_max_u32_e32 v98, v93, v92
	v_min_u32_e32 v92, v93, v92
	v_max_u32_e32 v93, v90, v96
	v_min_u32_e32 v96, v90, v96
	v_max_u32_e32 v90, v95, v94
	v_min_u32_e32 v94, v95, v94
	v_max_u32_e32 v95, v89, v100
	v_min_u32_e32 v100, v89, v100
	v_max_u32_e32 v89, v87, v91
	v_min_u32_e32 v91, v87, v91
	v_max_u32_e32 v87, v88, v70
	v_min_u32_e32 v70, v88, v70
	v_max_u32_e32 v88, v82, v98
	v_min_u32_e32 v98, v82, v98
	v_max_u32_e32 v82, v92, v97
	v_min_u32_e32 v97, v92, v97
	v_max_u32_e32 v92, v93, v90
	v_min_u32_e32 v90, v93, v90
	v_max_u32_e32 v93, v102, v99
	v_min_u32_e32 v99, v102, v99
	v_max_u32_e32 v102, v95, v89
	v_min_u32_e32 v89, v95, v89
	v_max_u32_e32 v95, v91, v96
	v_min_u32_e32 v96, v91, v96
	v_max_u32_e32 v91, v94, v100
	v_min_u32_e32 v100, v94, v100
	v_max_u32_e32 v94, v87, v88
	v_min_u32_e32 v88, v87, v88
	v_max_u32_e32 v87, v70, v98
	v_min_u32_e32 v98, v70, v98
	v_max_u32_e32 v70, v82, v102
	v_min_u32_e32 v102, v82, v102
	v_max_u32_e32 v82, v97, v89
	v_min_u32_e32 v89, v97, v89
	v_max_u32_e32 v97, v92, v93
	v_min_u32_e32 v93, v92, v93
	v_max_u32_e32 v92, v90, v99
	v_min_u32_e32 v99, v90, v99
	v_max_u32_e32 v90, v95, v91
	v_min_u32_e32 v91, v95, v91
	v_max_u32_e32 v95, v96, v100
	v_min_u32_e32 v100, v96, v100
	v_max_u32_e32 v96, v87, v88
	v_min_u32_e32 v88, v87, v88
	v_max_u32_e32 v87, v98, v90
; __device__ __forceinline__ unsigned f2key(float f) { const unsigned u = __float_as_uint(f); return (u & 0x80000000u) ? ~u : (u | 0x80000000u); }
; #define CE_DESC(a, b) do { const unsigned _mx = (a) > (b) ? (a) : (b), _mn = (a) > (b) ? (b) : (a); (a) = _mx; (b) = _mn; } while (0)
; __device__ __forceinline__ void sort16_desc(unsigned (&k)[16]) {
; #pragma unroll
;     for (int size = 2; size <= 16; size <<= 1)
; #pragma unroll
;         for (int stride = size >> 1; stride > 0; stride >>= 1)
; #pragma unroll
;             for (int i = 0; i < 16; ++i) { const int j = i ^ stride;
;                 if (j > i) { if ((i & size) == 0) CE_DESC(k[i], k[j]); else CE_DESC(k[j], k[i]); } }
; }
; __device__ __forceinline__ void merge16(unsigned (&a)[16], const unsigned (&b)[16]) {
; #pragma unroll
;     for (int i = 0; i < 16; ++i) a[i] = a[i] > b[15 - i] ? a[i] : b[15 - i];
; #pragma unroll
;     for (int stride = 8; stride > 0; stride >>= 1)
; #pragma unroll
;         for (int i = 0; i < 16; ++i) { const int j = i ^ stride; if (j > i) CE_DESC(a[i], a[j]); }
; }
; __device__ __forceinline__ void peer_tile(const Args& A, LAS unsigned char* lds, int tile) {
;     ...
;                   for (int i = 0; i < 16; ++i) {
;                       const float lo = (float)__builtin_bit_cast(_Float16, (unsigned short)(sw[i] & 0xffffu)), hi = (float)__builtin_bit_cast(_Float16, (unsigned short)(sw[i] >> 16));
;                       const unsigned klo = (f2key(lo) & ~127u) | (unsigned)(127 - (32 * g + 2 * i)), khi = (f2key(hi) & ~127u) | (unsigned)(127 - (32 * g + 2 * i + 1));
;                       if (i < 8) { k0[2 * i] = klo; k0[2 * i + 1] = khi; } else { k1[2 * (i - 8)] = klo; k1[2 * (i - 8) + 1] = khi; } } }
;                 sort16_desc(k0); sort16_desc(k1); merge16(k0, k1);
	v_min_u32_e32 v90, v98, v90
	v_max_u32_e32 v98, v70, v97
	v_min_u32_e32 v97, v70, v97
	v_max_u32_e32 v70, v82, v93
	v_min_u32_e32 v93, v82, v93
	v_max_u32_e32 v82, v92, v102
	v_min_u32_e32 v102, v92, v102
	v_max_u32_e32 v92, v99, v89
	v_min_u32_e32 v89, v99, v89
	v_max_u32_e32 v99, v95, v91
	v_min_u32_e32 v91, v95, v91
	v_max_u32_e32 v95, v96, v98
	v_min_u32_e32 v98, v96, v98
	v_max_u32_e32 v96, v88, v97
	v_min_u32_e32 v97, v88, v97
	v_max_u32_e32 v88, v70, v82
	v_min_u32_e32 v82, v70, v82
	v_max_u32_e32 v70, v93, v102
	v_min_u32_e32 v102, v93, v102
	v_max_u32_e32 v93, v92, v99
	v_min_u32_e32 v99, v92, v99
	v_max_u32_e32 v92, v89, v91
	v_min_u32_e32 v91, v89, v91
	v_max_u32_e32 v89, v96, v98
	v_min_u32_e32 v98, v96, v98
	v_max_u32_e32 v96, v87, v97
	v_min_u32_e32 v97, v87, v97
	v_max_u32_e32 v87, v93, v90
	v_min_u32_e32 v90, v93, v90
	v_max_u32_e32 v93, v92, v99
	v_min_u32_e32 v99, v92, v99
	v_max_u32_e32 v92, v96, v88
	v_min_u32_e32 v88, v96, v88
	v_max_u32_e32 v96, v97, v82
	v_min_u32_e32 v82, v97, v82
	v_max_u32_e32 v97, v70, v87
	v_min_u32_e32 v87, v70, v87
	v_max_u32_e32 v70, v102, v90
	v_min_u32_e32 v90, v102, v90
	v_max_u32_e32 v102, v92, v98
	v_min_u32_e32 v98, v92, v98
	v_max_u32_e32 v92, v88, v96
	v_min_u32_e32 v96, v88, v96
	v_max_u32_e32 v88, v97, v82
	v_min_u32_e32 v82, v97, v82
	v_max_u32_e32 v97, v87, v70
	v_min_u32_e32 v70, v87, v70
	v_max_u32_e32 v87, v93, v90
	v_min_u32_e32 v90, v93, v90
	v_max_u32_e32 v93, v96, v88
	v_min_u32_e32 v88, v96, v88
	v_max_u32_e32 v96, v82, v97
	v_min_u32_e32 v97, v82, v97
	v_max_u32_e32 v77, v77, v100
	v_max_u32_e32 v79, v79, v91
	v_max_u32_e32 v81, v81, v99
	v_max_u32_e32 v78, v78, v90
	v_max_u32_e32 v84, v84, v87
	v_max_u32_e32 v75, v75, v70
	v_max_u32_e32 v101, v101, v97
	v_max_u32_e32 v72, v72, v96
	v_max_u32_e32 v73, v73, v88
	v_max_u32_e32 v80, v80, v93
	v_max_u32_e32 v71, v71, v92
	v_max_u32_e32 v86, v86, v98
	v_max_u32_e32 v74, v74, v102
	v_max_u32_e32 v76, v76, v89
	v_max_u32_e32 v83, v83, v95
	v_max_u32_e32 v85, v85, v94
	v_max_u32_e32 v100, v77, v73
	v_min_u32_e32 v73, v77, v73
	v_max_u32_e32 v77, v79, v80
	v_min_u32_e32 v80, v79, v80
	v_max_u32_e32 v79, v81, v71
	v_min_u32_e32 v71, v81, v71
	v_max_u32_e32 v81, v78, v86
	v_min_u32_e32 v86, v78, v86
	v_max_u32_e32 v78, v84, v74
	v_min_u32_e32 v74, v84, v74
	v_max_u32_e32 v84, v75, v76
	v_min_u32_e32 v76, v75, v76
	v_max_u32_e32 v75, v101, v83
	v_min_u32_e32 v83, v101, v83
	v_max_u32_e32 v101, v72, v85
	v_min_u32_e32 v85, v72, v85
	v_max_u32_e32 v72, v100, v78
	v_min_u32_e32 v78, v100, v78
	v_max_u32_e32 v100, v77, v84
	v_min_u32_e32 v84, v77, v84
	v_max_u32_e32 v77, v79, v75
	v_min_u32_e32 v75, v79, v75
	v_max_u32_e32 v79, v81, v101
	v_min_u32_e32 v101, v81, v101
	v_max_u32_e32 v81, v73, v74
	v_min_u32_e32 v74, v73, v74
	v_max_u32_e32 v73, v80, v76
	v_min_u32_e32 v76, v80, v76
	v_max_u32_e32 v80, v71, v83
	v_min_u32_e32 v83, v71, v83
	v_max_u32_e32 v71, v86, v85
	v_min_u32_e32 v85, v86, v85
	v_max_u32_e32 v86, v72, v77
	v_min_u32_e32 v77, v72, v77
	v_max_u32_e32 v72, v100, v79
	v_min_u32_e32 v79, v100, v79
	v_max_u32_e32 v100, v78, v75
	v_min_u32_e32 v75, v78, v75
	v_max_u32_e32 v78, v84, v101
	v_min_u32_e32 v101, v84, v101
	v_max_u32_e32 v84, v81, v80
	v_min_u32_e32 v80, v81, v80
	v_max_u32_e32 v81, v73, v71
	v_min_u32_e32 v71, v73, v71
	v_max_u32_e32 v73, v74, v83
	v_min_u32_e32 v83, v74, v83
	v_max_u32_e32 v74, v76, v85
	v_min_u32_e32 v85, v76, v85
	v_max_u32_e32 v76, v86, v72
	v_min_u32_e32 v72, v86, v72
	v_max_u32_e32 v86, v77, v79
	v_min_u32_e32 v79, v77, v79
	v_max_u32_e32 v77, v100, v78
	v_min_u32_e32 v78, v100, v78
	v_max_u32_e32 v100, v75, v101
	v_min_u32_e32 v101, v75, v101
	v_max_u32_e32 v75, v84, v81
	v_min_u32_e32 v81, v84, v81
	v_max_u32_e32 v84, v80, v71
	v_min_u32_e32 v71, v80, v71
	v_max_u32_e32 v80, v73, v74
	v_min_u32_e32 v74, v73, v74
	v_max_u32_e32 v73, v83, v85
	v_min_u32_e32 v85, v83, v85
	v_cvt_f32_f16_e32 v83, v24
	v_cvt_f32_f16_sdwa v91, v24 dst_sel:DWORD dst_unused:UNUSED_PAD src0_sel:WORD_1
	v_ashrrev_i32_e32 v99, 31, v83
	v_bitop3_b32 v83, v83, v99, s40 bitop3:0x78
	v_xor_b32_e32 v83, 0x8000004f, v83
	v_ashrrev_i32_e32 v99, 31, v91
	v_bitop3_b32 v91, v91, v99, s40 bitop3:0x78
	v_xor_b32_e32 v91, 0x8000004e, v91
	v_cvt_f32_f16_e32 v99, v25
	v_cvt_f32_f16_sdwa v90, v25 dst_sel:DWORD dst_unused:UNUSED_PAD src0_sel:WORD_1
	v_ashrrev_i32_e32 v87, 31, v99
	v_bitop3_b32 v99, v99, v87, s40 bitop3:0x78
	v_xor_b32_e32 v99, 0x8000004d, v99
	v_ashrrev_i32_e32 v87, 31, v90
	v_bitop3_b32 v90, v90, v87, s40 bitop3:0x78
	v_xor_b32_e32 v90, 0x8000004c, v90
	v_cvt_f32_f16_e32 v87, v26
	v_cvt_f32_f16_sdwa v70, v26 dst_sel:DWORD dst_unused:UNUSED_PAD src0_sel:WORD_1
	v_ashrrev_i32_e32 v97, 31, v87
	v_bitop3_b32 v87, v87, v97, s40 bitop3:0x78
	v_xor_b32_e32 v87, 0x8000004b, v87
	v_ashrrev_i32_e32 v97, 31, v70
	v_bitop3_b32 v70, v70, v97, s40 bitop3:0x78
	v_xor_b32_e32 v70, 0x8000004a, v70
	v_cvt_f32_f16_e32 v97, v27
	v_cvt_f32_f16_sdwa v96, v27 dst_sel:DWORD dst_unused:UNUSED_PAD src0_sel:WORD_1
	v_ashrrev_i32_e32 v88, 31, v97
	v_bitop3_b32 v97, v97, v88, s40 bitop3:0x78
	v_xor_b32_e32 v97, 0x80000049, v97
	v_ashrrev_i32_e32 v88, 31, v96
	v_bitop3_b32 v96, v96, v88, s40 bitop3:0x78
	v_xor_b32_e32 v96, 0x80000048, v96
	v_cvt_f32_f16_e32 v88, v28
	v_cvt_f32_f16_sdwa v93, v28 dst_sel:DWORD dst_unused:UNUSED_PAD src0_sel:WORD_1
	v_ashrrev_i32_e32 v92, 31, v88
	v_bitop3_b32 v88, v88, v92, s40 bitop3:0x78
	v_xor_b32_e32 v88, 0x80000047, v88
	v_ashrrev_i32_e32 v92, 31, v93
	v_bitop3_b32 v93, v93, v92, s40 bitop3:0x78
	v_xor_b32_e32 v93, 0x80000046, v93
	v_cvt_f32_f16_e32 v92, v29
	v_cvt_f32_f16_sdwa v98, v29 dst_sel:DWORD dst_unused:UNUSED_PAD src0_sel:WORD_1
; __device__ __forceinline__ unsigned f2key(float f) { const unsigned u = __float_as_uint(f); return (u & 0x80000000u) ? ~u : (u | 0x80000000u); }
; #define CE_DESC(a, b) do { const unsigned _mx = (a) > (b) ? (a) : (b), _mn = (a) > (b) ? (b) : (a); (a) = _mx; (b) = _mn; } while (0)
; __device__ __forceinline__ void sort16_desc(unsigned (&k)[16]) {
; #pragma unroll
;     for (int size = 2; size <= 16; size <<= 1)
; #pragma unroll
;         for (int stride = size >> 1; stride > 0; stride >>= 1)
; #pragma unroll
;             for (int i = 0; i < 16; ++i) { const int j = i ^ stride;
;                 if (j > i) { if ((i & size) == 0) CE_DESC(k[i], k[j]); else CE_DESC(k[j], k[i]); } }
; }
; __device__ __forceinline__ void merge16(unsigned (&a)[16], const unsigned (&b)[16]) {
; #pragma unroll
;     for (int i = 0; i < 16; ++i) a[i] = a[i] > b[15 - i] ? a[i] : b[15 - i];
; #pragma unroll
;     for (int stride = 8; stride > 0; stride >>= 1)
; #pragma unroll
;         for (int i = 0; i < 16; ++i) { const int j = i ^ stride; if (j > i) CE_DESC(a[i], a[j]); }
; }
; __device__ __forceinline__ void peer_tile(const Args& A, LAS unsigned char* lds, int tile) {
;     ...
;                   for (int i = 0; i < 16; ++i) {
;                       const float lo = (float)__builtin_bit_cast(_Float16, (unsigned short)(sw[i] & 0xffffu)), hi = (float)__builtin_bit_cast(_Float16, (unsigned short)(sw[i] >> 16));
;                       const unsigned klo = (f2key(lo) & ~127u) | (unsigned)(127 - (32 * g + 2 * i)), khi = (f2key(hi) & ~127u) | (unsigned)(127 - (32 * g + 2 * i + 1));
;                       if (i < 8) { k0[2 * i] = klo; k0[2 * i + 1] = khi; } else { k1[2 * (i - 8)] = klo; k1[2 * (i - 8) + 1] = khi; } } }
;                 sort16_desc(k0); sort16_desc(k1); merge16(k0, k1);
	v_ashrrev_i32_e32 v102, 31, v92
	v_bitop3_b32 v92, v92, v102, s40 bitop3:0x78
	v_xor_b32_e32 v92, 0x80000045, v92
	v_ashrrev_i32_e32 v102, 31, v98
	v_bitop3_b32 v98, v98, v102, s40 bitop3:0x78
	v_xor_b32_e32 v98, 0x80000044, v98
	v_cvt_f32_f16_e32 v102, v30
	v_cvt_f32_f16_sdwa v89, v30 dst_sel:DWORD dst_unused:UNUSED_PAD src0_sel:WORD_1
	v_ashrrev_i32_e32 v95, 31, v102
	v_bitop3_b32 v102, v102, v95, s40 bitop3:0x78
	v_xor_b32_e32 v102, 0x80000043, v102
	v_ashrrev_i32_e32 v95, 31, v89
	v_bitop3_b32 v89, v89, v95, s40 bitop3:0x78
	v_xor_b32_e32 v89, 0x80000042, v89
	v_cvt_f32_f16_e32 v95, v31
	v_cvt_f32_f16_sdwa v94, v31 dst_sel:DWORD dst_unused:UNUSED_PAD src0_sel:WORD_1
	v_ashrrev_i32_e32 v82, 31, v95
	v_bitop3_b32 v95, v95, v82, s40 bitop3:0x78
	v_xor_b32_e32 v95, 0x80000041, v95
	v_ashrrev_i32_e32 v82, 31, v94
	v_bitop3_b32 v94, v94, v82, s40 bitop3:0x78
	v_xor_b32_e32 v94, 0x80000040, v94
	v_max_u32_e32 v82, v83, v89
	v_min_u32_e32 v89, v83, v89
	v_max_u32_e32 v83, v91, v102
	v_min_u32_e32 v102, v91, v102
	v_max_u32_e32 v91, v99, v94
	v_min_u32_e32 v94, v99, v94
	v_max_u32_e32 v99, v90, v95
	v_min_u32_e32 v95, v90, v95
	v_max_u32_e32 v90, v87, v88
	v_min_u32_e32 v88, v87, v88
	v_max_u32_e32 v87, v70, v97
	v_min_u32_e32 v97, v70, v97
	v_max_u32_e32 v70, v96, v98
	v_min_u32_e32 v98, v96, v98
	v_max_u32_e32 v96, v93, v92
	v_min_u32_e32 v92, v93, v92
	v_max_u32_e32 v93, v82, v87
	v_min_u32_e32 v87, v82, v87
	v_max_u32_e32 v82, v83, v70
	v_min_u32_e32 v70, v83, v70
	v_max_u32_e32 v83, v91, v96
	v_min_u32_e32 v96, v91, v96
	v_max_u32_e32 v91, v99, v90
	v_min_u32_e32 v90, v99, v90
	v_max_u32_e32 v99, v97, v89
	v_min_u32_e32 v89, v97, v89
	v_max_u32_e32 v97, v88, v95
	v_min_u32_e32 v95, v88, v95
	v_max_u32_e32 v88, v92, v94
	v_min_u32_e32 v94, v92, v94
	v_max_u32_e32 v92, v98, v102
	v_min_u32_e32 v102, v98, v102
	v_max_u32_e32 v98, v93, v82
	v_min_u32_e32 v82, v93, v82
	v_max_u32_e32 v93, v83, v91
	v_min_u32_e32 v91, v83, v91
	v_max_u32_e32 v83, v90, v87
	v_min_u32_e32 v87, v90, v87
	v_max_u32_e32 v90, v99, v97
	v_min_u32_e32 v97, v99, v97
	v_max_u32_e32 v99, v70, v96
	v_min_u32_e32 v96, v70, v96
	v_max_u32_e32 v70, v88, v92
	v_min_u32_e32 v92, v88, v92
	v_max_u32_e32 v88, v102, v89
	v_min_u32_e32 v89, v102, v89
	v_max_u32_e32 v102, v95, v94
	v_min_u32_e32 v94, v95, v94
	v_max_u32_e32 v95, v98, v93
	v_min_u32_e32 v93, v98, v93
	v_max_u32_e32 v98, v82, v91
	v_min_u32_e32 v91, v82, v91
	v_max_u32_e32 v82, v83, v70
	v_min_u32_e32 v70, v83, v70
	v_max_u32_e32 v83, v87, v92
	v_min_u32_e32 v92, v87, v92
	v_max_u32_e32 v87, v90, v99
	v_min_u32_e32 v99, v90, v99
	v_max_u32_e32 v90, v97, v96
	v_min_u32_e32 v96, v97, v96
	v_max_u32_e32 v97, v88, v102
	v_min_u32_e32 v102, v88, v102
	v_max_u32_e32 v88, v89, v94
	v_min_u32_e32 v94, v89, v94
	v_max_u32_e32 v89, v98, v93
	v_min_u32_e32 v93, v98, v93
	v_max_u32_e32 v98, v91, v97
	v_min_u32_e32 v97, v91, v97
	v_max_u32_e32 v91, v82, v87
	v_min_u32_e32 v87, v82, v87
	v_max_u32_e32 v82, v83, v99
	v_min_u32_e32 v99, v83, v99
	v_max_u32_e32 v83, v90, v70
	v_min_u32_e32 v70, v90, v70
	v_max_u32_e32 v90, v96, v92
	v_min_u32_e32 v92, v96, v92
	v_max_u32_e32 v96, v88, v102
	v_min_u32_e32 v102, v88, v102
	v_max_u32_e32 v88, v89, v91
	v_min_u32_e32 v91, v89, v91
	v_max_u32_e32 v89, v93, v87
	v_min_u32_e32 v87, v93, v87
	v_max_u32_e32 v93, v82, v83
	v_min_u32_e32 v83, v82, v83
	v_max_u32_e32 v82, v99, v70
	v_min_u32_e32 v70, v99, v70
	v_max_u32_e32 v99, v90, v96
	v_min_u32_e32 v96, v90, v96
	v_max_u32_e32 v90, v92, v102
	v_min_u32_e32 v102, v92, v102
	v_max_u32_e32 v92, v89, v91
	v_min_u32_e32 v91, v89, v91
	v_max_u32_e32 v89, v98, v87
	v_min_u32_e32 v87, v98, v87
	v_max_u32_e32 v98, v99, v97
	v_min_u32_e32 v97, v99, v97
	v_max_u32_e32 v99, v90, v96
	v_min_u32_e32 v96, v90, v96
	v_max_u32_e32 v90, v89, v93
	v_min_u32_e32 v93, v89, v93
	v_max_u32_e32 v89, v87, v83
	v_min_u32_e32 v83, v87, v83
	v_max_u32_e32 v87, v82, v98
	v_min_u32_e32 v98, v82, v98
	v_max_u32_e32 v82, v70, v97
	v_min_u32_e32 v97, v70, v97
	v_max_u32_e32 v70, v90, v91
	v_min_u32_e32 v91, v90, v91
	v_max_u32_e32 v90, v93, v89
	v_min_u32_e32 v89, v93, v89
	v_max_u32_e32 v93, v87, v83
	v_min_u32_e32 v83, v87, v83
	v_max_u32_e32 v87, v98, v82
	v_min_u32_e32 v82, v98, v82
	v_max_u32_e32 v98, v99, v97
	v_min_u32_e32 v97, v99, v97
	v_max_u32_e32 v99, v89, v93
	v_min_u32_e32 v93, v89, v93
	v_max_u32_e32 v89, v83, v87
	v_min_u32_e32 v87, v83, v87
	v_max_u32_e32 v76, v76, v94
	v_max_u32_e32 v72, v72, v102
	v_max_u32_e32 v86, v86, v96
	v_max_u32_e32 v79, v79, v97
	v_max_u32_e32 v77, v77, v98
	v_max_u32_e32 v78, v78, v82
	v_max_u32_e32 v100, v100, v87
	v_max_u32_e32 v101, v101, v89
	v_max_u32_e32 v75, v75, v93
	v_max_u32_e32 v81, v81, v99
	v_max_u32_e32 v84, v84, v90
	v_max_u32_e32 v71, v71, v91
	v_max_u32_e32 v80, v80, v70
	v_max_u32_e32 v74, v74, v92
	v_max_u32_e32 v73, v73, v88
	v_max_u32_e32 v85, v85, v95
	v_max_u32_e32 v94, v76, v75
	v_min_u32_e32 v75, v76, v75
	v_max_u32_e32 v76, v72, v81
	v_min_u32_e32 v81, v72, v81
	v_max_u32_e32 v72, v86, v84
	v_min_u32_e32 v84, v86, v84
	v_max_u32_e32 v86, v79, v71
	v_min_u32_e32 v71, v79, v71
	v_max_u32_e32 v79, v77, v80
	v_min_u32_e32 v80, v77, v80
	v_max_u32_e32 v77, v78, v74
	v_min_u32_e32 v74, v78, v74
	v_max_u32_e32 v78, v100, v73
	v_min_u32_e32 v73, v100, v73
	v_max_u32_e32 v100, v101, v85
	v_min_u32_e32 v85, v101, v85
	v_max_u32_e32 v101, v94, v79
	v_min_u32_e32 v79, v94, v79
	v_max_u32_e32 v94, v76, v77
	v_min_u32_e32 v77, v76, v77
	v_max_u32_e32 v76, v72, v78
	v_min_u32_e32 v78, v72, v78
	v_max_u32_e32 v72, v86, v100
	v_min_u32_e32 v100, v86, v100
	v_max_u32_e32 v86, v75, v80
	v_min_u32_e32 v80, v75, v80
; __device__ __forceinline__ unsigned f2key(float f) { const unsigned u = __float_as_uint(f); return (u & 0x80000000u) ? ~u : (u | 0x80000000u); }
; #define CE_DESC(a, b) do { const unsigned _mx = (a) > (b) ? (a) : (b), _mn = (a) > (b) ? (b) : (a); (a) = _mx; (b) = _mn; } while (0)
; __device__ __forceinline__ void sort16_desc(unsigned (&k)[16]) {
; #pragma unroll
;     for (int size = 2; size <= 16; size <<= 1)
; #pragma unroll
;         for (int stride = size >> 1; stride > 0; stride >>= 1)
; #pragma unroll
;             for (int i = 0; i < 16; ++i) { const int j = i ^ stride;
;                 if (j > i) { if ((i & size) == 0) CE_DESC(k[i], k[j]); else CE_DESC(k[j], k[i]); } }
; }
; __device__ __forceinline__ void merge16(unsigned (&a)[16], const unsigned (&b)[16]) {
; #pragma unroll
;     for (int i = 0; i < 16; ++i) a[i] = a[i] > b[15 - i] ? a[i] : b[15 - i];
; #pragma unroll
;     for (int stride = 8; stride > 0; stride >>= 1)
; #pragma unroll
;         for (int i = 0; i < 16; ++i) { const int j = i ^ stride; if (j > i) CE_DESC(a[i], a[j]); }
; }
; __device__ __forceinline__ void peer_tile(const Args& A, LAS unsigned char* lds, int tile) {
;     ...
;                 { const bf16_t* sp = QRY + m * 2048 + hp * 128 + 32 * g;
;                   const u32x4 s0 = *(const u32x4*)sp, s1 = *(const u32x4*)(sp + 8), s2 = *(const u32x4*)(sp + 16), s3 = *(const u32x4*)(sp + 24);
;                   const unsigned sw[16] = {s0.x, s0.y, s0.z, s0.w, s1.x, s1.y, s1.z, s1.w, s2.x, s2.y, s2.z, s2.w, s3.x, s3.y, s3.z, s3.w};
; #pragma unroll
;                   for (int i = 0; i < 16; ++i) {
;                       const float lo = (float)__builtin_bit_cast(_Float16, (unsigned short)(sw[i] & 0xffffu)), hi = (float)__builtin_bit_cast(_Float16, (unsigned short)(sw[i] >> 16));
;                       const unsigned klo = (f2key(lo) & ~127u) | (unsigned)(127 - (32 * g + 2 * i)), khi = (f2key(hi) & ~127u) | (unsigned)(127 - (32 * g + 2 * i + 1));
;                       if (i < 8) { k0[2 * i] = klo; k0[2 * i + 1] = khi; } else { k1[2 * (i - 8)] = klo; k1[2 * (i - 8) + 1] = khi; } } }
	v_max_u32_e32 v75, v81, v74
	v_min_u32_e32 v74, v81, v74
	v_max_u32_e32 v81, v84, v73
	v_min_u32_e32 v73, v84, v73
	v_max_u32_e32 v84, v71, v85
	v_min_u32_e32 v85, v71, v85
	v_max_u32_e32 v71, v101, v76
	v_min_u32_e32 v76, v101, v76
	v_max_u32_e32 v101, v94, v72
	v_min_u32_e32 v72, v94, v72
	v_max_u32_e32 v94, v79, v78
	v_min_u32_e32 v78, v79, v78
	v_max_u32_e32 v79, v77, v100
	v_min_u32_e32 v100, v77, v100
	v_max_u32_e32 v77, v86, v81
	v_min_u32_e32 v81, v86, v81
	v_max_u32_e32 v86, v75, v84
	v_min_u32_e32 v84, v75, v84
	v_max_u32_e32 v75, v80, v73
	v_min_u32_e32 v73, v80, v73
	v_max_u32_e32 v80, v74, v85
	v_min_u32_e32 v85, v74, v85
	v_max_u32_e32 v74, v71, v101
	v_min_u32_e32 v101, v71, v101
	v_max_u32_e32 v71, v76, v72
	v_min_u32_e32 v72, v76, v72
	v_max_u32_e32 v76, v94, v79
	v_min_u32_e32 v79, v94, v79
	v_max_u32_e32 v94, v78, v100
	v_min_u32_e32 v100, v78, v100
	v_max_u32_e32 v78, v77, v86
	v_min_u32_e32 v86, v77, v86
	v_max_u32_e32 v77, v81, v84
	v_min_u32_e32 v84, v81, v84
	v_max_u32_e32 v81, v75, v80
	v_min_u32_e32 v80, v75, v80
	v_max_u32_e32 v75, v73, v85
	v_min_u32_e32 v85, v73, v85
	s_mov_b64 s[38:39], s[34:35]
	global_load_dwordx4 v[0:3], v66, s[38:39] offset:256
	s_add_u32 s38, s38, 0x8000
	s_addc_u32 s39, s39, 0
	global_load_dwordx4 v[4:7], v66, s[38:39] offset:256
	s_add_u32 s38, s38, 0x8000
	s_addc_u32 s39, s39, 0
	global_load_dwordx4 v[8:11], v66, s[38:39] offset:256
	s_add_u32 s38, s38, 0x8000
	s_addc_u32 s39, s39, 0
	global_load_dwordx4 v[12:15], v66, s[38:39] offset:256
	s_add_u32 s38, s38, 0x8000
	s_addc_u32 s39, s39, 0
	global_load_dwordx4 v[16:19], v66, s[38:39] offset:256
	s_add_u32 s38, s38, 0x8000
	s_addc_u32 s39, s39, 0
	global_load_dwordx4 v[20:23], v66, s[38:39] offset:256
	s_add_u32 s38, s38, 0x8000
	s_addc_u32 s39, s39, 0
	global_load_dwordx4 v[24:27], v66, s[38:39] offset:256
	s_add_u32 s38, s38, 0x8000
	s_addc_u32 s39, s39, 0
	global_load_dwordx4 v[28:31], v66, s[38:39] offset:256
	s_waitcnt vmcnt(8)
	ds_write_b128 v64, v[32:35] offset:0
	ds_write_b128 v64, v[36:39] offset:1152
	ds_write_b128 v64, v[40:43] offset:2304
	ds_write_b128 v64, v[44:47] offset:3456
	ds_write_b128 v64, v[48:51] offset:4608
	ds_write_b128 v64, v[52:55] offset:5760
	ds_write_b128 v64, v[56:59] offset:6912
	ds_write_b128 v64, v[60:63] offset:8064
	s_waitcnt lgkmcnt(0)
	ds_read_b128 v[32:35], v65 offset:0
	ds_read_b128 v[36:39], v65 offset:16
	ds_read_b128 v[40:43], v65 offset:32
	ds_read_b128 v[44:47], v65 offset:48
	ds_read_b128 v[48:51], v65 offset:64
	ds_read_b128 v[52:55], v65 offset:80
	ds_read_b128 v[56:59], v65 offset:96
	ds_read_b128 v[60:63], v65 offset:112
	s_waitcnt lgkmcnt(0)
	v_cvt_f32_f16_e32 v73, v32
	v_cvt_f32_f16_sdwa v102, v32 dst_sel:DWORD dst_unused:UNUSED_PAD src0_sel:WORD_1
	v_ashrrev_i32_e32 v96, 31, v73
	v_bitop3_b32 v73, v73, v96, s40 bitop3:0x78
	v_xor_b32_e32 v73, 0x8000003f, v73
	v_ashrrev_i32_e32 v96, 31, v102
	v_bitop3_b32 v102, v102, v96, s40 bitop3:0x78
	v_xor_b32_e32 v102, 0x8000003e, v102
	v_cvt_f32_f16_e32 v96, v33
	v_cvt_f32_f16_sdwa v97, v33 dst_sel:DWORD dst_unused:UNUSED_PAD src0_sel:WORD_1
	v_ashrrev_i32_e32 v98, 31, v96
	v_bitop3_b32 v96, v96, v98, s40 bitop3:0x78
	v_xor_b32_e32 v96, 0x8000003d, v96
	v_ashrrev_i32_e32 v98, 31, v97
	v_bitop3_b32 v97, v97, v98, s40 bitop3:0x78
	v_xor_b32_e32 v97, 0x8000003c, v97
	v_cvt_f32_f16_e32 v98, v34
	v_cvt_f32_f16_sdwa v82, v34 dst_sel:DWORD dst_unused:UNUSED_PAD src0_sel:WORD_1
	v_ashrrev_i32_e32 v87, 31, v98
	v_bitop3_b32 v98, v98, v87, s40 bitop3:0x78
	v_xor_b32_e32 v98, 0x8000003b, v98
	v_ashrrev_i32_e32 v87, 31, v82
	v_bitop3_b32 v82, v82, v87, s40 bitop3:0x78
	v_xor_b32_e32 v82, 0x8000003a, v82
	v_cvt_f32_f16_e32 v87, v35
	v_cvt_f32_f16_sdwa v89, v35 dst_sel:DWORD dst_unused:UNUSED_PAD src0_sel:WORD_1
	v_ashrrev_i32_e32 v93, 31, v87
	v_bitop3_b32 v87, v87, v93, s40 bitop3:0x78
	v_xor_b32_e32 v87, 0x80000039, v87
	v_ashrrev_i32_e32 v93, 31, v89
	v_bitop3_b32 v89, v89, v93, s40 bitop3:0x78
	v_xor_b32_e32 v89, 0x80000038, v89
	v_cvt_f32_f16_e32 v93, v36
	v_cvt_f32_f16_sdwa v99, v36 dst_sel:DWORD dst_unused:UNUSED_PAD src0_sel:WORD_1
	v_ashrrev_i32_e32 v90, 31, v93
	v_bitop3_b32 v93, v93, v90, s40 bitop3:0x78
	v_xor_b32_e32 v93, 0x80000037, v93
	v_ashrrev_i32_e32 v90, 31, v99
	v_bitop3_b32 v99, v99, v90, s40 bitop3:0x78
	v_xor_b32_e32 v99, 0x80000036, v99
	v_cvt_f32_f16_e32 v90, v37
	v_cvt_f32_f16_sdwa v91, v37 dst_sel:DWORD dst_unused:UNUSED_PAD src0_sel:WORD_1
	v_ashrrev_i32_e32 v70, 31, v90
	v_bitop3_b32 v90, v90, v70, s40 bitop3:0x78
	v_xor_b32_e32 v90, 0x80000035, v90
	v_ashrrev_i32_e32 v70, 31, v91
	v_bitop3_b32 v91, v91, v70, s40 bitop3:0x78
	v_xor_b32_e32 v91, 0x80000034, v91
	v_cvt_f32_f16_e32 v70, v38
	v_cvt_f32_f16_sdwa v92, v38 dst_sel:DWORD dst_unused:UNUSED_PAD src0_sel:WORD_1
	v_ashrrev_i32_e32 v88, 31, v70
	v_bitop3_b32 v70, v70, v88, s40 bitop3:0x78
	v_xor_b32_e32 v70, 0x80000033, v70
	v_ashrrev_i32_e32 v88, 31, v92
	v_bitop3_b32 v92, v92, v88, s40 bitop3:0x78
	v_xor_b32_e32 v92, 0x80000032, v92
	v_cvt_f32_f16_e32 v88, v39
	v_cvt_f32_f16_sdwa v95, v39 dst_sel:DWORD dst_unused:UNUSED_PAD src0_sel:WORD_1
	v_ashrrev_i32_e32 v83, 31, v88
	v_bitop3_b32 v88, v88, v83, s40 bitop3:0x78
	v_xor_b32_e32 v88, 0x80000031, v88
	v_ashrrev_i32_e32 v83, 31, v95
	v_bitop3_b32 v95, v95, v83, s40 bitop3:0x78
	v_xor_b32_e32 v95, 0x80000030, v95
	v_max_u32_e32 v83, v73, v92
	v_min_u32_e32 v92, v73, v92
	v_max_u32_e32 v73, v102, v70
	v_min_u32_e32 v70, v102, v70
	v_max_u32_e32 v102, v96, v95
	v_min_u32_e32 v95, v96, v95
	v_max_u32_e32 v96, v97, v88
	v_min_u32_e32 v88, v97, v88
	v_max_u32_e32 v97, v98, v93
	v_min_u32_e32 v93, v98, v93
	v_max_u32_e32 v98, v82, v87
; __device__ __forceinline__ unsigned f2key(float f) { const unsigned u = __float_as_uint(f); return (u & 0x80000000u) ? ~u : (u | 0x80000000u); }
; #define CE_DESC(a, b) do { const unsigned _mx = (a) > (b) ? (a) : (b), _mn = (a) > (b) ? (b) : (a); (a) = _mx; (b) = _mn; } while (0)
; __device__ __forceinline__ void sort16_desc(unsigned (&k)[16]) {
; #pragma unroll
;     for (int size = 2; size <= 16; size <<= 1)
; #pragma unroll
;         for (int stride = size >> 1; stride > 0; stride >>= 1)
; #pragma unroll
;             for (int i = 0; i < 16; ++i) { const int j = i ^ stride;
;                 if (j > i) { if ((i & size) == 0) CE_DESC(k[i], k[j]); else CE_DESC(k[j], k[i]); } }
; }
; __device__ __forceinline__ void merge16(unsigned (&a)[16], const unsigned (&b)[16]) {
; #pragma unroll
;     for (int i = 0; i < 16; ++i) a[i] = a[i] > b[15 - i] ? a[i] : b[15 - i];
; #pragma unroll
;     for (int stride = 8; stride > 0; stride >>= 1)
; #pragma unroll
;         for (int i = 0; i < 16; ++i) { const int j = i ^ stride; if (j > i) CE_DESC(a[i], a[j]); }
; }
; __device__ __forceinline__ void peer_tile(const Args& A, LAS unsigned char* lds, int tile) {
;     ...
;                   for (int i = 0; i < 16; ++i) {
;                       const float lo = (float)__builtin_bit_cast(_Float16, (unsigned short)(sw[i] & 0xffffu)), hi = (float)__builtin_bit_cast(_Float16, (unsigned short)(sw[i] >> 16));
;                       const unsigned klo = (f2key(lo) & ~127u) | (unsigned)(127 - (32 * g + 2 * i)), khi = (f2key(hi) & ~127u) | (unsigned)(127 - (32 * g + 2 * i + 1));
;                       if (i < 8) { k0[2 * i] = klo; k0[2 * i + 1] = khi; } else { k1[2 * (i - 8)] = klo; k1[2 * (i - 8) + 1] = khi; } } }
;                 sort16_desc(k0); sort16_desc(k1); merge16(k0, k1);
	v_min_u32_e32 v87, v82, v87
	v_max_u32_e32 v82, v89, v91
	v_min_u32_e32 v91, v89, v91
	v_max_u32_e32 v89, v99, v90
	v_min_u32_e32 v90, v99, v90
	v_max_u32_e32 v99, v83, v98
	v_min_u32_e32 v98, v83, v98
	v_max_u32_e32 v83, v73, v82
	v_min_u32_e32 v82, v73, v82
	v_max_u32_e32 v73, v102, v89
	v_min_u32_e32 v89, v102, v89
	v_max_u32_e32 v102, v96, v97
	v_min_u32_e32 v97, v96, v97
	v_max_u32_e32 v96, v87, v92
	v_min_u32_e32 v92, v87, v92
	v_max_u32_e32 v87, v93, v88
	v_min_u32_e32 v88, v93, v88
	v_max_u32_e32 v93, v90, v95
	v_min_u32_e32 v95, v90, v95
	v_max_u32_e32 v90, v91, v70
	v_min_u32_e32 v70, v91, v70
	v_max_u32_e32 v91, v99, v83
	v_min_u32_e32 v83, v99, v83
	v_max_u32_e32 v99, v73, v102
	v_min_u32_e32 v102, v73, v102
	v_max_u32_e32 v73, v97, v98
	v_min_u32_e32 v98, v97, v98
	v_max_u32_e32 v97, v96, v87
	v_min_u32_e32 v87, v96, v87
	v_max_u32_e32 v96, v82, v89
	v_min_u32_e32 v89, v82, v89
	v_max_u32_e32 v82, v93, v90
	v_min_u32_e32 v90, v93, v90
	v_max_u32_e32 v93, v70, v92
	v_min_u32_e32 v92, v70, v92
	v_max_u32_e32 v70, v88, v95
	v_min_u32_e32 v95, v88, v95
	v_max_u32_e32 v88, v91, v99
	v_min_u32_e32 v99, v91, v99
	v_max_u32_e32 v91, v83, v102
	v_min_u32_e32 v102, v83, v102
	v_max_u32_e32 v83, v73, v82
	v_min_u32_e32 v82, v73, v82
	v_max_u32_e32 v73, v98, v90
	v_min_u32_e32 v90, v98, v90
	v_max_u32_e32 v98, v97, v96
	v_min_u32_e32 v96, v97, v96
	v_max_u32_e32 v97, v87, v89
	v_min_u32_e32 v89, v87, v89
	v_max_u32_e32 v87, v93, v70
	v_min_u32_e32 v70, v93, v70
	v_max_u32_e32 v93, v92, v95
	v_min_u32_e32 v95, v92, v95
	v_max_u32_e32 v92, v91, v99
	v_min_u32_e32 v99, v91, v99
	v_max_u32_e32 v91, v102, v87
	v_min_u32_e32 v87, v102, v87
	v_max_u32_e32 v102, v83, v98
	v_min_u32_e32 v98, v83, v98
	v_max_u32_e32 v83, v73, v96
	v_min_u32_e32 v96, v73, v96
	v_max_u32_e32 v73, v97, v82
	v_min_u32_e32 v82, v97, v82
	v_max_u32_e32 v97, v89, v90
	v_min_u32_e32 v90, v89, v90
	v_max_u32_e32 v89, v93, v70
	v_min_u32_e32 v70, v93, v70
	v_max_u32_e32 v93, v92, v102
	v_min_u32_e32 v102, v92, v102
	v_max_u32_e32 v92, v99, v98
	v_min_u32_e32 v98, v99, v98
	v_max_u32_e32 v99, v83, v73
	v_min_u32_e32 v73, v83, v73
	v_max_u32_e32 v83, v96, v82
	v_min_u32_e32 v82, v96, v82
	v_max_u32_e32 v96, v97, v89
	v_min_u32_e32 v89, v97, v89
	v_max_u32_e32 v97, v90, v70
	v_min_u32_e32 v70, v90, v70
	v_max_u32_e32 v90, v92, v102
	v_min_u32_e32 v102, v92, v102
	v_max_u32_e32 v92, v91, v98
	v_min_u32_e32 v98, v91, v98
	v_max_u32_e32 v91, v96, v87
	v_min_u32_e32 v87, v96, v87
	v_max_u32_e32 v96, v97, v89
	v_min_u32_e32 v89, v97, v89
	v_max_u32_e32 v97, v92, v99
	v_min_u32_e32 v99, v92, v99
	v_max_u32_e32 v92, v98, v73
	v_min_u32_e32 v73, v98, v73
	v_max_u32_e32 v98, v83, v91
	v_min_u32_e32 v91, v83, v91
	v_max_u32_e32 v83, v82, v87
	v_min_u32_e32 v87, v82, v87
	v_max_u32_e32 v82, v97, v102
	v_min_u32_e32 v102, v97, v102
	v_max_u32_e32 v97, v99, v92
	v_min_u32_e32 v92, v99, v92
	v_max_u32_e32 v99, v98, v73
	v_min_u32_e32 v73, v98, v73
	v_max_u32_e32 v98, v91, v83
	v_min_u32_e32 v83, v91, v83
	v_max_u32_e32 v91, v96, v87
	v_min_u32_e32 v87, v96, v87
	v_max_u32_e32 v96, v92, v99
	v_min_u32_e32 v99, v92, v99
	v_max_u32_e32 v92, v73, v98
	v_min_u32_e32 v98, v73, v98
	v_max_u32_e32 v74, v74, v95
	v_max_u32_e32 v101, v101, v70
	v_max_u32_e32 v71, v71, v89
	v_max_u32_e32 v72, v72, v87
	v_max_u32_e32 v76, v76, v91
	v_max_u32_e32 v79, v79, v83
	v_max_u32_e32 v94, v94, v98
	v_max_u32_e32 v100, v100, v92
	v_max_u32_e32 v78, v78, v99
	v_max_u32_e32 v86, v86, v96
	v_max_u32_e32 v77, v77, v97
	v_max_u32_e32 v84, v84, v102
	v_max_u32_e32 v81, v81, v82
	v_max_u32_e32 v80, v80, v90
	v_max_u32_e32 v75, v75, v93
	v_max_u32_e32 v85, v85, v88
	v_max_u32_e32 v95, v74, v78
	v_min_u32_e32 v78, v74, v78
	v_max_u32_e32 v74, v101, v86
	v_min_u32_e32 v86, v101, v86
	v_max_u32_e32 v101, v71, v77
	v_min_u32_e32 v77, v71, v77
	v_max_u32_e32 v71, v72, v84
	v_min_u32_e32 v84, v72, v84
	v_max_u32_e32 v72, v76, v81
	v_min_u32_e32 v81, v76, v81
	v_max_u32_e32 v76, v79, v80
	v_min_u32_e32 v80, v79, v80
	v_max_u32_e32 v79, v94, v75
	v_min_u32_e32 v75, v94, v75
	v_max_u32_e32 v94, v100, v85
	v_min_u32_e32 v85, v100, v85
	v_max_u32_e32 v100, v95, v72
	v_min_u32_e32 v72, v95, v72
	v_max_u32_e32 v95, v74, v76
	v_min_u32_e32 v76, v74, v76
	v_max_u32_e32 v74, v101, v79
	v_min_u32_e32 v79, v101, v79
	v_max_u32_e32 v101, v71, v94
	v_min_u32_e32 v94, v71, v94
	v_max_u32_e32 v71, v78, v81
	v_min_u32_e32 v81, v78, v81
	v_max_u32_e32 v78, v86, v80
	v_min_u32_e32 v80, v86, v80
	v_max_u32_e32 v86, v77, v75
	v_min_u32_e32 v75, v77, v75
	v_max_u32_e32 v77, v84, v85
	v_min_u32_e32 v85, v84, v85
	v_max_u32_e32 v84, v100, v74
	v_min_u32_e32 v74, v100, v74
	v_max_u32_e32 v100, v95, v101
	v_min_u32_e32 v101, v95, v101
	v_max_u32_e32 v95, v72, v79
	v_min_u32_e32 v79, v72, v79
	v_max_u32_e32 v72, v76, v94
	v_min_u32_e32 v94, v76, v94
	v_max_u32_e32 v76, v71, v86
	v_min_u32_e32 v86, v71, v86
	v_max_u32_e32 v71, v78, v77
	v_min_u32_e32 v77, v78, v77
	v_max_u32_e32 v78, v81, v75
	v_min_u32_e32 v75, v81, v75
	v_max_u32_e32 v81, v80, v85
	v_min_u32_e32 v85, v80, v85
	v_max_u32_e32 v80, v84, v100
	v_min_u32_e32 v100, v84, v100
	v_max_u32_e32 v84, v74, v101
	v_min_u32_e32 v101, v74, v101
	v_max_u32_e32 v74, v95, v72
	v_min_u32_e32 v72, v95, v72
	v_max_u32_e32 v95, v79, v94
	v_min_u32_e32 v94, v79, v94
	v_max_u32_e32 v79, v76, v71
	v_min_u32_e32 v71, v76, v71
	v_max_u32_e32 v76, v86, v77
	v_min_u32_e32 v77, v86, v77
	v_max_u32_e32 v86, v78, v81
	v_min_u32_e32 v81, v78, v81
	v_max_u32_e32 v78, v75, v85
	v_min_u32_e32 v85, v75, v85
	v_cvt_f32_f16_e32 v75, v40
	v_cvt_f32_f16_sdwa v70, v40 dst_sel:DWORD dst_unused:UNUSED_PAD src0_sel:WORD_1
; __device__ __forceinline__ unsigned f2key(float f) { const unsigned u = __float_as_uint(f); return (u & 0x80000000u) ? ~u : (u | 0x80000000u); }
; #define CE_DESC(a, b) do { const unsigned _mx = (a) > (b) ? (a) : (b), _mn = (a) > (b) ? (b) : (a); (a) = _mx; (b) = _mn; } while (0)
; __device__ __forceinline__ void sort16_desc(unsigned (&k)[16]) {
; #pragma unroll
;     for (int size = 2; size <= 16; size <<= 1)
; #pragma unroll
;         for (int stride = size >> 1; stride > 0; stride >>= 1)
; #pragma unroll
;             for (int i = 0; i < 16; ++i) { const int j = i ^ stride;
;                 if (j > i) { if ((i & size) == 0) CE_DESC(k[i], k[j]); else CE_DESC(k[j], k[i]); } }
; }
; __device__ __forceinline__ void merge16(unsigned (&a)[16], const unsigned (&b)[16]) {
; #pragma unroll
;     for (int i = 0; i < 16; ++i) a[i] = a[i] > b[15 - i] ? a[i] : b[15 - i];
; #pragma unroll
;     for (int stride = 8; stride > 0; stride >>= 1)
; #pragma unroll
;         for (int i = 0; i < 16; ++i) { const int j = i ^ stride; if (j > i) CE_DESC(a[i], a[j]); }
; }
; __device__ __forceinline__ void peer_tile(const Args& A, LAS unsigned char* lds, int tile) {
;     ...
;                   for (int i = 0; i < 16; ++i) {
;                       const float lo = (float)__builtin_bit_cast(_Float16, (unsigned short)(sw[i] & 0xffffu)), hi = (float)__builtin_bit_cast(_Float16, (unsigned short)(sw[i] >> 16));
;                       const unsigned klo = (f2key(lo) & ~127u) | (unsigned)(127 - (32 * g + 2 * i)), khi = (f2key(hi) & ~127u) | (unsigned)(127 - (32 * g + 2 * i + 1));
;                       if (i < 8) { k0[2 * i] = klo; k0[2 * i + 1] = khi; } else { k1[2 * (i - 8)] = klo; k1[2 * (i - 8) + 1] = khi; } } }
	v_ashrrev_i32_e32 v89, 31, v75
	v_bitop3_b32 v75, v75, v89, s40 bitop3:0x78
	v_xor_b32_e32 v75, 0x8000002f, v75
	v_ashrrev_i32_e32 v89, 31, v70
	v_bitop3_b32 v70, v70, v89, s40 bitop3:0x78
	v_xor_b32_e32 v70, 0x8000002e, v70
	v_cvt_f32_f16_e32 v89, v41
	v_cvt_f32_f16_sdwa v87, v41 dst_sel:DWORD dst_unused:UNUSED_PAD src0_sel:WORD_1
	v_ashrrev_i32_e32 v91, 31, v89
	v_bitop3_b32 v89, v89, v91, s40 bitop3:0x78
	v_xor_b32_e32 v89, 0x8000002d, v89
	v_ashrrev_i32_e32 v91, 31, v87
	v_bitop3_b32 v87, v87, v91, s40 bitop3:0x78
	v_xor_b32_e32 v87, 0x8000002c, v87
	v_cvt_f32_f16_e32 v91, v42
	v_cvt_f32_f16_sdwa v83, v42 dst_sel:DWORD dst_unused:UNUSED_PAD src0_sel:WORD_1
	v_ashrrev_i32_e32 v98, 31, v91
	v_bitop3_b32 v91, v91, v98, s40 bitop3:0x78
	v_xor_b32_e32 v91, 0x8000002b, v91
	v_ashrrev_i32_e32 v98, 31, v83
	v_bitop3_b32 v83, v83, v98, s40 bitop3:0x78
	v_xor_b32_e32 v83, 0x8000002a, v83
	v_cvt_f32_f16_e32 v98, v43
	v_cvt_f32_f16_sdwa v92, v43 dst_sel:DWORD dst_unused:UNUSED_PAD src0_sel:WORD_1
	v_ashrrev_i32_e32 v99, 31, v98
	v_bitop3_b32 v98, v98, v99, s40 bitop3:0x78
	v_xor_b32_e32 v98, 0x80000029, v98
	v_ashrrev_i32_e32 v99, 31, v92
	v_bitop3_b32 v92, v92, v99, s40 bitop3:0x78
	v_xor_b32_e32 v92, 0x80000028, v92
	v_cvt_f32_f16_e32 v99, v44
	v_cvt_f32_f16_sdwa v96, v44 dst_sel:DWORD dst_unused:UNUSED_PAD src0_sel:WORD_1
	v_ashrrev_i32_e32 v97, 31, v99
	v_bitop3_b32 v99, v99, v97, s40 bitop3:0x78
	v_xor_b32_e32 v99, 0x80000027, v99
	v_ashrrev_i32_e32 v97, 31, v96
	v_bitop3_b32 v96, v96, v97, s40 bitop3:0x78
	v_xor_b32_e32 v96, 0x80000026, v96
	v_cvt_f32_f16_e32 v97, v45
	v_cvt_f32_f16_sdwa v102, v45 dst_sel:DWORD dst_unused:UNUSED_PAD src0_sel:WORD_1
	v_ashrrev_i32_e32 v82, 31, v97
	v_bitop3_b32 v97, v97, v82, s40 bitop3:0x78
	v_xor_b32_e32 v97, 0x80000025, v97
	v_ashrrev_i32_e32 v82, 31, v102
	v_bitop3_b32 v102, v102, v82, s40 bitop3:0x78
	v_xor_b32_e32 v102, 0x80000024, v102
	v_cvt_f32_f16_e32 v82, v46
	v_cvt_f32_f16_sdwa v90, v46 dst_sel:DWORD dst_unused:UNUSED_PAD src0_sel:WORD_1
	v_ashrrev_i32_e32 v93, 31, v82
	v_bitop3_b32 v82, v82, v93, s40 bitop3:0x78
	v_xor_b32_e32 v82, 0x80000023, v82
	v_ashrrev_i32_e32 v93, 31, v90
	v_bitop3_b32 v90, v90, v93, s40 bitop3:0x78
	v_xor_b32_e32 v90, 0x80000022, v90
	v_cvt_f32_f16_e32 v93, v47
	v_cvt_f32_f16_sdwa v88, v47 dst_sel:DWORD dst_unused:UNUSED_PAD src0_sel:WORD_1
	v_ashrrev_i32_e32 v73, 31, v93
	v_bitop3_b32 v93, v93, v73, s40 bitop3:0x78
	v_xor_b32_e32 v93, 0x80000021, v93
	v_ashrrev_i32_e32 v73, 31, v88
	v_bitop3_b32 v88, v88, v73, s40 bitop3:0x78
	v_xor_b32_e32 v88, 0x80000020, v88
	v_max_u32_e32 v73, v75, v90
	v_min_u32_e32 v90, v75, v90
	v_max_u32_e32 v75, v70, v82
	v_min_u32_e32 v82, v70, v82
	v_max_u32_e32 v70, v89, v88
	v_min_u32_e32 v88, v89, v88
	v_max_u32_e32 v89, v87, v93
	v_min_u32_e32 v93, v87, v93
	v_max_u32_e32 v87, v91, v99
	v_min_u32_e32 v99, v91, v99
	v_max_u32_e32 v91, v83, v98
	v_min_u32_e32 v98, v83, v98
	v_max_u32_e32 v83, v92, v102
	v_min_u32_e32 v102, v92, v102
	v_max_u32_e32 v92, v96, v97
	v_min_u32_e32 v97, v96, v97
	v_max_u32_e32 v96, v73, v91
	v_min_u32_e32 v91, v73, v91
	v_max_u32_e32 v73, v75, v83
	v_min_u32_e32 v83, v75, v83
	v_max_u32_e32 v75, v70, v92
	v_min_u32_e32 v92, v70, v92
	v_max_u32_e32 v70, v89, v87
	v_min_u32_e32 v87, v89, v87
	v_max_u32_e32 v89, v98, v90
	v_min_u32_e32 v90, v98, v90
	v_max_u32_e32 v98, v99, v93
	v_min_u32_e32 v93, v99, v93
	v_max_u32_e32 v99, v97, v88
	v_min_u32_e32 v88, v97, v88
	v_max_u32_e32 v97, v102, v82
	v_min_u32_e32 v82, v102, v82
	v_max_u32_e32 v102, v96, v73
	v_min_u32_e32 v73, v96, v73
	v_max_u32_e32 v96, v75, v70
	v_min_u32_e32 v70, v75, v70
	v_max_u32_e32 v75, v87, v91
	v_min_u32_e32 v91, v87, v91
	v_max_u32_e32 v87, v89, v98
	v_min_u32_e32 v98, v89, v98
	v_max_u32_e32 v89, v83, v92
	v_min_u32_e32 v92, v83, v92
	v_max_u32_e32 v83, v99, v97
	v_min_u32_e32 v97, v99, v97
	v_max_u32_e32 v99, v82, v90
	v_min_u32_e32 v90, v82, v90
	v_max_u32_e32 v82, v93, v88
	v_min_u32_e32 v88, v93, v88
	v_max_u32_e32 v93, v102, v96
	v_min_u32_e32 v96, v102, v96
	v_max_u32_e32 v102, v73, v70
	v_min_u32_e32 v70, v73, v70
	v_max_u32_e32 v73, v75, v83
	v_min_u32_e32 v83, v75, v83
	v_max_u32_e32 v75, v91, v97
	v_min_u32_e32 v97, v91, v97
	v_max_u32_e32 v91, v87, v89
	v_min_u32_e32 v89, v87, v89
	v_max_u32_e32 v87, v98, v92
	v_min_u32_e32 v92, v98, v92
	v_max_u32_e32 v98, v99, v82
	v_min_u32_e32 v82, v99, v82
	v_max_u32_e32 v99, v90, v88
	v_min_u32_e32 v88, v90, v88
	v_max_u32_e32 v90, v102, v96
	v_min_u32_e32 v96, v102, v96
	v_max_u32_e32 v102, v70, v98
	v_min_u32_e32 v98, v70, v98
	v_max_u32_e32 v70, v73, v91
	v_min_u32_e32 v91, v73, v91
	v_max_u32_e32 v73, v75, v89
	v_min_u32_e32 v89, v75, v89
	v_max_u32_e32 v75, v87, v83
	v_min_u32_e32 v83, v87, v83
	v_max_u32_e32 v87, v92, v97
	v_min_u32_e32 v97, v92, v97
	v_max_u32_e32 v92, v99, v82
	v_min_u32_e32 v82, v99, v82
	v_max_u32_e32 v99, v90, v70
	v_min_u32_e32 v70, v90, v70
	v_max_u32_e32 v90, v96, v91
	v_min_u32_e32 v91, v96, v91
	v_max_u32_e32 v96, v73, v75
	v_min_u32_e32 v75, v73, v75
	v_max_u32_e32 v73, v89, v83
	v_min_u32_e32 v83, v89, v83
	v_max_u32_e32 v89, v87, v92
	v_min_u32_e32 v92, v87, v92
	v_max_u32_e32 v87, v97, v82
	v_min_u32_e32 v82, v97, v82
	v_max_u32_e32 v97, v90, v70
	v_min_u32_e32 v70, v90, v70
	v_max_u32_e32 v90, v102, v91
	v_min_u32_e32 v91, v102, v91
	v_max_u32_e32 v102, v89, v98
	v_min_u32_e32 v98, v89, v98
	v_max_u32_e32 v89, v87, v92
	v_min_u32_e32 v92, v87, v92
	v_max_u32_e32 v87, v90, v96
	v_min_u32_e32 v96, v90, v96
	v_max_u32_e32 v90, v91, v75
	v_min_u32_e32 v75, v91, v75
	v_max_u32_e32 v91, v73, v102
	v_min_u32_e32 v102, v73, v102
	v_max_u32_e32 v73, v83, v98
; __device__ __forceinline__ unsigned f2key(float f) { const unsigned u = __float_as_uint(f); return (u & 0x80000000u) ? ~u : (u | 0x80000000u); }
; #define CE_DESC(a, b) do { const unsigned _mx = (a) > (b) ? (a) : (b), _mn = (a) > (b) ? (b) : (a); (a) = _mx; (b) = _mn; } while (0)
; __device__ __forceinline__ void sort16_desc(unsigned (&k)[16]) {
; #pragma unroll
;     for (int size = 2; size <= 16; size <<= 1)
; #pragma unroll
;         for (int stride = size >> 1; stride > 0; stride >>= 1)
; #pragma unroll
;             for (int i = 0; i < 16; ++i) { const int j = i ^ stride;
;                 if (j > i) { if ((i & size) == 0) CE_DESC(k[i], k[j]); else CE_DESC(k[j], k[i]); } }
; }
; __device__ __forceinline__ void merge16(unsigned (&a)[16], const unsigned (&b)[16]) {
; #pragma unroll
;     for (int i = 0; i < 16; ++i) a[i] = a[i] > b[15 - i] ? a[i] : b[15 - i];
; #pragma unroll
;     for (int stride = 8; stride > 0; stride >>= 1)
; #pragma unroll
;         for (int i = 0; i < 16; ++i) { const int j = i ^ stride; if (j > i) CE_DESC(a[i], a[j]); }
; }
; __device__ __forceinline__ void peer_tile(const Args& A, LAS unsigned char* lds, int tile) {
;     ...
;                   for (int i = 0; i < 16; ++i) {
;                       const float lo = (float)__builtin_bit_cast(_Float16, (unsigned short)(sw[i] & 0xffffu)), hi = (float)__builtin_bit_cast(_Float16, (unsigned short)(sw[i] >> 16));
;                       const unsigned klo = (f2key(lo) & ~127u) | (unsigned)(127 - (32 * g + 2 * i)), khi = (f2key(hi) & ~127u) | (unsigned)(127 - (32 * g + 2 * i + 1));
;                       if (i < 8) { k0[2 * i] = klo; k0[2 * i + 1] = khi; } else { k1[2 * (i - 8)] = klo; k1[2 * (i - 8) + 1] = khi; } } }
;                 sort16_desc(k0); sort16_desc(k1); merge16(k0, k1);
	v_min_u32_e32 v98, v83, v98
	v_max_u32_e32 v83, v87, v70
	v_min_u32_e32 v70, v87, v70
	v_max_u32_e32 v87, v96, v90
	v_min_u32_e32 v90, v96, v90
	v_max_u32_e32 v96, v91, v75
	v_min_u32_e32 v75, v91, v75
	v_max_u32_e32 v91, v102, v73
	v_min_u32_e32 v73, v102, v73
	v_max_u32_e32 v102, v89, v98
	v_min_u32_e32 v98, v89, v98
	v_max_u32_e32 v89, v90, v96
	v_min_u32_e32 v96, v90, v96
	v_max_u32_e32 v90, v75, v91
	v_min_u32_e32 v91, v75, v91
	v_max_u32_e32 v80, v80, v88
	v_max_u32_e32 v100, v100, v82
	v_max_u32_e32 v84, v84, v92
	v_max_u32_e32 v101, v101, v98
	v_max_u32_e32 v74, v74, v102
	v_max_u32_e32 v72, v72, v73
	v_max_u32_e32 v95, v95, v91
	v_max_u32_e32 v94, v94, v90
	v_max_u32_e32 v79, v79, v96
	v_max_u32_e32 v71, v71, v89
	v_max_u32_e32 v76, v76, v87
	v_max_u32_e32 v77, v77, v70
	v_max_u32_e32 v86, v86, v83
	v_max_u32_e32 v81, v81, v97
	v_max_u32_e32 v78, v78, v99
	v_max_u32_e32 v85, v85, v93
	v_max_u32_e32 v88, v80, v79
	v_min_u32_e32 v79, v80, v79
	v_max_u32_e32 v80, v100, v71
	v_min_u32_e32 v71, v100, v71
	v_max_u32_e32 v100, v84, v76
	v_min_u32_e32 v76, v84, v76
	v_max_u32_e32 v84, v101, v77
	v_min_u32_e32 v77, v101, v77
	v_max_u32_e32 v101, v74, v86
	v_min_u32_e32 v86, v74, v86
	v_max_u32_e32 v74, v72, v81
	v_min_u32_e32 v81, v72, v81
	v_max_u32_e32 v72, v95, v78
	v_min_u32_e32 v78, v95, v78
	v_max_u32_e32 v95, v94, v85
	v_min_u32_e32 v85, v94, v85
	v_max_u32_e32 v94, v88, v101
	v_min_u32_e32 v101, v88, v101
	v_max_u32_e32 v88, v80, v74
	v_min_u32_e32 v74, v80, v74
	v_max_u32_e32 v80, v100, v72
	v_min_u32_e32 v72, v100, v72
	v_max_u32_e32 v100, v84, v95
	v_min_u32_e32 v95, v84, v95
	v_max_u32_e32 v84, v79, v86
	v_min_u32_e32 v86, v79, v86
	v_max_u32_e32 v79, v71, v81
	v_min_u32_e32 v81, v71, v81
	v_max_u32_e32 v71, v76, v78
	v_min_u32_e32 v78, v76, v78
	v_max_u32_e32 v76, v77, v85
	v_min_u32_e32 v85, v77, v85
	v_max_u32_e32 v77, v94, v80
	v_min_u32_e32 v80, v94, v80
	v_max_u32_e32 v94, v88, v100
	v_min_u32_e32 v100, v88, v100
	v_max_u32_e32 v88, v101, v72
	v_min_u32_e32 v72, v101, v72
	v_max_u32_e32 v101, v74, v95
	v_min_u32_e32 v95, v74, v95
	v_max_u32_e32 v74, v84, v71
	v_min_u32_e32 v71, v84, v71
	v_max_u32_e32 v84, v79, v76
	v_min_u32_e32 v76, v79, v76
	v_max_u32_e32 v79, v86, v78
	v_min_u32_e32 v78, v86, v78
	v_max_u32_e32 v86, v81, v85
	v_min_u32_e32 v85, v81, v85
	v_max_u32_e32 v81, v77, v94
	v_min_u32_e32 v94, v77, v94
	v_max_u32_e32 v77, v80, v100
	v_min_u32_e32 v100, v80, v100
	v_max_u32_e32 v80, v88, v101
	v_min_u32_e32 v101, v88, v101
	v_max_u32_e32 v88, v72, v95
	v_min_u32_e32 v95, v72, v95
	v_max_u32_e32 v72, v74, v84
	v_min_u32_e32 v84, v74, v84
	v_max_u32_e32 v74, v71, v76
	v_min_u32_e32 v76, v71, v76
	v_max_u32_e32 v71, v79, v86
	v_min_u32_e32 v86, v79, v86
	v_max_u32_e32 v79, v78, v85
	v_min_u32_e32 v85, v78, v85
	v_cvt_f32_f16_e32 v78, v48
	v_cvt_f32_f16_sdwa v82, v48 dst_sel:DWORD dst_unused:UNUSED_PAD src0_sel:WORD_1
	v_ashrrev_i32_e32 v92, 31, v78
	v_bitop3_b32 v78, v78, v92, s40 bitop3:0x78
	v_xor_b32_e32 v78, 0x8000001f, v78
	v_ashrrev_i32_e32 v92, 31, v82
	v_bitop3_b32 v82, v82, v92, s40 bitop3:0x78
	v_xor_b32_e32 v82, 0x8000001e, v82
	v_cvt_f32_f16_e32 v92, v49
	v_cvt_f32_f16_sdwa v98, v49 dst_sel:DWORD dst_unused:UNUSED_PAD src0_sel:WORD_1
	v_ashrrev_i32_e32 v102, 31, v92
	v_bitop3_b32 v92, v92, v102, s40 bitop3:0x78
	v_xor_b32_e32 v92, 0x8000001d, v92
	v_ashrrev_i32_e32 v102, 31, v98
	v_bitop3_b32 v98, v98, v102, s40 bitop3:0x78
	v_xor_b32_e32 v98, 0x8000001c, v98
	v_cvt_f32_f16_e32 v102, v50
	v_cvt_f32_f16_sdwa v73, v50 dst_sel:DWORD dst_unused:UNUSED_PAD src0_sel:WORD_1
	v_ashrrev_i32_e32 v91, 31, v102
	v_bitop3_b32 v102, v102, v91, s40 bitop3:0x78
	v_xor_b32_e32 v102, 0x8000001b, v102
	v_ashrrev_i32_e32 v91, 31, v73
	v_bitop3_b32 v73, v73, v91, s40 bitop3:0x78
	v_xor_b32_e32 v73, 0x8000001a, v73
	v_cvt_f32_f16_e32 v91, v51
	v_cvt_f32_f16_sdwa v90, v51 dst_sel:DWORD dst_unused:UNUSED_PAD src0_sel:WORD_1
	v_ashrrev_i32_e32 v96, 31, v91
	v_bitop3_b32 v91, v91, v96, s40 bitop3:0x78
	v_xor_b32_e32 v91, 0x80000019, v91
	v_ashrrev_i32_e32 v96, 31, v90
	v_bitop3_b32 v90, v90, v96, s40 bitop3:0x78
	v_xor_b32_e32 v90, 0x80000018, v90
	v_cvt_f32_f16_e32 v96, v52
	v_cvt_f32_f16_sdwa v89, v52 dst_sel:DWORD dst_unused:UNUSED_PAD src0_sel:WORD_1
	v_ashrrev_i32_e32 v87, 31, v96
	v_bitop3_b32 v96, v96, v87, s40 bitop3:0x78
	v_xor_b32_e32 v96, 0x80000017, v96
	v_ashrrev_i32_e32 v87, 31, v89
	v_bitop3_b32 v89, v89, v87, s40 bitop3:0x78
	v_xor_b32_e32 v89, 0x80000016, v89
	v_cvt_f32_f16_e32 v87, v53
	v_cvt_f32_f16_sdwa v70, v53 dst_sel:DWORD dst_unused:UNUSED_PAD src0_sel:WORD_1
	v_ashrrev_i32_e32 v83, 31, v87
	v_bitop3_b32 v87, v87, v83, s40 bitop3:0x78
	v_xor_b32_e32 v87, 0x80000015, v87
	v_ashrrev_i32_e32 v83, 31, v70
	v_bitop3_b32 v70, v70, v83, s40 bitop3:0x78
	v_xor_b32_e32 v70, 0x80000014, v70
	v_cvt_f32_f16_e32 v83, v54
	v_cvt_f32_f16_sdwa v97, v54 dst_sel:DWORD dst_unused:UNUSED_PAD src0_sel:WORD_1
	v_ashrrev_i32_e32 v99, 31, v83
	v_bitop3_b32 v83, v83, v99, s40 bitop3:0x78
	v_xor_b32_e32 v83, 0x80000013, v83
	v_ashrrev_i32_e32 v99, 31, v97
	v_bitop3_b32 v97, v97, v99, s40 bitop3:0x78
	v_xor_b32_e32 v97, 0x80000012, v97
	v_cvt_f32_f16_e32 v99, v55
	v_cvt_f32_f16_sdwa v93, v55 dst_sel:DWORD dst_unused:UNUSED_PAD src0_sel:WORD_1
	v_ashrrev_i32_e32 v75, 31, v99
	v_bitop3_b32 v99, v99, v75, s40 bitop3:0x78
	v_xor_b32_e32 v99, 0x80000011, v99
	v_ashrrev_i32_e32 v75, 31, v93
	v_bitop3_b32 v93, v93, v75, s40 bitop3:0x78
	v_xor_b32_e32 v93, 0x80000010, v93
	v_max_u32_e32 v75, v78, v97
	v_min_u32_e32 v97, v78, v97
	v_max_u32_e32 v78, v82, v83
	v_min_u32_e32 v83, v82, v83
	v_max_u32_e32 v82, v92, v93
	v_min_u32_e32 v93, v92, v93
; __device__ __forceinline__ unsigned f2key(float f) { const unsigned u = __float_as_uint(f); return (u & 0x80000000u) ? ~u : (u | 0x80000000u); }
; #define CE_DESC(a, b) do { const unsigned _mx = (a) > (b) ? (a) : (b), _mn = (a) > (b) ? (b) : (a); (a) = _mx; (b) = _mn; } while (0)
; __device__ __forceinline__ void sort16_desc(unsigned (&k)[16]) {
; #pragma unroll
;     for (int size = 2; size <= 16; size <<= 1)
; #pragma unroll
;         for (int stride = size >> 1; stride > 0; stride >>= 1)
; #pragma unroll
;             for (int i = 0; i < 16; ++i) { const int j = i ^ stride;
;                 if (j > i) { if ((i & size) == 0) CE_DESC(k[i], k[j]); else CE_DESC(k[j], k[i]); } }
; }
; __device__ __forceinline__ void merge16(unsigned (&a)[16], const unsigned (&b)[16]) {
; #pragma unroll
;     for (int i = 0; i < 16; ++i) a[i] = a[i] > b[15 - i] ? a[i] : b[15 - i];
; #pragma unroll
;     for (int stride = 8; stride > 0; stride >>= 1)
; #pragma unroll
;         for (int i = 0; i < 16; ++i) { const int j = i ^ stride; if (j > i) CE_DESC(a[i], a[j]); }
; }
; __device__ __forceinline__ void peer_tile(const Args& A, LAS unsigned char* lds, int tile) {
;     ...
;                   for (int i = 0; i < 16; ++i) {
;                       const float lo = (float)__builtin_bit_cast(_Float16, (unsigned short)(sw[i] & 0xffffu)), hi = (float)__builtin_bit_cast(_Float16, (unsigned short)(sw[i] >> 16));
;                       const unsigned klo = (f2key(lo) & ~127u) | (unsigned)(127 - (32 * g + 2 * i)), khi = (f2key(hi) & ~127u) | (unsigned)(127 - (32 * g + 2 * i + 1));
;                       if (i < 8) { k0[2 * i] = klo; k0[2 * i + 1] = khi; } else { k1[2 * (i - 8)] = klo; k1[2 * (i - 8) + 1] = khi; } } }
;                 sort16_desc(k0); sort16_desc(k1); merge16(k0, k1);
	v_max_u32_e32 v92, v98, v99
	v_min_u32_e32 v99, v98, v99
	v_max_u32_e32 v98, v102, v96
	v_min_u32_e32 v96, v102, v96
	v_max_u32_e32 v102, v73, v91
	v_min_u32_e32 v91, v73, v91
	v_max_u32_e32 v73, v90, v70
	v_min_u32_e32 v70, v90, v70
	v_max_u32_e32 v90, v89, v87
	v_min_u32_e32 v87, v89, v87
	v_max_u32_e32 v89, v75, v102
	v_min_u32_e32 v102, v75, v102
	v_max_u32_e32 v75, v78, v73
	v_min_u32_e32 v73, v78, v73
	v_max_u32_e32 v78, v82, v90
	v_min_u32_e32 v90, v82, v90
	v_max_u32_e32 v82, v92, v98
	v_min_u32_e32 v98, v92, v98
	v_max_u32_e32 v92, v91, v97
	v_min_u32_e32 v97, v91, v97
	v_max_u32_e32 v91, v96, v99
	v_min_u32_e32 v99, v96, v99
	v_max_u32_e32 v96, v87, v93
	v_min_u32_e32 v93, v87, v93
	v_max_u32_e32 v87, v70, v83
	v_min_u32_e32 v83, v70, v83
	v_max_u32_e32 v70, v89, v75
	v_min_u32_e32 v75, v89, v75
	v_max_u32_e32 v89, v78, v82
	v_min_u32_e32 v82, v78, v82
	v_max_u32_e32 v78, v98, v102
	v_min_u32_e32 v102, v98, v102
	v_max_u32_e32 v98, v92, v91
	v_min_u32_e32 v91, v92, v91
	v_max_u32_e32 v92, v73, v90
	v_min_u32_e32 v90, v73, v90
	v_max_u32_e32 v73, v96, v87
	v_min_u32_e32 v87, v96, v87
	v_max_u32_e32 v96, v83, v97
	v_min_u32_e32 v97, v83, v97
	v_max_u32_e32 v83, v99, v93
	v_min_u32_e32 v93, v99, v93
	v_max_u32_e32 v99, v70, v89
	v_min_u32_e32 v89, v70, v89
	v_max_u32_e32 v70, v75, v82
	v_min_u32_e32 v82, v75, v82
	v_max_u32_e32 v75, v78, v73
	v_min_u32_e32 v73, v78, v73
	v_max_u32_e32 v78, v102, v87
	v_min_u32_e32 v87, v102, v87
	v_max_u32_e32 v102, v98, v92
	v_min_u32_e32 v92, v98, v92
	v_max_u32_e32 v98, v91, v90
	v_min_u32_e32 v90, v91, v90
	v_max_u32_e32 v91, v96, v83
	v_min_u32_e32 v83, v96, v83
	v_max_u32_e32 v96, v97, v93
	v_min_u32_e32 v93, v97, v93
	v_max_u32_e32 v97, v70, v89
	v_min_u32_e32 v89, v70, v89
	v_max_u32_e32 v70, v82, v91
	v_min_u32_e32 v91, v82, v91
	v_max_u32_e32 v82, v75, v102
	v_min_u32_e32 v102, v75, v102
	v_max_u32_e32 v75, v78, v92
	v_min_u32_e32 v92, v78, v92
	v_max_u32_e32 v78, v98, v73
	v_min_u32_e32 v73, v98, v73
	v_max_u32_e32 v98, v90, v87
	v_min_u32_e32 v87, v90, v87
	v_max_u32_e32 v90, v96, v83
	v_min_u32_e32 v83, v96, v83
	v_max_u32_e32 v96, v97, v82
	v_min_u32_e32 v82, v97, v82
	v_max_u32_e32 v97, v89, v102
	v_min_u32_e32 v102, v89, v102
	v_max_u32_e32 v89, v75, v78
	v_min_u32_e32 v78, v75, v78
	v_max_u32_e32 v75, v92, v73
	v_min_u32_e32 v73, v92, v73
	v_max_u32_e32 v92, v98, v90
	v_min_u32_e32 v90, v98, v90
	v_max_u32_e32 v98, v87, v83
	v_min_u32_e32 v83, v87, v83
	v_max_u32_e32 v87, v97, v82
	v_min_u32_e32 v82, v97, v82
	v_max_u32_e32 v97, v70, v102
	v_min_u32_e32 v102, v70, v102
	v_max_u32_e32 v70, v92, v91
	v_min_u32_e32 v91, v92, v91
	v_max_u32_e32 v92, v98, v90
	v_min_u32_e32 v90, v98, v90
	v_max_u32_e32 v98, v97, v89
	v_min_u32_e32 v89, v97, v89
	v_max_u32_e32 v97, v102, v78
	v_min_u32_e32 v78, v102, v78
	v_max_u32_e32 v102, v75, v70
	v_min_u32_e32 v70, v75, v70
	v_max_u32_e32 v75, v73, v91
	v_min_u32_e32 v91, v73, v91
	v_max_u32_e32 v73, v98, v82
	v_min_u32_e32 v82, v98, v82
	v_max_u32_e32 v98, v89, v97
	v_min_u32_e32 v97, v89, v97
	v_max_u32_e32 v89, v102, v78
	v_min_u32_e32 v78, v102, v78
	v_max_u32_e32 v102, v70, v75
	v_min_u32_e32 v75, v70, v75
	v_max_u32_e32 v70, v92, v91
	v_min_u32_e32 v91, v92, v91
	v_max_u32_e32 v92, v97, v89
	v_min_u32_e32 v89, v97, v89
	v_max_u32_e32 v97, v78, v102
	v_min_u32_e32 v102, v78, v102
	v_max_u32_e32 v81, v81, v93
	v_max_u32_e32 v94, v94, v83
	v_max_u32_e32 v77, v77, v90
	v_max_u32_e32 v100, v100, v91
	v_max_u32_e32 v80, v80, v70
	v_max_u32_e32 v101, v101, v75
	v_max_u32_e32 v88, v88, v102
	v_max_u32_e32 v95, v95, v97
	v_max_u32_e32 v72, v72, v89
	v_max_u32_e32 v84, v84, v92
	v_max_u32_e32 v74, v74, v98
	v_max_u32_e32 v76, v76, v82
	v_max_u32_e32 v71, v71, v73
	v_max_u32_e32 v86, v86, v87
	v_max_u32_e32 v79, v79, v96
	v_max_u32_e32 v85, v85, v99
	v_max_u32_e32 v93, v81, v72
	v_min_u32_e32 v72, v81, v72
	v_max_u32_e32 v81, v94, v84
	v_min_u32_e32 v84, v94, v84
	v_max_u32_e32 v94, v77, v74
	v_min_u32_e32 v74, v77, v74
	v_max_u32_e32 v77, v100, v76
	v_min_u32_e32 v76, v100, v76
	v_max_u32_e32 v100, v80, v71
	v_min_u32_e32 v71, v80, v71
	v_max_u32_e32 v80, v101, v86
	v_min_u32_e32 v86, v101, v86
	v_max_u32_e32 v101, v88, v79
	v_min_u32_e32 v79, v88, v79
	v_max_u32_e32 v88, v95, v85
	v_min_u32_e32 v85, v95, v85
	v_max_u32_e32 v95, v93, v100
	v_min_u32_e32 v100, v93, v100
	v_max_u32_e32 v93, v81, v80
	v_min_u32_e32 v80, v81, v80
	v_max_u32_e32 v81, v94, v101
	v_min_u32_e32 v101, v94, v101
	v_max_u32_e32 v94, v77, v88
	v_min_u32_e32 v88, v77, v88
	v_max_u32_e32 v77, v72, v71
	v_min_u32_e32 v71, v72, v71
	v_max_u32_e32 v72, v84, v86
	v_min_u32_e32 v86, v84, v86
	v_max_u32_e32 v84, v74, v79
	v_min_u32_e32 v79, v74, v79
	v_max_u32_e32 v74, v76, v85
	v_min_u32_e32 v85, v76, v85
	v_max_u32_e32 v76, v95, v81
	v_min_u32_e32 v81, v95, v81
	v_max_u32_e32 v95, v93, v94
	v_min_u32_e32 v94, v93, v94
	v_max_u32_e32 v93, v100, v101
	v_min_u32_e32 v101, v100, v101
	v_max_u32_e32 v100, v80, v88
	v_min_u32_e32 v88, v80, v88
	v_max_u32_e32 v80, v77, v84
	v_min_u32_e32 v84, v77, v84
	v_max_u32_e32 v77, v72, v74
	v_min_u32_e32 v74, v72, v74
	v_max_u32_e32 v72, v71, v79
	v_min_u32_e32 v79, v71, v79
	v_max_u32_e32 v71, v86, v85
	v_min_u32_e32 v85, v86, v85
	v_max_u32_e32 v86, v76, v95
	v_min_u32_e32 v95, v76, v95
	v_max_u32_e32 v76, v81, v94
	v_min_u32_e32 v94, v81, v94
	v_max_u32_e32 v81, v93, v100
	v_min_u32_e32 v100, v93, v100
	v_max_u32_e32 v93, v101, v88
	v_min_u32_e32 v88, v101, v88
	v_max_u32_e32 v101, v80, v77
	v_min_u32_e32 v77, v80, v77
	v_max_u32_e32 v80, v84, v74
	v_min_u32_e32 v74, v84, v74
	v_max_u32_e32 v84, v72, v71
	v_min_u32_e32 v71, v72, v71
; __device__ __forceinline__ unsigned f2key(float f) { const unsigned u = __float_as_uint(f); return (u & 0x80000000u) ? ~u : (u | 0x80000000u); }
; __device__ __forceinline__ void peer_tile(const Args& A, LAS unsigned char* lds, int tile) {
;     ...
;                 unsigned k0[16], k1[16];
;                 { const bf16_t* sp = QRY + m * 2048 + hp * 128 + 32 * g;
;                   const u32x4 s0 = *(const u32x4*)sp, s1 = *(const u32x4*)(sp + 8), s2 = *(const u32x4*)(sp + 16), s3 = *(const u32x4*)(sp + 24);
;                   const unsigned sw[16] = {s0.x, s0.y, s0.z, s0.w, s1.x, s1.y, s1.z, s1.w, s2.x, s2.y, s2.z, s2.w, s3.x, s3.y, s3.z, s3.w};
; #pragma unroll
;                   for (int i = 0; i < 16; ++i) {
;                       const float lo = (float)__builtin_bit_cast(_Float16, (unsigned short)(sw[i] & 0xffffu)), hi = (float)__builtin_bit_cast(_Float16, (unsigned short)(sw[i] >> 16));
;                       const unsigned klo = (f2key(lo) & ~127u) | (unsigned)(127 - (32 * g + 2 * i)), khi = (f2key(hi) & ~127u) | (unsigned)(127 - (32 * g + 2 * i + 1));
;                       if (i < 8) { k0[2 * i] = klo; k0[2 * i + 1] = khi; } else { k1[2 * (i - 8)] = klo; k1[2 * (i - 8) + 1] = khi; } } }
;                 sort16_desc(k0); sort16_desc(k1); merge16(k0, k1);
	v_max_u32_e32 v72, v79, v85
	v_min_u32_e32 v85, v79, v85
	v_cvt_f32_f16_e32 v79, v56
	v_cvt_f32_f16_sdwa v83, v56 dst_sel:DWORD dst_unused:UNUSED_PAD src0_sel:WORD_1
	v_ashrrev_i32_e32 v90, 31, v79
	v_bitop3_b32 v79, v79, v90, s40 bitop3:0x78
	v_xor_b32_e32 v79, 0x8000000f, v79
	v_ashrrev_i32_e32 v90, 31, v83
	v_bitop3_b32 v83, v83, v90, s40 bitop3:0x78
	v_xor_b32_e32 v83, 0x8000000e, v83
	v_cvt_f32_f16_e32 v90, v57
	v_cvt_f32_f16_sdwa v91, v57 dst_sel:DWORD dst_unused:UNUSED_PAD src0_sel:WORD_1
	v_ashrrev_i32_e32 v70, 31, v90
	v_bitop3_b32 v90, v90, v70, s40 bitop3:0x78
	v_xor_b32_e32 v90, 0x8000000d, v90
	v_ashrrev_i32_e32 v70, 31, v91
	v_bitop3_b32 v91, v91, v70, s40 bitop3:0x78
	v_xor_b32_e32 v91, 0x8000000c, v91
	v_cvt_f32_f16_e32 v70, v58
	v_cvt_f32_f16_sdwa v75, v58 dst_sel:DWORD dst_unused:UNUSED_PAD src0_sel:WORD_1
	v_ashrrev_i32_e32 v102, 31, v70
	v_bitop3_b32 v70, v70, v102, s40 bitop3:0x78
	v_xor_b32_e32 v70, 0x8000000b, v70
	v_ashrrev_i32_e32 v102, 31, v75
	v_bitop3_b32 v75, v75, v102, s40 bitop3:0x78
	v_xor_b32_e32 v75, 0x8000000a, v75
	v_cvt_f32_f16_e32 v102, v59
	v_cvt_f32_f16_sdwa v97, v59 dst_sel:DWORD dst_unused:UNUSED_PAD src0_sel:WORD_1
	v_ashrrev_i32_e32 v89, 31, v102
	v_bitop3_b32 v102, v102, v89, s40 bitop3:0x78
	v_xor_b32_e32 v102, 0x80000009, v102
	v_ashrrev_i32_e32 v89, 31, v97
	v_bitop3_b32 v97, v97, v89, s40 bitop3:0x78
	v_xor_b32_e32 v97, 0x80000008, v97
	v_cvt_f32_f16_e32 v89, v60
	v_cvt_f32_f16_sdwa v92, v60 dst_sel:DWORD dst_unused:UNUSED_PAD src0_sel:WORD_1
	v_ashrrev_i32_e32 v98, 31, v89
	v_bitop3_b32 v89, v89, v98, s40 bitop3:0x78
	v_xor_b32_e32 v89, 0x80000007, v89
	v_ashrrev_i32_e32 v98, 31, v92
	v_bitop3_b32 v92, v92, v98, s40 bitop3:0x78
	v_xor_b32_e32 v92, 0x80000006, v92
	v_cvt_f32_f16_e32 v98, v61
	v_cvt_f32_f16_sdwa v82, v61 dst_sel:DWORD dst_unused:UNUSED_PAD src0_sel:WORD_1
	v_ashrrev_i32_e32 v73, 31, v98
	v_bitop3_b32 v98, v98, v73, s40 bitop3:0x78
	v_xor_b32_e32 v98, 0x80000005, v98
	v_ashrrev_i32_e32 v73, 31, v82
	v_bitop3_b32 v82, v82, v73, s40 bitop3:0x78
	v_xor_b32_e32 v82, 0x80000004, v82
	v_cvt_f32_f16_e32 v73, v62
	v_cvt_f32_f16_sdwa v87, v62 dst_sel:DWORD dst_unused:UNUSED_PAD src0_sel:WORD_1
	v_ashrrev_i32_e32 v96, 31, v73
	v_bitop3_b32 v73, v73, v96, s40 bitop3:0x78
	v_xor_b32_e32 v73, 0x80000003, v73
	v_ashrrev_i32_e32 v96, 31, v87
	v_bitop3_b32 v87, v87, v96, s40 bitop3:0x78
	v_xor_b32_e32 v87, 0x80000002, v87
	v_cvt_f32_f16_e32 v96, v63
	v_cvt_f32_f16_sdwa v99, v63 dst_sel:DWORD dst_unused:UNUSED_PAD src0_sel:WORD_1
	v_ashrrev_i32_e32 v78, 31, v96
	v_bitop3_b32 v96, v96, v78, s40 bitop3:0x78
	v_xor_b32_e32 v96, 0x80000001, v96
	v_ashrrev_i32_e32 v78, 31, v99
	v_bitop3_b32 v99, v99, v78, s40 bitop3:0x78
	v_xor_b32_e32 v99, 0x80000000, v99
	v_max_u32_e32 v78, v79, v87
	v_min_u32_e32 v87, v79, v87
	v_max_u32_e32 v79, v83, v73
	v_min_u32_e32 v73, v83, v73
	v_max_u32_e32 v83, v90, v99
	v_min_u32_e32 v99, v90, v99
	v_max_u32_e32 v90, v91, v96
	v_min_u32_e32 v96, v91, v96
	v_max_u32_e32 v91, v70, v89
	v_min_u32_e32 v89, v70, v89
	v_max_u32_e32 v70, v75, v102
	v_min_u32_e32 v102, v75, v102
	v_max_u32_e32 v75, v97, v82
	v_min_u32_e32 v82, v97, v82
	v_max_u32_e32 v97, v92, v98
	v_min_u32_e32 v98, v92, v98
	v_max_u32_e32 v92, v78, v70
	v_min_u32_e32 v70, v78, v70
	v_max_u32_e32 v78, v79, v75
	v_min_u32_e32 v75, v79, v75
	v_max_u32_e32 v79, v83, v97
	v_min_u32_e32 v97, v83, v97
	v_max_u32_e32 v83, v90, v91
	v_min_u32_e32 v91, v90, v91
	v_max_u32_e32 v90, v102, v87
	v_min_u32_e32 v87, v102, v87
	v_max_u32_e32 v102, v89, v96
	v_min_u32_e32 v96, v89, v96
	v_max_u32_e32 v89, v98, v99
	v_min_u32_e32 v99, v98, v99
	v_max_u32_e32 v98, v82, v73
	v_min_u32_e32 v73, v82, v73
	v_max_u32_e32 v82, v92, v78
	v_min_u32_e32 v78, v92, v78
	v_max_u32_e32 v92, v79, v83
	v_min_u32_e32 v83, v79, v83
	v_max_u32_e32 v79, v91, v70
	v_min_u32_e32 v70, v91, v70
	v_max_u32_e32 v91, v90, v102
	v_min_u32_e32 v102, v90, v102
	v_max_u32_e32 v90, v75, v97
	v_min_u32_e32 v97, v75, v97
	v_max_u32_e32 v75, v89, v98
	v_min_u32_e32 v98, v89, v98
	v_max_u32_e32 v89, v73, v87
	v_min_u32_e32 v87, v73, v87
	v_max_u32_e32 v73, v96, v99
	v_min_u32_e32 v99, v96, v99
	v_max_u32_e32 v96, v82, v92
	v_min_u32_e32 v92, v82, v92
	v_max_u32_e32 v82, v78, v83
	v_min_u32_e32 v83, v78, v83
	v_max_u32_e32 v78, v79, v75
	v_min_u32_e32 v75, v79, v75
	v_max_u32_e32 v79, v70, v98
	v_min_u32_e32 v98, v70, v98
	v_max_u32_e32 v70, v91, v90
	v_min_u32_e32 v90, v91, v90
	v_max_u32_e32 v91, v102, v97
	v_min_u32_e32 v97, v102, v97
	v_max_u32_e32 v102, v89, v73
	v_min_u32_e32 v73, v89, v73
	v_max_u32_e32 v89, v87, v99
	v_min_u32_e32 v99, v87, v99
	v_max_u32_e32 v87, v82, v92
	v_min_u32_e32 v92, v82, v92
	v_max_u32_e32 v82, v83, v102
	v_min_u32_e32 v102, v83, v102
	v_max_u32_e32 v83, v78, v70
	v_min_u32_e32 v70, v78, v70
	v_max_u32_e32 v78, v79, v90
	v_min_u32_e32 v90, v79, v90
	v_max_u32_e32 v79, v91, v75
	v_min_u32_e32 v75, v91, v75
	v_max_u32_e32 v91, v97, v98
	v_min_u32_e32 v98, v97, v98
	v_max_u32_e32 v97, v89, v73
	v_min_u32_e32 v73, v89, v73
	v_max_u32_e32 v89, v87, v83
	v_min_u32_e32 v83, v87, v83
	v_max_u32_e32 v87, v92, v70
	v_min_u32_e32 v70, v92, v70
	v_max_u32_e32 v92, v78, v79
	v_min_u32_e32 v79, v78, v79
	v_max_u32_e32 v78, v90, v75
	v_min_u32_e32 v75, v90, v75
	v_max_u32_e32 v90, v91, v97
	v_min_u32_e32 v97, v91, v97
	v_max_u32_e32 v91, v98, v73
	v_min_u32_e32 v73, v98, v73
	v_max_u32_e32 v98, v87, v83
	v_min_u32_e32 v83, v87, v83
	v_max_u32_e32 v87, v82, v70
	v_min_u32_e32 v70, v82, v70
	v_max_u32_e32 v82, v90, v102
	v_min_u32_e32 v102, v90, v102
	v_max_u32_e32 v90, v91, v97
	v_min_u32_e32 v97, v91, v97
	v_max_u32_e32 v91, v87, v92
; #define CE_DESC(a, b) do { const unsigned _mx = (a) > (b) ? (a) : (b), _mn = (a) > (b) ? (b) : (a); (a) = _mx; (b) = _mn; } while (0)
; __device__ __forceinline__ void merge16(unsigned (&a)[16], const unsigned (&b)[16]) {
; #pragma unroll
;     for (int i = 0; i < 16; ++i) a[i] = a[i] > b[15 - i] ? a[i] : b[15 - i];
; #pragma unroll
;     for (int stride = 8; stride > 0; stride >>= 1)
; #pragma unroll
;         for (int i = 0; i < 16; ++i) { const int j = i ^ stride; if (j > i) CE_DESC(a[i], a[j]); }
; }
; __device__ __forceinline__ void peer_tile(const Args& A, LAS unsigned char* lds, int tile) {
;     ...
;                 { const bf16_t* sp = QRY + m * 2048 + hp * 128 + 32 * g;
;                   const u32x4 s0 = *(const u32x4*)sp, s1 = *(const u32x4*)(sp + 8), s2 = *(const u32x4*)(sp + 16), s3 = *(const u32x4*)(sp + 24);
	v_min_u32_e32 v92, v87, v92
	v_max_u32_e32 v87, v70, v79
	v_min_u32_e32 v79, v70, v79
	v_max_u32_e32 v70, v78, v82
	v_min_u32_e32 v82, v78, v82
	v_max_u32_e32 v78, v75, v102
	v_min_u32_e32 v102, v75, v102
	v_max_u32_e32 v75, v91, v83
	v_min_u32_e32 v83, v91, v83
	v_max_u32_e32 v91, v92, v87
	v_min_u32_e32 v87, v92, v87
	v_max_u32_e32 v92, v70, v79
	v_min_u32_e32 v79, v70, v79
	v_max_u32_e32 v70, v82, v78
	v_min_u32_e32 v78, v82, v78
	v_max_u32_e32 v82, v90, v102
	v_min_u32_e32 v102, v90, v102
	v_max_u32_e32 v90, v87, v92
	v_min_u32_e32 v92, v87, v92
	v_max_u32_e32 v87, v79, v70
	v_min_u32_e32 v70, v79, v70
	v_max_u32_e32 v86, v86, v99
	v_max_u32_e32 v95, v95, v73
	v_max_u32_e32 v76, v76, v97
	v_max_u32_e32 v94, v94, v102
	v_max_u32_e32 v81, v81, v82
	v_max_u32_e32 v100, v100, v78
	v_max_u32_e32 v93, v93, v70
	v_max_u32_e32 v88, v88, v87
	v_max_u32_e32 v101, v101, v92
	v_max_u32_e32 v77, v77, v90
	v_max_u32_e32 v80, v80, v91
	v_max_u32_e32 v74, v74, v83
	v_max_u32_e32 v84, v84, v75
	v_max_u32_e32 v71, v71, v98
	v_max_u32_e32 v72, v72, v89
	v_max_u32_e32 v85, v85, v96
	v_max_u32_e32 v99, v86, v101
	v_min_u32_e32 v101, v86, v101
	v_max_u32_e32 v86, v95, v77
	v_min_u32_e32 v77, v95, v77
	v_max_u32_e32 v95, v76, v80
	v_min_u32_e32 v80, v76, v80
	v_max_u32_e32 v76, v94, v74
	v_min_u32_e32 v74, v94, v74
	v_max_u32_e32 v94, v81, v84
	v_min_u32_e32 v84, v81, v84
	v_max_u32_e32 v81, v100, v71
	v_min_u32_e32 v71, v100, v71
	v_max_u32_e32 v100, v93, v72
	v_min_u32_e32 v72, v93, v72
	v_max_u32_e32 v93, v88, v85
	v_min_u32_e32 v85, v88, v85
	v_max_u32_e32 v88, v99, v94
	v_min_u32_e32 v94, v99, v94
	v_max_u32_e32 v99, v86, v81
	v_min_u32_e32 v81, v86, v81
	v_max_u32_e32 v86, v95, v100
	v_min_u32_e32 v100, v95, v100
	v_max_u32_e32 v95, v76, v93
	v_min_u32_e32 v93, v76, v93
	v_max_u32_e32 v76, v101, v84
	v_min_u32_e32 v84, v101, v84
	v_max_u32_e32 v101, v77, v71
	v_min_u32_e32 v71, v77, v71
	v_max_u32_e32 v77, v80, v72
	v_min_u32_e32 v72, v80, v72
	v_max_u32_e32 v80, v74, v85
	v_min_u32_e32 v85, v74, v85
	v_max_u32_e32 v74, v88, v86
	v_min_u32_e32 v86, v88, v86
	v_max_u32_e32 v88, v99, v95
	v_min_u32_e32 v95, v99, v95
	v_max_u32_e32 v99, v94, v100
	v_min_u32_e32 v100, v94, v100
	v_max_u32_e32 v94, v81, v93
	v_min_u32_e32 v93, v81, v93
	v_max_u32_e32 v81, v76, v77
	v_min_u32_e32 v77, v76, v77
	v_max_u32_e32 v76, v101, v80
	v_min_u32_e32 v80, v101, v80
	v_max_u32_e32 v101, v84, v72
	v_min_u32_e32 v72, v84, v72
	v_max_u32_e32 v84, v71, v85
	v_min_u32_e32 v85, v71, v85
	v_max_u32_e32 v71, v74, v88
	v_min_u32_e32 v88, v74, v88
	v_max_u32_e32 v74, v86, v95
	v_min_u32_e32 v95, v86, v95
	v_max_u32_e32 v86, v99, v94
	v_min_u32_e32 v94, v99, v94
	v_max_u32_e32 v99, v100, v93
	v_min_u32_e32 v93, v100, v93
	v_max_u32_e32 v100, v81, v76
	v_min_u32_e32 v76, v81, v76
	v_max_u32_e32 v81, v77, v80
	v_min_u32_e32 v80, v77, v80
	v_max_u32_e32 v77, v101, v84
	v_min_u32_e32 v84, v101, v84
	v_max_u32_e32 v101, v72, v85
	v_min_u32_e32 v85, v72, v85
	s_mov_b64 s[38:39], s[34:35]
	global_load_dwordx4 v[32:35], v66, s[38:39] offset:384
	s_add_u32 s38, s38, 0x8000
	s_addc_u32 s39, s39, 0
	global_load_dwordx4 v[36:39], v66, s[38:39] offset:384
	s_add_u32 s38, s38, 0x8000
	s_addc_u32 s39, s39, 0
	global_load_dwordx4 v[40:43], v66, s[38:39] offset:384
	s_add_u32 s38, s38, 0x8000
	s_addc_u32 s39, s39, 0
	global_load_dwordx4 v[44:47], v66, s[38:39] offset:384
	s_add_u32 s38, s38, 0x8000
	s_addc_u32 s39, s39, 0
	global_load_dwordx4 v[48:51], v66, s[38:39] offset:384
	s_add_u32 s38, s38, 0x8000
	s_addc_u32 s39, s39, 0
	global_load_dwordx4 v[52:55], v66, s[38:39] offset:384
	s_add_u32 s38, s38, 0x8000
	s_addc_u32 s39, s39, 0
	global_load_dwordx4 v[56:59], v66, s[38:39] offset:384
	s_add_u32 s38, s38, 0x8000
	s_addc_u32 s39, s39, 0
	global_load_dwordx4 v[60:63], v66, s[38:39] offset:384
	s_waitcnt vmcnt(8)
	ds_write_b128 v64, v[0:3] offset:0
	ds_write_b128 v64, v[4:7] offset:1152
	ds_write_b128 v64, v[8:11] offset:2304
	ds_write_b128 v64, v[12:15] offset:3456
	ds_write_b128 v64, v[16:19] offset:4608
	ds_write_b128 v64, v[20:23] offset:5760
	ds_write_b128 v64, v[24:27] offset:6912
	ds_write_b128 v64, v[28:31] offset:8064
	s_waitcnt lgkmcnt(0)
	ds_read_b128 v[0:3], v65 offset:0
	ds_read_b128 v[4:7], v65 offset:16
	ds_read_b128 v[8:11], v65 offset:32
	ds_read_b128 v[12:15], v65 offset:48
	ds_read_b128 v[16:19], v65 offset:64
	ds_read_b128 v[20:23], v65 offset:80
	ds_read_b128 v[24:27], v65 offset:96
	ds_read_b128 v[28:31], v65 offset:112
	s_waitcnt lgkmcnt(0)
; __device__ __forceinline__ unsigned f2key(float f) { const unsigned u = __float_as_uint(f); return (u & 0x80000000u) ? ~u : (u | 0x80000000u); }
; #define CE_DESC(a, b) do { const unsigned _mx = (a) > (b) ? (a) : (b), _mn = (a) > (b) ? (b) : (a); (a) = _mx; (b) = _mn; } while (0)
; __device__ __forceinline__ void sort16_desc(unsigned (&k)[16]) {
; #pragma unroll
;     for (int size = 2; size <= 16; size <<= 1)
; #pragma unroll
;         for (int stride = size >> 1; stride > 0; stride >>= 1)
; #pragma unroll
;             for (int i = 0; i < 16; ++i) { const int j = i ^ stride;
;                 if (j > i) { if ((i & size) == 0) CE_DESC(k[i], k[j]); else CE_DESC(k[j], k[i]); } }
; }
; __device__ __forceinline__ void peer_tile(const Args& A, LAS unsigned char* lds, int tile) {
;     ...
;                   for (int i = 0; i < 16; ++i) {
;                       const float lo = (float)__builtin_bit_cast(_Float16, (unsigned short)(sw[i] & 0xffffu)), hi = (float)__builtin_bit_cast(_Float16, (unsigned short)(sw[i] >> 16));
;                       const unsigned klo = (f2key(lo) & ~127u) | (unsigned)(127 - (32 * g + 2 * i)), khi = (f2key(hi) & ~127u) | (unsigned)(127 - (32 * g + 2 * i + 1));
;                       if (i < 8) { k0[2 * i] = klo; k0[2 * i + 1] = khi; } else { k1[2 * (i - 8)] = klo; k1[2 * (i - 8) + 1] = khi; } } }
	v_cvt_f32_f16_e32 v72, v0
	v_cvt_f32_f16_sdwa v73, v0 dst_sel:DWORD dst_unused:UNUSED_PAD src0_sel:WORD_1
	v_ashrrev_i32_e32 v97, 31, v72
	v_bitop3_b32 v72, v72, v97, s40 bitop3:0x78
	v_xor_b32_e32 v72, 0x8000007f, v72
	v_ashrrev_i32_e32 v97, 31, v73
	v_bitop3_b32 v73, v73, v97, s40 bitop3:0x78
	v_xor_b32_e32 v73, 0x8000007e, v73
	v_cvt_f32_f16_e32 v97, v1
	v_cvt_f32_f16_sdwa v102, v1 dst_sel:DWORD dst_unused:UNUSED_PAD src0_sel:WORD_1
	v_ashrrev_i32_e32 v82, 31, v97
	v_bitop3_b32 v97, v97, v82, s40 bitop3:0x78
	v_xor_b32_e32 v97, 0x8000007d, v97
	v_ashrrev_i32_e32 v82, 31, v102
	v_bitop3_b32 v102, v102, v82, s40 bitop3:0x78
	v_xor_b32_e32 v102, 0x8000007c, v102
	v_cvt_f32_f16_e32 v82, v2
	v_cvt_f32_f16_sdwa v78, v2 dst_sel:DWORD dst_unused:UNUSED_PAD src0_sel:WORD_1
	v_ashrrev_i32_e32 v70, 31, v82
	v_bitop3_b32 v82, v82, v70, s40 bitop3:0x78
	v_xor_b32_e32 v82, 0x8000007b, v82
	v_ashrrev_i32_e32 v70, 31, v78
	v_bitop3_b32 v78, v78, v70, s40 bitop3:0x78
	v_xor_b32_e32 v78, 0x8000007a, v78
	v_cvt_f32_f16_e32 v70, v3
	v_cvt_f32_f16_sdwa v87, v3 dst_sel:DWORD dst_unused:UNUSED_PAD src0_sel:WORD_1
	v_ashrrev_i32_e32 v92, 31, v70
	v_bitop3_b32 v70, v70, v92, s40 bitop3:0x78
	v_xor_b32_e32 v70, 0x80000079, v70
	v_ashrrev_i32_e32 v92, 31, v87
	v_bitop3_b32 v87, v87, v92, s40 bitop3:0x78
	v_xor_b32_e32 v87, 0x80000078, v87
	v_cvt_f32_f16_e32 v92, v4
	v_cvt_f32_f16_sdwa v90, v4 dst_sel:DWORD dst_unused:UNUSED_PAD src0_sel:WORD_1
	v_ashrrev_i32_e32 v91, 31, v92
	v_bitop3_b32 v92, v92, v91, s40 bitop3:0x78
	v_xor_b32_e32 v92, 0x80000077, v92
	v_ashrrev_i32_e32 v91, 31, v90
	v_bitop3_b32 v90, v90, v91, s40 bitop3:0x78
	v_xor_b32_e32 v90, 0x80000076, v90
	v_cvt_f32_f16_e32 v91, v5
	v_cvt_f32_f16_sdwa v83, v5 dst_sel:DWORD dst_unused:UNUSED_PAD src0_sel:WORD_1
	v_ashrrev_i32_e32 v75, 31, v91
	v_bitop3_b32 v91, v91, v75, s40 bitop3:0x78
	v_xor_b32_e32 v91, 0x80000075, v91
	v_ashrrev_i32_e32 v75, 31, v83
	v_bitop3_b32 v83, v83, v75, s40 bitop3:0x78
	v_xor_b32_e32 v83, 0x80000074, v83
	v_cvt_f32_f16_e32 v75, v6
	v_cvt_f32_f16_sdwa v98, v6 dst_sel:DWORD dst_unused:UNUSED_PAD src0_sel:WORD_1
	v_ashrrev_i32_e32 v89, 31, v75
	v_bitop3_b32 v75, v75, v89, s40 bitop3:0x78
	v_xor_b32_e32 v75, 0x80000073, v75
	v_ashrrev_i32_e32 v89, 31, v98
	v_bitop3_b32 v98, v98, v89, s40 bitop3:0x78
	v_xor_b32_e32 v98, 0x80000072, v98
	v_cvt_f32_f16_e32 v89, v7
	v_cvt_f32_f16_sdwa v96, v7 dst_sel:DWORD dst_unused:UNUSED_PAD src0_sel:WORD_1
	v_ashrrev_i32_e32 v79, 31, v89
	v_bitop3_b32 v89, v89, v79, s40 bitop3:0x78
	v_xor_b32_e32 v89, 0x80000071, v89
	v_ashrrev_i32_e32 v79, 31, v96
	v_bitop3_b32 v96, v96, v79, s40 bitop3:0x78
	v_xor_b32_e32 v96, 0x80000070, v96
	v_max_u32_e32 v79, v72, v98
	v_min_u32_e32 v98, v72, v98
	v_max_u32_e32 v72, v73, v75
	v_min_u32_e32 v75, v73, v75
	v_max_u32_e32 v73, v97, v96
	v_min_u32_e32 v96, v97, v96
	v_max_u32_e32 v97, v102, v89
	v_min_u32_e32 v89, v102, v89
	v_max_u32_e32 v102, v82, v92
	v_min_u32_e32 v92, v82, v92
	v_max_u32_e32 v82, v78, v70
	v_min_u32_e32 v70, v78, v70
	v_max_u32_e32 v78, v87, v83
	v_min_u32_e32 v83, v87, v83
	v_max_u32_e32 v87, v90, v91
	v_min_u32_e32 v91, v90, v91
	v_max_u32_e32 v90, v79, v82
	v_min_u32_e32 v82, v79, v82
	v_max_u32_e32 v79, v72, v78
	v_min_u32_e32 v78, v72, v78
	v_max_u32_e32 v72, v73, v87
	v_min_u32_e32 v87, v73, v87
	v_max_u32_e32 v73, v97, v102
	v_min_u32_e32 v102, v97, v102
	v_max_u32_e32 v97, v70, v98
	v_min_u32_e32 v98, v70, v98
	v_max_u32_e32 v70, v92, v89
	v_min_u32_e32 v89, v92, v89
	v_max_u32_e32 v92, v91, v96
	v_min_u32_e32 v96, v91, v96
	v_max_u32_e32 v91, v83, v75
	v_min_u32_e32 v75, v83, v75
	v_max_u32_e32 v83, v90, v79
	v_min_u32_e32 v79, v90, v79
	v_max_u32_e32 v90, v72, v73
	v_min_u32_e32 v73, v72, v73
	v_max_u32_e32 v72, v102, v82
	v_min_u32_e32 v82, v102, v82
	v_max_u32_e32 v102, v97, v70
	v_min_u32_e32 v70, v97, v70
	v_max_u32_e32 v97, v78, v87
	v_min_u32_e32 v87, v78, v87
	v_max_u32_e32 v78, v92, v91
	v_min_u32_e32 v91, v92, v91
	v_max_u32_e32 v92, v75, v98
	v_min_u32_e32 v98, v75, v98
	v_max_u32_e32 v75, v89, v96
	v_min_u32_e32 v96, v89, v96
	v_max_u32_e32 v89, v83, v90
	v_min_u32_e32 v90, v83, v90
	v_max_u32_e32 v83, v79, v73
	v_min_u32_e32 v73, v79, v73
	v_max_u32_e32 v79, v72, v78
	v_min_u32_e32 v78, v72, v78
	v_max_u32_e32 v72, v82, v91
	v_min_u32_e32 v91, v82, v91
	v_max_u32_e32 v82, v102, v97
	v_min_u32_e32 v97, v102, v97
	v_max_u32_e32 v102, v70, v87
	v_min_u32_e32 v87, v70, v87
	v_max_u32_e32 v70, v92, v75
	v_min_u32_e32 v75, v92, v75
	v_max_u32_e32 v92, v98, v96
	v_min_u32_e32 v96, v98, v96
	v_max_u32_e32 v98, v83, v90
	v_min_u32_e32 v90, v83, v90
	v_max_u32_e32 v83, v73, v70
	v_min_u32_e32 v70, v73, v70
	v_max_u32_e32 v73, v79, v82
	v_min_u32_e32 v82, v79, v82
	v_max_u32_e32 v79, v72, v97
	v_min_u32_e32 v97, v72, v97
	v_max_u32_e32 v72, v102, v78
	v_min_u32_e32 v78, v102, v78
	v_max_u32_e32 v102, v87, v91
	v_min_u32_e32 v91, v87, v91
	v_max_u32_e32 v87, v92, v75
	v_min_u32_e32 v75, v92, v75
	v_max_u32_e32 v92, v98, v73
	v_min_u32_e32 v73, v98, v73
	v_max_u32_e32 v98, v90, v82
	v_min_u32_e32 v82, v90, v82
	v_max_u32_e32 v90, v79, v72
	v_min_u32_e32 v72, v79, v72
	v_max_u32_e32 v79, v97, v78
	v_min_u32_e32 v78, v97, v78
	v_max_u32_e32 v97, v102, v87
	v_min_u32_e32 v87, v102, v87
	v_max_u32_e32 v102, v91, v75
	v_min_u32_e32 v75, v91, v75
	v_max_u32_e32 v91, v98, v73
	v_min_u32_e32 v73, v98, v73
	v_max_u32_e32 v98, v83, v82
	v_min_u32_e32 v82, v83, v82
	v_max_u32_e32 v83, v97, v70
	v_min_u32_e32 v70, v97, v70
	v_max_u32_e32 v97, v102, v87
	v_min_u32_e32 v87, v102, v87
	v_max_u32_e32 v102, v98, v90
	v_min_u32_e32 v90, v98, v90
	v_max_u32_e32 v98, v82, v72
	v_min_u32_e32 v72, v82, v72
; __device__ __forceinline__ unsigned f2key(float f) { const unsigned u = __float_as_uint(f); return (u & 0x80000000u) ? ~u : (u | 0x80000000u); }
; #define CE_DESC(a, b) do { const unsigned _mx = (a) > (b) ? (a) : (b), _mn = (a) > (b) ? (b) : (a); (a) = _mx; (b) = _mn; } while (0)
; __device__ __forceinline__ void sort16_desc(unsigned (&k)[16]) {
; #pragma unroll
;     for (int size = 2; size <= 16; size <<= 1)
; #pragma unroll
;         for (int stride = size >> 1; stride > 0; stride >>= 1)
; #pragma unroll
;             for (int i = 0; i < 16; ++i) { const int j = i ^ stride;
;                 if (j > i) { if ((i & size) == 0) CE_DESC(k[i], k[j]); else CE_DESC(k[j], k[i]); } }
; }
; __device__ __forceinline__ void peer_tile(const Args& A, LAS unsigned char* lds, int tile) {
;     ...
;                   for (int i = 0; i < 16; ++i) {
;                       const float lo = (float)__builtin_bit_cast(_Float16, (unsigned short)(sw[i] & 0xffffu)), hi = (float)__builtin_bit_cast(_Float16, (unsigned short)(sw[i] >> 16));
;                       const unsigned klo = (f2key(lo) & ~127u) | (unsigned)(127 - (32 * g + 2 * i)), khi = (f2key(hi) & ~127u) | (unsigned)(127 - (32 * g + 2 * i + 1));
;                       if (i < 8) { k0[2 * i] = klo; k0[2 * i + 1] = khi; } else { k1[2 * (i - 8)] = klo; k1[2 * (i - 8) + 1] = khi; } } }
	v_max_u32_e32 v82, v79, v83
	v_min_u32_e32 v83, v79, v83
	v_max_u32_e32 v79, v78, v70
	v_min_u32_e32 v70, v78, v70
	v_max_u32_e32 v78, v102, v73
	v_min_u32_e32 v73, v102, v73
	v_max_u32_e32 v102, v90, v98
	v_min_u32_e32 v98, v90, v98
	v_max_u32_e32 v90, v82, v72
	v_min_u32_e32 v72, v82, v72
	v_max_u32_e32 v82, v83, v79
	v_min_u32_e32 v79, v83, v79
	v_max_u32_e32 v83, v97, v70
	v_min_u32_e32 v70, v97, v70
	v_max_u32_e32 v97, v98, v90
	v_min_u32_e32 v90, v98, v90
	v_max_u32_e32 v98, v72, v82
	v_min_u32_e32 v82, v72, v82
	v_cvt_f32_f16_e32 v72, v8
	v_cvt_f32_f16_sdwa v103, v8 dst_sel:DWORD dst_unused:UNUSED_PAD src0_sel:WORD_1
	v_ashrrev_i32_e32 v104, 31, v72
	v_bitop3_b32 v72, v72, v104, s40 bitop3:0x78
	v_xor_b32_e32 v72, 0x8000006f, v72
	v_ashrrev_i32_e32 v104, 31, v103
	v_bitop3_b32 v103, v103, v104, s40 bitop3:0x78
	v_xor_b32_e32 v103, 0x8000006e, v103
	v_cvt_f32_f16_e32 v104, v9
	v_cvt_f32_f16_sdwa v105, v9 dst_sel:DWORD dst_unused:UNUSED_PAD src0_sel:WORD_1
	v_ashrrev_i32_e32 v106, 31, v104
	v_bitop3_b32 v104, v104, v106, s40 bitop3:0x78
	v_xor_b32_e32 v104, 0x8000006d, v104
	v_ashrrev_i32_e32 v106, 31, v105
	v_bitop3_b32 v105, v105, v106, s40 bitop3:0x78
	v_xor_b32_e32 v105, 0x8000006c, v105
	v_cvt_f32_f16_e32 v106, v10
	v_cvt_f32_f16_sdwa v107, v10 dst_sel:DWORD dst_unused:UNUSED_PAD src0_sel:WORD_1
	v_ashrrev_i32_e32 v108, 31, v106
	v_bitop3_b32 v106, v106, v108, s40 bitop3:0x78
	v_xor_b32_e32 v106, 0x8000006b, v106
	v_ashrrev_i32_e32 v108, 31, v107
	v_bitop3_b32 v107, v107, v108, s40 bitop3:0x78
	v_xor_b32_e32 v107, 0x8000006a, v107
	v_cvt_f32_f16_e32 v108, v11
	v_cvt_f32_f16_sdwa v109, v11 dst_sel:DWORD dst_unused:UNUSED_PAD src0_sel:WORD_1
	v_ashrrev_i32_e32 v110, 31, v108
	v_bitop3_b32 v108, v108, v110, s40 bitop3:0x78
	v_xor_b32_e32 v108, 0x80000069, v108
	v_ashrrev_i32_e32 v110, 31, v109
	v_bitop3_b32 v109, v109, v110, s40 bitop3:0x78
	v_xor_b32_e32 v109, 0x80000068, v109
	v_cvt_f32_f16_e32 v110, v12
	v_cvt_f32_f16_sdwa v111, v12 dst_sel:DWORD dst_unused:UNUSED_PAD src0_sel:WORD_1
	v_ashrrev_i32_e32 v112, 31, v110
	v_bitop3_b32 v110, v110, v112, s40 bitop3:0x78
	v_xor_b32_e32 v110, 0x80000067, v110
	v_ashrrev_i32_e32 v112, 31, v111
	v_bitop3_b32 v111, v111, v112, s40 bitop3:0x78
	v_xor_b32_e32 v111, 0x80000066, v111
	v_cvt_f32_f16_e32 v112, v13
	v_cvt_f32_f16_sdwa v114, v13 dst_sel:DWORD dst_unused:UNUSED_PAD src0_sel:WORD_1
	v_ashrrev_i32_e32 v115, 31, v112
	v_bitop3_b32 v112, v112, v115, s40 bitop3:0x78
	v_xor_b32_e32 v112, 0x80000065, v112
	v_ashrrev_i32_e32 v115, 31, v114
	v_bitop3_b32 v114, v114, v115, s40 bitop3:0x78
	v_xor_b32_e32 v114, 0x80000064, v114
	v_cvt_f32_f16_e32 v115, v14
	v_cvt_f32_f16_sdwa v116, v14 dst_sel:DWORD dst_unused:UNUSED_PAD src0_sel:WORD_1
	v_ashrrev_i32_e32 v117, 31, v115
	v_bitop3_b32 v115, v115, v117, s40 bitop3:0x78
	v_xor_b32_e32 v115, 0x80000063, v115
	v_ashrrev_i32_e32 v117, 31, v116
	v_bitop3_b32 v116, v116, v117, s40 bitop3:0x78
	v_xor_b32_e32 v116, 0x80000062, v116
	v_cvt_f32_f16_e32 v117, v15
	v_cvt_f32_f16_sdwa v118, v15 dst_sel:DWORD dst_unused:UNUSED_PAD src0_sel:WORD_1
	v_ashrrev_i32_e32 v119, 31, v117
	v_bitop3_b32 v117, v117, v119, s40 bitop3:0x78
	v_xor_b32_e32 v117, 0x80000061, v117
	v_ashrrev_i32_e32 v119, 31, v118
	v_bitop3_b32 v118, v118, v119, s40 bitop3:0x78
	v_xor_b32_e32 v118, 0x80000060, v118
	v_max_u32_e32 v119, v72, v116
	v_min_u32_e32 v116, v72, v116
	v_max_u32_e32 v72, v103, v115
	v_min_u32_e32 v115, v103, v115
	v_max_u32_e32 v103, v104, v118
	v_min_u32_e32 v118, v104, v118
	v_max_u32_e32 v104, v105, v117
	v_min_u32_e32 v117, v105, v117
	v_max_u32_e32 v105, v106, v110
	v_min_u32_e32 v110, v106, v110
	v_max_u32_e32 v106, v107, v108
	v_min_u32_e32 v108, v107, v108
	v_max_u32_e32 v107, v109, v114
	v_min_u32_e32 v114, v109, v114
	v_max_u32_e32 v109, v111, v112
	v_min_u32_e32 v112, v111, v112
	v_max_u32_e32 v111, v119, v106
	v_min_u32_e32 v106, v119, v106
	v_max_u32_e32 v119, v72, v107
	v_min_u32_e32 v107, v72, v107
	v_max_u32_e32 v72, v103, v109
	v_min_u32_e32 v109, v103, v109
	v_max_u32_e32 v103, v104, v105
	v_min_u32_e32 v105, v104, v105
	v_max_u32_e32 v104, v108, v116
	v_min_u32_e32 v116, v108, v116
	v_max_u32_e32 v108, v110, v117
	v_min_u32_e32 v117, v110, v117
	v_max_u32_e32 v110, v112, v118
	v_min_u32_e32 v118, v112, v118
	v_max_u32_e32 v112, v114, v115
	v_min_u32_e32 v115, v114, v115
	v_max_u32_e32 v114, v111, v119
	v_min_u32_e32 v119, v111, v119
	v_max_u32_e32 v111, v72, v103
	v_min_u32_e32 v103, v72, v103
	v_max_u32_e32 v72, v105, v106
	v_min_u32_e32 v106, v105, v106
	v_max_u32_e32 v105, v104, v108
	v_min_u32_e32 v108, v104, v108
	v_max_u32_e32 v104, v107, v109
	v_min_u32_e32 v109, v107, v109
	v_max_u32_e32 v107, v110, v112
	v_min_u32_e32 v112, v110, v112
	v_max_u32_e32 v110, v115, v116
	v_min_u32_e32 v116, v115, v116
	v_max_u32_e32 v115, v117, v118
	v_min_u32_e32 v118, v117, v118
	v_max_u32_e32 v117, v114, v111
	v_min_u32_e32 v111, v114, v111
	v_max_u32_e32 v114, v119, v103
	v_min_u32_e32 v103, v119, v103
	v_max_u32_e32 v119, v72, v107
	v_min_u32_e32 v107, v72, v107
	v_max_u32_e32 v72, v106, v112
	v_min_u32_e32 v112, v106, v112
	v_max_u32_e32 v106, v105, v104
	v_min_u32_e32 v104, v105, v104
	v_max_u32_e32 v105, v108, v109
	v_min_u32_e32 v109, v108, v109
	v_max_u32_e32 v108, v110, v115
	v_min_u32_e32 v115, v110, v115
	v_max_u32_e32 v110, v116, v118
	v_min_u32_e32 v118, v116, v118
	v_max_u32_e32 v116, v114, v111
	v_min_u32_e32 v111, v114, v111
	v_max_u32_e32 v114, v103, v108
	v_min_u32_e32 v108, v103, v108
	v_max_u32_e32 v103, v119, v106
	v_min_u32_e32 v106, v119, v106
	v_max_u32_e32 v119, v72, v104
	v_min_u32_e32 v104, v72, v104
	v_max_u32_e32 v72, v105, v107
; __device__ __forceinline__ unsigned f2key(float f) { const unsigned u = __float_as_uint(f); return (u & 0x80000000u) ? ~u : (u | 0x80000000u); }
; #define CE_DESC(a, b) do { const unsigned _mx = (a) > (b) ? (a) : (b), _mn = (a) > (b) ? (b) : (a); (a) = _mx; (b) = _mn; } while (0)
; __device__ __forceinline__ void sort16_desc(unsigned (&k)[16]) {
; #pragma unroll
;     for (int size = 2; size <= 16; size <<= 1)
; #pragma unroll
;         for (int stride = size >> 1; stride > 0; stride >>= 1)
; #pragma unroll
;             for (int i = 0; i < 16; ++i) { const int j = i ^ stride;
;                 if (j > i) { if ((i & size) == 0) CE_DESC(k[i], k[j]); else CE_DESC(k[j], k[i]); } }
; }
; __device__ __forceinline__ void merge16(unsigned (&a)[16], const unsigned (&b)[16]) {
; #pragma unroll
;     for (int i = 0; i < 16; ++i) a[i] = a[i] > b[15 - i] ? a[i] : b[15 - i];
; #pragma unroll
;     for (int stride = 8; stride > 0; stride >>= 1)
; #pragma unroll
;         for (int i = 0; i < 16; ++i) { const int j = i ^ stride; if (j > i) CE_DESC(a[i], a[j]); }
; }
; __device__ __forceinline__ void peer_tile(const Args& A, LAS unsigned char* lds, int tile) {
;     ...
;                   for (int i = 0; i < 16; ++i) {
;                       const float lo = (float)__builtin_bit_cast(_Float16, (unsigned short)(sw[i] & 0xffffu)), hi = (float)__builtin_bit_cast(_Float16, (unsigned short)(sw[i] >> 16));
;                       const unsigned klo = (f2key(lo) & ~127u) | (unsigned)(127 - (32 * g + 2 * i)), khi = (f2key(hi) & ~127u) | (unsigned)(127 - (32 * g + 2 * i + 1));
;                       if (i < 8) { k0[2 * i] = klo; k0[2 * i + 1] = khi; } else { k1[2 * (i - 8)] = klo; k1[2 * (i - 8) + 1] = khi; } } }
	v_min_u32_e32 v107, v105, v107
	v_max_u32_e32 v105, v109, v112
	v_min_u32_e32 v112, v109, v112
	v_max_u32_e32 v109, v110, v115
	v_min_u32_e32 v115, v110, v115
	v_max_u32_e32 v110, v116, v103
	v_min_u32_e32 v103, v116, v103
	v_max_u32_e32 v116, v111, v106
	v_min_u32_e32 v106, v111, v106
	v_max_u32_e32 v111, v119, v72
	v_min_u32_e32 v72, v119, v72
	v_max_u32_e32 v119, v104, v107
	v_min_u32_e32 v107, v104, v107
	v_max_u32_e32 v104, v105, v109
	v_min_u32_e32 v109, v105, v109
	v_max_u32_e32 v105, v112, v115
	v_min_u32_e32 v115, v112, v115
	v_max_u32_e32 v112, v116, v103
	v_min_u32_e32 v103, v116, v103
	v_max_u32_e32 v116, v114, v106
	v_min_u32_e32 v106, v114, v106
	v_max_u32_e32 v114, v104, v108
	v_min_u32_e32 v108, v104, v108
	v_max_u32_e32 v104, v105, v109
	v_min_u32_e32 v109, v105, v109
	v_max_u32_e32 v105, v116, v111
	v_min_u32_e32 v111, v116, v111
	v_max_u32_e32 v116, v106, v72
	v_min_u32_e32 v72, v106, v72
	v_max_u32_e32 v106, v119, v114
	v_min_u32_e32 v114, v119, v114
	v_max_u32_e32 v119, v107, v108
	v_min_u32_e32 v108, v107, v108
	v_max_u32_e32 v107, v105, v103
	v_min_u32_e32 v103, v105, v103
	v_max_u32_e32 v105, v111, v116
	v_min_u32_e32 v116, v111, v116
	v_max_u32_e32 v111, v106, v72
	v_min_u32_e32 v72, v106, v72
	v_max_u32_e32 v106, v114, v119
	v_min_u32_e32 v119, v114, v119
	v_max_u32_e32 v114, v104, v108
	v_min_u32_e32 v108, v104, v108
	v_max_u32_e32 v104, v116, v111
	v_min_u32_e32 v111, v116, v111
	v_max_u32_e32 v116, v72, v106
	v_min_u32_e32 v106, v72, v106
	v_max_u32_e32 v89, v89, v118
	v_max_u32_e32 v92, v92, v115
	v_max_u32_e32 v91, v91, v109
	v_max_u32_e32 v78, v78, v108
	v_max_u32_e32 v73, v73, v114
	v_max_u32_e32 v102, v102, v119
	v_max_u32_e32 v97, v97, v106
	v_max_u32_e32 v90, v90, v116
	v_max_u32_e32 v98, v98, v111
	v_max_u32_e32 v82, v82, v104
	v_max_u32_e32 v79, v79, v105
	v_max_u32_e32 v83, v83, v103
	v_max_u32_e32 v70, v70, v107
	v_max_u32_e32 v87, v87, v112
	v_max_u32_e32 v75, v75, v110
	v_max_u32_e32 v96, v96, v117
	v_max_u32_e32 v118, v89, v98
	v_min_u32_e32 v98, v89, v98
	v_max_u32_e32 v89, v92, v82
	v_min_u32_e32 v82, v92, v82
	v_max_u32_e32 v92, v91, v79
	v_min_u32_e32 v79, v91, v79
	v_max_u32_e32 v91, v78, v83
	v_min_u32_e32 v83, v78, v83
	v_max_u32_e32 v78, v73, v70
	v_min_u32_e32 v70, v73, v70
	v_max_u32_e32 v73, v102, v87
	v_min_u32_e32 v87, v102, v87
	v_max_u32_e32 v102, v97, v75
	v_min_u32_e32 v75, v97, v75
	v_max_u32_e32 v97, v90, v96
	v_min_u32_e32 v96, v90, v96
	v_max_u32_e32 v90, v118, v78
	v_min_u32_e32 v78, v118, v78
	v_max_u32_e32 v118, v89, v73
	v_min_u32_e32 v73, v89, v73
	v_max_u32_e32 v89, v92, v102
	v_min_u32_e32 v102, v92, v102
	v_max_u32_e32 v92, v91, v97
	v_min_u32_e32 v97, v91, v97
	v_max_u32_e32 v91, v98, v70
	v_min_u32_e32 v70, v98, v70
	v_max_u32_e32 v98, v82, v87
	v_min_u32_e32 v87, v82, v87
	v_max_u32_e32 v82, v79, v75
	v_min_u32_e32 v75, v79, v75
	v_max_u32_e32 v79, v83, v96
	v_min_u32_e32 v96, v83, v96
	v_max_u32_e32 v83, v90, v89
	v_min_u32_e32 v89, v90, v89
	v_max_u32_e32 v90, v118, v92
	v_min_u32_e32 v92, v118, v92
	v_max_u32_e32 v118, v78, v102
	v_min_u32_e32 v102, v78, v102
	v_max_u32_e32 v78, v73, v97
	v_min_u32_e32 v97, v73, v97
	v_max_u32_e32 v73, v91, v82
	v_min_u32_e32 v82, v91, v82
	v_max_u32_e32 v91, v98, v79
	v_min_u32_e32 v79, v98, v79
	v_max_u32_e32 v98, v70, v75
	v_min_u32_e32 v75, v70, v75
	v_max_u32_e32 v70, v87, v96
	v_min_u32_e32 v96, v87, v96
	v_max_u32_e32 v87, v83, v90
	v_min_u32_e32 v90, v83, v90
	v_max_u32_e32 v83, v89, v92
	v_min_u32_e32 v92, v89, v92
	v_max_u32_e32 v89, v118, v78
	v_min_u32_e32 v78, v118, v78
	v_max_u32_e32 v118, v102, v97
	v_min_u32_e32 v97, v102, v97
	v_max_u32_e32 v102, v73, v91
	v_min_u32_e32 v91, v73, v91
	v_max_u32_e32 v73, v82, v79
	v_min_u32_e32 v79, v82, v79
	v_max_u32_e32 v82, v98, v70
	v_min_u32_e32 v70, v98, v70
	v_max_u32_e32 v98, v75, v96
	v_min_u32_e32 v96, v75, v96
	v_cvt_f32_f16_e32 v75, v16
	v_cvt_f32_f16_sdwa v115, v16 dst_sel:DWORD dst_unused:UNUSED_PAD src0_sel:WORD_1
	v_ashrrev_i32_e32 v109, 31, v75
	v_bitop3_b32 v75, v75, v109, s40 bitop3:0x78
	v_xor_b32_e32 v75, 0x8000005f, v75
	v_ashrrev_i32_e32 v109, 31, v115
	v_bitop3_b32 v115, v115, v109, s40 bitop3:0x78
	v_xor_b32_e32 v115, 0x8000005e, v115
	v_cvt_f32_f16_e32 v109, v17
	v_cvt_f32_f16_sdwa v108, v17 dst_sel:DWORD dst_unused:UNUSED_PAD src0_sel:WORD_1
	v_ashrrev_i32_e32 v114, 31, v109
	v_bitop3_b32 v109, v109, v114, s40 bitop3:0x78
	v_xor_b32_e32 v109, 0x8000005d, v109
	v_ashrrev_i32_e32 v114, 31, v108
	v_bitop3_b32 v108, v108, v114, s40 bitop3:0x78
	v_xor_b32_e32 v108, 0x8000005c, v108
	v_cvt_f32_f16_e32 v114, v18
	v_cvt_f32_f16_sdwa v119, v18 dst_sel:DWORD dst_unused:UNUSED_PAD src0_sel:WORD_1
	v_ashrrev_i32_e32 v106, 31, v114
	v_bitop3_b32 v114, v114, v106, s40 bitop3:0x78
	v_xor_b32_e32 v114, 0x8000005b, v114
	v_ashrrev_i32_e32 v106, 31, v119
	v_bitop3_b32 v119, v119, v106, s40 bitop3:0x78
	v_xor_b32_e32 v119, 0x8000005a, v119
	v_cvt_f32_f16_e32 v106, v19
	v_cvt_f32_f16_sdwa v116, v19 dst_sel:DWORD dst_unused:UNUSED_PAD src0_sel:WORD_1
	v_ashrrev_i32_e32 v111, 31, v106
	v_bitop3_b32 v106, v106, v111, s40 bitop3:0x78
	v_xor_b32_e32 v106, 0x80000059, v106
	v_ashrrev_i32_e32 v111, 31, v116
	v_bitop3_b32 v116, v116, v111, s40 bitop3:0x78
	v_xor_b32_e32 v116, 0x80000058, v116
	v_cvt_f32_f16_e32 v111, v20
	v_cvt_f32_f16_sdwa v104, v20 dst_sel:DWORD dst_unused:UNUSED_PAD src0_sel:WORD_1
	v_ashrrev_i32_e32 v105, 31, v111
	v_bitop3_b32 v111, v111, v105, s40 bitop3:0x78
	v_xor_b32_e32 v111, 0x80000057, v111
	v_ashrrev_i32_e32 v105, 31, v104
	v_bitop3_b32 v104, v104, v105, s40 bitop3:0x78
	v_xor_b32_e32 v104, 0x80000056, v104
	v_cvt_f32_f16_e32 v105, v21
; __device__ __forceinline__ unsigned f2key(float f) { const unsigned u = __float_as_uint(f); return (u & 0x80000000u) ? ~u : (u | 0x80000000u); }
; #define CE_DESC(a, b) do { const unsigned _mx = (a) > (b) ? (a) : (b), _mn = (a) > (b) ? (b) : (a); (a) = _mx; (b) = _mn; } while (0)
; __device__ __forceinline__ void sort16_desc(unsigned (&k)[16]) {
; #pragma unroll
;     for (int size = 2; size <= 16; size <<= 1)
; #pragma unroll
;         for (int stride = size >> 1; stride > 0; stride >>= 1)
; #pragma unroll
;             for (int i = 0; i < 16; ++i) { const int j = i ^ stride;
;                 if (j > i) { if ((i & size) == 0) CE_DESC(k[i], k[j]); else CE_DESC(k[j], k[i]); } }
; }
; __device__ __forceinline__ void merge16(unsigned (&a)[16], const unsigned (&b)[16]) {
; #pragma unroll
;     for (int i = 0; i < 16; ++i) a[i] = a[i] > b[15 - i] ? a[i] : b[15 - i];
; #pragma unroll
;     for (int stride = 8; stride > 0; stride >>= 1)
; #pragma unroll
;         for (int i = 0; i < 16; ++i) { const int j = i ^ stride; if (j > i) CE_DESC(a[i], a[j]); }
; }
; __device__ __forceinline__ void peer_tile(const Args& A, LAS unsigned char* lds, int tile) {
;     ...
;                   for (int i = 0; i < 16; ++i) {
;                       const float lo = (float)__builtin_bit_cast(_Float16, (unsigned short)(sw[i] & 0xffffu)), hi = (float)__builtin_bit_cast(_Float16, (unsigned short)(sw[i] >> 16));
;                       const unsigned klo = (f2key(lo) & ~127u) | (unsigned)(127 - (32 * g + 2 * i)), khi = (f2key(hi) & ~127u) | (unsigned)(127 - (32 * g + 2 * i + 1));
;                       if (i < 8) { k0[2 * i] = klo; k0[2 * i + 1] = khi; } else { k1[2 * (i - 8)] = klo; k1[2 * (i - 8) + 1] = khi; } } }
	v_cvt_f32_f16_sdwa v103, v21 dst_sel:DWORD dst_unused:UNUSED_PAD src0_sel:WORD_1
	v_ashrrev_i32_e32 v107, 31, v105
	v_bitop3_b32 v105, v105, v107, s40 bitop3:0x78
	v_xor_b32_e32 v105, 0x80000055, v105
	v_ashrrev_i32_e32 v107, 31, v103
	v_bitop3_b32 v103, v103, v107, s40 bitop3:0x78
	v_xor_b32_e32 v103, 0x80000054, v103
	v_cvt_f32_f16_e32 v107, v22
	v_cvt_f32_f16_sdwa v112, v22 dst_sel:DWORD dst_unused:UNUSED_PAD src0_sel:WORD_1
	v_ashrrev_i32_e32 v110, 31, v107
	v_bitop3_b32 v107, v107, v110, s40 bitop3:0x78
	v_xor_b32_e32 v107, 0x80000053, v107
	v_ashrrev_i32_e32 v110, 31, v112
	v_bitop3_b32 v112, v112, v110, s40 bitop3:0x78
	v_xor_b32_e32 v112, 0x80000052, v112
	v_cvt_f32_f16_e32 v110, v23
	v_cvt_f32_f16_sdwa v117, v23 dst_sel:DWORD dst_unused:UNUSED_PAD src0_sel:WORD_1
	v_ashrrev_i32_e32 v72, 31, v110
	v_bitop3_b32 v110, v110, v72, s40 bitop3:0x78
	v_xor_b32_e32 v110, 0x80000051, v110
	v_ashrrev_i32_e32 v72, 31, v117
	v_bitop3_b32 v117, v117, v72, s40 bitop3:0x78
	v_xor_b32_e32 v117, 0x80000050, v117
	v_max_u32_e32 v72, v75, v112
	v_min_u32_e32 v112, v75, v112
	v_max_u32_e32 v75, v115, v107
	v_min_u32_e32 v107, v115, v107
	v_max_u32_e32 v115, v109, v117
	v_min_u32_e32 v117, v109, v117
	v_max_u32_e32 v109, v108, v110
	v_min_u32_e32 v110, v108, v110
	v_max_u32_e32 v108, v114, v111
	v_min_u32_e32 v111, v114, v111
	v_max_u32_e32 v114, v119, v106
	v_min_u32_e32 v106, v119, v106
	v_max_u32_e32 v119, v116, v103
	v_min_u32_e32 v103, v116, v103
	v_max_u32_e32 v116, v104, v105
	v_min_u32_e32 v105, v104, v105
	v_max_u32_e32 v104, v72, v114
	v_min_u32_e32 v114, v72, v114
	v_max_u32_e32 v72, v75, v119
	v_min_u32_e32 v119, v75, v119
	v_max_u32_e32 v75, v115, v116
	v_min_u32_e32 v116, v115, v116
	v_max_u32_e32 v115, v109, v108
	v_min_u32_e32 v108, v109, v108
	v_max_u32_e32 v109, v106, v112
	v_min_u32_e32 v112, v106, v112
	v_max_u32_e32 v106, v111, v110
	v_min_u32_e32 v110, v111, v110
	v_max_u32_e32 v111, v105, v117
	v_min_u32_e32 v117, v105, v117
	v_max_u32_e32 v105, v103, v107
	v_min_u32_e32 v107, v103, v107
	v_max_u32_e32 v103, v104, v72
	v_min_u32_e32 v72, v104, v72
	v_max_u32_e32 v104, v75, v115
	v_min_u32_e32 v115, v75, v115
	v_max_u32_e32 v75, v108, v114
	v_min_u32_e32 v114, v108, v114
	v_max_u32_e32 v108, v109, v106
	v_min_u32_e32 v106, v109, v106
	v_max_u32_e32 v109, v119, v116
	v_min_u32_e32 v116, v119, v116
	v_max_u32_e32 v119, v111, v105
	v_min_u32_e32 v105, v111, v105
	v_max_u32_e32 v111, v107, v112
	v_min_u32_e32 v112, v107, v112
	v_max_u32_e32 v107, v110, v117
	v_min_u32_e32 v117, v110, v117
	v_max_u32_e32 v110, v103, v104
	v_min_u32_e32 v104, v103, v104
	v_max_u32_e32 v103, v72, v115
	v_min_u32_e32 v115, v72, v115
	v_max_u32_e32 v72, v75, v119
	v_min_u32_e32 v119, v75, v119
	v_max_u32_e32 v75, v114, v105
	v_min_u32_e32 v105, v114, v105
	v_max_u32_e32 v114, v108, v109
	v_min_u32_e32 v109, v108, v109
	v_max_u32_e32 v108, v106, v116
	v_min_u32_e32 v116, v106, v116
	v_max_u32_e32 v106, v111, v107
	v_min_u32_e32 v107, v111, v107
	v_max_u32_e32 v111, v112, v117
	v_min_u32_e32 v117, v112, v117
	v_max_u32_e32 v112, v103, v104
	v_min_u32_e32 v104, v103, v104
	v_max_u32_e32 v103, v115, v106
	v_min_u32_e32 v106, v115, v106
	v_max_u32_e32 v115, v72, v114
	v_min_u32_e32 v114, v72, v114
	v_max_u32_e32 v72, v75, v109
	v_min_u32_e32 v109, v75, v109
	v_max_u32_e32 v75, v108, v119
	v_min_u32_e32 v119, v108, v119
	v_max_u32_e32 v108, v116, v105
	v_min_u32_e32 v105, v116, v105
	v_max_u32_e32 v116, v111, v107
	v_min_u32_e32 v107, v111, v107
	v_max_u32_e32 v111, v112, v115
	v_min_u32_e32 v115, v112, v115
	v_max_u32_e32 v112, v104, v114
	v_min_u32_e32 v114, v104, v114
	v_max_u32_e32 v104, v72, v75
	v_min_u32_e32 v75, v72, v75
	v_max_u32_e32 v72, v109, v119
	v_min_u32_e32 v119, v109, v119
	v_max_u32_e32 v109, v108, v116
	v_min_u32_e32 v116, v108, v116
	v_max_u32_e32 v108, v105, v107
	v_min_u32_e32 v107, v105, v107
	v_max_u32_e32 v105, v112, v115
	v_min_u32_e32 v115, v112, v115
	v_max_u32_e32 v112, v103, v114
	v_min_u32_e32 v114, v103, v114
	v_max_u32_e32 v103, v109, v106
	v_min_u32_e32 v106, v109, v106
	v_max_u32_e32 v109, v108, v116
	v_min_u32_e32 v116, v108, v116
	v_max_u32_e32 v108, v112, v104
	v_min_u32_e32 v104, v112, v104
	v_max_u32_e32 v112, v114, v75
	v_min_u32_e32 v75, v114, v75
	v_max_u32_e32 v114, v72, v103
	v_min_u32_e32 v103, v72, v103
	v_max_u32_e32 v72, v119, v106
	v_min_u32_e32 v106, v119, v106
	v_max_u32_e32 v119, v108, v115
	v_min_u32_e32 v115, v108, v115
	v_max_u32_e32 v108, v104, v112
	v_min_u32_e32 v112, v104, v112
	v_max_u32_e32 v104, v114, v75
	v_min_u32_e32 v75, v114, v75
	v_max_u32_e32 v114, v103, v72
	v_min_u32_e32 v72, v103, v72
	v_max_u32_e32 v103, v109, v106
	v_min_u32_e32 v106, v109, v106
	v_max_u32_e32 v109, v112, v104
	v_min_u32_e32 v104, v112, v104
	v_max_u32_e32 v112, v75, v114
	v_min_u32_e32 v114, v75, v114
	v_max_u32_e32 v87, v87, v117
	v_max_u32_e32 v90, v90, v107
	v_max_u32_e32 v83, v83, v116
	v_max_u32_e32 v92, v92, v106
	v_max_u32_e32 v89, v89, v103
	v_max_u32_e32 v78, v78, v72
	v_max_u32_e32 v118, v118, v114
	v_max_u32_e32 v97, v97, v112
	v_max_u32_e32 v102, v102, v104
	v_max_u32_e32 v91, v91, v109
	v_max_u32_e32 v73, v73, v108
	v_max_u32_e32 v79, v79, v115
	v_max_u32_e32 v82, v82, v119
	v_max_u32_e32 v70, v70, v105
	v_max_u32_e32 v98, v98, v111
	v_max_u32_e32 v96, v96, v110
	v_max_u32_e32 v117, v87, v102
	v_min_u32_e32 v102, v87, v102
	v_max_u32_e32 v87, v90, v91
	v_min_u32_e32 v91, v90, v91
	v_max_u32_e32 v90, v83, v73
	v_min_u32_e32 v73, v83, v73
	v_max_u32_e32 v83, v92, v79
	v_min_u32_e32 v79, v92, v79
	v_max_u32_e32 v92, v89, v82
	v_min_u32_e32 v82, v89, v82
	v_max_u32_e32 v89, v78, v70
	v_min_u32_e32 v70, v78, v70
; __device__ __forceinline__ unsigned f2key(float f) { const unsigned u = __float_as_uint(f); return (u & 0x80000000u) ? ~u : (u | 0x80000000u); }
; #define CE_DESC(a, b) do { const unsigned _mx = (a) > (b) ? (a) : (b), _mn = (a) > (b) ? (b) : (a); (a) = _mx; (b) = _mn; } while (0)
; __device__ __forceinline__ void sort16_desc(unsigned (&k)[16]) {
; #pragma unroll
;     for (int size = 2; size <= 16; size <<= 1)
; #pragma unroll
;         for (int stride = size >> 1; stride > 0; stride >>= 1)
; #pragma unroll
;             for (int i = 0; i < 16; ++i) { const int j = i ^ stride;
;                 if (j > i) { if ((i & size) == 0) CE_DESC(k[i], k[j]); else CE_DESC(k[j], k[i]); } }
; }
; __device__ __forceinline__ void merge16(unsigned (&a)[16], const unsigned (&b)[16]) {
; #pragma unroll
;     for (int i = 0; i < 16; ++i) a[i] = a[i] > b[15 - i] ? a[i] : b[15 - i];
; #pragma unroll
;     for (int stride = 8; stride > 0; stride >>= 1)
; #pragma unroll
;         for (int i = 0; i < 16; ++i) { const int j = i ^ stride; if (j > i) CE_DESC(a[i], a[j]); }
; }
; __device__ __forceinline__ void peer_tile(const Args& A, LAS unsigned char* lds, int tile) {
;     ...
;                   for (int i = 0; i < 16; ++i) {
;                       const float lo = (float)__builtin_bit_cast(_Float16, (unsigned short)(sw[i] & 0xffffu)), hi = (float)__builtin_bit_cast(_Float16, (unsigned short)(sw[i] >> 16));
;                       const unsigned klo = (f2key(lo) & ~127u) | (unsigned)(127 - (32 * g + 2 * i)), khi = (f2key(hi) & ~127u) | (unsigned)(127 - (32 * g + 2 * i + 1));
;                       if (i < 8) { k0[2 * i] = klo; k0[2 * i + 1] = khi; } else { k1[2 * (i - 8)] = klo; k1[2 * (i - 8) + 1] = khi; } } }
	v_max_u32_e32 v78, v118, v98
	v_min_u32_e32 v98, v118, v98
	v_max_u32_e32 v118, v97, v96
	v_min_u32_e32 v96, v97, v96
	v_max_u32_e32 v97, v117, v92
	v_min_u32_e32 v92, v117, v92
	v_max_u32_e32 v117, v87, v89
	v_min_u32_e32 v89, v87, v89
	v_max_u32_e32 v87, v90, v78
	v_min_u32_e32 v78, v90, v78
	v_max_u32_e32 v90, v83, v118
	v_min_u32_e32 v118, v83, v118
	v_max_u32_e32 v83, v102, v82
	v_min_u32_e32 v82, v102, v82
	v_max_u32_e32 v102, v91, v70
	v_min_u32_e32 v70, v91, v70
	v_max_u32_e32 v91, v73, v98
	v_min_u32_e32 v98, v73, v98
	v_max_u32_e32 v73, v79, v96
	v_min_u32_e32 v96, v79, v96
	v_max_u32_e32 v79, v97, v87
	v_min_u32_e32 v87, v97, v87
	v_max_u32_e32 v97, v117, v90
	v_min_u32_e32 v90, v117, v90
	v_max_u32_e32 v117, v92, v78
	v_min_u32_e32 v78, v92, v78
	v_max_u32_e32 v92, v89, v118
	v_min_u32_e32 v118, v89, v118
	v_max_u32_e32 v89, v83, v91
	v_min_u32_e32 v91, v83, v91
	v_max_u32_e32 v83, v102, v73
	v_min_u32_e32 v73, v102, v73
	v_max_u32_e32 v102, v82, v98
	v_min_u32_e32 v98, v82, v98
	v_max_u32_e32 v82, v70, v96
	v_min_u32_e32 v96, v70, v96
	v_max_u32_e32 v70, v79, v97
	v_min_u32_e32 v97, v79, v97
	v_max_u32_e32 v79, v87, v90
	v_min_u32_e32 v90, v87, v90
	v_max_u32_e32 v87, v117, v92
	v_min_u32_e32 v92, v117, v92
	v_max_u32_e32 v117, v78, v118
	v_min_u32_e32 v118, v78, v118
	v_max_u32_e32 v78, v89, v83
	v_min_u32_e32 v83, v89, v83
	v_max_u32_e32 v89, v91, v73
	v_min_u32_e32 v73, v91, v73
	v_max_u32_e32 v91, v102, v82
	v_min_u32_e32 v82, v102, v82
	v_max_u32_e32 v102, v98, v96
	v_min_u32_e32 v96, v98, v96
	v_cvt_f32_f16_e32 v98, v24
	v_cvt_f32_f16_sdwa v107, v24 dst_sel:DWORD dst_unused:UNUSED_PAD src0_sel:WORD_1
	v_ashrrev_i32_e32 v116, 31, v98
	v_bitop3_b32 v98, v98, v116, s40 bitop3:0x78
	v_xor_b32_e32 v98, 0x8000004f, v98
	v_ashrrev_i32_e32 v116, 31, v107
	v_bitop3_b32 v107, v107, v116, s40 bitop3:0x78
	v_xor_b32_e32 v107, 0x8000004e, v107
	v_cvt_f32_f16_e32 v116, v25
	v_cvt_f32_f16_sdwa v106, v25 dst_sel:DWORD dst_unused:UNUSED_PAD src0_sel:WORD_1
	v_ashrrev_i32_e32 v103, 31, v116
	v_bitop3_b32 v116, v116, v103, s40 bitop3:0x78
	v_xor_b32_e32 v116, 0x8000004d, v116
	v_ashrrev_i32_e32 v103, 31, v106
	v_bitop3_b32 v106, v106, v103, s40 bitop3:0x78
	v_xor_b32_e32 v106, 0x8000004c, v106
	v_cvt_f32_f16_e32 v103, v26
	v_cvt_f32_f16_sdwa v72, v26 dst_sel:DWORD dst_unused:UNUSED_PAD src0_sel:WORD_1
	v_ashrrev_i32_e32 v114, 31, v103
	v_bitop3_b32 v103, v103, v114, s40 bitop3:0x78
	v_xor_b32_e32 v103, 0x8000004b, v103
	v_ashrrev_i32_e32 v114, 31, v72
	v_bitop3_b32 v72, v72, v114, s40 bitop3:0x78
	v_xor_b32_e32 v72, 0x8000004a, v72
	v_cvt_f32_f16_e32 v114, v27
	v_cvt_f32_f16_sdwa v112, v27 dst_sel:DWORD dst_unused:UNUSED_PAD src0_sel:WORD_1
	v_ashrrev_i32_e32 v104, 31, v114
	v_bitop3_b32 v114, v114, v104, s40 bitop3:0x78
	v_xor_b32_e32 v114, 0x80000049, v114
	v_ashrrev_i32_e32 v104, 31, v112
	v_bitop3_b32 v112, v112, v104, s40 bitop3:0x78
	v_xor_b32_e32 v112, 0x80000048, v112
	v_cvt_f32_f16_e32 v104, v28
	v_cvt_f32_f16_sdwa v109, v28 dst_sel:DWORD dst_unused:UNUSED_PAD src0_sel:WORD_1
	v_ashrrev_i32_e32 v108, 31, v104
	v_bitop3_b32 v104, v104, v108, s40 bitop3:0x78
	v_xor_b32_e32 v104, 0x80000047, v104
	v_ashrrev_i32_e32 v108, 31, v109
	v_bitop3_b32 v109, v109, v108, s40 bitop3:0x78
	v_xor_b32_e32 v109, 0x80000046, v109
	v_cvt_f32_f16_e32 v108, v29
	v_cvt_f32_f16_sdwa v115, v29 dst_sel:DWORD dst_unused:UNUSED_PAD src0_sel:WORD_1
	v_ashrrev_i32_e32 v119, 31, v108
	v_bitop3_b32 v108, v108, v119, s40 bitop3:0x78
	v_xor_b32_e32 v108, 0x80000045, v108
	v_ashrrev_i32_e32 v119, 31, v115
	v_bitop3_b32 v115, v115, v119, s40 bitop3:0x78
	v_xor_b32_e32 v115, 0x80000044, v115
	v_cvt_f32_f16_e32 v119, v30
	v_cvt_f32_f16_sdwa v105, v30 dst_sel:DWORD dst_unused:UNUSED_PAD src0_sel:WORD_1
	v_ashrrev_i32_e32 v111, 31, v119
	v_bitop3_b32 v119, v119, v111, s40 bitop3:0x78
	v_xor_b32_e32 v119, 0x80000043, v119
	v_ashrrev_i32_e32 v111, 31, v105
	v_bitop3_b32 v105, v105, v111, s40 bitop3:0x78
	v_xor_b32_e32 v105, 0x80000042, v105
	v_cvt_f32_f16_e32 v111, v31
	v_cvt_f32_f16_sdwa v110, v31 dst_sel:DWORD dst_unused:UNUSED_PAD src0_sel:WORD_1
	v_ashrrev_i32_e32 v75, 31, v111
	v_bitop3_b32 v111, v111, v75, s40 bitop3:0x78
	v_xor_b32_e32 v111, 0x80000041, v111
	v_ashrrev_i32_e32 v75, 31, v110
	v_bitop3_b32 v110, v110, v75, s40 bitop3:0x78
	v_xor_b32_e32 v110, 0x80000040, v110
	v_max_u32_e32 v75, v98, v105
	v_min_u32_e32 v105, v98, v105
	v_max_u32_e32 v98, v107, v119
	v_min_u32_e32 v119, v107, v119
	v_max_u32_e32 v107, v116, v110
	v_min_u32_e32 v110, v116, v110
	v_max_u32_e32 v116, v106, v111
	v_min_u32_e32 v111, v106, v111
	v_max_u32_e32 v106, v103, v104
	v_min_u32_e32 v104, v103, v104
	v_max_u32_e32 v103, v72, v114
	v_min_u32_e32 v114, v72, v114
	v_max_u32_e32 v72, v112, v115
	v_min_u32_e32 v115, v112, v115
	v_max_u32_e32 v112, v109, v108
	v_min_u32_e32 v108, v109, v108
	v_max_u32_e32 v109, v75, v103
	v_min_u32_e32 v103, v75, v103
	v_max_u32_e32 v75, v98, v72
	v_min_u32_e32 v72, v98, v72
	v_max_u32_e32 v98, v107, v112
	v_min_u32_e32 v112, v107, v112
	v_max_u32_e32 v107, v116, v106
	v_min_u32_e32 v106, v116, v106
	v_max_u32_e32 v116, v114, v105
	v_min_u32_e32 v105, v114, v105
	v_max_u32_e32 v114, v104, v111
	v_min_u32_e32 v111, v104, v111
	v_max_u32_e32 v104, v108, v110
	v_min_u32_e32 v110, v108, v110
	v_max_u32_e32 v108, v115, v119
	v_min_u32_e32 v119, v115, v119
	v_max_u32_e32 v115, v109, v75
	v_min_u32_e32 v75, v109, v75
	v_max_u32_e32 v109, v98, v107
	v_min_u32_e32 v107, v98, v107
	v_max_u32_e32 v98, v106, v103
	v_min_u32_e32 v103, v106, v103
	v_max_u32_e32 v106, v116, v114
	v_min_u32_e32 v114, v116, v114
	v_max_u32_e32 v116, v72, v112
	v_min_u32_e32 v112, v72, v112
; #define CE_DESC(a, b) do { const unsigned _mx = (a) > (b) ? (a) : (b), _mn = (a) > (b) ? (b) : (a); (a) = _mx; (b) = _mn; } while (0)
; __device__ __forceinline__ void sort16_desc(unsigned (&k)[16]) {
; #pragma unroll
;     for (int size = 2; size <= 16; size <<= 1)
; #pragma unroll
;         for (int stride = size >> 1; stride > 0; stride >>= 1)
; #pragma unroll
;             for (int i = 0; i < 16; ++i) { const int j = i ^ stride;
;                 if (j > i) { if ((i & size) == 0) CE_DESC(k[i], k[j]); else CE_DESC(k[j], k[i]); } }
; }
; __device__ __forceinline__ void merge16(unsigned (&a)[16], const unsigned (&b)[16]) {
; #pragma unroll
;     for (int i = 0; i < 16; ++i) a[i] = a[i] > b[15 - i] ? a[i] : b[15 - i];
; #pragma unroll
;     for (int stride = 8; stride > 0; stride >>= 1)
; #pragma unroll
;         for (int i = 0; i < 16; ++i) { const int j = i ^ stride; if (j > i) CE_DESC(a[i], a[j]); }
; }
; __device__ __forceinline__ void peer_tile(const Args& A, LAS unsigned char* lds, int tile) {
;     ...
;                 { const bf16_t* sp = QRY + m * 2048 + hp * 128 + 32 * g;
;                   const u32x4 s0 = *(const u32x4*)sp, s1 = *(const u32x4*)(sp + 8), s2 = *(const u32x4*)(sp + 16), s3 = *(const u32x4*)(sp + 24);
	v_max_u32_e32 v72, v104, v108
	v_min_u32_e32 v108, v104, v108
	v_max_u32_e32 v104, v119, v105
	v_min_u32_e32 v105, v119, v105
	v_max_u32_e32 v119, v111, v110
	v_min_u32_e32 v110, v111, v110
	v_max_u32_e32 v111, v115, v109
	v_min_u32_e32 v109, v115, v109
	v_max_u32_e32 v115, v75, v107
	v_min_u32_e32 v107, v75, v107
	v_max_u32_e32 v75, v98, v72
	v_min_u32_e32 v72, v98, v72
	v_max_u32_e32 v98, v103, v108
	v_min_u32_e32 v108, v103, v108
	v_max_u32_e32 v103, v106, v116
	v_min_u32_e32 v116, v106, v116
	v_max_u32_e32 v106, v114, v112
	v_min_u32_e32 v112, v114, v112
	v_max_u32_e32 v114, v104, v119
	v_min_u32_e32 v119, v104, v119
	v_max_u32_e32 v104, v105, v110
	v_min_u32_e32 v110, v105, v110
	v_max_u32_e32 v105, v115, v109
	v_min_u32_e32 v109, v115, v109
	v_max_u32_e32 v115, v107, v114
	v_min_u32_e32 v114, v107, v114
	v_max_u32_e32 v107, v75, v103
	v_min_u32_e32 v103, v75, v103
	v_max_u32_e32 v75, v98, v116
	v_min_u32_e32 v116, v98, v116
	v_max_u32_e32 v98, v106, v72
	v_min_u32_e32 v72, v106, v72
	v_max_u32_e32 v106, v112, v108
	v_min_u32_e32 v108, v112, v108
	v_max_u32_e32 v112, v104, v119
	v_min_u32_e32 v119, v104, v119
	v_max_u32_e32 v104, v105, v107
	v_min_u32_e32 v107, v105, v107
	v_max_u32_e32 v105, v109, v103
	v_min_u32_e32 v103, v109, v103
	v_max_u32_e32 v109, v75, v98
	v_min_u32_e32 v98, v75, v98
	v_max_u32_e32 v75, v116, v72
	v_min_u32_e32 v72, v116, v72
	v_max_u32_e32 v116, v106, v112
	v_min_u32_e32 v112, v106, v112
	v_max_u32_e32 v106, v108, v119
	v_min_u32_e32 v119, v108, v119
	v_max_u32_e32 v108, v105, v107
	v_min_u32_e32 v107, v105, v107
	v_max_u32_e32 v105, v115, v103
	v_min_u32_e32 v103, v115, v103
	v_max_u32_e32 v115, v116, v114
	v_min_u32_e32 v114, v116, v114
	v_max_u32_e32 v116, v106, v112
	v_min_u32_e32 v112, v106, v112
	v_max_u32_e32 v106, v105, v109
	v_min_u32_e32 v109, v105, v109
	v_max_u32_e32 v105, v103, v98
	v_min_u32_e32 v98, v103, v98
	v_max_u32_e32 v103, v75, v115
	v_min_u32_e32 v115, v75, v115
	v_max_u32_e32 v75, v72, v114
	v_min_u32_e32 v114, v72, v114
	v_max_u32_e32 v72, v106, v107
	v_min_u32_e32 v107, v106, v107
	v_max_u32_e32 v106, v109, v105
	v_min_u32_e32 v105, v109, v105
	v_max_u32_e32 v109, v103, v98
	v_min_u32_e32 v98, v103, v98
	v_max_u32_e32 v103, v115, v75
	v_min_u32_e32 v75, v115, v75
	v_max_u32_e32 v115, v116, v114
	v_min_u32_e32 v114, v116, v114
	v_max_u32_e32 v116, v105, v109
	v_min_u32_e32 v109, v105, v109
	v_max_u32_e32 v105, v98, v103
	v_min_u32_e32 v103, v98, v103
	v_max_u32_e32 v70, v70, v110
	v_max_u32_e32 v97, v97, v119
	v_max_u32_e32 v79, v79, v112
	v_max_u32_e32 v90, v90, v114
	v_max_u32_e32 v87, v87, v115
	v_max_u32_e32 v92, v92, v75
	v_max_u32_e32 v117, v117, v103
	v_max_u32_e32 v118, v118, v105
	v_max_u32_e32 v78, v78, v109
	v_max_u32_e32 v83, v83, v116
	v_max_u32_e32 v89, v89, v106
	v_max_u32_e32 v73, v73, v107
	v_max_u32_e32 v91, v91, v72
	v_max_u32_e32 v82, v82, v108
	v_max_u32_e32 v102, v102, v104
	v_max_u32_e32 v96, v96, v111
	v_max_u32_e32 v110, v70, v78
	v_min_u32_e32 v78, v70, v78
	v_max_u32_e32 v70, v97, v83
	v_min_u32_e32 v83, v97, v83
	v_max_u32_e32 v97, v79, v89
	v_min_u32_e32 v89, v79, v89
	v_max_u32_e32 v79, v90, v73
	v_min_u32_e32 v73, v90, v73
	v_max_u32_e32 v90, v87, v91
	v_min_u32_e32 v91, v87, v91
	v_max_u32_e32 v87, v92, v82
	v_min_u32_e32 v82, v92, v82
	v_max_u32_e32 v92, v117, v102
	v_min_u32_e32 v102, v117, v102
	v_max_u32_e32 v117, v118, v96
	v_min_u32_e32 v96, v118, v96
	v_max_u32_e32 v118, v110, v90
	v_min_u32_e32 v90, v110, v90
	v_max_u32_e32 v110, v70, v87
	v_min_u32_e32 v87, v70, v87
	v_max_u32_e32 v70, v97, v92
	v_min_u32_e32 v92, v97, v92
	v_max_u32_e32 v97, v79, v117
	v_min_u32_e32 v117, v79, v117
	v_max_u32_e32 v79, v78, v91
	v_min_u32_e32 v91, v78, v91
	v_max_u32_e32 v78, v83, v82
	v_min_u32_e32 v82, v83, v82
	v_max_u32_e32 v83, v89, v102
	v_min_u32_e32 v102, v89, v102
	v_max_u32_e32 v89, v73, v96
	v_min_u32_e32 v96, v73, v96
	v_max_u32_e32 v73, v118, v70
	v_min_u32_e32 v70, v118, v70
	v_max_u32_e32 v118, v110, v97
	v_min_u32_e32 v97, v110, v97
	v_max_u32_e32 v110, v90, v92
	v_min_u32_e32 v92, v90, v92
	v_max_u32_e32 v90, v87, v117
	v_min_u32_e32 v117, v87, v117
	v_max_u32_e32 v87, v79, v83
	v_min_u32_e32 v83, v79, v83
	v_max_u32_e32 v79, v78, v89
	v_min_u32_e32 v89, v78, v89
	v_max_u32_e32 v78, v91, v102
	v_min_u32_e32 v102, v91, v102
	v_max_u32_e32 v91, v82, v96
	v_min_u32_e32 v96, v82, v96
	v_max_u32_e32 v82, v73, v118
	v_min_u32_e32 v118, v73, v118
	v_max_u32_e32 v73, v70, v97
	v_min_u32_e32 v97, v70, v97
	v_max_u32_e32 v70, v110, v90
	v_min_u32_e32 v90, v110, v90
	v_max_u32_e32 v110, v92, v117
	v_min_u32_e32 v117, v92, v117
	v_max_u32_e32 v92, v87, v79
	v_min_u32_e32 v79, v87, v79
	v_max_u32_e32 v87, v83, v89
	v_min_u32_e32 v89, v83, v89
	v_max_u32_e32 v83, v78, v91
	v_min_u32_e32 v91, v78, v91
	v_max_u32_e32 v78, v102, v96
	v_min_u32_e32 v96, v102, v96
	s_waitcnt vmcnt(0)
	ds_write_b128 v64, v[32:35] offset:0
	ds_write_b128 v64, v[36:39] offset:1152
	ds_write_b128 v64, v[40:43] offset:2304
	ds_write_b128 v64, v[44:47] offset:3456
	ds_write_b128 v64, v[48:51] offset:4608
	ds_write_b128 v64, v[52:55] offset:5760
	ds_write_b128 v64, v[56:59] offset:6912
	ds_write_b128 v64, v[60:63] offset:8064
	s_waitcnt lgkmcnt(0)
	ds_read_b128 v[32:35], v65 offset:0
	ds_read_b128 v[36:39], v65 offset:16
	ds_read_b128 v[40:43], v65 offset:32
	ds_read_b128 v[44:47], v65 offset:48
	ds_read_b128 v[48:51], v65 offset:64
	ds_read_b128 v[52:55], v65 offset:80
	ds_read_b128 v[56:59], v65 offset:96
	ds_read_b128 v[60:63], v65 offset:112
	s_waitcnt lgkmcnt(0)
; __device__ __forceinline__ unsigned f2key(float f) { const unsigned u = __float_as_uint(f); return (u & 0x80000000u) ? ~u : (u | 0x80000000u); }
; #define CE_DESC(a, b) do { const unsigned _mx = (a) > (b) ? (a) : (b), _mn = (a) > (b) ? (b) : (a); (a) = _mx; (b) = _mn; } while (0)
; __device__ __forceinline__ void sort16_desc(unsigned (&k)[16]) {
; #pragma unroll
;     for (int size = 2; size <= 16; size <<= 1)
; #pragma unroll
;         for (int stride = size >> 1; stride > 0; stride >>= 1)
; #pragma unroll
;             for (int i = 0; i < 16; ++i) { const int j = i ^ stride;
;                 if (j > i) { if ((i & size) == 0) CE_DESC(k[i], k[j]); else CE_DESC(k[j], k[i]); } }
; }
; __device__ __forceinline__ void peer_tile(const Args& A, LAS unsigned char* lds, int tile) {
;     ...
;                   for (int i = 0; i < 16; ++i) {
;                       const float lo = (float)__builtin_bit_cast(_Float16, (unsigned short)(sw[i] & 0xffffu)), hi = (float)__builtin_bit_cast(_Float16, (unsigned short)(sw[i] >> 16));
;                       const unsigned klo = (f2key(lo) & ~127u) | (unsigned)(127 - (32 * g + 2 * i)), khi = (f2key(hi) & ~127u) | (unsigned)(127 - (32 * g + 2 * i + 1));
;                       if (i < 8) { k0[2 * i] = klo; k0[2 * i + 1] = khi; } else { k1[2 * (i - 8)] = klo; k1[2 * (i - 8) + 1] = khi; } } }
	v_cvt_f32_f16_e32 v102, v32
	v_cvt_f32_f16_sdwa v119, v32 dst_sel:DWORD dst_unused:UNUSED_PAD src0_sel:WORD_1
	v_ashrrev_i32_e32 v112, 31, v102
	v_bitop3_b32 v102, v102, v112, s40 bitop3:0x78
	v_xor_b32_e32 v102, 0x8000003f, v102
	v_ashrrev_i32_e32 v112, 31, v119
	v_bitop3_b32 v119, v119, v112, s40 bitop3:0x78
	v_xor_b32_e32 v119, 0x8000003e, v119
	v_cvt_f32_f16_e32 v112, v33
	v_cvt_f32_f16_sdwa v114, v33 dst_sel:DWORD dst_unused:UNUSED_PAD src0_sel:WORD_1
	v_ashrrev_i32_e32 v115, 31, v112
	v_bitop3_b32 v112, v112, v115, s40 bitop3:0x78
	v_xor_b32_e32 v112, 0x8000003d, v112
	v_ashrrev_i32_e32 v115, 31, v114
	v_bitop3_b32 v114, v114, v115, s40 bitop3:0x78
	v_xor_b32_e32 v114, 0x8000003c, v114
	v_cvt_f32_f16_e32 v115, v34
	v_cvt_f32_f16_sdwa v75, v34 dst_sel:DWORD dst_unused:UNUSED_PAD src0_sel:WORD_1
	v_ashrrev_i32_e32 v103, 31, v115
	v_bitop3_b32 v115, v115, v103, s40 bitop3:0x78
	v_xor_b32_e32 v115, 0x8000003b, v115
	v_ashrrev_i32_e32 v103, 31, v75
	v_bitop3_b32 v75, v75, v103, s40 bitop3:0x78
	v_xor_b32_e32 v75, 0x8000003a, v75
	v_cvt_f32_f16_e32 v103, v35
	v_cvt_f32_f16_sdwa v105, v35 dst_sel:DWORD dst_unused:UNUSED_PAD src0_sel:WORD_1
	v_ashrrev_i32_e32 v109, 31, v103
	v_bitop3_b32 v103, v103, v109, s40 bitop3:0x78
	v_xor_b32_e32 v103, 0x80000039, v103
	v_ashrrev_i32_e32 v109, 31, v105
	v_bitop3_b32 v105, v105, v109, s40 bitop3:0x78
	v_xor_b32_e32 v105, 0x80000038, v105
	v_cvt_f32_f16_e32 v109, v36
	v_cvt_f32_f16_sdwa v116, v36 dst_sel:DWORD dst_unused:UNUSED_PAD src0_sel:WORD_1
	v_ashrrev_i32_e32 v106, 31, v109
	v_bitop3_b32 v109, v109, v106, s40 bitop3:0x78
	v_xor_b32_e32 v109, 0x80000037, v109
	v_ashrrev_i32_e32 v106, 31, v116
	v_bitop3_b32 v116, v116, v106, s40 bitop3:0x78
	v_xor_b32_e32 v116, 0x80000036, v116
	v_cvt_f32_f16_e32 v106, v37
	v_cvt_f32_f16_sdwa v107, v37 dst_sel:DWORD dst_unused:UNUSED_PAD src0_sel:WORD_1
	v_ashrrev_i32_e32 v72, 31, v106
	v_bitop3_b32 v106, v106, v72, s40 bitop3:0x78
	v_xor_b32_e32 v106, 0x80000035, v106
	v_ashrrev_i32_e32 v72, 31, v107
	v_bitop3_b32 v107, v107, v72, s40 bitop3:0x78
	v_xor_b32_e32 v107, 0x80000034, v107
	v_cvt_f32_f16_e32 v72, v38
	v_cvt_f32_f16_sdwa v108, v38 dst_sel:DWORD dst_unused:UNUSED_PAD src0_sel:WORD_1
	v_ashrrev_i32_e32 v104, 31, v72
	v_bitop3_b32 v72, v72, v104, s40 bitop3:0x78
	v_xor_b32_e32 v72, 0x80000033, v72
	v_ashrrev_i32_e32 v104, 31, v108
	v_bitop3_b32 v108, v108, v104, s40 bitop3:0x78
	v_xor_b32_e32 v108, 0x80000032, v108
	v_cvt_f32_f16_e32 v104, v39
	v_cvt_f32_f16_sdwa v111, v39 dst_sel:DWORD dst_unused:UNUSED_PAD src0_sel:WORD_1
	v_ashrrev_i32_e32 v98, 31, v104
	v_bitop3_b32 v104, v104, v98, s40 bitop3:0x78
	v_xor_b32_e32 v104, 0x80000031, v104
	v_ashrrev_i32_e32 v98, 31, v111
	v_bitop3_b32 v111, v111, v98, s40 bitop3:0x78
	v_xor_b32_e32 v111, 0x80000030, v111
	v_max_u32_e32 v98, v102, v108
	v_min_u32_e32 v108, v102, v108
	v_max_u32_e32 v102, v119, v72
	v_min_u32_e32 v72, v119, v72
	v_max_u32_e32 v119, v112, v111
	v_min_u32_e32 v111, v112, v111
	v_max_u32_e32 v112, v114, v104
	v_min_u32_e32 v104, v114, v104
	v_max_u32_e32 v114, v115, v109
	v_min_u32_e32 v109, v115, v109
	v_max_u32_e32 v115, v75, v103
	v_min_u32_e32 v103, v75, v103
	v_max_u32_e32 v75, v105, v107
	v_min_u32_e32 v107, v105, v107
	v_max_u32_e32 v105, v116, v106
	v_min_u32_e32 v106, v116, v106
	v_max_u32_e32 v116, v98, v115
	v_min_u32_e32 v115, v98, v115
	v_max_u32_e32 v98, v102, v75
	v_min_u32_e32 v75, v102, v75
	v_max_u32_e32 v102, v119, v105
	v_min_u32_e32 v105, v119, v105
	v_max_u32_e32 v119, v112, v114
	v_min_u32_e32 v114, v112, v114
	v_max_u32_e32 v112, v103, v108
	v_min_u32_e32 v108, v103, v108
	v_max_u32_e32 v103, v109, v104
	v_min_u32_e32 v104, v109, v104
	v_max_u32_e32 v109, v106, v111
	v_min_u32_e32 v111, v106, v111
	v_max_u32_e32 v106, v107, v72
	v_min_u32_e32 v72, v107, v72
	v_max_u32_e32 v107, v116, v98
	v_min_u32_e32 v98, v116, v98
	v_max_u32_e32 v116, v102, v119
	v_min_u32_e32 v119, v102, v119
	v_max_u32_e32 v102, v114, v115
	v_min_u32_e32 v115, v114, v115
	v_max_u32_e32 v114, v112, v103
	v_min_u32_e32 v103, v112, v103
	v_max_u32_e32 v112, v75, v105
	v_min_u32_e32 v105, v75, v105
	v_max_u32_e32 v75, v109, v106
	v_min_u32_e32 v106, v109, v106
	v_max_u32_e32 v109, v72, v108
	v_min_u32_e32 v108, v72, v108
	v_max_u32_e32 v72, v104, v111
	v_min_u32_e32 v111, v104, v111
	v_max_u32_e32 v104, v107, v116
	v_min_u32_e32 v116, v107, v116
	v_max_u32_e32 v107, v98, v119
	v_min_u32_e32 v119, v98, v119
	v_max_u32_e32 v98, v102, v75
	v_min_u32_e32 v75, v102, v75
	v_max_u32_e32 v102, v115, v106
	v_min_u32_e32 v106, v115, v106
	v_max_u32_e32 v115, v114, v112
	v_min_u32_e32 v112, v114, v112
	v_max_u32_e32 v114, v103, v105
	v_min_u32_e32 v105, v103, v105
	v_max_u32_e32 v103, v109, v72
	v_min_u32_e32 v72, v109, v72
	v_max_u32_e32 v109, v108, v111
	v_min_u32_e32 v111, v108, v111
	v_max_u32_e32 v108, v107, v116
	v_min_u32_e32 v116, v107, v116
	v_max_u32_e32 v107, v119, v103
	v_min_u32_e32 v103, v119, v103
	v_max_u32_e32 v119, v98, v115
	v_min_u32_e32 v115, v98, v115
	v_max_u32_e32 v98, v102, v112
	v_min_u32_e32 v112, v102, v112
	v_max_u32_e32 v102, v114, v75
	v_min_u32_e32 v75, v114, v75
	v_max_u32_e32 v114, v105, v106
	v_min_u32_e32 v106, v105, v106
	v_max_u32_e32 v105, v109, v72
	v_min_u32_e32 v72, v109, v72
	v_max_u32_e32 v109, v108, v119
	v_min_u32_e32 v119, v108, v119
	v_max_u32_e32 v108, v116, v115
	v_min_u32_e32 v115, v116, v115
	v_max_u32_e32 v116, v98, v102
	v_min_u32_e32 v102, v98, v102
	v_max_u32_e32 v98, v112, v75
	v_min_u32_e32 v75, v112, v75
	v_max_u32_e32 v112, v114, v105
	v_min_u32_e32 v105, v114, v105
	v_max_u32_e32 v114, v106, v72
	v_min_u32_e32 v72, v106, v72
	v_max_u32_e32 v106, v108, v119
; __device__ __forceinline__ unsigned f2key(float f) { const unsigned u = __float_as_uint(f); return (u & 0x80000000u) ? ~u : (u | 0x80000000u); }
; #define CE_DESC(a, b) do { const unsigned _mx = (a) > (b) ? (a) : (b), _mn = (a) > (b) ? (b) : (a); (a) = _mx; (b) = _mn; } while (0)
; __device__ __forceinline__ void sort16_desc(unsigned (&k)[16]) {
; #pragma unroll
;     for (int size = 2; size <= 16; size <<= 1)
; #pragma unroll
;         for (int stride = size >> 1; stride > 0; stride >>= 1)
; #pragma unroll
;             for (int i = 0; i < 16; ++i) { const int j = i ^ stride;
;                 if (j > i) { if ((i & size) == 0) CE_DESC(k[i], k[j]); else CE_DESC(k[j], k[i]); } }
; }
; __device__ __forceinline__ void merge16(unsigned (&a)[16], const unsigned (&b)[16]) {
; #pragma unroll
;     for (int i = 0; i < 16; ++i) a[i] = a[i] > b[15 - i] ? a[i] : b[15 - i];
; #pragma unroll
;     for (int stride = 8; stride > 0; stride >>= 1)
; #pragma unroll
;         for (int i = 0; i < 16; ++i) { const int j = i ^ stride; if (j > i) CE_DESC(a[i], a[j]); }
; }
; __device__ __forceinline__ void peer_tile(const Args& A, LAS unsigned char* lds, int tile) {
;     ...
;                   for (int i = 0; i < 16; ++i) {
;                       const float lo = (float)__builtin_bit_cast(_Float16, (unsigned short)(sw[i] & 0xffffu)), hi = (float)__builtin_bit_cast(_Float16, (unsigned short)(sw[i] >> 16));
;                       const unsigned klo = (f2key(lo) & ~127u) | (unsigned)(127 - (32 * g + 2 * i)), khi = (f2key(hi) & ~127u) | (unsigned)(127 - (32 * g + 2 * i + 1));
;                       if (i < 8) { k0[2 * i] = klo; k0[2 * i + 1] = khi; } else { k1[2 * (i - 8)] = klo; k1[2 * (i - 8) + 1] = khi; } } }
	v_min_u32_e32 v119, v108, v119
	v_max_u32_e32 v108, v107, v115
	v_min_u32_e32 v115, v107, v115
	v_max_u32_e32 v107, v112, v103
	v_min_u32_e32 v103, v112, v103
	v_max_u32_e32 v112, v114, v105
	v_min_u32_e32 v105, v114, v105
	v_max_u32_e32 v114, v108, v116
	v_min_u32_e32 v116, v108, v116
	v_max_u32_e32 v108, v115, v102
	v_min_u32_e32 v102, v115, v102
	v_max_u32_e32 v115, v98, v107
	v_min_u32_e32 v107, v98, v107
	v_max_u32_e32 v98, v75, v103
	v_min_u32_e32 v103, v75, v103
	v_max_u32_e32 v75, v114, v119
	v_min_u32_e32 v119, v114, v119
	v_max_u32_e32 v114, v116, v108
	v_min_u32_e32 v108, v116, v108
	v_max_u32_e32 v116, v115, v102
	v_min_u32_e32 v102, v115, v102
	v_max_u32_e32 v115, v107, v98
	v_min_u32_e32 v98, v107, v98
	v_max_u32_e32 v107, v112, v103
	v_min_u32_e32 v103, v112, v103
	v_max_u32_e32 v112, v108, v116
	v_min_u32_e32 v116, v108, v116
	v_max_u32_e32 v108, v102, v115
	v_min_u32_e32 v115, v102, v115
	v_max_u32_e32 v82, v82, v111
	v_max_u32_e32 v118, v118, v72
	v_max_u32_e32 v73, v73, v105
	v_max_u32_e32 v97, v97, v103
	v_max_u32_e32 v70, v70, v107
	v_max_u32_e32 v90, v90, v98
	v_max_u32_e32 v110, v110, v115
	v_max_u32_e32 v117, v117, v108
	v_max_u32_e32 v92, v92, v116
	v_max_u32_e32 v79, v79, v112
	v_max_u32_e32 v87, v87, v114
	v_max_u32_e32 v89, v89, v119
	v_max_u32_e32 v83, v83, v75
	v_max_u32_e32 v91, v91, v106
	v_max_u32_e32 v78, v78, v109
	v_max_u32_e32 v96, v96, v104
	v_max_u32_e32 v111, v82, v92
	v_min_u32_e32 v92, v82, v92
	v_max_u32_e32 v82, v118, v79
	v_min_u32_e32 v79, v118, v79
	v_max_u32_e32 v118, v73, v87
	v_min_u32_e32 v87, v73, v87
	v_max_u32_e32 v73, v97, v89
	v_min_u32_e32 v89, v97, v89
	v_max_u32_e32 v97, v70, v83
	v_min_u32_e32 v83, v70, v83
	v_max_u32_e32 v70, v90, v91
	v_min_u32_e32 v91, v90, v91
	v_max_u32_e32 v90, v110, v78
	v_min_u32_e32 v78, v110, v78
	v_max_u32_e32 v110, v117, v96
	v_min_u32_e32 v96, v117, v96
	v_max_u32_e32 v117, v111, v97
	v_min_u32_e32 v97, v111, v97
	v_max_u32_e32 v111, v82, v70
	v_min_u32_e32 v70, v82, v70
	v_max_u32_e32 v82, v118, v90
	v_min_u32_e32 v90, v118, v90
	v_max_u32_e32 v118, v73, v110
	v_min_u32_e32 v110, v73, v110
	v_max_u32_e32 v73, v92, v83
	v_min_u32_e32 v83, v92, v83
	v_max_u32_e32 v92, v79, v91
	v_min_u32_e32 v91, v79, v91
	v_max_u32_e32 v79, v87, v78
	v_min_u32_e32 v78, v87, v78
	v_max_u32_e32 v87, v89, v96
	v_min_u32_e32 v96, v89, v96
	v_max_u32_e32 v89, v117, v82
	v_min_u32_e32 v82, v117, v82
	v_max_u32_e32 v117, v111, v118
	v_min_u32_e32 v118, v111, v118
	v_max_u32_e32 v111, v97, v90
	v_min_u32_e32 v90, v97, v90
	v_max_u32_e32 v97, v70, v110
	v_min_u32_e32 v110, v70, v110
	v_max_u32_e32 v70, v73, v79
	v_min_u32_e32 v79, v73, v79
	v_max_u32_e32 v73, v92, v87
	v_min_u32_e32 v87, v92, v87
	v_max_u32_e32 v92, v83, v78
	v_min_u32_e32 v78, v83, v78
	v_max_u32_e32 v83, v91, v96
	v_min_u32_e32 v96, v91, v96
	v_max_u32_e32 v91, v89, v117
	v_min_u32_e32 v117, v89, v117
	v_max_u32_e32 v89, v82, v118
	v_min_u32_e32 v118, v82, v118
	v_max_u32_e32 v82, v111, v97
	v_min_u32_e32 v97, v111, v97
	v_max_u32_e32 v111, v90, v110
	v_min_u32_e32 v110, v90, v110
	v_max_u32_e32 v90, v70, v73
	v_min_u32_e32 v73, v70, v73
	v_max_u32_e32 v70, v79, v87
	v_min_u32_e32 v87, v79, v87
	v_max_u32_e32 v79, v92, v83
	v_min_u32_e32 v83, v92, v83
	v_max_u32_e32 v92, v78, v96
	v_min_u32_e32 v96, v78, v96
	v_cvt_f32_f16_e32 v78, v40
	v_cvt_f32_f16_sdwa v72, v40 dst_sel:DWORD dst_unused:UNUSED_PAD src0_sel:WORD_1
	v_ashrrev_i32_e32 v105, 31, v78
	v_bitop3_b32 v78, v78, v105, s40 bitop3:0x78
	v_xor_b32_e32 v78, 0x8000002f, v78
	v_ashrrev_i32_e32 v105, 31, v72
	v_bitop3_b32 v72, v72, v105, s40 bitop3:0x78
	v_xor_b32_e32 v72, 0x8000002e, v72
	v_cvt_f32_f16_e32 v105, v41
	v_cvt_f32_f16_sdwa v103, v41 dst_sel:DWORD dst_unused:UNUSED_PAD src0_sel:WORD_1
	v_ashrrev_i32_e32 v107, 31, v105
	v_bitop3_b32 v105, v105, v107, s40 bitop3:0x78
	v_xor_b32_e32 v105, 0x8000002d, v105
	v_ashrrev_i32_e32 v107, 31, v103
	v_bitop3_b32 v103, v103, v107, s40 bitop3:0x78
	v_xor_b32_e32 v103, 0x8000002c, v103
	v_cvt_f32_f16_e32 v107, v42
	v_cvt_f32_f16_sdwa v98, v42 dst_sel:DWORD dst_unused:UNUSED_PAD src0_sel:WORD_1
	v_ashrrev_i32_e32 v115, 31, v107
	v_bitop3_b32 v107, v107, v115, s40 bitop3:0x78
	v_xor_b32_e32 v107, 0x8000002b, v107
	v_ashrrev_i32_e32 v115, 31, v98
	v_bitop3_b32 v98, v98, v115, s40 bitop3:0x78
	v_xor_b32_e32 v98, 0x8000002a, v98
	v_cvt_f32_f16_e32 v115, v43
	v_cvt_f32_f16_sdwa v108, v43 dst_sel:DWORD dst_unused:UNUSED_PAD src0_sel:WORD_1
	v_ashrrev_i32_e32 v116, 31, v115
	v_bitop3_b32 v115, v115, v116, s40 bitop3:0x78
	v_xor_b32_e32 v115, 0x80000029, v115
	v_ashrrev_i32_e32 v116, 31, v108
	v_bitop3_b32 v108, v108, v116, s40 bitop3:0x78
	v_xor_b32_e32 v108, 0x80000028, v108
	v_cvt_f32_f16_e32 v116, v44
	v_cvt_f32_f16_sdwa v112, v44 dst_sel:DWORD dst_unused:UNUSED_PAD src0_sel:WORD_1
	v_ashrrev_i32_e32 v114, 31, v116
	v_bitop3_b32 v116, v116, v114, s40 bitop3:0x78
	v_xor_b32_e32 v116, 0x80000027, v116
	v_ashrrev_i32_e32 v114, 31, v112
	v_bitop3_b32 v112, v112, v114, s40 bitop3:0x78
	v_xor_b32_e32 v112, 0x80000026, v112
	v_cvt_f32_f16_e32 v114, v45
	v_cvt_f32_f16_sdwa v119, v45 dst_sel:DWORD dst_unused:UNUSED_PAD src0_sel:WORD_1
	v_ashrrev_i32_e32 v75, 31, v114
	v_bitop3_b32 v114, v114, v75, s40 bitop3:0x78
	v_xor_b32_e32 v114, 0x80000025, v114
	v_ashrrev_i32_e32 v75, 31, v119
	v_bitop3_b32 v119, v119, v75, s40 bitop3:0x78
	v_xor_b32_e32 v119, 0x80000024, v119
	v_cvt_f32_f16_e32 v75, v46
	v_cvt_f32_f16_sdwa v106, v46 dst_sel:DWORD dst_unused:UNUSED_PAD src0_sel:WORD_1
	v_ashrrev_i32_e32 v109, 31, v75
	v_bitop3_b32 v75, v75, v109, s40 bitop3:0x78
	v_xor_b32_e32 v75, 0x80000023, v75
	v_ashrrev_i32_e32 v109, 31, v106
; __device__ __forceinline__ unsigned f2key(float f) { const unsigned u = __float_as_uint(f); return (u & 0x80000000u) ? ~u : (u | 0x80000000u); }
; #define CE_DESC(a, b) do { const unsigned _mx = (a) > (b) ? (a) : (b), _mn = (a) > (b) ? (b) : (a); (a) = _mx; (b) = _mn; } while (0)
; __device__ __forceinline__ void sort16_desc(unsigned (&k)[16]) {
; #pragma unroll
;     for (int size = 2; size <= 16; size <<= 1)
; #pragma unroll
;         for (int stride = size >> 1; stride > 0; stride >>= 1)
; #pragma unroll
;             for (int i = 0; i < 16; ++i) { const int j = i ^ stride;
;                 if (j > i) { if ((i & size) == 0) CE_DESC(k[i], k[j]); else CE_DESC(k[j], k[i]); } }
; }
; __device__ __forceinline__ void merge16(unsigned (&a)[16], const unsigned (&b)[16]) {
; #pragma unroll
;     for (int i = 0; i < 16; ++i) a[i] = a[i] > b[15 - i] ? a[i] : b[15 - i];
; #pragma unroll
;     for (int stride = 8; stride > 0; stride >>= 1)
; #pragma unroll
;         for (int i = 0; i < 16; ++i) { const int j = i ^ stride; if (j > i) CE_DESC(a[i], a[j]); }
; }
; __device__ __forceinline__ void peer_tile(const Args& A, LAS unsigned char* lds, int tile) {
;     ...
;                   for (int i = 0; i < 16; ++i) {
;                       const float lo = (float)__builtin_bit_cast(_Float16, (unsigned short)(sw[i] & 0xffffu)), hi = (float)__builtin_bit_cast(_Float16, (unsigned short)(sw[i] >> 16));
;                       const unsigned klo = (f2key(lo) & ~127u) | (unsigned)(127 - (32 * g + 2 * i)), khi = (f2key(hi) & ~127u) | (unsigned)(127 - (32 * g + 2 * i + 1));
;                       if (i < 8) { k0[2 * i] = klo; k0[2 * i + 1] = khi; } else { k1[2 * (i - 8)] = klo; k1[2 * (i - 8) + 1] = khi; } } }
	v_bitop3_b32 v106, v106, v109, s40 bitop3:0x78
	v_xor_b32_e32 v106, 0x80000022, v106
	v_cvt_f32_f16_e32 v109, v47
	v_cvt_f32_f16_sdwa v104, v47 dst_sel:DWORD dst_unused:UNUSED_PAD src0_sel:WORD_1
	v_ashrrev_i32_e32 v102, 31, v109
	v_bitop3_b32 v109, v109, v102, s40 bitop3:0x78
	v_xor_b32_e32 v109, 0x80000021, v109
	v_ashrrev_i32_e32 v102, 31, v104
	v_bitop3_b32 v104, v104, v102, s40 bitop3:0x78
	v_xor_b32_e32 v104, 0x80000020, v104
	v_max_u32_e32 v102, v78, v106
	v_min_u32_e32 v106, v78, v106
	v_max_u32_e32 v78, v72, v75
	v_min_u32_e32 v75, v72, v75
	v_max_u32_e32 v72, v105, v104
	v_min_u32_e32 v104, v105, v104
	v_max_u32_e32 v105, v103, v109
	v_min_u32_e32 v109, v103, v109
	v_max_u32_e32 v103, v107, v116
	v_min_u32_e32 v116, v107, v116
	v_max_u32_e32 v107, v98, v115
	v_min_u32_e32 v115, v98, v115
	v_max_u32_e32 v98, v108, v119
	v_min_u32_e32 v119, v108, v119
	v_max_u32_e32 v108, v112, v114
	v_min_u32_e32 v114, v112, v114
	v_max_u32_e32 v112, v102, v107
	v_min_u32_e32 v107, v102, v107
	v_max_u32_e32 v102, v78, v98
	v_min_u32_e32 v98, v78, v98
	v_max_u32_e32 v78, v72, v108
	v_min_u32_e32 v108, v72, v108
	v_max_u32_e32 v72, v105, v103
	v_min_u32_e32 v103, v105, v103
	v_max_u32_e32 v105, v115, v106
	v_min_u32_e32 v106, v115, v106
	v_max_u32_e32 v115, v116, v109
	v_min_u32_e32 v109, v116, v109
	v_max_u32_e32 v116, v114, v104
	v_min_u32_e32 v104, v114, v104
	v_max_u32_e32 v114, v119, v75
	v_min_u32_e32 v75, v119, v75
	v_max_u32_e32 v119, v112, v102
	v_min_u32_e32 v102, v112, v102
	v_max_u32_e32 v112, v78, v72
	v_min_u32_e32 v72, v78, v72
	v_max_u32_e32 v78, v103, v107
	v_min_u32_e32 v107, v103, v107
	v_max_u32_e32 v103, v105, v115
	v_min_u32_e32 v115, v105, v115
	v_max_u32_e32 v105, v98, v108
	v_min_u32_e32 v108, v98, v108
	v_max_u32_e32 v98, v116, v114
	v_min_u32_e32 v114, v116, v114
	v_max_u32_e32 v116, v75, v106
	v_min_u32_e32 v106, v75, v106
	v_max_u32_e32 v75, v109, v104
	v_min_u32_e32 v104, v109, v104
	v_max_u32_e32 v109, v119, v112
	v_min_u32_e32 v112, v119, v112
	v_max_u32_e32 v119, v102, v72
	v_min_u32_e32 v72, v102, v72
	v_max_u32_e32 v102, v78, v98
	v_min_u32_e32 v98, v78, v98
	v_max_u32_e32 v78, v107, v114
	v_min_u32_e32 v114, v107, v114
	v_max_u32_e32 v107, v103, v105
	v_min_u32_e32 v105, v103, v105
	v_max_u32_e32 v103, v115, v108
	v_min_u32_e32 v108, v115, v108
	v_max_u32_e32 v115, v116, v75
	v_min_u32_e32 v75, v116, v75
	v_max_u32_e32 v116, v106, v104
	v_min_u32_e32 v104, v106, v104
	v_max_u32_e32 v106, v119, v112
	v_min_u32_e32 v112, v119, v112
	v_max_u32_e32 v119, v72, v115
	v_min_u32_e32 v115, v72, v115
	v_max_u32_e32 v72, v102, v107
	v_min_u32_e32 v107, v102, v107
	v_max_u32_e32 v102, v78, v105
	v_min_u32_e32 v105, v78, v105
	v_max_u32_e32 v78, v103, v98
	v_min_u32_e32 v98, v103, v98
	v_max_u32_e32 v103, v108, v114
	v_min_u32_e32 v114, v108, v114
	v_max_u32_e32 v108, v116, v75
	v_min_u32_e32 v75, v116, v75
	v_max_u32_e32 v116, v106, v72
	v_min_u32_e32 v72, v106, v72
	v_max_u32_e32 v106, v112, v107
	v_min_u32_e32 v107, v112, v107
	v_max_u32_e32 v112, v102, v78
	v_min_u32_e32 v78, v102, v78
	v_max_u32_e32 v102, v105, v98
	v_min_u32_e32 v98, v105, v98
	v_max_u32_e32 v105, v103, v108
	v_min_u32_e32 v108, v103, v108
	v_max_u32_e32 v103, v114, v75
	v_min_u32_e32 v75, v114, v75
	v_max_u32_e32 v114, v106, v72
	v_min_u32_e32 v72, v106, v72
	v_max_u32_e32 v106, v119, v107
	v_min_u32_e32 v107, v119, v107
	v_max_u32_e32 v119, v105, v115
	v_min_u32_e32 v115, v105, v115
	v_max_u32_e32 v105, v103, v108
	v_min_u32_e32 v108, v103, v108
	v_max_u32_e32 v103, v106, v112
	v_min_u32_e32 v112, v106, v112
	v_max_u32_e32 v106, v107, v78
	v_min_u32_e32 v78, v107, v78
	v_max_u32_e32 v107, v102, v119
	v_min_u32_e32 v119, v102, v119
	v_max_u32_e32 v102, v98, v115
	v_min_u32_e32 v115, v98, v115
	v_max_u32_e32 v98, v103, v72
	v_min_u32_e32 v72, v103, v72
	v_max_u32_e32 v103, v112, v106
	v_min_u32_e32 v106, v112, v106
	v_max_u32_e32 v112, v107, v78
	v_min_u32_e32 v78, v107, v78
	v_max_u32_e32 v107, v119, v102
	v_min_u32_e32 v102, v119, v102
	v_max_u32_e32 v119, v105, v115
	v_min_u32_e32 v115, v105, v115
	v_max_u32_e32 v105, v106, v112
	v_min_u32_e32 v112, v106, v112
	v_max_u32_e32 v106, v78, v107
	v_min_u32_e32 v107, v78, v107
	v_max_u32_e32 v91, v91, v104
	v_max_u32_e32 v117, v117, v75
	v_max_u32_e32 v89, v89, v108
	v_max_u32_e32 v118, v118, v115
	v_max_u32_e32 v82, v82, v119
	v_max_u32_e32 v97, v97, v102
	v_max_u32_e32 v111, v111, v107
	v_max_u32_e32 v110, v110, v106
	v_max_u32_e32 v90, v90, v112
	v_max_u32_e32 v73, v73, v105
	v_max_u32_e32 v70, v70, v103
	v_max_u32_e32 v87, v87, v72
	v_max_u32_e32 v79, v79, v98
	v_max_u32_e32 v83, v83, v114
	v_max_u32_e32 v92, v92, v116
	v_max_u32_e32 v96, v96, v109
	v_max_u32_e32 v104, v91, v90
	v_min_u32_e32 v90, v91, v90
	v_max_u32_e32 v91, v117, v73
	v_min_u32_e32 v73, v117, v73
	v_max_u32_e32 v117, v89, v70
	v_min_u32_e32 v70, v89, v70
	v_max_u32_e32 v89, v118, v87
	v_min_u32_e32 v87, v118, v87
	v_max_u32_e32 v118, v82, v79
	v_min_u32_e32 v79, v82, v79
	v_max_u32_e32 v82, v97, v83
	v_min_u32_e32 v83, v97, v83
	v_max_u32_e32 v97, v111, v92
	v_min_u32_e32 v92, v111, v92
	v_max_u32_e32 v111, v110, v96
	v_min_u32_e32 v96, v110, v96
	v_max_u32_e32 v110, v104, v118
	v_min_u32_e32 v118, v104, v118
	v_max_u32_e32 v104, v91, v82
	v_min_u32_e32 v82, v91, v82
	v_max_u32_e32 v91, v117, v97
	v_min_u32_e32 v97, v117, v97
	v_max_u32_e32 v117, v89, v111
	v_min_u32_e32 v111, v89, v111
	v_max_u32_e32 v89, v90, v79
	v_min_u32_e32 v79, v90, v79
	v_max_u32_e32 v90, v73, v83
	v_min_u32_e32 v83, v73, v83
	v_max_u32_e32 v73, v70, v92
	v_min_u32_e32 v92, v70, v92
	v_max_u32_e32 v70, v87, v96
	v_min_u32_e32 v96, v87, v96
; __device__ __forceinline__ unsigned f2key(float f) { const unsigned u = __float_as_uint(f); return (u & 0x80000000u) ? ~u : (u | 0x80000000u); }
; #define CE_DESC(a, b) do { const unsigned _mx = (a) > (b) ? (a) : (b), _mn = (a) > (b) ? (b) : (a); (a) = _mx; (b) = _mn; } while (0)
; __device__ __forceinline__ void sort16_desc(unsigned (&k)[16]) {
; #pragma unroll
;     for (int size = 2; size <= 16; size <<= 1)
; #pragma unroll
;         for (int stride = size >> 1; stride > 0; stride >>= 1)
; #pragma unroll
;             for (int i = 0; i < 16; ++i) { const int j = i ^ stride;
;                 if (j > i) { if ((i & size) == 0) CE_DESC(k[i], k[j]); else CE_DESC(k[j], k[i]); } }
; }
; __device__ __forceinline__ void merge16(unsigned (&a)[16], const unsigned (&b)[16]) {
; #pragma unroll
;     for (int i = 0; i < 16; ++i) a[i] = a[i] > b[15 - i] ? a[i] : b[15 - i];
; #pragma unroll
;     for (int stride = 8; stride > 0; stride >>= 1)
; #pragma unroll
;         for (int i = 0; i < 16; ++i) { const int j = i ^ stride; if (j > i) CE_DESC(a[i], a[j]); }
; }
; __device__ __forceinline__ void peer_tile(const Args& A, LAS unsigned char* lds, int tile) {
;     ...
;                   for (int i = 0; i < 16; ++i) {
;                       const float lo = (float)__builtin_bit_cast(_Float16, (unsigned short)(sw[i] & 0xffffu)), hi = (float)__builtin_bit_cast(_Float16, (unsigned short)(sw[i] >> 16));
;                       const unsigned klo = (f2key(lo) & ~127u) | (unsigned)(127 - (32 * g + 2 * i)), khi = (f2key(hi) & ~127u) | (unsigned)(127 - (32 * g + 2 * i + 1));
;                       if (i < 8) { k0[2 * i] = klo; k0[2 * i + 1] = khi; } else { k1[2 * (i - 8)] = klo; k1[2 * (i - 8) + 1] = khi; } } }
	v_max_u32_e32 v87, v110, v91
	v_min_u32_e32 v91, v110, v91
	v_max_u32_e32 v110, v104, v117
	v_min_u32_e32 v117, v104, v117
	v_max_u32_e32 v104, v118, v97
	v_min_u32_e32 v97, v118, v97
	v_max_u32_e32 v118, v82, v111
	v_min_u32_e32 v111, v82, v111
	v_max_u32_e32 v82, v89, v73
	v_min_u32_e32 v73, v89, v73
	v_max_u32_e32 v89, v90, v70
	v_min_u32_e32 v70, v90, v70
	v_max_u32_e32 v90, v79, v92
	v_min_u32_e32 v92, v79, v92
	v_max_u32_e32 v79, v83, v96
	v_min_u32_e32 v96, v83, v96
	v_max_u32_e32 v83, v87, v110
	v_min_u32_e32 v110, v87, v110
	v_max_u32_e32 v87, v91, v117
	v_min_u32_e32 v117, v91, v117
	v_max_u32_e32 v91, v104, v118
	v_min_u32_e32 v118, v104, v118
	v_max_u32_e32 v104, v97, v111
	v_min_u32_e32 v111, v97, v111
	v_max_u32_e32 v97, v82, v89
	v_min_u32_e32 v89, v82, v89
	v_max_u32_e32 v82, v73, v70
	v_min_u32_e32 v70, v73, v70
	v_max_u32_e32 v73, v90, v79
	v_min_u32_e32 v79, v90, v79
	v_max_u32_e32 v90, v92, v96
	v_min_u32_e32 v96, v92, v96
	v_cvt_f32_f16_e32 v92, v48
	v_cvt_f32_f16_sdwa v75, v48 dst_sel:DWORD dst_unused:UNUSED_PAD src0_sel:WORD_1
	v_ashrrev_i32_e32 v108, 31, v92
	v_bitop3_b32 v92, v92, v108, s40 bitop3:0x78
	v_xor_b32_e32 v92, 0x8000001f, v92
	v_ashrrev_i32_e32 v108, 31, v75
	v_bitop3_b32 v75, v75, v108, s40 bitop3:0x78
	v_xor_b32_e32 v75, 0x8000001e, v75
	v_cvt_f32_f16_e32 v108, v49
	v_cvt_f32_f16_sdwa v115, v49 dst_sel:DWORD dst_unused:UNUSED_PAD src0_sel:WORD_1
	v_ashrrev_i32_e32 v119, 31, v108
	v_bitop3_b32 v108, v108, v119, s40 bitop3:0x78
	v_xor_b32_e32 v108, 0x8000001d, v108
	v_ashrrev_i32_e32 v119, 31, v115
	v_bitop3_b32 v115, v115, v119, s40 bitop3:0x78
	v_xor_b32_e32 v115, 0x8000001c, v115
	v_cvt_f32_f16_e32 v119, v50
	v_cvt_f32_f16_sdwa v102, v50 dst_sel:DWORD dst_unused:UNUSED_PAD src0_sel:WORD_1
	v_ashrrev_i32_e32 v107, 31, v119
	v_bitop3_b32 v119, v119, v107, s40 bitop3:0x78
	v_xor_b32_e32 v119, 0x8000001b, v119
	v_ashrrev_i32_e32 v107, 31, v102
	v_bitop3_b32 v102, v102, v107, s40 bitop3:0x78
	v_xor_b32_e32 v102, 0x8000001a, v102
	v_cvt_f32_f16_e32 v107, v51
	v_cvt_f32_f16_sdwa v106, v51 dst_sel:DWORD dst_unused:UNUSED_PAD src0_sel:WORD_1
	v_ashrrev_i32_e32 v112, 31, v107
	v_bitop3_b32 v107, v107, v112, s40 bitop3:0x78
	v_xor_b32_e32 v107, 0x80000019, v107
	v_ashrrev_i32_e32 v112, 31, v106
	v_bitop3_b32 v106, v106, v112, s40 bitop3:0x78
	v_xor_b32_e32 v106, 0x80000018, v106
	v_cvt_f32_f16_e32 v112, v52
	v_cvt_f32_f16_sdwa v105, v52 dst_sel:DWORD dst_unused:UNUSED_PAD src0_sel:WORD_1
	v_ashrrev_i32_e32 v103, 31, v112
	v_bitop3_b32 v112, v112, v103, s40 bitop3:0x78
	v_xor_b32_e32 v112, 0x80000017, v112
	v_ashrrev_i32_e32 v103, 31, v105
	v_bitop3_b32 v105, v105, v103, s40 bitop3:0x78
	v_xor_b32_e32 v105, 0x80000016, v105
	v_cvt_f32_f16_e32 v103, v53
	v_cvt_f32_f16_sdwa v72, v53 dst_sel:DWORD dst_unused:UNUSED_PAD src0_sel:WORD_1
	v_ashrrev_i32_e32 v98, 31, v103
	v_bitop3_b32 v103, v103, v98, s40 bitop3:0x78
	v_xor_b32_e32 v103, 0x80000015, v103
	v_ashrrev_i32_e32 v98, 31, v72
	v_bitop3_b32 v72, v72, v98, s40 bitop3:0x78
	v_xor_b32_e32 v72, 0x80000014, v72
	v_cvt_f32_f16_e32 v98, v54
	v_cvt_f32_f16_sdwa v114, v54 dst_sel:DWORD dst_unused:UNUSED_PAD src0_sel:WORD_1
	v_ashrrev_i32_e32 v116, 31, v98
	v_bitop3_b32 v98, v98, v116, s40 bitop3:0x78
	v_xor_b32_e32 v98, 0x80000013, v98
	v_ashrrev_i32_e32 v116, 31, v114
	v_bitop3_b32 v114, v114, v116, s40 bitop3:0x78
	v_xor_b32_e32 v114, 0x80000012, v114
	v_cvt_f32_f16_e32 v116, v55
	v_cvt_f32_f16_sdwa v109, v55 dst_sel:DWORD dst_unused:UNUSED_PAD src0_sel:WORD_1
	v_ashrrev_i32_e32 v78, 31, v116
	v_bitop3_b32 v116, v116, v78, s40 bitop3:0x78
	v_xor_b32_e32 v116, 0x80000011, v116
	v_ashrrev_i32_e32 v78, 31, v109
	v_bitop3_b32 v109, v109, v78, s40 bitop3:0x78
	v_xor_b32_e32 v109, 0x80000010, v109
	v_max_u32_e32 v78, v92, v114
	v_min_u32_e32 v114, v92, v114
	v_max_u32_e32 v92, v75, v98
	v_min_u32_e32 v98, v75, v98
	v_max_u32_e32 v75, v108, v109
	v_min_u32_e32 v109, v108, v109
	v_max_u32_e32 v108, v115, v116
	v_min_u32_e32 v116, v115, v116
	v_max_u32_e32 v115, v119, v112
	v_min_u32_e32 v112, v119, v112
	v_max_u32_e32 v119, v102, v107
	v_min_u32_e32 v107, v102, v107
	v_max_u32_e32 v102, v106, v72
	v_min_u32_e32 v72, v106, v72
	v_max_u32_e32 v106, v105, v103
	v_min_u32_e32 v103, v105, v103
	v_max_u32_e32 v105, v78, v119
	v_min_u32_e32 v119, v78, v119
	v_max_u32_e32 v78, v92, v102
	v_min_u32_e32 v102, v92, v102
	v_max_u32_e32 v92, v75, v106
	v_min_u32_e32 v106, v75, v106
	v_max_u32_e32 v75, v108, v115
	v_min_u32_e32 v115, v108, v115
	v_max_u32_e32 v108, v107, v114
	v_min_u32_e32 v114, v107, v114
	v_max_u32_e32 v107, v112, v116
	v_min_u32_e32 v116, v112, v116
	v_max_u32_e32 v112, v103, v109
	v_min_u32_e32 v109, v103, v109
	v_max_u32_e32 v103, v72, v98
	v_min_u32_e32 v98, v72, v98
	v_max_u32_e32 v72, v105, v78
	v_min_u32_e32 v78, v105, v78
	v_max_u32_e32 v105, v92, v75
	v_min_u32_e32 v75, v92, v75
	v_max_u32_e32 v92, v115, v119
	v_min_u32_e32 v119, v115, v119
	v_max_u32_e32 v115, v108, v107
	v_min_u32_e32 v107, v108, v107
	v_max_u32_e32 v108, v102, v106
	v_min_u32_e32 v106, v102, v106
	v_max_u32_e32 v102, v112, v103
	v_min_u32_e32 v103, v112, v103
	v_max_u32_e32 v112, v98, v114
	v_min_u32_e32 v114, v98, v114
	v_max_u32_e32 v98, v116, v109
	v_min_u32_e32 v109, v116, v109
	v_max_u32_e32 v116, v72, v105
	v_min_u32_e32 v105, v72, v105
	v_max_u32_e32 v72, v78, v75
	v_min_u32_e32 v75, v78, v75
	v_max_u32_e32 v78, v92, v102
	v_min_u32_e32 v102, v92, v102
	v_max_u32_e32 v92, v119, v103
	v_min_u32_e32 v103, v119, v103
	v_max_u32_e32 v119, v115, v108
	v_min_u32_e32 v108, v115, v108
	v_max_u32_e32 v115, v107, v106
	v_min_u32_e32 v106, v107, v106
	v_max_u32_e32 v107, v112, v98
; __device__ __forceinline__ unsigned f2key(float f) { const unsigned u = __float_as_uint(f); return (u & 0x80000000u) ? ~u : (u | 0x80000000u); }
; #define CE_DESC(a, b) do { const unsigned _mx = (a) > (b) ? (a) : (b), _mn = (a) > (b) ? (b) : (a); (a) = _mx; (b) = _mn; } while (0)
; __device__ __forceinline__ void sort16_desc(unsigned (&k)[16]) {
; #pragma unroll
;     for (int size = 2; size <= 16; size <<= 1)
; #pragma unroll
;         for (int stride = size >> 1; stride > 0; stride >>= 1)
; #pragma unroll
;             for (int i = 0; i < 16; ++i) { const int j = i ^ stride;
;                 if (j > i) { if ((i & size) == 0) CE_DESC(k[i], k[j]); else CE_DESC(k[j], k[i]); } }
; }
; __device__ __forceinline__ void merge16(unsigned (&a)[16], const unsigned (&b)[16]) {
; #pragma unroll
;     for (int i = 0; i < 16; ++i) a[i] = a[i] > b[15 - i] ? a[i] : b[15 - i];
; #pragma unroll
;     for (int stride = 8; stride > 0; stride >>= 1)
; #pragma unroll
;         for (int i = 0; i < 16; ++i) { const int j = i ^ stride; if (j > i) CE_DESC(a[i], a[j]); }
; }
; __device__ __forceinline__ void peer_tile(const Args& A, LAS unsigned char* lds, int tile) {
;     ...
;                   for (int i = 0; i < 16; ++i) {
;                       const float lo = (float)__builtin_bit_cast(_Float16, (unsigned short)(sw[i] & 0xffffu)), hi = (float)__builtin_bit_cast(_Float16, (unsigned short)(sw[i] >> 16));
;                       const unsigned klo = (f2key(lo) & ~127u) | (unsigned)(127 - (32 * g + 2 * i)), khi = (f2key(hi) & ~127u) | (unsigned)(127 - (32 * g + 2 * i + 1));
;                       if (i < 8) { k0[2 * i] = klo; k0[2 * i + 1] = khi; } else { k1[2 * (i - 8)] = klo; k1[2 * (i - 8) + 1] = khi; } } }
	v_min_u32_e32 v98, v112, v98
	v_max_u32_e32 v112, v114, v109
	v_min_u32_e32 v109, v114, v109
	v_max_u32_e32 v114, v72, v105
	v_min_u32_e32 v105, v72, v105
	v_max_u32_e32 v72, v75, v107
	v_min_u32_e32 v107, v75, v107
	v_max_u32_e32 v75, v78, v119
	v_min_u32_e32 v119, v78, v119
	v_max_u32_e32 v78, v92, v108
	v_min_u32_e32 v108, v92, v108
	v_max_u32_e32 v92, v115, v102
	v_min_u32_e32 v102, v115, v102
	v_max_u32_e32 v115, v106, v103
	v_min_u32_e32 v103, v106, v103
	v_max_u32_e32 v106, v112, v98
	v_min_u32_e32 v98, v112, v98
	v_max_u32_e32 v112, v114, v75
	v_min_u32_e32 v75, v114, v75
	v_max_u32_e32 v114, v105, v119
	v_min_u32_e32 v119, v105, v119
	v_max_u32_e32 v105, v78, v92
	v_min_u32_e32 v92, v78, v92
	v_max_u32_e32 v78, v108, v102
	v_min_u32_e32 v102, v108, v102
	v_max_u32_e32 v108, v115, v106
	v_min_u32_e32 v106, v115, v106
	v_max_u32_e32 v115, v103, v98
	v_min_u32_e32 v98, v103, v98
	v_max_u32_e32 v103, v114, v75
	v_min_u32_e32 v75, v114, v75
	v_max_u32_e32 v114, v72, v119
	v_min_u32_e32 v119, v72, v119
	v_max_u32_e32 v72, v108, v107
	v_min_u32_e32 v107, v108, v107
	v_max_u32_e32 v108, v115, v106
	v_min_u32_e32 v106, v115, v106
	v_max_u32_e32 v115, v114, v105
	v_min_u32_e32 v105, v114, v105
	v_max_u32_e32 v114, v119, v92
	v_min_u32_e32 v92, v119, v92
	v_max_u32_e32 v119, v78, v72
	v_min_u32_e32 v72, v78, v72
	v_max_u32_e32 v78, v102, v107
	v_min_u32_e32 v107, v102, v107
	v_max_u32_e32 v102, v115, v75
	v_min_u32_e32 v75, v115, v75
	v_max_u32_e32 v115, v105, v114
	v_min_u32_e32 v114, v105, v114
	v_max_u32_e32 v105, v119, v92
	v_min_u32_e32 v92, v119, v92
	v_max_u32_e32 v119, v72, v78
	v_min_u32_e32 v78, v72, v78
	v_max_u32_e32 v72, v108, v107
	v_min_u32_e32 v107, v108, v107
	v_max_u32_e32 v108, v114, v105
	v_min_u32_e32 v105, v114, v105
	v_max_u32_e32 v114, v92, v119
	v_min_u32_e32 v119, v92, v119
	v_max_u32_e32 v83, v83, v109
	v_max_u32_e32 v110, v110, v98
	v_max_u32_e32 v87, v87, v106
	v_max_u32_e32 v117, v117, v107
	v_max_u32_e32 v91, v91, v72
	v_max_u32_e32 v118, v118, v78
	v_max_u32_e32 v104, v104, v119
	v_max_u32_e32 v111, v111, v114
	v_max_u32_e32 v97, v97, v105
	v_max_u32_e32 v89, v89, v108
	v_max_u32_e32 v82, v82, v115
	v_max_u32_e32 v70, v70, v75
	v_max_u32_e32 v73, v73, v102
	v_max_u32_e32 v79, v79, v103
	v_max_u32_e32 v90, v90, v112
	v_max_u32_e32 v96, v96, v116
	v_max_u32_e32 v109, v83, v97
	v_min_u32_e32 v97, v83, v97
	v_max_u32_e32 v83, v110, v89
	v_min_u32_e32 v89, v110, v89
	v_max_u32_e32 v110, v87, v82
	v_min_u32_e32 v82, v87, v82
	v_max_u32_e32 v87, v117, v70
	v_min_u32_e32 v70, v117, v70
	v_max_u32_e32 v117, v91, v73
	v_min_u32_e32 v73, v91, v73
	v_max_u32_e32 v91, v118, v79
	v_min_u32_e32 v79, v118, v79
	v_max_u32_e32 v118, v104, v90
	v_min_u32_e32 v90, v104, v90
	v_max_u32_e32 v104, v111, v96
	v_min_u32_e32 v96, v111, v96
	v_max_u32_e32 v111, v109, v117
	v_min_u32_e32 v117, v109, v117
	v_max_u32_e32 v109, v83, v91
	v_min_u32_e32 v91, v83, v91
	v_max_u32_e32 v83, v110, v118
	v_min_u32_e32 v118, v110, v118
	v_max_u32_e32 v110, v87, v104
	v_min_u32_e32 v104, v87, v104
	v_max_u32_e32 v87, v97, v73
	v_min_u32_e32 v73, v97, v73
	v_max_u32_e32 v97, v89, v79
	v_min_u32_e32 v79, v89, v79
	v_max_u32_e32 v89, v82, v90
	v_min_u32_e32 v90, v82, v90
	v_max_u32_e32 v82, v70, v96
	v_min_u32_e32 v96, v70, v96
	v_max_u32_e32 v70, v111, v83
	v_min_u32_e32 v83, v111, v83
	v_max_u32_e32 v111, v109, v110
	v_min_u32_e32 v110, v109, v110
	v_max_u32_e32 v109, v117, v118
	v_min_u32_e32 v118, v117, v118
	v_max_u32_e32 v117, v91, v104
	v_min_u32_e32 v104, v91, v104
	v_max_u32_e32 v91, v87, v89
	v_min_u32_e32 v89, v87, v89
	v_max_u32_e32 v87, v97, v82
	v_min_u32_e32 v82, v97, v82
	v_max_u32_e32 v97, v73, v90
	v_min_u32_e32 v90, v73, v90
	v_max_u32_e32 v73, v79, v96
	v_min_u32_e32 v96, v79, v96
	v_max_u32_e32 v79, v70, v111
	v_min_u32_e32 v111, v70, v111
	v_max_u32_e32 v70, v83, v110
	v_min_u32_e32 v110, v83, v110
	v_max_u32_e32 v83, v109, v117
	v_min_u32_e32 v117, v109, v117
	v_max_u32_e32 v109, v118, v104
	v_min_u32_e32 v104, v118, v104
	v_max_u32_e32 v118, v91, v87
	v_min_u32_e32 v87, v91, v87
	v_max_u32_e32 v91, v89, v82
	v_min_u32_e32 v82, v89, v82
	v_max_u32_e32 v89, v97, v73
	v_min_u32_e32 v73, v97, v73
	v_max_u32_e32 v97, v90, v96
	v_min_u32_e32 v96, v90, v96
	v_cvt_f32_f16_e32 v90, v56
	v_cvt_f32_f16_sdwa v98, v56 dst_sel:DWORD dst_unused:UNUSED_PAD src0_sel:WORD_1
	v_ashrrev_i32_e32 v106, 31, v90
	v_bitop3_b32 v90, v90, v106, s40 bitop3:0x78
	v_xor_b32_e32 v90, 0x8000000f, v90
	v_ashrrev_i32_e32 v106, 31, v98
	v_bitop3_b32 v98, v98, v106, s40 bitop3:0x78
	v_xor_b32_e32 v98, 0x8000000e, v98
	v_cvt_f32_f16_e32 v106, v57
	v_cvt_f32_f16_sdwa v107, v57 dst_sel:DWORD dst_unused:UNUSED_PAD src0_sel:WORD_1
	v_ashrrev_i32_e32 v72, 31, v106
	v_bitop3_b32 v106, v106, v72, s40 bitop3:0x78
	v_xor_b32_e32 v106, 0x8000000d, v106
	v_ashrrev_i32_e32 v72, 31, v107
	v_bitop3_b32 v107, v107, v72, s40 bitop3:0x78
	v_xor_b32_e32 v107, 0x8000000c, v107
	v_cvt_f32_f16_e32 v72, v58
	v_cvt_f32_f16_sdwa v78, v58 dst_sel:DWORD dst_unused:UNUSED_PAD src0_sel:WORD_1
	v_ashrrev_i32_e32 v119, 31, v72
	v_bitop3_b32 v72, v72, v119, s40 bitop3:0x78
	v_xor_b32_e32 v72, 0x8000000b, v72
	v_ashrrev_i32_e32 v119, 31, v78
	v_bitop3_b32 v78, v78, v119, s40 bitop3:0x78
	v_xor_b32_e32 v78, 0x8000000a, v78
	v_cvt_f32_f16_e32 v119, v59
	v_cvt_f32_f16_sdwa v114, v59 dst_sel:DWORD dst_unused:UNUSED_PAD src0_sel:WORD_1
	v_ashrrev_i32_e32 v105, 31, v119
	v_bitop3_b32 v119, v119, v105, s40 bitop3:0x78
	v_xor_b32_e32 v119, 0x80000009, v119
	v_ashrrev_i32_e32 v105, 31, v114
	v_bitop3_b32 v114, v114, v105, s40 bitop3:0x78
	v_xor_b32_e32 v114, 0x80000008, v114
	v_cvt_f32_f16_e32 v105, v60
; __device__ __forceinline__ unsigned f2key(float f) { const unsigned u = __float_as_uint(f); return (u & 0x80000000u) ? ~u : (u | 0x80000000u); }
; #define CE_DESC(a, b) do { const unsigned _mx = (a) > (b) ? (a) : (b), _mn = (a) > (b) ? (b) : (a); (a) = _mx; (b) = _mn; } while (0)
; __device__ __forceinline__ void sort16_desc(unsigned (&k)[16]) {
; #pragma unroll
;     for (int size = 2; size <= 16; size <<= 1)
; #pragma unroll
;         for (int stride = size >> 1; stride > 0; stride >>= 1)
; #pragma unroll
;             for (int i = 0; i < 16; ++i) { const int j = i ^ stride;
;                 if (j > i) { if ((i & size) == 0) CE_DESC(k[i], k[j]); else CE_DESC(k[j], k[i]); } }
; }
; __device__ __forceinline__ void merge16(unsigned (&a)[16], const unsigned (&b)[16]) {
; #pragma unroll
;     for (int i = 0; i < 16; ++i) a[i] = a[i] > b[15 - i] ? a[i] : b[15 - i];
; #pragma unroll
;     for (int stride = 8; stride > 0; stride >>= 1)
; #pragma unroll
;         for (int i = 0; i < 16; ++i) { const int j = i ^ stride; if (j > i) CE_DESC(a[i], a[j]); }
; }
; __device__ __forceinline__ void peer_tile(const Args& A, LAS unsigned char* lds, int tile) {
;     ...
;                   for (int i = 0; i < 16; ++i) {
;                       const float lo = (float)__builtin_bit_cast(_Float16, (unsigned short)(sw[i] & 0xffffu)), hi = (float)__builtin_bit_cast(_Float16, (unsigned short)(sw[i] >> 16));
;                       const unsigned klo = (f2key(lo) & ~127u) | (unsigned)(127 - (32 * g + 2 * i)), khi = (f2key(hi) & ~127u) | (unsigned)(127 - (32 * g + 2 * i + 1));
;                       if (i < 8) { k0[2 * i] = klo; k0[2 * i + 1] = khi; } else { k1[2 * (i - 8)] = klo; k1[2 * (i - 8) + 1] = khi; } } }
	v_cvt_f32_f16_sdwa v108, v60 dst_sel:DWORD dst_unused:UNUSED_PAD src0_sel:WORD_1
	v_ashrrev_i32_e32 v115, 31, v105
	v_bitop3_b32 v105, v105, v115, s40 bitop3:0x78
	v_xor_b32_e32 v105, 0x80000007, v105
	v_ashrrev_i32_e32 v115, 31, v108
	v_bitop3_b32 v108, v108, v115, s40 bitop3:0x78
	v_xor_b32_e32 v108, 0x80000006, v108
	v_cvt_f32_f16_e32 v115, v61
	v_cvt_f32_f16_sdwa v75, v61 dst_sel:DWORD dst_unused:UNUSED_PAD src0_sel:WORD_1
	v_ashrrev_i32_e32 v102, 31, v115
	v_bitop3_b32 v115, v115, v102, s40 bitop3:0x78
	v_xor_b32_e32 v115, 0x80000005, v115
	v_ashrrev_i32_e32 v102, 31, v75
	v_bitop3_b32 v75, v75, v102, s40 bitop3:0x78
	v_xor_b32_e32 v75, 0x80000004, v75
	v_cvt_f32_f16_e32 v102, v62
	v_cvt_f32_f16_sdwa v103, v62 dst_sel:DWORD dst_unused:UNUSED_PAD src0_sel:WORD_1
	v_ashrrev_i32_e32 v112, 31, v102
	v_bitop3_b32 v102, v102, v112, s40 bitop3:0x78
	v_xor_b32_e32 v102, 0x80000003, v102
	v_ashrrev_i32_e32 v112, 31, v103
	v_bitop3_b32 v103, v103, v112, s40 bitop3:0x78
	v_xor_b32_e32 v103, 0x80000002, v103
	v_cvt_f32_f16_e32 v112, v63
	v_cvt_f32_f16_sdwa v116, v63 dst_sel:DWORD dst_unused:UNUSED_PAD src0_sel:WORD_1
	v_ashrrev_i32_e32 v92, 31, v112
	v_bitop3_b32 v112, v112, v92, s40 bitop3:0x78
	v_xor_b32_e32 v112, 0x80000001, v112
	v_ashrrev_i32_e32 v92, 31, v116
	v_bitop3_b32 v116, v116, v92, s40 bitop3:0x78
	v_xor_b32_e32 v116, 0x80000000, v116
	v_max_u32_e32 v92, v90, v103
	v_min_u32_e32 v103, v90, v103
	v_max_u32_e32 v90, v98, v102
	v_min_u32_e32 v102, v98, v102
	v_max_u32_e32 v98, v106, v116
	v_min_u32_e32 v116, v106, v116
	v_max_u32_e32 v106, v107, v112
	v_min_u32_e32 v112, v107, v112
	v_max_u32_e32 v107, v72, v105
	v_min_u32_e32 v105, v72, v105
	v_max_u32_e32 v72, v78, v119
	v_min_u32_e32 v119, v78, v119
	v_max_u32_e32 v78, v114, v75
	v_min_u32_e32 v75, v114, v75
	v_max_u32_e32 v114, v108, v115
	v_min_u32_e32 v115, v108, v115
	v_max_u32_e32 v108, v92, v72
	v_min_u32_e32 v72, v92, v72
	v_max_u32_e32 v92, v90, v78
	v_min_u32_e32 v78, v90, v78
	v_max_u32_e32 v90, v98, v114
	v_min_u32_e32 v114, v98, v114
	v_max_u32_e32 v98, v106, v107
	v_min_u32_e32 v107, v106, v107
	v_max_u32_e32 v106, v119, v103
	v_min_u32_e32 v103, v119, v103
	v_max_u32_e32 v119, v105, v112
	v_min_u32_e32 v112, v105, v112
	v_max_u32_e32 v105, v115, v116
	v_min_u32_e32 v116, v115, v116
	v_max_u32_e32 v115, v75, v102
	v_min_u32_e32 v102, v75, v102
	v_max_u32_e32 v75, v108, v92
	v_min_u32_e32 v92, v108, v92
	v_max_u32_e32 v108, v90, v98
	v_min_u32_e32 v98, v90, v98
	v_max_u32_e32 v90, v107, v72
	v_min_u32_e32 v72, v107, v72
	v_max_u32_e32 v107, v106, v119
	v_min_u32_e32 v119, v106, v119
	v_max_u32_e32 v106, v78, v114
	v_min_u32_e32 v114, v78, v114
	v_max_u32_e32 v78, v105, v115
	v_min_u32_e32 v115, v105, v115
	v_max_u32_e32 v105, v102, v103
	v_min_u32_e32 v103, v102, v103
	v_max_u32_e32 v102, v112, v116
	v_min_u32_e32 v116, v112, v116
	v_max_u32_e32 v112, v75, v108
	v_min_u32_e32 v108, v75, v108
	v_max_u32_e32 v75, v92, v98
	v_min_u32_e32 v98, v92, v98
	v_max_u32_e32 v92, v90, v78
	v_min_u32_e32 v78, v90, v78
	v_max_u32_e32 v90, v72, v115
	v_min_u32_e32 v115, v72, v115
	v_max_u32_e32 v72, v107, v106
	v_min_u32_e32 v106, v107, v106
	v_max_u32_e32 v107, v119, v114
	v_min_u32_e32 v114, v119, v114
	v_max_u32_e32 v119, v105, v102
	v_min_u32_e32 v102, v105, v102
	v_max_u32_e32 v105, v103, v116
	v_min_u32_e32 v116, v103, v116
	v_max_u32_e32 v103, v75, v108
	v_min_u32_e32 v108, v75, v108
	v_max_u32_e32 v75, v98, v119
	v_min_u32_e32 v119, v98, v119
	v_max_u32_e32 v98, v92, v72
	v_min_u32_e32 v72, v92, v72
	v_max_u32_e32 v92, v90, v106
	v_min_u32_e32 v106, v90, v106
	v_max_u32_e32 v90, v107, v78
	v_min_u32_e32 v78, v107, v78
	v_max_u32_e32 v107, v114, v115
	v_min_u32_e32 v115, v114, v115
	v_max_u32_e32 v114, v105, v102
	v_min_u32_e32 v102, v105, v102
	v_max_u32_e32 v105, v103, v98
	v_min_u32_e32 v98, v103, v98
	v_max_u32_e32 v103, v108, v72
	v_min_u32_e32 v72, v108, v72
	v_max_u32_e32 v108, v92, v90
	v_min_u32_e32 v90, v92, v90
	v_max_u32_e32 v92, v106, v78
	v_min_u32_e32 v78, v106, v78
	v_max_u32_e32 v106, v107, v114
	v_min_u32_e32 v114, v107, v114
	v_max_u32_e32 v107, v115, v102
	v_min_u32_e32 v102, v115, v102
	v_max_u32_e32 v115, v103, v98
	v_min_u32_e32 v98, v103, v98
	v_max_u32_e32 v103, v75, v72
	v_min_u32_e32 v72, v75, v72
	v_max_u32_e32 v75, v106, v119
	v_min_u32_e32 v119, v106, v119
	v_max_u32_e32 v106, v107, v114
	v_min_u32_e32 v114, v107, v114
	v_max_u32_e32 v107, v103, v108
	v_min_u32_e32 v108, v103, v108
	v_max_u32_e32 v103, v72, v90
	v_min_u32_e32 v90, v72, v90
	v_max_u32_e32 v72, v92, v75
	v_min_u32_e32 v75, v92, v75
	v_max_u32_e32 v92, v78, v119
	v_min_u32_e32 v119, v78, v119
	v_max_u32_e32 v78, v107, v98
	v_min_u32_e32 v98, v107, v98
	v_max_u32_e32 v107, v108, v103
	v_min_u32_e32 v103, v108, v103
	v_max_u32_e32 v108, v72, v90
	v_min_u32_e32 v90, v72, v90
	v_max_u32_e32 v72, v75, v92
	v_min_u32_e32 v92, v75, v92
	v_max_u32_e32 v75, v106, v119
	v_min_u32_e32 v119, v106, v119
	v_max_u32_e32 v106, v103, v108
	v_min_u32_e32 v108, v103, v108
	v_max_u32_e32 v103, v90, v72
	v_min_u32_e32 v72, v90, v72
	v_max_u32_e32 v79, v79, v116
	v_max_u32_e32 v111, v111, v102
	v_max_u32_e32 v70, v70, v114
	v_max_u32_e32 v110, v110, v119
	v_max_u32_e32 v83, v83, v75
	v_max_u32_e32 v117, v117, v92
	v_max_u32_e32 v109, v109, v72
	v_max_u32_e32 v104, v104, v103
	v_max_u32_e32 v118, v118, v108
	v_max_u32_e32 v87, v87, v106
	v_max_u32_e32 v91, v91, v107
	v_max_u32_e32 v82, v82, v98
	v_max_u32_e32 v89, v89, v78
	v_max_u32_e32 v73, v73, v115
	v_max_u32_e32 v97, v97, v105
	v_max_u32_e32 v96, v96, v112
	v_max_u32_e32 v116, v79, v118
	v_min_u32_e32 v118, v79, v118
	v_max_u32_e32 v79, v111, v87
; __device__ __forceinline__ float key2f(unsigned k) { const unsigned u = (k & 0x80000000u) ? (k & 0x7fffffffu) : ~k; return __uint_as_float(u); }
; #define CE_DESC(a, b) do { const unsigned _mx = (a) > (b) ? (a) : (b), _mn = (a) > (b) ? (b) : (a); (a) = _mx; (b) = _mn; } while (0)
; __device__ __forceinline__ void merge16(unsigned (&a)[16], const unsigned (&b)[16]) {
; #pragma unroll
;     for (int i = 0; i < 16; ++i) a[i] = a[i] > b[15 - i] ? a[i] : b[15 - i];
; #pragma unroll
;     for (int stride = 8; stride > 0; stride >>= 1)
; #pragma unroll
;         for (int i = 0; i < 16; ++i) { const int j = i ^ stride; if (j > i) CE_DESC(a[i], a[j]); }
; }
; __device__ __forceinline__ void peer_tile(const Args& A, LAS unsigned char* lds, int tile) {
;     ...
;                 for (int i = 0; i < 16; ++i) L2[p][i] = (g & 2) ? ((g & 1) ? LA[3][p][i] : LA[2][p][i]) : ((g & 1) ? LA[1][p][i] : LA[0][p][i]);
;             float va[16], vb[16];
; #pragma unroll
;             for (int i = 0; i < 16; ++i) { va[i] = key2f(L2[0][i] & ~127u); vb[i] = key2f(L2[1][i] & ~127u); idx[i] = 127u - (L2[0][i] & 127u); idx[16 + i] = 127u - (L2[1][i] & 127u); }
	v_min_u32_e32 v87, v111, v87
	v_max_u32_e32 v111, v70, v91
	v_min_u32_e32 v91, v70, v91
	v_max_u32_e32 v70, v110, v82
	v_min_u32_e32 v82, v110, v82
	v_max_u32_e32 v110, v83, v89
	v_min_u32_e32 v89, v83, v89
	v_max_u32_e32 v83, v117, v73
	v_min_u32_e32 v73, v117, v73
	v_max_u32_e32 v117, v109, v97
	v_min_u32_e32 v97, v109, v97
	v_max_u32_e32 v109, v104, v96
	v_min_u32_e32 v96, v104, v96
	v_max_u32_e32 v104, v116, v110
	v_min_u32_e32 v110, v116, v110
	v_max_u32_e32 v116, v79, v83
	v_min_u32_e32 v83, v79, v83
	v_max_u32_e32 v79, v111, v117
	v_min_u32_e32 v117, v111, v117
	v_max_u32_e32 v111, v70, v109
	v_min_u32_e32 v109, v70, v109
	v_max_u32_e32 v70, v118, v89
	v_min_u32_e32 v89, v118, v89
	v_max_u32_e32 v118, v87, v73
	v_min_u32_e32 v73, v87, v73
	v_max_u32_e32 v87, v91, v97
	v_min_u32_e32 v97, v91, v97
	v_max_u32_e32 v91, v82, v96
	v_min_u32_e32 v96, v82, v96
	v_max_u32_e32 v82, v104, v79
	v_min_u32_e32 v79, v104, v79
	v_max_u32_e32 v104, v116, v111
	v_min_u32_e32 v111, v116, v111
	v_max_u32_e32 v116, v110, v117
	v_min_u32_e32 v117, v110, v117
	v_max_u32_e32 v110, v83, v109
	v_min_u32_e32 v109, v83, v109
	v_max_u32_e32 v83, v70, v87
	v_min_u32_e32 v87, v70, v87
	v_max_u32_e32 v70, v118, v91
	v_min_u32_e32 v91, v118, v91
	v_max_u32_e32 v118, v89, v97
	v_min_u32_e32 v97, v89, v97
	v_max_u32_e32 v89, v73, v96
	v_min_u32_e32 v96, v73, v96
	v_max_u32_e32 v73, v82, v104
	v_min_u32_e32 v104, v82, v104
	v_max_u32_e32 v82, v79, v111
	v_min_u32_e32 v111, v79, v111
	v_max_u32_e32 v79, v116, v110
	v_min_u32_e32 v110, v116, v110
	v_max_u32_e32 v116, v117, v109
	v_min_u32_e32 v109, v117, v109
	v_max_u32_e32 v117, v83, v70
	v_min_u32_e32 v70, v83, v70
	v_max_u32_e32 v83, v87, v91
	v_min_u32_e32 v91, v87, v91
	v_max_u32_e32 v87, v118, v89
	v_min_u32_e32 v89, v118, v89
	v_max_u32_e32 v118, v97, v96
	v_min_u32_e32 v96, v97, v96
	v_xor_b32_e32 v97, 0x7f, v71
	v_xor_b32_e32 v102, 0x7f, v88
	v_and_b32_e32 v97, 0x7f, v97
	v_and_b32_e32 v102, 0x7f, v102
	ds_write2_b32 v67, v97, v102 offset0:0 offset1:1
	v_xor_b32_e32 v102, 0x7f, v74
	v_xor_b32_e32 v97, 0x7f, v95
	v_and_b32_e32 v102, 0x7f, v102
	v_and_b32_e32 v97, 0x7f, v97
	ds_write2_b32 v67, v102, v97 offset0:2 offset1:3
	v_xor_b32_e32 v97, 0x7f, v86
	v_xor_b32_e32 v102, 0x7f, v94
	v_and_b32_e32 v97, 0x7f, v97
	v_and_b32_e32 v102, 0x7f, v102
	ds_write2_b32 v67, v97, v102 offset0:4 offset1:5
	v_xor_b32_e32 v102, 0x7f, v99
	v_xor_b32_e32 v97, 0x7f, v93
	v_and_b32_e32 v102, 0x7f, v102
	v_and_b32_e32 v97, 0x7f, v97
	ds_write2_b32 v67, v102, v97 offset0:6 offset1:7
	v_xor_b32_e32 v97, 0x7f, v100
	v_xor_b32_e32 v102, 0x7f, v76
	v_and_b32_e32 v97, 0x7f, v97
	v_and_b32_e32 v102, 0x7f, v102
	ds_write2_b32 v67, v97, v102 offset0:8 offset1:9
	v_xor_b32_e32 v102, 0x7f, v81
	v_xor_b32_e32 v97, 0x7f, v80
	v_and_b32_e32 v102, 0x7f, v102
	v_and_b32_e32 v97, 0x7f, v97
	ds_write2_b32 v67, v102, v97 offset0:10 offset1:11
	v_xor_b32_e32 v97, 0x7f, v77
	v_xor_b32_e32 v102, 0x7f, v84
	v_and_b32_e32 v97, 0x7f, v97
	v_and_b32_e32 v102, 0x7f, v102
	ds_write2_b32 v67, v97, v102 offset0:12 offset1:13
	v_xor_b32_e32 v102, 0x7f, v101
	v_xor_b32_e32 v97, 0x7f, v85
	v_and_b32_e32 v102, 0x7f, v102
	v_and_b32_e32 v97, 0x7f, v97
	ds_write2_b32 v67, v102, v97 offset0:14 offset1:15
	v_xor_b32_e32 v97, 0x7f, v73
	v_xor_b32_e32 v102, 0x7f, v104
	v_and_b32_e32 v97, 0x7f, v97
	v_and_b32_e32 v102, 0x7f, v102
	ds_write2_b32 v67, v97, v102 offset0:16 offset1:17
	v_xor_b32_e32 v102, 0x7f, v82
	v_xor_b32_e32 v97, 0x7f, v111
	v_and_b32_e32 v102, 0x7f, v102
	v_and_b32_e32 v97, 0x7f, v97
	ds_write2_b32 v67, v102, v97 offset0:18 offset1:19
	v_xor_b32_e32 v97, 0x7f, v79
	v_xor_b32_e32 v102, 0x7f, v110
	v_and_b32_e32 v97, 0x7f, v97
	v_and_b32_e32 v102, 0x7f, v102
	ds_write2_b32 v67, v97, v102 offset0:20 offset1:21
	v_xor_b32_e32 v102, 0x7f, v116
	v_xor_b32_e32 v97, 0x7f, v109
	v_and_b32_e32 v102, 0x7f, v102
	v_and_b32_e32 v97, 0x7f, v97
	ds_write2_b32 v67, v102, v97 offset0:22 offset1:23
	v_xor_b32_e32 v97, 0x7f, v117
	v_xor_b32_e32 v102, 0x7f, v70
	v_and_b32_e32 v97, 0x7f, v97
	v_and_b32_e32 v102, 0x7f, v102
	ds_write2_b32 v67, v97, v102 offset0:24 offset1:25
	v_xor_b32_e32 v102, 0x7f, v83
	v_xor_b32_e32 v97, 0x7f, v91
	v_and_b32_e32 v102, 0x7f, v102
	v_and_b32_e32 v97, 0x7f, v97
	ds_write2_b32 v67, v102, v97 offset0:26 offset1:27
	v_xor_b32_e32 v97, 0x7f, v87
	v_xor_b32_e32 v102, 0x7f, v89
	v_and_b32_e32 v97, 0x7f, v97
	v_and_b32_e32 v102, 0x7f, v102
	ds_write2_b32 v67, v97, v102 offset0:28 offset1:29
	v_xor_b32_e32 v102, 0x7f, v118
	v_xor_b32_e32 v97, 0x7f, v96
	v_and_b32_e32 v102, 0x7f, v102
	v_and_b32_e32 v97, 0x7f, v97
	ds_write2_b32 v67, v102, v97 offset0:30 offset1:31
	v_ashrrev_i32_e32 v102, 31, v71
	v_and_b32_e32 v97, 0xffffff80, v71
	v_bitop3_b32 v97, v97, v102, s41 bitop3:0x87
	v_ashrrev_i32_e32 v114, 31, v88
	v_and_b32_e32 v102, 0xffffff80, v88
	v_bitop3_b32 v102, v102, v114, s41 bitop3:0x87
	v_ashrrev_i32_e32 v119, 31, v74
	v_and_b32_e32 v114, 0xffffff80, v74
	v_bitop3_b32 v114, v114, v119, s41 bitop3:0x87
	v_ashrrev_i32_e32 v75, 31, v95
	v_and_b32_e32 v119, 0xffffff80, v95
	v_bitop3_b32 v119, v119, v75, s41 bitop3:0x87
	v_ashrrev_i32_e32 v92, 31, v86
	v_and_b32_e32 v75, 0xffffff80, v86
	v_bitop3_b32 v75, v75, v92, s41 bitop3:0x87
	v_ashrrev_i32_e32 v72, 31, v94
	v_and_b32_e32 v92, 0xffffff80, v94
	v_bitop3_b32 v92, v92, v72, s41 bitop3:0x87
	v_ashrrev_i32_e32 v103, 31, v99
	v_and_b32_e32 v72, 0xffffff80, v99
	v_bitop3_b32 v72, v72, v103, s41 bitop3:0x87
	v_ashrrev_i32_e32 v108, 31, v93
	v_and_b32_e32 v103, 0xffffff80, v93
	v_bitop3_b32 v103, v103, v108, s41 bitop3:0x87
	v_ashrrev_i32_e32 v106, 31, v100
	v_and_b32_e32 v108, 0xffffff80, v100
; __device__ __forceinline__ float key2f(unsigned k) { const unsigned u = (k & 0x80000000u) ? (k & 0x7fffffffu) : ~k; return __uint_as_float(u); }
; #define CK(i, j) ((f2key(va[i] + vb[j]) & ~255u) | (unsigned)(255 - (16 * (i) + (j))))
; __device__ __forceinline__ void peer_tile(const Args& A, LAS unsigned char* lds, int tile) {
;     ...
;             for (int i = 0; i < 16; ++i) { va[i] = key2f(L2[0][i] & ~127u); vb[i] = key2f(L2[1][i] & ~127u); idx[i] = 127u - (L2[0][i] & 127u); idx[16 + i] = 127u - (L2[1][i] & 127u); }
;     ...
;             unsigned Lf[16], Bt[16];
; #pragma unroll
;             for (int j = 0; j < 16; ++j) Lf[j] = CK(0, j);
	v_bitop3_b32 v108, v108, v106, s41 bitop3:0x87
	v_ashrrev_i32_e32 v107, 31, v76
	v_and_b32_e32 v106, 0xffffff80, v76
	v_bitop3_b32 v106, v106, v107, s41 bitop3:0x87
	v_ashrrev_i32_e32 v98, 31, v81
	v_and_b32_e32 v107, 0xffffff80, v81
	v_bitop3_b32 v107, v107, v98, s41 bitop3:0x87
	v_ashrrev_i32_e32 v78, 31, v80
	v_and_b32_e32 v98, 0xffffff80, v80
	v_bitop3_b32 v98, v98, v78, s41 bitop3:0x87
	v_ashrrev_i32_e32 v115, 31, v77
	v_and_b32_e32 v78, 0xffffff80, v77
	v_bitop3_b32 v78, v78, v115, s41 bitop3:0x87
	v_ashrrev_i32_e32 v105, 31, v84
	v_and_b32_e32 v115, 0xffffff80, v84
	v_bitop3_b32 v115, v115, v105, s41 bitop3:0x87
	v_ashrrev_i32_e32 v112, 31, v101
	v_and_b32_e32 v105, 0xffffff80, v101
	v_bitop3_b32 v105, v105, v112, s41 bitop3:0x87
	v_ashrrev_i32_e32 v90, 31, v85
	v_and_b32_e32 v112, 0xffffff80, v85
	v_bitop3_b32 v112, v112, v90, s41 bitop3:0x87
	v_ashrrev_i32_e32 v120, 31, v73
	v_and_b32_e32 v90, 0xffffff80, v73
	v_bitop3_b32 v90, v90, v120, s41 bitop3:0x87
	v_ashrrev_i32_e32 v121, 31, v104
	v_and_b32_e32 v120, 0xffffff80, v104
	v_bitop3_b32 v120, v120, v121, s41 bitop3:0x87
	v_ashrrev_i32_e32 v122, 31, v82
	v_and_b32_e32 v121, 0xffffff80, v82
	v_bitop3_b32 v121, v121, v122, s41 bitop3:0x87
	v_ashrrev_i32_e32 v123, 31, v111
	v_and_b32_e32 v122, 0xffffff80, v111
	v_bitop3_b32 v122, v122, v123, s41 bitop3:0x87
	v_ashrrev_i32_e32 v124, 31, v79
	v_and_b32_e32 v123, 0xffffff80, v79
	v_bitop3_b32 v123, v123, v124, s41 bitop3:0x87
	v_ashrrev_i32_e32 v125, 31, v110
	v_and_b32_e32 v124, 0xffffff80, v110
	v_bitop3_b32 v124, v124, v125, s41 bitop3:0x87
	v_ashrrev_i32_e32 v126, 31, v116
	v_and_b32_e32 v125, 0xffffff80, v116
	v_bitop3_b32 v125, v125, v126, s41 bitop3:0x87
	v_ashrrev_i32_e32 v127, 31, v109
	v_and_b32_e32 v126, 0xffffff80, v109
	v_bitop3_b32 v126, v126, v127, s41 bitop3:0x87
	v_ashrrev_i32_e32 v128, 31, v117
	v_and_b32_e32 v127, 0xffffff80, v117
	v_bitop3_b32 v127, v127, v128, s41 bitop3:0x87
	v_ashrrev_i32_e32 v129, 31, v70
	v_and_b32_e32 v128, 0xffffff80, v70
	v_bitop3_b32 v128, v128, v129, s41 bitop3:0x87
	v_ashrrev_i32_e32 v130, 31, v83
	v_and_b32_e32 v129, 0xffffff80, v83
	v_bitop3_b32 v129, v129, v130, s41 bitop3:0x87
	v_ashrrev_i32_e32 v131, 31, v91
	v_and_b32_e32 v130, 0xffffff80, v91
	v_bitop3_b32 v130, v130, v131, s41 bitop3:0x87
	v_ashrrev_i32_e32 v132, 31, v87
	v_and_b32_e32 v131, 0xffffff80, v87
	v_bitop3_b32 v131, v131, v132, s41 bitop3:0x87
	v_ashrrev_i32_e32 v133, 31, v89
	v_and_b32_e32 v132, 0xffffff80, v89
	v_bitop3_b32 v132, v132, v133, s41 bitop3:0x87
	v_ashrrev_i32_e32 v134, 31, v118
	v_and_b32_e32 v133, 0xffffff80, v118
	v_bitop3_b32 v133, v133, v134, s41 bitop3:0x87
	v_ashrrev_i32_e32 v135, 31, v96
	v_and_b32_e32 v134, 0xffffff80, v96
	v_bitop3_b32 v134, v134, v135, s41 bitop3:0x87
	v_add_f32_e32 v96, v97, v90
	v_ashrrev_i32_e32 v118, 31, v96
	v_and_b32_e32 v96, 0xffffff00, v96
	v_lshl_or_b32 v118, v118, 8, s33
	v_xor_b32_e32 v96, v96, v118
	v_xor_b32_e32 v96, 0xff, v96
	v_add_f32_e32 v118, v97, v120
	v_ashrrev_i32_e32 v89, 31, v118
	v_and_b32_e32 v118, 0xffffff00, v118
	v_lshl_or_b32 v89, v89, 8, s33
	v_xor_b32_e32 v118, v118, v89
	v_xor_b32_e32 v118, 0xfe, v118
	v_add_f32_e32 v89, v97, v121
	v_ashrrev_i32_e32 v87, 31, v89
	v_and_b32_e32 v89, 0xffffff00, v89
	v_lshl_or_b32 v87, v87, 8, s33
	v_xor_b32_e32 v89, v89, v87
	v_xor_b32_e32 v89, 0xfd, v89
	v_add_f32_e32 v87, v97, v122
	v_ashrrev_i32_e32 v91, 31, v87
	v_and_b32_e32 v87, 0xffffff00, v87
	v_lshl_or_b32 v91, v91, 8, s33
	v_xor_b32_e32 v87, v87, v91
	v_xor_b32_e32 v87, 0xfc, v87
	v_add_f32_e32 v91, v97, v123
	v_ashrrev_i32_e32 v83, 31, v91
	v_and_b32_e32 v91, 0xffffff00, v91
	v_lshl_or_b32 v83, v83, 8, s33
	v_xor_b32_e32 v91, v91, v83
	v_xor_b32_e32 v91, 0xfb, v91
	v_add_f32_e32 v83, v97, v124
	v_ashrrev_i32_e32 v70, 31, v83
	v_and_b32_e32 v83, 0xffffff00, v83
	v_lshl_or_b32 v70, v70, 8, s33
	v_xor_b32_e32 v83, v83, v70
	v_xor_b32_e32 v83, 0xfa, v83
	v_add_f32_e32 v70, v97, v125
	v_ashrrev_i32_e32 v117, 31, v70
	v_and_b32_e32 v70, 0xffffff00, v70
	v_lshl_or_b32 v117, v117, 8, s33
	v_xor_b32_e32 v70, v70, v117
	v_xor_b32_e32 v70, 0xf9, v70
	v_add_f32_e32 v117, v97, v126
	v_ashrrev_i32_e32 v109, 31, v117
	v_and_b32_e32 v117, 0xffffff00, v117
	v_lshl_or_b32 v109, v109, 8, s33
	v_xor_b32_e32 v117, v117, v109
	v_xor_b32_e32 v117, 0xf8, v117
	v_add_f32_e32 v109, v97, v127
	v_ashrrev_i32_e32 v116, 31, v109
	v_and_b32_e32 v109, 0xffffff00, v109
	v_lshl_or_b32 v116, v116, 8, s33
	v_xor_b32_e32 v109, v109, v116
	v_xor_b32_e32 v109, 0xf7, v109
	v_add_f32_e32 v116, v97, v128
	v_ashrrev_i32_e32 v110, 31, v116
	v_and_b32_e32 v116, 0xffffff00, v116
	v_lshl_or_b32 v110, v110, 8, s33
	v_xor_b32_e32 v116, v116, v110
	v_xor_b32_e32 v116, 0xf6, v116
	v_add_f32_e32 v110, v97, v129
	v_ashrrev_i32_e32 v79, 31, v110
	v_and_b32_e32 v110, 0xffffff00, v110
	v_lshl_or_b32 v79, v79, 8, s33
	v_xor_b32_e32 v110, v110, v79
	v_xor_b32_e32 v110, 0xf5, v110
	v_add_f32_e32 v79, v97, v130
	v_ashrrev_i32_e32 v111, 31, v79
	v_and_b32_e32 v79, 0xffffff00, v79
	v_lshl_or_b32 v111, v111, 8, s33
	v_xor_b32_e32 v79, v79, v111
	v_xor_b32_e32 v79, 0xf4, v79
	v_add_f32_e32 v111, v97, v131
	v_ashrrev_i32_e32 v82, 31, v111
	v_and_b32_e32 v111, 0xffffff00, v111
	v_lshl_or_b32 v82, v82, 8, s33
	v_xor_b32_e32 v111, v111, v82
	v_xor_b32_e32 v111, 0xf3, v111
	v_add_f32_e32 v82, v97, v132
	v_ashrrev_i32_e32 v104, 31, v82
	v_and_b32_e32 v82, 0xffffff00, v82
	v_lshl_or_b32 v104, v104, 8, s33
	v_xor_b32_e32 v82, v82, v104
	v_xor_b32_e32 v82, 0xf2, v82
	v_add_f32_e32 v104, v97, v133
	v_ashrrev_i32_e32 v73, 31, v104
	v_and_b32_e32 v104, 0xffffff00, v104
	v_lshl_or_b32 v73, v73, 8, s33
	v_xor_b32_e32 v104, v104, v73
; #define CK(i, j) ((f2key(va[i] + vb[j]) & ~255u) | (unsigned)(255 - (16 * (i) + (j))))
; __device__ __forceinline__ void peer_tile(const Args& A, LAS unsigned char* lds, int tile) {
;     ...
;             unsigned Lf[16], Bt[16];
; #pragma unroll
;             for (int j = 0; j < 16; ++j) Lf[j] = CK(0, j);
; #pragma unroll
;             for (int j = 0; j < 8; ++j) Bt[j] = CK(1, j);
; #pragma unroll
;             for (int j = 0; j < 5; ++j) Bt[8 + j] = CK(2, j);
; #pragma unroll
;             for (int j = 0; j < 3; ++j) Bt[13 + j] = CK(4, j);
;             sort16_desc(Bt); merge16(Lf, Bt);
	v_xor_b32_e32 v104, 0xf1, v104
	v_add_f32_e32 v73, v97, v134
	v_ashrrev_i32_e32 v85, 31, v73
	v_and_b32_e32 v73, 0xffffff00, v73
	v_lshl_or_b32 v85, v85, 8, s33
	v_xor_b32_e32 v73, v73, v85
	v_xor_b32_e32 v73, 0xf0, v73
	v_add_f32_e32 v85, v102, v90
	v_ashrrev_i32_e32 v101, 31, v85
	v_and_b32_e32 v85, 0xffffff00, v85
	v_lshl_or_b32 v101, v101, 8, s33
	v_xor_b32_e32 v85, v85, v101
	v_xor_b32_e32 v85, 0xef, v85
	v_add_f32_e32 v101, v102, v120
	v_ashrrev_i32_e32 v84, 31, v101
	v_and_b32_e32 v101, 0xffffff00, v101
	v_lshl_or_b32 v84, v84, 8, s33
	v_xor_b32_e32 v101, v101, v84
	v_xor_b32_e32 v101, 0xee, v101
	v_add_f32_e32 v84, v102, v121
	v_ashrrev_i32_e32 v77, 31, v84
	v_and_b32_e32 v84, 0xffffff00, v84
	v_lshl_or_b32 v77, v77, 8, s33
	v_xor_b32_e32 v84, v84, v77
	v_xor_b32_e32 v84, 0xed, v84
	v_add_f32_e32 v77, v102, v122
	v_ashrrev_i32_e32 v80, 31, v77
	v_and_b32_e32 v77, 0xffffff00, v77
	v_lshl_or_b32 v80, v80, 8, s33
	v_xor_b32_e32 v77, v77, v80
	v_xor_b32_e32 v77, 0xec, v77
	v_add_f32_e32 v80, v102, v123
	v_ashrrev_i32_e32 v81, 31, v80
	v_and_b32_e32 v80, 0xffffff00, v80
	v_lshl_or_b32 v81, v81, 8, s33
	v_xor_b32_e32 v80, v80, v81
	v_xor_b32_e32 v80, 0xeb, v80
	v_add_f32_e32 v81, v102, v124
	v_ashrrev_i32_e32 v76, 31, v81
	v_and_b32_e32 v81, 0xffffff00, v81
	v_lshl_or_b32 v76, v76, 8, s33
	v_xor_b32_e32 v81, v81, v76
	v_xor_b32_e32 v81, 0xea, v81
	v_add_f32_e32 v76, v102, v125
	v_ashrrev_i32_e32 v100, 31, v76
	v_and_b32_e32 v76, 0xffffff00, v76
	v_lshl_or_b32 v100, v100, 8, s33
	v_xor_b32_e32 v76, v76, v100
	v_xor_b32_e32 v76, 0xe9, v76
	v_add_f32_e32 v100, v102, v126
	v_ashrrev_i32_e32 v93, 31, v100
	v_and_b32_e32 v100, 0xffffff00, v100
	v_lshl_or_b32 v93, v93, 8, s33
	v_xor_b32_e32 v100, v100, v93
	v_xor_b32_e32 v100, 0xe8, v100
	v_add_f32_e32 v93, v114, v90
	v_ashrrev_i32_e32 v99, 31, v93
	v_and_b32_e32 v93, 0xffffff00, v93
	v_lshl_or_b32 v99, v99, 8, s33
	v_xor_b32_e32 v93, v93, v99
	v_xor_b32_e32 v93, 0xdf, v93
	v_add_f32_e32 v99, v114, v120
	v_ashrrev_i32_e32 v94, 31, v99
	v_and_b32_e32 v99, 0xffffff00, v99
	v_lshl_or_b32 v94, v94, 8, s33
	v_xor_b32_e32 v99, v99, v94
	v_xor_b32_e32 v99, 0xde, v99
	v_add_f32_e32 v94, v114, v121
	v_ashrrev_i32_e32 v86, 31, v94
	v_and_b32_e32 v94, 0xffffff00, v94
	v_lshl_or_b32 v86, v86, 8, s33
	v_xor_b32_e32 v94, v94, v86
	v_xor_b32_e32 v94, 0xdd, v94
	v_add_f32_e32 v86, v114, v122
	v_ashrrev_i32_e32 v95, 31, v86
	v_and_b32_e32 v86, 0xffffff00, v86
	v_lshl_or_b32 v95, v95, 8, s33
	v_xor_b32_e32 v86, v86, v95
	v_xor_b32_e32 v86, 0xdc, v86
	v_add_f32_e32 v95, v114, v123
	v_ashrrev_i32_e32 v74, 31, v95
	v_and_b32_e32 v95, 0xffffff00, v95
	v_lshl_or_b32 v74, v74, 8, s33
	v_xor_b32_e32 v95, v95, v74
	v_xor_b32_e32 v95, 0xdb, v95
	v_add_f32_e32 v74, v75, v90
	v_ashrrev_i32_e32 v88, 31, v74
	v_and_b32_e32 v74, 0xffffff00, v74
	v_lshl_or_b32 v88, v88, 8, s33
	v_xor_b32_e32 v74, v74, v88
	v_xor_b32_e32 v74, 0xbf, v74
	v_add_f32_e32 v88, v75, v120
	v_ashrrev_i32_e32 v71, 31, v88
	v_and_b32_e32 v88, 0xffffff00, v88
	v_lshl_or_b32 v71, v71, 8, s33
	v_xor_b32_e32 v88, v88, v71
	v_xor_b32_e32 v88, 0xbe, v88
	v_add_f32_e32 v71, v75, v121
	v_ashrrev_i32_e32 v135, 31, v71
	v_and_b32_e32 v71, 0xffffff00, v71
	v_lshl_or_b32 v135, v135, 8, s33
	v_xor_b32_e32 v71, v71, v135
	v_xor_b32_e32 v71, 0xbd, v71
	v_max_u32_e32 v135, v85, v74
	v_min_u32_e32 v74, v85, v74
	v_max_u32_e32 v85, v101, v95
	v_min_u32_e32 v95, v101, v95
	v_max_u32_e32 v101, v84, v71
	v_min_u32_e32 v71, v84, v71
	v_max_u32_e32 v84, v77, v88
	v_min_u32_e32 v88, v77, v88
	v_max_u32_e32 v77, v80, v93
	v_min_u32_e32 v93, v80, v93
	v_max_u32_e32 v80, v81, v76
	v_min_u32_e32 v76, v81, v76
	v_max_u32_e32 v81, v100, v86
	v_min_u32_e32 v86, v100, v86
	v_max_u32_e32 v100, v99, v94
	v_min_u32_e32 v94, v99, v94
	v_max_u32_e32 v99, v135, v80
	v_min_u32_e32 v80, v135, v80
	v_max_u32_e32 v135, v85, v81
	v_min_u32_e32 v81, v85, v81
	v_max_u32_e32 v85, v101, v100
	v_min_u32_e32 v100, v101, v100
	v_max_u32_e32 v101, v84, v77
	v_min_u32_e32 v77, v84, v77
	v_max_u32_e32 v84, v76, v74
	v_min_u32_e32 v74, v76, v74
	v_max_u32_e32 v76, v93, v88
	v_min_u32_e32 v88, v93, v88
	v_max_u32_e32 v93, v94, v71
	v_min_u32_e32 v71, v94, v71
	v_max_u32_e32 v94, v86, v95
	v_min_u32_e32 v95, v86, v95
	v_max_u32_e32 v86, v99, v135
	v_min_u32_e32 v135, v99, v135
	v_max_u32_e32 v99, v85, v101
	v_min_u32_e32 v101, v85, v101
	v_max_u32_e32 v85, v77, v80
	v_min_u32_e32 v80, v77, v80
	v_max_u32_e32 v77, v84, v76
	v_min_u32_e32 v76, v84, v76
	v_max_u32_e32 v84, v81, v100
	v_min_u32_e32 v100, v81, v100
	v_max_u32_e32 v81, v93, v94
	v_min_u32_e32 v94, v93, v94
	v_max_u32_e32 v93, v95, v74
	v_min_u32_e32 v74, v95, v74
	v_max_u32_e32 v95, v88, v71
	v_min_u32_e32 v71, v88, v71
	v_max_u32_e32 v88, v86, v99
	v_min_u32_e32 v99, v86, v99
	v_max_u32_e32 v86, v135, v101
	v_min_u32_e32 v101, v135, v101
	v_max_u32_e32 v135, v85, v81
	v_min_u32_e32 v81, v85, v81
	v_max_u32_e32 v85, v80, v94
	v_min_u32_e32 v94, v80, v94
	v_max_u32_e32 v80, v77, v84
	v_min_u32_e32 v84, v77, v84
	v_max_u32_e32 v77, v76, v100
	v_min_u32_e32 v100, v76, v100
	v_max_u32_e32 v76, v93, v95
	v_min_u32_e32 v95, v93, v95
	v_max_u32_e32 v93, v74, v71
	v_min_u32_e32 v71, v74, v71
	v_max_u32_e32 v74, v86, v99
	v_min_u32_e32 v99, v86, v99
	v_max_u32_e32 v86, v101, v76
	v_min_u32_e32 v76, v101, v76
	v_max_u32_e32 v101, v135, v80
	v_min_u32_e32 v80, v135, v80
	v_max_u32_e32 v135, v85, v84
	v_min_u32_e32 v84, v85, v84
	v_max_u32_e32 v85, v77, v81
	v_min_u32_e32 v81, v77, v81
	v_max_u32_e32 v77, v100, v94
	v_min_u32_e32 v94, v100, v94
	v_max_u32_e32 v100, v93, v95
	v_min_u32_e32 v95, v93, v95
	v_max_u32_e32 v93, v74, v101
	v_min_u32_e32 v101, v74, v101
; #define CK(i, j) ((f2key(va[i] + vb[j]) & ~255u) | (unsigned)(255 - (16 * (i) + (j))))
; __device__ __forceinline__ void peer_tile(const Args& A, LAS unsigned char* lds, int tile) {
;     ...
;             sort16_desc(Bt); merge16(Lf, Bt);
; #pragma unroll
;             for (int j = 0; j < 4; ++j) Bt[j] = CK(3, j);
;             Bt[4] = CK(5, 0); Bt[5] = CK(5, 1); Bt[6] = CK(6, 0); Bt[7] = CK(6, 1); Bt[8] = CK(7, 0); Bt[9] = CK(7, 1);
;             Bt[10] = CK(8, 0); Bt[11] = CK(9, 0); Bt[12] = CK(10, 0); Bt[13] = CK(11, 0); Bt[14] = CK(12, 0); Bt[15] = CK(13, 0);
	v_max_u32_e32 v74, v99, v80
	v_min_u32_e32 v80, v99, v80
	v_max_u32_e32 v99, v135, v85
	v_min_u32_e32 v85, v135, v85
	v_max_u32_e32 v135, v84, v81
	v_min_u32_e32 v81, v84, v81
	v_max_u32_e32 v84, v77, v100
	v_min_u32_e32 v100, v77, v100
	v_max_u32_e32 v77, v94, v95
	v_min_u32_e32 v95, v94, v95
	v_max_u32_e32 v94, v74, v101
	v_min_u32_e32 v101, v74, v101
	v_max_u32_e32 v74, v86, v80
	v_min_u32_e32 v80, v86, v80
	v_max_u32_e32 v86, v84, v76
	v_min_u32_e32 v76, v84, v76
	v_max_u32_e32 v84, v77, v100
	v_min_u32_e32 v100, v77, v100
	v_max_u32_e32 v77, v74, v99
	v_min_u32_e32 v99, v74, v99
	v_max_u32_e32 v74, v80, v85
	v_min_u32_e32 v85, v80, v85
	v_max_u32_e32 v80, v135, v86
	v_min_u32_e32 v86, v135, v86
	v_max_u32_e32 v135, v81, v76
	v_min_u32_e32 v76, v81, v76
	v_max_u32_e32 v81, v77, v101
	v_min_u32_e32 v101, v77, v101
	v_max_u32_e32 v77, v99, v74
	v_min_u32_e32 v74, v99, v74
	v_max_u32_e32 v99, v80, v85
	v_min_u32_e32 v85, v80, v85
	v_max_u32_e32 v80, v86, v135
	v_min_u32_e32 v135, v86, v135
	v_max_u32_e32 v86, v84, v76
	v_min_u32_e32 v76, v84, v76
	v_max_u32_e32 v84, v74, v99
	v_min_u32_e32 v99, v74, v99
	v_max_u32_e32 v74, v85, v80
	v_min_u32_e32 v80, v85, v80
	v_max_u32_e32 v96, v96, v71
	v_max_u32_e32 v118, v118, v95
	v_max_u32_e32 v89, v89, v100
	v_max_u32_e32 v87, v87, v76
	v_max_u32_e32 v91, v91, v86
	v_max_u32_e32 v83, v83, v135
	v_max_u32_e32 v70, v70, v80
	v_max_u32_e32 v117, v117, v74
	v_max_u32_e32 v109, v109, v99
	v_max_u32_e32 v116, v116, v84
	v_max_u32_e32 v110, v110, v77
	v_max_u32_e32 v79, v79, v101
	v_max_u32_e32 v111, v111, v81
	v_max_u32_e32 v82, v82, v94
	v_max_u32_e32 v104, v104, v93
	v_max_u32_e32 v73, v73, v88
	v_max_u32_e32 v71, v96, v109
	v_min_u32_e32 v109, v96, v109
	v_max_u32_e32 v96, v118, v116
	v_min_u32_e32 v116, v118, v116
	v_max_u32_e32 v118, v89, v110
	v_min_u32_e32 v110, v89, v110
	v_max_u32_e32 v89, v87, v79
	v_min_u32_e32 v79, v87, v79
	v_max_u32_e32 v87, v91, v111
	v_min_u32_e32 v111, v91, v111
	v_max_u32_e32 v91, v83, v82
	v_min_u32_e32 v82, v83, v82
	v_max_u32_e32 v83, v70, v104
	v_min_u32_e32 v104, v70, v104
	v_max_u32_e32 v70, v117, v73
	v_min_u32_e32 v73, v117, v73
	v_max_u32_e32 v117, v71, v87
	v_min_u32_e32 v87, v71, v87
	v_max_u32_e32 v71, v96, v91
	v_min_u32_e32 v91, v96, v91
	v_max_u32_e32 v96, v118, v83
	v_min_u32_e32 v83, v118, v83
	v_max_u32_e32 v118, v89, v70
	v_min_u32_e32 v70, v89, v70
	v_max_u32_e32 v89, v109, v111
	v_min_u32_e32 v111, v109, v111
	v_max_u32_e32 v109, v116, v82
	v_min_u32_e32 v82, v116, v82
	v_max_u32_e32 v116, v110, v104
	v_min_u32_e32 v104, v110, v104
	v_max_u32_e32 v110, v79, v73
	v_min_u32_e32 v73, v79, v73
	v_max_u32_e32 v79, v117, v96
	v_min_u32_e32 v96, v117, v96
	v_max_u32_e32 v117, v71, v118
	v_min_u32_e32 v118, v71, v118
	v_max_u32_e32 v71, v87, v83
	v_min_u32_e32 v83, v87, v83
	v_max_u32_e32 v87, v91, v70
	v_min_u32_e32 v70, v91, v70
	v_max_u32_e32 v91, v89, v116
	v_min_u32_e32 v116, v89, v116
	v_max_u32_e32 v89, v109, v110
	v_min_u32_e32 v110, v109, v110
	v_max_u32_e32 v109, v111, v104
	v_min_u32_e32 v104, v111, v104
	v_max_u32_e32 v111, v82, v73
	v_min_u32_e32 v73, v82, v73
	v_max_u32_e32 v82, v79, v117
	v_min_u32_e32 v117, v79, v117
	v_max_u32_e32 v79, v96, v118
	v_min_u32_e32 v118, v96, v118
	v_max_u32_e32 v96, v71, v87
	v_min_u32_e32 v87, v71, v87
	v_max_u32_e32 v71, v83, v70
	v_min_u32_e32 v70, v83, v70
	v_max_u32_e32 v83, v91, v89
	v_min_u32_e32 v89, v91, v89
	v_max_u32_e32 v91, v116, v110
	v_min_u32_e32 v110, v116, v110
	v_max_u32_e32 v116, v109, v111
	v_min_u32_e32 v111, v109, v111
	v_max_u32_e32 v109, v104, v73
	v_min_u32_e32 v73, v104, v73
	v_add_f32_e32 v104, v119, v90
	v_ashrrev_i32_e32 v95, 31, v104
	v_and_b32_e32 v104, 0xffffff00, v104
	v_lshl_or_b32 v95, v95, 8, s33
	v_xor_b32_e32 v104, v104, v95
	v_xor_b32_e32 v104, 0xcf, v104
	v_add_f32_e32 v95, v119, v120
	v_ashrrev_i32_e32 v100, 31, v95
	v_and_b32_e32 v95, 0xffffff00, v95
	v_lshl_or_b32 v100, v100, 8, s33
	v_xor_b32_e32 v95, v95, v100
	v_xor_b32_e32 v95, 0xce, v95
	v_add_f32_e32 v100, v119, v121
	v_ashrrev_i32_e32 v76, 31, v100
	v_and_b32_e32 v100, 0xffffff00, v100
	v_lshl_or_b32 v76, v76, 8, s33
	v_xor_b32_e32 v100, v100, v76
	v_xor_b32_e32 v100, 0xcd, v100
	v_add_f32_e32 v76, v119, v122
	v_ashrrev_i32_e32 v86, 31, v76
	v_and_b32_e32 v76, 0xffffff00, v76
	v_lshl_or_b32 v86, v86, 8, s33
	v_xor_b32_e32 v76, v76, v86
	v_xor_b32_e32 v76, 0xcc, v76
	v_add_f32_e32 v86, v92, v90
	v_ashrrev_i32_e32 v135, 31, v86
	v_and_b32_e32 v86, 0xffffff00, v86
	v_lshl_or_b32 v135, v135, 8, s33
	v_xor_b32_e32 v86, v86, v135
	v_xor_b32_e32 v86, 0xaf, v86
	v_add_f32_e32 v135, v92, v120
	v_ashrrev_i32_e32 v80, 31, v135
	v_and_b32_e32 v135, 0xffffff00, v135
	v_lshl_or_b32 v80, v80, 8, s33
	v_xor_b32_e32 v135, v135, v80
	v_xor_b32_e32 v135, 0xae, v135
	v_add_f32_e32 v80, v72, v90
	v_ashrrev_i32_e32 v74, 31, v80
	v_and_b32_e32 v80, 0xffffff00, v80
	v_lshl_or_b32 v74, v74, 8, s33
	v_xor_b32_e32 v80, v80, v74
	v_xor_b32_e32 v80, 0x9f, v80
	v_add_f32_e32 v74, v72, v120
	v_ashrrev_i32_e32 v99, 31, v74
	v_and_b32_e32 v74, 0xffffff00, v74
	v_lshl_or_b32 v99, v99, 8, s33
	v_xor_b32_e32 v74, v74, v99
	v_xor_b32_e32 v74, 0x9e, v74
	v_add_f32_e32 v99, v103, v90
	v_ashrrev_i32_e32 v84, 31, v99
	v_and_b32_e32 v99, 0xffffff00, v99
	v_lshl_or_b32 v84, v84, 8, s33
	v_xor_b32_e32 v99, v99, v84
	v_xor_b32_e32 v99, 0x8f, v99
	v_add_f32_e32 v84, v103, v120
	v_ashrrev_i32_e32 v77, 31, v84
	v_and_b32_e32 v84, 0xffffff00, v84
	v_lshl_or_b32 v77, v77, 8, s33
	v_xor_b32_e32 v84, v84, v77
	v_xor_b32_e32 v84, 0x8e, v84
	v_add_f32_e32 v77, v108, v90
	v_ashrrev_i32_e32 v101, 31, v77
	v_and_b32_e32 v77, 0xffffff00, v77
	v_lshl_or_b32 v101, v101, 8, s33
; #define CE_DESC(a, b) do { const unsigned _mx = (a) > (b) ? (a) : (b), _mn = (a) > (b) ? (b) : (a); (a) = _mx; (b) = _mn; } while (0)
; #define CK(i, j) ((f2key(va[i] + vb[j]) & ~255u) | (unsigned)(255 - (16 * (i) + (j))))
; __device__ __forceinline__ void sort16_desc(unsigned (&k)[16]) {
; #pragma unroll
;     for (int size = 2; size <= 16; size <<= 1)
; #pragma unroll
;         for (int stride = size >> 1; stride > 0; stride >>= 1)
; #pragma unroll
;             for (int i = 0; i < 16; ++i) { const int j = i ^ stride;
;                 if (j > i) { if ((i & size) == 0) CE_DESC(k[i], k[j]); else CE_DESC(k[j], k[i]); } }
; }
; __device__ __forceinline__ void merge16(unsigned (&a)[16], const unsigned (&b)[16]) {
; #pragma unroll
;     for (int i = 0; i < 16; ++i) a[i] = a[i] > b[15 - i] ? a[i] : b[15 - i];
; #pragma unroll
;     for (int stride = 8; stride > 0; stride >>= 1)
; #pragma unroll
;         for (int i = 0; i < 16; ++i) { const int j = i ^ stride; if (j > i) CE_DESC(a[i], a[j]); }
; }
; __device__ __forceinline__ void peer_tile(const Args& A, LAS unsigned char* lds, int tile) {
;     ...
;             for (int j = 0; j < 4; ++j) Bt[j] = CK(3, j);
;             Bt[4] = CK(5, 0); Bt[5] = CK(5, 1); Bt[6] = CK(6, 0); Bt[7] = CK(6, 1); Bt[8] = CK(7, 0); Bt[9] = CK(7, 1);
;             Bt[10] = CK(8, 0); Bt[11] = CK(9, 0); Bt[12] = CK(10, 0); Bt[13] = CK(11, 0); Bt[14] = CK(12, 0); Bt[15] = CK(13, 0);
;             sort16_desc(Bt); merge16(Lf, Bt);
;             { unsigned x0 = CK(14, 0), x1 = CK(15, 0);
; #pragma unroll
;               for (int i = 0; i < 16; ++i) CE_DESC(Lf[i], x0);
; #pragma unroll
;               for (int i = 0; i < 16; ++i) CE_DESC(Lf[i], x1); }
	v_xor_b32_e32 v77, v77, v101
	v_xor_b32_e32 v77, 0x7f, v77
	v_add_f32_e32 v101, v106, v90
	v_ashrrev_i32_e32 v81, 31, v101
	v_and_b32_e32 v101, 0xffffff00, v101
	v_lshl_or_b32 v81, v81, 8, s33
	v_xor_b32_e32 v101, v101, v81
	v_xor_b32_e32 v101, 0x6f, v101
	v_add_f32_e32 v81, v107, v90
	v_ashrrev_i32_e32 v94, 31, v81
	v_and_b32_e32 v81, 0xffffff00, v81
	v_lshl_or_b32 v94, v94, 8, s33
	v_xor_b32_e32 v81, v81, v94
	v_xor_b32_e32 v81, 0x5f, v81
	v_add_f32_e32 v94, v98, v90
	v_ashrrev_i32_e32 v93, 31, v94
	v_and_b32_e32 v94, 0xffffff00, v94
	v_lshl_or_b32 v93, v93, 8, s33
	v_xor_b32_e32 v94, v94, v93
	v_xor_b32_e32 v94, 0x4f, v94
	v_add_f32_e32 v93, v78, v90
	v_ashrrev_i32_e32 v88, 31, v93
	v_and_b32_e32 v93, 0xffffff00, v93
	v_lshl_or_b32 v88, v88, 8, s33
	v_xor_b32_e32 v93, v93, v88
	v_xor_b32_e32 v93, 63, v93
	v_add_f32_e32 v88, v115, v90
	v_ashrrev_i32_e32 v85, 31, v88
	v_and_b32_e32 v88, 0xffffff00, v88
	v_lshl_or_b32 v85, v85, 8, s33
	v_xor_b32_e32 v88, v88, v85
	v_xor_b32_e32 v88, 47, v88
	v_max_u32_e32 v85, v104, v94
	v_min_u32_e32 v94, v104, v94
	v_max_u32_e32 v104, v95, v81
	v_min_u32_e32 v81, v95, v81
	v_max_u32_e32 v95, v100, v88
	v_min_u32_e32 v88, v100, v88
	v_max_u32_e32 v100, v76, v93
	v_min_u32_e32 v93, v76, v93
	v_max_u32_e32 v76, v86, v99
	v_min_u32_e32 v99, v86, v99
	v_max_u32_e32 v86, v135, v80
	v_min_u32_e32 v80, v135, v80
	v_max_u32_e32 v135, v74, v101
	v_min_u32_e32 v101, v74, v101
	v_max_u32_e32 v74, v84, v77
	v_min_u32_e32 v77, v84, v77
	v_max_u32_e32 v84, v85, v86
	v_min_u32_e32 v86, v85, v86
	v_max_u32_e32 v85, v104, v135
	v_min_u32_e32 v135, v104, v135
	v_max_u32_e32 v104, v95, v74
	v_min_u32_e32 v74, v95, v74
	v_max_u32_e32 v95, v100, v76
	v_min_u32_e32 v76, v100, v76
	v_max_u32_e32 v100, v80, v94
	v_min_u32_e32 v94, v80, v94
	v_max_u32_e32 v80, v99, v93
	v_min_u32_e32 v93, v99, v93
	v_max_u32_e32 v99, v77, v88
	v_min_u32_e32 v88, v77, v88
	v_max_u32_e32 v77, v101, v81
	v_min_u32_e32 v81, v101, v81
	v_max_u32_e32 v101, v84, v85
	v_min_u32_e32 v85, v84, v85
	v_max_u32_e32 v84, v104, v95
	v_min_u32_e32 v95, v104, v95
	v_max_u32_e32 v104, v76, v86
	v_min_u32_e32 v86, v76, v86
	v_max_u32_e32 v76, v100, v80
	v_min_u32_e32 v80, v100, v80
	v_max_u32_e32 v100, v135, v74
	v_min_u32_e32 v74, v135, v74
	v_max_u32_e32 v135, v99, v77
	v_min_u32_e32 v77, v99, v77
	v_max_u32_e32 v99, v81, v94
	v_min_u32_e32 v94, v81, v94
	v_max_u32_e32 v81, v93, v88
	v_min_u32_e32 v88, v93, v88
	v_max_u32_e32 v93, v101, v84
	v_min_u32_e32 v84, v101, v84
	v_max_u32_e32 v101, v85, v95
	v_min_u32_e32 v95, v85, v95
	v_max_u32_e32 v85, v104, v135
	v_min_u32_e32 v135, v104, v135
	v_max_u32_e32 v104, v86, v77
	v_min_u32_e32 v77, v86, v77
	v_max_u32_e32 v86, v76, v100
	v_min_u32_e32 v100, v76, v100
	v_max_u32_e32 v76, v80, v74
	v_min_u32_e32 v74, v80, v74
	v_max_u32_e32 v80, v99, v81
	v_min_u32_e32 v81, v99, v81
	v_max_u32_e32 v99, v94, v88
	v_min_u32_e32 v88, v94, v88
	v_max_u32_e32 v94, v101, v84
	v_min_u32_e32 v84, v101, v84
	v_max_u32_e32 v101, v95, v80
	v_min_u32_e32 v80, v95, v80
	v_max_u32_e32 v95, v85, v86
	v_min_u32_e32 v86, v85, v86
	v_max_u32_e32 v85, v104, v100
	v_min_u32_e32 v100, v104, v100
	v_max_u32_e32 v104, v76, v135
	v_min_u32_e32 v135, v76, v135
	v_max_u32_e32 v76, v74, v77
	v_min_u32_e32 v77, v74, v77
	v_max_u32_e32 v74, v99, v81
	v_min_u32_e32 v81, v99, v81
	v_max_u32_e32 v99, v94, v95
	v_min_u32_e32 v95, v94, v95
	v_max_u32_e32 v94, v84, v86
	v_min_u32_e32 v86, v84, v86
	v_max_u32_e32 v84, v85, v104
	v_min_u32_e32 v104, v85, v104
	v_max_u32_e32 v85, v100, v135
	v_min_u32_e32 v135, v100, v135
	v_max_u32_e32 v100, v76, v74
	v_min_u32_e32 v74, v76, v74
	v_max_u32_e32 v76, v77, v81
	v_min_u32_e32 v81, v77, v81
	v_max_u32_e32 v77, v94, v95
	v_min_u32_e32 v95, v94, v95
	v_max_u32_e32 v94, v101, v86
	v_min_u32_e32 v86, v101, v86
	v_max_u32_e32 v101, v100, v80
	v_min_u32_e32 v80, v100, v80
	v_max_u32_e32 v100, v76, v74
	v_min_u32_e32 v74, v76, v74
	v_max_u32_e32 v76, v94, v84
	v_min_u32_e32 v84, v94, v84
	v_max_u32_e32 v94, v86, v104
	v_min_u32_e32 v104, v86, v104
	v_max_u32_e32 v86, v85, v101
	v_min_u32_e32 v101, v85, v101
	v_max_u32_e32 v85, v135, v80
	v_min_u32_e32 v80, v135, v80
	v_max_u32_e32 v135, v76, v95
	v_min_u32_e32 v95, v76, v95
	v_max_u32_e32 v76, v84, v94
	v_min_u32_e32 v94, v84, v94
	v_max_u32_e32 v84, v86, v104
	v_min_u32_e32 v104, v86, v104
	v_max_u32_e32 v86, v101, v85
	v_min_u32_e32 v85, v101, v85
	v_max_u32_e32 v101, v100, v80
	v_min_u32_e32 v80, v100, v80
	v_max_u32_e32 v100, v94, v84
	v_min_u32_e32 v84, v94, v84
	v_max_u32_e32 v94, v104, v86
	v_min_u32_e32 v86, v104, v86
	v_max_u32_e32 v82, v82, v88
	v_max_u32_e32 v117, v117, v81
	v_max_u32_e32 v79, v79, v74
	v_max_u32_e32 v118, v118, v80
	v_max_u32_e32 v96, v96, v101
	v_max_u32_e32 v87, v87, v85
	v_max_u32_e32 v71, v71, v86
	v_max_u32_e32 v70, v70, v94
	v_max_u32_e32 v83, v83, v84
	v_max_u32_e32 v89, v89, v100
	v_max_u32_e32 v91, v91, v76
	v_max_u32_e32 v110, v110, v95
	v_max_u32_e32 v116, v116, v135
	v_max_u32_e32 v111, v111, v77
	v_max_u32_e32 v109, v109, v99
	v_max_u32_e32 v73, v73, v93
	v_max_u32_e32 v88, v82, v83
	v_min_u32_e32 v83, v82, v83
	v_max_u32_e32 v82, v117, v89
	v_min_u32_e32 v89, v117, v89
	v_max_u32_e32 v117, v79, v91
	v_min_u32_e32 v91, v79, v91
	v_max_u32_e32 v79, v118, v110
	v_min_u32_e32 v110, v118, v110
	v_max_u32_e32 v118, v96, v116
	v_min_u32_e32 v116, v96, v116
	v_max_u32_e32 v96, v87, v111
	v_min_u32_e32 v111, v87, v111
	v_max_u32_e32 v87, v71, v109
	v_min_u32_e32 v109, v71, v109
	v_max_u32_e32 v71, v70, v73
	v_min_u32_e32 v73, v70, v73
	v_max_u32_e32 v70, v88, v118
	v_min_u32_e32 v118, v88, v118
	v_max_u32_e32 v88, v82, v96
; __device__ __forceinline__ float key2f(unsigned k) { const unsigned u = (k & 0x80000000u) ? (k & 0x7fffffffu) : ~k; return __uint_as_float(u); }
; #define CE_DESC(a, b) do { const unsigned _mx = (a) > (b) ? (a) : (b), _mn = (a) > (b) ? (b) : (a); (a) = _mx; (b) = _mn; } while (0)
; #define CK(i, j) ((f2key(va[i] + vb[j]) & ~255u) | (unsigned)(255 - (16 * (i) + (j))))
; __device__ __forceinline__ void peer_tile(const Args& A, LAS unsigned char* lds, int tile) {
;     ...
;             { unsigned x0 = CK(14, 0), x1 = CK(15, 0);
; #pragma unroll
;               for (int i = 0; i < 16; ++i) CE_DESC(Lf[i], x0);
; #pragma unroll
;               for (int i = 0; i < 16; ++i) CE_DESC(Lf[i], x1); }
;     ...
;             float fv[16], den = 0.f; const float f0 = key2f(Lf[0] & ~255u);
; #pragma unroll
;             for (int k = 0; k < 16; ++k) { fv[k] = __expf(key2f(Lf[k] & ~255u) - f0); den += fv[k]; }
	v_min_u32_e32 v96, v82, v96
	v_max_u32_e32 v82, v117, v87
	v_min_u32_e32 v87, v117, v87
	v_max_u32_e32 v117, v79, v71
	v_min_u32_e32 v71, v79, v71
	v_max_u32_e32 v79, v83, v116
	v_min_u32_e32 v116, v83, v116
	v_max_u32_e32 v83, v89, v111
	v_min_u32_e32 v111, v89, v111
	v_max_u32_e32 v89, v91, v109
	v_min_u32_e32 v109, v91, v109
	v_max_u32_e32 v91, v110, v73
	v_min_u32_e32 v73, v110, v73
	v_max_u32_e32 v110, v70, v82
	v_min_u32_e32 v82, v70, v82
	v_max_u32_e32 v70, v88, v117
	v_min_u32_e32 v117, v88, v117
	v_max_u32_e32 v88, v118, v87
	v_min_u32_e32 v87, v118, v87
	v_max_u32_e32 v118, v96, v71
	v_min_u32_e32 v71, v96, v71
	v_max_u32_e32 v96, v79, v89
	v_min_u32_e32 v89, v79, v89
	v_max_u32_e32 v79, v83, v91
	v_min_u32_e32 v91, v83, v91
	v_max_u32_e32 v83, v116, v109
	v_min_u32_e32 v109, v116, v109
	v_max_u32_e32 v116, v111, v73
	v_min_u32_e32 v73, v111, v73
	v_max_u32_e32 v111, v110, v70
	v_min_u32_e32 v70, v110, v70
	v_max_u32_e32 v110, v82, v117
	v_min_u32_e32 v117, v82, v117
	v_max_u32_e32 v82, v88, v118
	v_min_u32_e32 v118, v88, v118
	v_max_u32_e32 v88, v87, v71
	v_min_u32_e32 v71, v87, v71
	v_max_u32_e32 v87, v96, v79
	v_min_u32_e32 v79, v96, v79
	v_max_u32_e32 v96, v89, v91
	v_min_u32_e32 v91, v89, v91
	v_max_u32_e32 v89, v83, v116
	v_min_u32_e32 v116, v83, v116
	v_max_u32_e32 v83, v109, v73
	v_min_u32_e32 v73, v109, v73
	v_add_f32_e32 v109, v105, v90
	v_ashrrev_i32_e32 v81, 31, v109
	v_and_b32_e32 v109, 0xffffff00, v109
	v_lshl_or_b32 v81, v81, 8, s33
	v_xor_b32_e32 v109, v109, v81
	v_xor_b32_e32 v109, 31, v109
	v_max_u32_e32 v81, v111, v109
	v_min_u32_e32 v109, v111, v109
	v_max_u32_e32 v111, v70, v109
	v_min_u32_e32 v109, v70, v109
	v_max_u32_e32 v70, v110, v109
	v_min_u32_e32 v109, v110, v109
	v_max_u32_e32 v110, v117, v109
	v_min_u32_e32 v109, v117, v109
	v_max_u32_e32 v117, v82, v109
	v_min_u32_e32 v109, v82, v109
	v_max_u32_e32 v82, v118, v109
	v_min_u32_e32 v109, v118, v109
	v_max_u32_e32 v118, v88, v109
	v_min_u32_e32 v109, v88, v109
	v_max_u32_e32 v88, v71, v109
	v_min_u32_e32 v109, v71, v109
	v_max_u32_e32 v71, v87, v109
	v_min_u32_e32 v109, v87, v109
	v_max_u32_e32 v87, v79, v109
	v_min_u32_e32 v109, v79, v109
	v_max_u32_e32 v79, v96, v109
	v_min_u32_e32 v109, v96, v109
	v_max_u32_e32 v96, v91, v109
	v_min_u32_e32 v109, v91, v109
	v_max_u32_e32 v91, v89, v109
	v_min_u32_e32 v109, v89, v109
	v_max_u32_e32 v89, v116, v109
	v_min_u32_e32 v109, v116, v109
	v_max_u32_e32 v116, v83, v109
	v_min_u32_e32 v109, v83, v109
	v_max_u32_e32 v83, v73, v109
	v_min_u32_e32 v109, v73, v109
	v_add_f32_e32 v109, v112, v90
	v_ashrrev_i32_e32 v73, 31, v109
	v_and_b32_e32 v109, 0xffffff00, v109
	v_lshl_or_b32 v73, v73, 8, s33
	v_xor_b32_e32 v109, v109, v73
	v_xor_b32_e32 v109, 15, v109
	v_max_u32_e32 v73, v81, v109
	v_min_u32_e32 v109, v81, v109
	v_max_u32_e32 v81, v111, v109
	v_min_u32_e32 v109, v111, v109
	v_max_u32_e32 v111, v70, v109
	v_min_u32_e32 v109, v70, v109
	v_max_u32_e32 v70, v110, v109
	v_min_u32_e32 v109, v110, v109
	v_max_u32_e32 v110, v117, v109
	v_min_u32_e32 v109, v117, v109
	v_max_u32_e32 v117, v82, v109
	v_min_u32_e32 v109, v82, v109
	v_max_u32_e32 v82, v118, v109
	v_min_u32_e32 v109, v118, v109
	v_max_u32_e32 v118, v88, v109
	v_min_u32_e32 v109, v88, v109
	v_max_u32_e32 v88, v71, v109
	v_min_u32_e32 v109, v71, v109
	v_max_u32_e32 v71, v87, v109
	v_min_u32_e32 v109, v87, v109
	v_max_u32_e32 v87, v79, v109
	v_min_u32_e32 v109, v79, v109
	v_max_u32_e32 v79, v96, v109
	v_min_u32_e32 v109, v96, v109
	v_max_u32_e32 v96, v91, v109
	v_min_u32_e32 v109, v91, v109
	v_max_u32_e32 v91, v89, v109
	v_min_u32_e32 v109, v89, v109
	v_max_u32_e32 v89, v116, v109
	v_min_u32_e32 v109, v116, v109
	v_max_u32_e32 v116, v83, v109
	v_min_u32_e32 v109, v83, v109
	v_ashrrev_i32_e32 v133, 31, v73
	v_and_b32_e32 v134, 0xffffff00, v73
	v_bitop3_b32 v134, v134, v133, s41 bitop3:0x87
	v_ashrrev_i32_e32 v131, 31, v73
	v_and_b32_e32 v132, 0xffffff00, v73
	v_bitop3_b32 v132, v132, v131, s41 bitop3:0x87
	v_sub_f32_e32 v132, v132, v134
	v_mul_f32_e32 v132, 0x3fb8aa3b, v132
	v_exp_f32_e32 v132, v132
	v_ashrrev_i32_e32 v130, 31, v81
	v_and_b32_e32 v131, 0xffffff00, v81
	v_bitop3_b32 v131, v131, v130, s41 bitop3:0x87
	v_sub_f32_e32 v131, v131, v134
	v_mul_f32_e32 v131, 0x3fb8aa3b, v131
	v_exp_f32_e32 v131, v131
	v_ashrrev_i32_e32 v129, 31, v111
	v_and_b32_e32 v130, 0xffffff00, v111
	v_bitop3_b32 v130, v130, v129, s41 bitop3:0x87
	v_sub_f32_e32 v130, v130, v134
	v_mul_f32_e32 v130, 0x3fb8aa3b, v130
	v_exp_f32_e32 v130, v130
	v_ashrrev_i32_e32 v128, 31, v70
	v_and_b32_e32 v129, 0xffffff00, v70
	v_bitop3_b32 v129, v129, v128, s41 bitop3:0x87
	v_sub_f32_e32 v129, v129, v134
	v_mul_f32_e32 v129, 0x3fb8aa3b, v129
	v_exp_f32_e32 v129, v129
	v_ashrrev_i32_e32 v127, 31, v110
	v_and_b32_e32 v128, 0xffffff00, v110
	v_bitop3_b32 v128, v128, v127, s41 bitop3:0x87
	v_sub_f32_e32 v128, v128, v134
	v_mul_f32_e32 v128, 0x3fb8aa3b, v128
	v_exp_f32_e32 v128, v128
	v_ashrrev_i32_e32 v126, 31, v117
	v_and_b32_e32 v127, 0xffffff00, v117
	v_bitop3_b32 v127, v127, v126, s41 bitop3:0x87
	v_sub_f32_e32 v127, v127, v134
	v_mul_f32_e32 v127, 0x3fb8aa3b, v127
	v_exp_f32_e32 v127, v127
	v_ashrrev_i32_e32 v125, 31, v82
	v_and_b32_e32 v126, 0xffffff00, v82
	v_bitop3_b32 v126, v126, v125, s41 bitop3:0x87
	v_sub_f32_e32 v126, v126, v134
	v_mul_f32_e32 v126, 0x3fb8aa3b, v126
	v_exp_f32_e32 v126, v126
	v_ashrrev_i32_e32 v124, 31, v118
	v_and_b32_e32 v125, 0xffffff00, v118
	v_bitop3_b32 v125, v125, v124, s41 bitop3:0x87
	v_sub_f32_e32 v125, v125, v134
	v_mul_f32_e32 v125, 0x3fb8aa3b, v125
	v_exp_f32_e32 v125, v125
	v_ashrrev_i32_e32 v123, 31, v88
	v_and_b32_e32 v124, 0xffffff00, v88
; __device__ __forceinline__ float key2f(unsigned k) { const unsigned u = (k & 0x80000000u) ? (k & 0x7fffffffu) : ~k; return __uint_as_float(u); }
; __device__ __forceinline__ void peer_tile(const Args& A, LAS unsigned char* lds, int tile) {
;     ...
;             float fv[16], den = 0.f; const float f0 = key2f(Lf[0] & ~255u);
; #pragma unroll
;             for (int k = 0; k < 16; ++k) { fv[k] = __expf(key2f(Lf[k] & ~255u) - f0); den += fv[k]; }
;             const float rden = 1.f / den;
	v_bitop3_b32 v124, v124, v123, s41 bitop3:0x87
	v_sub_f32_e32 v124, v124, v134
	v_mul_f32_e32 v124, 0x3fb8aa3b, v124
	v_exp_f32_e32 v124, v124
	v_ashrrev_i32_e32 v122, 31, v71
	v_and_b32_e32 v123, 0xffffff00, v71
	v_bitop3_b32 v123, v123, v122, s41 bitop3:0x87
	v_sub_f32_e32 v123, v123, v134
	v_mul_f32_e32 v123, 0x3fb8aa3b, v123
	v_exp_f32_e32 v123, v123
	v_ashrrev_i32_e32 v121, 31, v87
	v_and_b32_e32 v122, 0xffffff00, v87
	v_bitop3_b32 v122, v122, v121, s41 bitop3:0x87
	v_sub_f32_e32 v122, v122, v134
	v_mul_f32_e32 v122, 0x3fb8aa3b, v122
	v_exp_f32_e32 v122, v122
	v_ashrrev_i32_e32 v120, 31, v79
	v_and_b32_e32 v121, 0xffffff00, v79
	v_bitop3_b32 v121, v121, v120, s41 bitop3:0x87
	v_sub_f32_e32 v121, v121, v134
	v_mul_f32_e32 v121, 0x3fb8aa3b, v121
	v_exp_f32_e32 v121, v121
	v_ashrrev_i32_e32 v90, 31, v96
	v_and_b32_e32 v120, 0xffffff00, v96
	v_bitop3_b32 v120, v120, v90, s41 bitop3:0x87
	v_sub_f32_e32 v120, v120, v134
	v_mul_f32_e32 v120, 0x3fb8aa3b, v120
	v_exp_f32_e32 v120, v120
	v_ashrrev_i32_e32 v112, 31, v91
	v_and_b32_e32 v90, 0xffffff00, v91
	v_bitop3_b32 v90, v90, v112, s41 bitop3:0x87
	v_sub_f32_e32 v90, v90, v134
	v_mul_f32_e32 v90, 0x3fb8aa3b, v90
	v_exp_f32_e32 v90, v90
	v_ashrrev_i32_e32 v105, 31, v89
	v_and_b32_e32 v112, 0xffffff00, v89
	v_bitop3_b32 v112, v112, v105, s41 bitop3:0x87
	v_sub_f32_e32 v112, v112, v134
	v_mul_f32_e32 v112, 0x3fb8aa3b, v112
	v_exp_f32_e32 v112, v112
	v_ashrrev_i32_e32 v115, 31, v116
	v_and_b32_e32 v105, 0xffffff00, v116
	v_bitop3_b32 v105, v105, v115, s41 bitop3:0x87
	v_sub_f32_e32 v105, v105, v134
	v_mul_f32_e32 v105, 0x3fb8aa3b, v105
	v_exp_f32_e32 v105, v105
	v_add_f32_e32 v133, 0, v132
	v_add_f32_e32 v133, v133, v131
	v_add_f32_e32 v133, v133, v130
	v_add_f32_e32 v133, v133, v129
	v_add_f32_e32 v133, v133, v128
	v_add_f32_e32 v133, v133, v127
	v_add_f32_e32 v133, v133, v126
	v_add_f32_e32 v133, v133, v125
	v_add_f32_e32 v133, v133, v124
	v_add_f32_e32 v133, v133, v123
	v_add_f32_e32 v133, v133, v122
	v_add_f32_e32 v133, v133, v121
	v_add_f32_e32 v133, v133, v120
	v_add_f32_e32 v133, v133, v90
	v_add_f32_e32 v133, v133, v112
	v_add_f32_e32 v133, v133, v105
	v_div_scale_f32 v115, s[0:1], v133, v133, 1.0
	v_rcp_f32_e32 v78, v115
	s_nop 0
	v_fma_f32 v98, -v115, v78, 1.0
	v_fmac_f32_e32 v78, v98, v78
	v_div_scale_f32 v98, vcc, 1.0, v133, 1.0
	v_mul_f32_e32 v107, v98, v78
	v_fma_f32 v106, -v115, v107, v98
	v_fmac_f32_e32 v107, v106, v78
	v_fma_f32 v115, -v115, v107, v98
	s_nop 1
	v_div_fmas_f32 v115, v115, v78, v107
	v_div_fixup_f32 v115, v115, v133, 1.0
	s_waitcnt lgkmcnt(0)
; #define LDS_WAIT() asm volatile("s_waitcnt lgkmcnt(0)" ::: "memory")
; __device__ __forceinline__ void peer_tile(const Args& A, LAS unsigned char* lds, int tile) {
;     ...
;             LDS_WAIT();
; #pragma unroll
;             for (int k = 0; k < 16; ++k) { const unsigned code = 255u - (Lf[k] & 255u); const unsigned e = idx[code >> 4] * 128u + idx[16 + (code & 15u)];
;                 u32x2 sv; sv.x = e; sv.y = __float_as_uint(fv[k] * rden); SEL[(tl * 8 + h) * 16 + k] = sv; }
	v_xor_b32_e32 v106, 0xff, v73
	v_bfe_u32 v107, v106, 4, 4
	v_and_b32_e32 v106, 15, v106
	v_lshl_add_u32 v107, v107, 2, v67
	v_lshl_add_u32 v106, v106, 2, v67
	ds_read_b32 v107, v107
	ds_read_b32 v106, v106 offset:64
	v_xor_b32_e32 v98, 0xff, v81
	v_bfe_u32 v78, v98, 4, 4
	v_and_b32_e32 v98, 15, v98
	v_lshl_add_u32 v78, v78, 2, v67
	v_lshl_add_u32 v98, v98, 2, v67
	ds_read_b32 v78, v78
	ds_read_b32 v98, v98 offset:64
	v_xor_b32_e32 v108, 0xff, v111
	v_bfe_u32 v103, v108, 4, 4
	v_and_b32_e32 v108, 15, v108
	v_lshl_add_u32 v103, v103, 2, v67
	v_lshl_add_u32 v108, v108, 2, v67
	ds_read_b32 v103, v103
	ds_read_b32 v108, v108 offset:64
	v_xor_b32_e32 v72, 0xff, v70
	v_bfe_u32 v92, v72, 4, 4
	v_and_b32_e32 v72, 15, v72
	v_lshl_add_u32 v92, v92, 2, v67
	v_lshl_add_u32 v72, v72, 2, v67
	ds_read_b32 v92, v92
	ds_read_b32 v72, v72 offset:64
	v_xor_b32_e32 v75, 0xff, v110
	v_bfe_u32 v119, v75, 4, 4
	v_and_b32_e32 v75, 15, v75
	v_lshl_add_u32 v119, v119, 2, v67
	v_lshl_add_u32 v75, v75, 2, v67
	ds_read_b32 v119, v119
	ds_read_b32 v75, v75 offset:64
	v_xor_b32_e32 v114, 0xff, v117
	v_bfe_u32 v102, v114, 4, 4
	v_and_b32_e32 v114, 15, v114
	v_lshl_add_u32 v102, v102, 2, v67
	v_lshl_add_u32 v114, v114, 2, v67
	ds_read_b32 v102, v102
	ds_read_b32 v114, v114 offset:64
	v_xor_b32_e32 v97, 0xff, v82
	v_bfe_u32 v109, v97, 4, 4
	v_and_b32_e32 v97, 15, v97
	v_lshl_add_u32 v109, v109, 2, v67
	v_lshl_add_u32 v97, v97, 2, v67
	ds_read_b32 v109, v109
	ds_read_b32 v97, v97 offset:64
	v_xor_b32_e32 v83, 0xff, v118
	v_bfe_u32 v74, v83, 4, 4
	v_and_b32_e32 v83, 15, v83
	v_lshl_add_u32 v74, v74, 2, v67
	v_lshl_add_u32 v83, v83, 2, v67
	ds_read_b32 v74, v74
	ds_read_b32 v83, v83 offset:64
	v_xor_b32_e32 v80, 0xff, v88
	v_bfe_u32 v101, v80, 4, 4
	v_and_b32_e32 v80, 15, v80
	v_lshl_add_u32 v101, v101, 2, v67
	v_lshl_add_u32 v80, v80, 2, v67
	ds_read_b32 v101, v101
	ds_read_b32 v80, v80 offset:64
	v_xor_b32_e32 v85, 0xff, v71
	v_bfe_u32 v86, v85, 4, 4
	v_and_b32_e32 v85, 15, v85
	v_lshl_add_u32 v86, v86, 2, v67
	v_lshl_add_u32 v85, v85, 2, v67
	ds_read_b32 v86, v86
	ds_read_b32 v85, v85 offset:64
	v_xor_b32_e32 v94, 0xff, v87
	v_bfe_u32 v84, v94, 4, 4
	v_and_b32_e32 v94, 15, v94
	v_lshl_add_u32 v84, v84, 2, v67
	v_lshl_add_u32 v94, v94, 2, v67
	ds_read_b32 v84, v84
	ds_read_b32 v94, v94 offset:64
	v_xor_b32_e32 v100, 0xff, v79
	v_bfe_u32 v76, v100, 4, 4
	v_and_b32_e32 v100, 15, v100
	v_lshl_add_u32 v76, v76, 2, v67
	v_lshl_add_u32 v100, v100, 2, v67
	ds_read_b32 v76, v76
	ds_read_b32 v100, v100 offset:64
	v_xor_b32_e32 v95, 0xff, v96
	v_bfe_u32 v135, v95, 4, 4
	v_and_b32_e32 v95, 15, v95
	v_lshl_add_u32 v135, v135, 2, v67
	v_lshl_add_u32 v95, v95, 2, v67
	ds_read_b32 v135, v135
	ds_read_b32 v95, v95 offset:64
	v_xor_b32_e32 v77, 0xff, v91
	v_bfe_u32 v99, v77, 4, 4
	v_and_b32_e32 v77, 15, v77
	v_lshl_add_u32 v99, v99, 2, v67
	v_lshl_add_u32 v77, v77, 2, v67
	ds_read_b32 v99, v99
	ds_read_b32 v77, v77 offset:64
	v_xor_b32_e32 v93, 0xff, v89
	v_bfe_u32 v104, v93, 4, 4
	v_and_b32_e32 v93, 15, v93
	v_lshl_add_u32 v104, v104, 2, v67
	v_lshl_add_u32 v93, v93, 2, v67
	ds_read_b32 v104, v104
	ds_read_b32 v93, v93 offset:64
	v_xor_b32_e32 v136, 0xff, v116
	v_bfe_u32 v137, v136, 4, 4
	v_and_b32_e32 v136, 15, v136
	v_lshl_add_u32 v137, v137, 2, v67
	v_lshl_add_u32 v136, v136, 2, v67
	ds_read_b32 v137, v137
	ds_read_b32 v136, v136 offset:64
	s_waitcnt lgkmcnt(0)
	v_lshl_add_u32 v138, v107, 7, v106
	v_mul_f32_e32 v139, v132, v115
	v_lshl_add_u32 v140, v78, 7, v98
	v_mul_f32_e32 v141, v131, v115
	ds_write_b128 v68, v[138:141] offset:0
	v_lshl_add_u32 v138, v103, 7, v108
	v_mul_f32_e32 v139, v130, v115
	v_lshl_add_u32 v140, v92, 7, v72
	v_mul_f32_e32 v141, v129, v115
	ds_write_b128 v68, v[138:141] offset:16
	v_lshl_add_u32 v138, v119, 7, v75
	v_mul_f32_e32 v139, v128, v115
	v_lshl_add_u32 v140, v102, 7, v114
	v_mul_f32_e32 v141, v127, v115
	ds_write_b128 v68, v[138:141] offset:32
	v_lshl_add_u32 v138, v109, 7, v97
	v_mul_f32_e32 v139, v126, v115
	v_lshl_add_u32 v140, v74, 7, v83
	v_mul_f32_e32 v141, v125, v115
	ds_write_b128 v68, v[138:141] offset:48
	v_lshl_add_u32 v138, v101, 7, v80
	v_mul_f32_e32 v139, v124, v115
	v_lshl_add_u32 v140, v86, 7, v85
	v_mul_f32_e32 v141, v123, v115
	ds_write_b128 v68, v[138:141] offset:64
	v_lshl_add_u32 v138, v84, 7, v94
	v_mul_f32_e32 v139, v122, v115
	v_lshl_add_u32 v140, v76, 7, v100
	v_mul_f32_e32 v141, v121, v115
	ds_write_b128 v68, v[138:141] offset:80
	v_lshl_add_u32 v138, v135, 7, v95
	v_mul_f32_e32 v139, v120, v115
	v_lshl_add_u32 v140, v99, 7, v77
	v_mul_f32_e32 v141, v90, v115
	ds_write_b128 v68, v[138:141] offset:96
	v_lshl_add_u32 v138, v104, 7, v93
	v_mul_f32_e32 v139, v112, v115
	v_lshl_add_u32 v140, v137, 7, v136
	v_mul_f32_e32 v141, v105, v115
	ds_write_b128 v68, v[138:141] offset:112

; __device__ __forceinline__ unsigned pk2(float lo, float hi) { const f32x2 v = {lo, hi}; const bf16x2_t b = __builtin_convertvector(v, bf16x2_t); return __builtin_bit_cast(unsigned, b); }
; __device__ __forceinline__ float bflo(unsigned u) { return __uint_as_float(u << 16); }
; __device__ __forceinline__ float bfhi(unsigned u) { return __uint_as_float(u & 0xffff0000u); }
; __device__ __forceinline__ void peer_tile(const Args& A, LAS unsigned char* lds, int tile) {
;     ...
;         const int tb = 8 * w + 4 * pass;
;         u32x4 xpa[4], xpb[4]; f32x2 oacc[4][8];
; #pragma unroll
;         for (int tk = 0; tk < 4; ++tk) { const size_t m = (size_t)tile * 64 + tb + tk;
;             { const u32x4 ra = *(const u32x4*)(A3 + m * 1024 + 16 * lane), rb = *(const u32x4*)(A3 + m * 1024 + 16 * lane + 8);
;               float xr_; { const f32x4 p0 = *(const f32x4*)(RSq + m * 16), p1 = *(const f32x4*)(RSq + m * 16 + 4), p2 = *(const f32x4*)(RSq + m * 16 + 8), p3 = *(const f32x4*)(RSq + m * 16 + 12);
;                 const f32x4 ps = (p0 + p1) + (p2 + p3); xr_ = rsqrtf(((ps[0] + ps[1]) + (ps[2] + ps[3])) * (1.f / 1024.f) + 1e-6f); }
;               const unsigned rr[8] = {ra.x, ra.y, ra.z, ra.w, rb.x, rb.y, rb.z, rb.w}; unsigned hh[8];
;               const float* sp = MOD + (int)(m >> 11) * 6144 + 3072 + 16 * lane;
; #pragma unroll
;               for (int q = 0; q < 8; ++q) { const f32x2 sh = *(const f32x2*)(sp + 2 * q); hh[q] = pk2(bflo(rr[q]) * xr_ + sh[0], bfhi(rr[q]) * xr_ + sh[1]); }
;               xpa[tk] = (u32x4){hh[0], hh[1], hh[2], hh[3]}; xpb[tk] = (u32x4){hh[4], hh[5], hh[6], hh[7]}; }
; #pragma unroll
;             for (int q = 0; q < 8; ++q) oacc[tk][q] = (f32x2){0.f, 0.f}; }
	s_mov_b64 exec, -1
	v_and_b32_e32 v240, 63, v214
	v_lshrrev_b32_e32 v242, 6, v214
	v_lshlrev_b32_e32 v240, 4, v240
	v_readfirstlane_b32 s16, v242
	v_lshlrev_b32_e32 v245, 1, v240
	v_lshlrev_b32_e32 v246, 2, v240
	v_lshrrev_b32_e32 v247, 4, v240
	v_and_b32_e32 v247, 48, v247
	v_mov_b32_e32 v244, 0
	v_mov_b32_e32 v243, 0x358637bd
	v_mov_b32_e32 v242, 0xbf3a00e3
	s_add_u32 s4, s50, 0x1000000
	s_addc_u32 s5, s51, 0
	s_add_u32 s6, s50, 0x2000000
	s_addc_u32 s7, s51, 0
	s_add_u32 s8, s50, 0x3000000
	s_addc_u32 s9, s51, 0
	s_add_u32 s52, s50, 0x3010000
	s_addc_u32 s53, s51, 0
	s_add_u32 s12, s50, 0xb000000
	s_addc_u32 s13, s51, 0
	s_add_u32 s14, s50, 0xd000000
	s_addc_u32 s15, s51, 0
	s_lshr_b32 s0, s2, 5
	s_mul_i32 s0, s0, 0x6000
	s_add_u32 s10, s50, s0
	s_addc_u32 s11, s51, 0
	s_add_u32 s80, s10, 0x4000
	s_addc_u32 s81, s11, 0
	s_add_u32 s82, s10, 0x6000
	s_addc_u32 s83, s11, 0
	s_mul_i32 s22, s16, 9920
	s_cmp_eq_u32 s16, 7
	s_cselect_b32 s22, 0x21000, s22
	s_mov_b32 s85, 0xffffffff
	s_mov_b32 s72, 0x3e6d3388
	s_mov_b32 s56, s4
	s_and_b32 s57, s5, 0xffff
	s_or_b32 s57, s57, 0x04000000
	s_mov_b32 s58, 32768
	s_mov_b32 s59, 0x00027000
	s_mov_b32 s60, s6
	s_and_b32 s61, s7, 0xffff
	s_or_b32 s61, s61, 0x04000000
	s_mov_b32 s62, 16384
	s_mov_b32 s63, 0x00027000
	s_lshl_b32 s76, s16, 3
	s_lshl_b32 s0, s2, 6
	s_add_i32 s77, s0, s76
	global_load_dwordx4 v[192:195], v246, s[80:81] offset:0
	global_load_dwordx4 v[196:199], v246, s[80:81] offset:16
	global_load_dwordx4 v[200:203], v246, s[80:81] offset:32
	global_load_dwordx4 v[204:207], v246, s[80:81] offset:48
	s_add_i32 s0, s77, 0
	s_lshl_b32 s1, s0, 11
	s_add_u32 s78, s12, s1
	s_addc_u32 s79, s13, 0
	global_load_dwordx4 v[128:131], v245, s[78:79]
	global_load_dwordx4 v[132:135], v245, s[78:79] offset:16
	global_load_dwordx4 v[136:139], v245, s[78:79] offset:2048
	global_load_dwordx4 v[140:143], v245, s[78:79] offset:2064
	s_lshl_b32 s1, s0, 6
	s_add_u32 s78, s14, s1
	s_addc_u32 s79, s15, 0
	global_load_dwordx4 v[144:147], v244, s[78:79] offset:0
	global_load_dwordx4 v[148:151], v244, s[78:79] offset:16
	global_load_dwordx4 v[152:155], v244, s[78:79] offset:32
	global_load_dwordx4 v[156:159], v244, s[78:79] offset:48
	global_load_dwordx4 v[160:163], v244, s[78:79] offset:64
	global_load_dwordx4 v[164:167], v244, s[78:79] offset:80
	global_load_dwordx4 v[168:171], v244, s[78:79] offset:96
	global_load_dwordx4 v[172:175], v244, s[78:79] offset:112
	s_waitcnt lgkmcnt(0)
	s_barrier
	s_add_i32 s0, s77, 2
	s_lshl_b32 s1, s0, 11
	s_add_u32 s78, s12, s1
	s_addc_u32 s79, s13, 0
	global_load_dwordx4 v[176:179], v245, s[78:79]
	global_load_dwordx4 v[180:183], v245, s[78:79] offset:16
	global_load_dwordx4 v[184:187], v245, s[78:79] offset:2048
	global_load_dwordx4 v[188:191], v245, s[78:79] offset:2064
	s_lshl_b32 s1, s0, 6
	s_add_u32 s78, s14, s1
	s_addc_u32 s79, s15, 0
	global_load_dwordx4 v[216:219], v244, s[78:79] offset:0
	global_load_dwordx4 v[220:223], v244, s[78:79] offset:16
	global_load_dwordx4 v[224:227], v244, s[78:79] offset:32
	global_load_dwordx4 v[228:231], v244, s[78:79] offset:48
	global_load_dwordx4 v[232:235], v244, s[78:79] offset:64
	global_load_dwordx4 v[236:239], v244, s[78:79] offset:80
	global_load_dwordx4 v[248:251], v244, s[78:79] offset:96
	global_load_dwordx4 v[252:255], v244, s[78:79] offset:112
	s_waitcnt vmcnt(12)
	v_pk_add_f32 v[144:145], v[144:145], v[148:149]
	v_pk_add_f32 v[146:147], v[146:147], v[150:151]
	v_pk_add_f32 v[152:153], v[152:153], v[156:157]
	v_pk_add_f32 v[154:155], v[154:155], v[158:159]
	v_pk_add_f32 v[144:145], v[144:145], v[152:153]
	v_pk_add_f32 v[146:147], v[146:147], v[154:155]
	v_add_f32_e32 v144, v144, v145
	v_add_f32_e32 v146, v146, v147
	v_add_f32_e32 v144, v144, v146
	v_fmamk_f32 v144, v144, 0x3a800000, v243
	v_rsq_f32_e32 v144, v144
	v_pk_add_f32 v[160:161], v[160:161], v[164:165]
	v_pk_add_f32 v[162:163], v[162:163], v[166:167]
	v_pk_add_f32 v[168:169], v[168:169], v[172:173]
	v_pk_add_f32 v[170:171], v[170:171], v[174:175]
	v_pk_add_f32 v[160:161], v[160:161], v[168:169]
	v_pk_add_f32 v[162:163], v[162:163], v[170:171]
	v_add_f32_e32 v160, v160, v161
	v_add_f32_e32 v162, v162, v163
	v_add_f32_e32 v160, v160, v162
	v_fmamk_f32 v160, v160, 0x3a800000, v243
	v_rsq_f32_e32 v160, v160
	v_lshlrev_b32_e32 v208, 16, v128
	v_and_b32_e32 v209, 0xffff0000, v128
	v_fma_f32 v208, v208, v144, v192
	v_fma_f32 v209, v209, v144, v193
	v_cvt_pk_bf16_f32 v210, v208, v209
	v_lshlrev_b32_e32 v0, 16, v210
	v_and_b32_e32 v1, 0xffff0000, v210
	v_lshlrev_b32_e32 v208, 16, v129
	v_and_b32_e32 v209, 0xffff0000, v129
	v_fma_f32 v208, v208, v144, v194
	v_fma_f32 v209, v209, v144, v195
	v_cvt_pk_bf16_f32 v210, v208, v209
	v_lshlrev_b32_e32 v2, 16, v210
	v_and_b32_e32 v3, 0xffff0000, v210
	v_lshlrev_b32_e32 v208, 16, v130
	v_and_b32_e32 v209, 0xffff0000, v130
	v_fma_f32 v208, v208, v144, v196
	v_fma_f32 v209, v209, v144, v197
	v_cvt_pk_bf16_f32 v210, v208, v209
	v_lshlrev_b32_e32 v4, 16, v210
	v_and_b32_e32 v5, 0xffff0000, v210
	v_lshlrev_b32_e32 v208, 16, v131
	v_and_b32_e32 v209, 0xffff0000, v131
	v_fma_f32 v208, v208, v144, v198
	v_fma_f32 v209, v209, v144, v199
	v_cvt_pk_bf16_f32 v210, v208, v209
	v_lshlrev_b32_e32 v6, 16, v210
	v_and_b32_e32 v7, 0xffff0000, v210
	v_lshlrev_b32_e32 v208, 16, v132
	v_and_b32_e32 v209, 0xffff0000, v132
	v_fma_f32 v208, v208, v144, v200
	v_fma_f32 v209, v209, v144, v201
	v_cvt_pk_bf16_f32 v210, v208, v209
	v_lshlrev_b32_e32 v8, 16, v210
	v_and_b32_e32 v9, 0xffff0000, v210
	v_lshlrev_b32_e32 v208, 16, v133
	v_and_b32_e32 v209, 0xffff0000, v133
	v_fma_f32 v208, v208, v144, v202
	v_fma_f32 v209, v209, v144, v203
	v_cvt_pk_bf16_f32 v210, v208, v209
; __device__ __forceinline__ unsigned pk2(float lo, float hi) { const f32x2 v = {lo, hi}; const bf16x2_t b = __builtin_convertvector(v, bf16x2_t); return __builtin_bit_cast(unsigned, b); }
; __device__ __forceinline__ float bflo(unsigned u) { return __uint_as_float(u << 16); }
; __device__ __forceinline__ float bfhi(unsigned u) { return __uint_as_float(u & 0xffff0000u); }
; __device__ __forceinline__ void peer_tile(const Args& A, LAS unsigned char* lds, int tile) {
;     ...
;         for (int tk = 0; tk < 4; ++tk) { const size_t m = (size_t)tile * 64 + tb + tk;
;             { const u32x4 ra = *(const u32x4*)(A3 + m * 1024 + 16 * lane), rb = *(const u32x4*)(A3 + m * 1024 + 16 * lane + 8);
;               float xr_; { const f32x4 p0 = *(const f32x4*)(RSq + m * 16), p1 = *(const f32x4*)(RSq + m * 16 + 4), p2 = *(const f32x4*)(RSq + m * 16 + 8), p3 = *(const f32x4*)(RSq + m * 16 + 12);
;                 const f32x4 ps = (p0 + p1) + (p2 + p3); xr_ = rsqrtf(((ps[0] + ps[1]) + (ps[2] + ps[3])) * (1.f / 1024.f) + 1e-6f); }
;               const unsigned rr[8] = {ra.x, ra.y, ra.z, ra.w, rb.x, rb.y, rb.z, rb.w}; unsigned hh[8];
;               const float* sp = MOD + (int)(m >> 11) * 6144 + 3072 + 16 * lane;
; #pragma unroll
;               for (int q = 0; q < 8; ++q) { const f32x2 sh = *(const f32x2*)(sp + 2 * q); hh[q] = pk2(bflo(rr[q]) * xr_ + sh[0], bfhi(rr[q]) * xr_ + sh[1]); }
;               xpa[tk] = (u32x4){hh[0], hh[1], hh[2], hh[3]}; xpb[tk] = (u32x4){hh[4], hh[5], hh[6], hh[7]}; }
	v_lshlrev_b32_e32 v10, 16, v210
	v_and_b32_e32 v11, 0xffff0000, v210
	v_lshlrev_b32_e32 v208, 16, v134
	v_and_b32_e32 v209, 0xffff0000, v134
	v_fma_f32 v208, v208, v144, v204
	v_fma_f32 v209, v209, v144, v205
	v_cvt_pk_bf16_f32 v210, v208, v209
	v_lshlrev_b32_e32 v12, 16, v210
	v_and_b32_e32 v13, 0xffff0000, v210
	v_lshlrev_b32_e32 v208, 16, v135
	v_and_b32_e32 v209, 0xffff0000, v135
	v_fma_f32 v208, v208, v144, v206
	v_fma_f32 v209, v209, v144, v207
	v_cvt_pk_bf16_f32 v210, v208, v209
	v_lshlrev_b32_e32 v14, 16, v210
	v_and_b32_e32 v15, 0xffff0000, v210
	v_lshlrev_b32_e32 v208, 16, v136
	v_and_b32_e32 v209, 0xffff0000, v136
	v_fma_f32 v208, v208, v160, v192
	v_fma_f32 v209, v209, v160, v193
	v_cvt_pk_bf16_f32 v210, v208, v209
	v_lshlrev_b32_e32 v16, 16, v210
	v_and_b32_e32 v17, 0xffff0000, v210
	v_lshlrev_b32_e32 v208, 16, v137
	v_and_b32_e32 v209, 0xffff0000, v137
	v_fma_f32 v208, v208, v160, v194
	v_fma_f32 v209, v209, v160, v195
	v_cvt_pk_bf16_f32 v210, v208, v209
	v_lshlrev_b32_e32 v18, 16, v210
	v_and_b32_e32 v19, 0xffff0000, v210
	v_lshlrev_b32_e32 v208, 16, v138
	v_and_b32_e32 v209, 0xffff0000, v138
	v_fma_f32 v208, v208, v160, v196
	v_fma_f32 v209, v209, v160, v197
	v_cvt_pk_bf16_f32 v210, v208, v209
	v_lshlrev_b32_e32 v20, 16, v210
	v_and_b32_e32 v21, 0xffff0000, v210
	v_lshlrev_b32_e32 v208, 16, v139
	v_and_b32_e32 v209, 0xffff0000, v139
	v_fma_f32 v208, v208, v160, v198
	v_fma_f32 v209, v209, v160, v199
	v_cvt_pk_bf16_f32 v210, v208, v209
	v_lshlrev_b32_e32 v22, 16, v210
	v_and_b32_e32 v23, 0xffff0000, v210
	v_lshlrev_b32_e32 v208, 16, v140
	v_and_b32_e32 v209, 0xffff0000, v140
	v_fma_f32 v208, v208, v160, v200
	v_fma_f32 v209, v209, v160, v201
	v_cvt_pk_bf16_f32 v210, v208, v209
	v_lshlrev_b32_e32 v24, 16, v210
	v_and_b32_e32 v25, 0xffff0000, v210
	v_lshlrev_b32_e32 v208, 16, v141
	v_and_b32_e32 v209, 0xffff0000, v141
	v_fma_f32 v208, v208, v160, v202
	v_fma_f32 v209, v209, v160, v203
	v_cvt_pk_bf16_f32 v210, v208, v209
	v_lshlrev_b32_e32 v26, 16, v210
	v_and_b32_e32 v27, 0xffff0000, v210
	v_lshlrev_b32_e32 v208, 16, v142
	v_and_b32_e32 v209, 0xffff0000, v142
	v_fma_f32 v208, v208, v160, v204
	v_fma_f32 v209, v209, v160, v205
	v_cvt_pk_bf16_f32 v210, v208, v209
	v_lshlrev_b32_e32 v28, 16, v210
	v_and_b32_e32 v29, 0xffff0000, v210
	v_lshlrev_b32_e32 v208, 16, v143
	v_and_b32_e32 v209, 0xffff0000, v143
	v_fma_f32 v208, v208, v160, v206
	v_fma_f32 v209, v209, v160, v207
	v_cvt_pk_bf16_f32 v210, v208, v209
	v_lshlrev_b32_e32 v30, 16, v210
	v_and_b32_e32 v31, 0xffff0000, v210
	s_nop 0
	s_add_i32 s0, s77, 4
	s_lshl_b32 s1, s0, 11
	s_add_u32 s78, s12, s1
	s_addc_u32 s79, s13, 0
	global_load_dwordx4 v[128:131], v245, s[78:79]
	global_load_dwordx4 v[132:135], v245, s[78:79] offset:16
	global_load_dwordx4 v[136:139], v245, s[78:79] offset:2048
	global_load_dwordx4 v[140:143], v245, s[78:79] offset:2064
	s_lshl_b32 s1, s0, 6
	s_add_u32 s78, s14, s1
	s_addc_u32 s79, s15, 0
	global_load_dwordx4 v[144:147], v244, s[78:79] offset:0
	global_load_dwordx4 v[148:151], v244, s[78:79] offset:16
	global_load_dwordx4 v[152:155], v244, s[78:79] offset:32
	global_load_dwordx4 v[156:159], v244, s[78:79] offset:48
	global_load_dwordx4 v[160:163], v244, s[78:79] offset:64
	global_load_dwordx4 v[164:167], v244, s[78:79] offset:80
	global_load_dwordx4 v[168:171], v244, s[78:79] offset:96
	global_load_dwordx4 v[172:175], v244, s[78:79] offset:112
	s_waitcnt vmcnt(12)
	v_pk_add_f32 v[216:217], v[216:217], v[220:221]
	v_pk_add_f32 v[218:219], v[218:219], v[222:223]
	v_pk_add_f32 v[224:225], v[224:225], v[228:229]
	v_pk_add_f32 v[226:227], v[226:227], v[230:231]
	v_pk_add_f32 v[216:217], v[216:217], v[224:225]
	v_pk_add_f32 v[218:219], v[218:219], v[226:227]
	v_add_f32_e32 v216, v216, v217
	v_add_f32_e32 v218, v218, v219
	v_add_f32_e32 v216, v216, v218
	v_fmamk_f32 v216, v216, 0x3a800000, v243
	v_rsq_f32_e32 v216, v216
	v_pk_add_f32 v[232:233], v[232:233], v[236:237]
	v_pk_add_f32 v[234:235], v[234:235], v[238:239]
	v_pk_add_f32 v[248:249], v[248:249], v[252:253]
	v_pk_add_f32 v[250:251], v[250:251], v[254:255]
	v_pk_add_f32 v[232:233], v[232:233], v[248:249]
	v_pk_add_f32 v[234:235], v[234:235], v[250:251]
	v_add_f32_e32 v232, v232, v233
	v_add_f32_e32 v234, v234, v235
	v_add_f32_e32 v232, v232, v234
	v_fmamk_f32 v232, v232, 0x3a800000, v243
	v_rsq_f32_e32 v232, v232
	v_lshlrev_b32_e32 v208, 16, v176
	v_and_b32_e32 v209, 0xffff0000, v176
	v_fma_f32 v208, v208, v216, v192
	v_fma_f32 v209, v209, v216, v193
	v_cvt_pk_bf16_f32 v210, v208, v209
	v_lshlrev_b32_e32 v32, 16, v210
	v_and_b32_e32 v33, 0xffff0000, v210
	v_lshlrev_b32_e32 v208, 16, v177
	v_and_b32_e32 v209, 0xffff0000, v177
	v_fma_f32 v208, v208, v216, v194
	v_fma_f32 v209, v209, v216, v195
	v_cvt_pk_bf16_f32 v210, v208, v209
	v_lshlrev_b32_e32 v34, 16, v210
	v_and_b32_e32 v35, 0xffff0000, v210
	v_lshlrev_b32_e32 v208, 16, v178
	v_and_b32_e32 v209, 0xffff0000, v178
	v_fma_f32 v208, v208, v216, v196
	v_fma_f32 v209, v209, v216, v197
	v_cvt_pk_bf16_f32 v210, v208, v209
	v_lshlrev_b32_e32 v36, 16, v210
	v_and_b32_e32 v37, 0xffff0000, v210
	v_lshlrev_b32_e32 v208, 16, v179
	v_and_b32_e32 v209, 0xffff0000, v179
	v_fma_f32 v208, v208, v216, v198
	v_fma_f32 v209, v209, v216, v199
	v_cvt_pk_bf16_f32 v210, v208, v209
	v_lshlrev_b32_e32 v38, 16, v210
	v_and_b32_e32 v39, 0xffff0000, v210
	v_lshlrev_b32_e32 v208, 16, v180
	v_and_b32_e32 v209, 0xffff0000, v180
	v_fma_f32 v208, v208, v216, v200
	v_fma_f32 v209, v209, v216, v201
	v_cvt_pk_bf16_f32 v210, v208, v209
	v_lshlrev_b32_e32 v40, 16, v210
	v_and_b32_e32 v41, 0xffff0000, v210
	v_lshlrev_b32_e32 v208, 16, v181
	v_and_b32_e32 v209, 0xffff0000, v181
; __device__ __forceinline__ unsigned pk2(float lo, float hi) { const f32x2 v = {lo, hi}; const bf16x2_t b = __builtin_convertvector(v, bf16x2_t); return __builtin_bit_cast(unsigned, b); }
; __device__ __forceinline__ float bflo(unsigned u) { return __uint_as_float(u << 16); }
; __device__ __forceinline__ float bfhi(unsigned u) { return __uint_as_float(u & 0xffff0000u); }
; __device__ __forceinline__ void peer_tile(const Args& A, LAS unsigned char* lds, int tile) {
;     ...
;         for (int tk = 0; tk < 4; ++tk) { const size_t m = (size_t)tile * 64 + tb + tk;
;             { const u32x4 ra = *(const u32x4*)(A3 + m * 1024 + 16 * lane), rb = *(const u32x4*)(A3 + m * 1024 + 16 * lane + 8);
;               float xr_; { const f32x4 p0 = *(const f32x4*)(RSq + m * 16), p1 = *(const f32x4*)(RSq + m * 16 + 4), p2 = *(const f32x4*)(RSq + m * 16 + 8), p3 = *(const f32x4*)(RSq + m * 16 + 12);
;                 const f32x4 ps = (p0 + p1) + (p2 + p3); xr_ = rsqrtf(((ps[0] + ps[1]) + (ps[2] + ps[3])) * (1.f / 1024.f) + 1e-6f); }
;               const unsigned rr[8] = {ra.x, ra.y, ra.z, ra.w, rb.x, rb.y, rb.z, rb.w}; unsigned hh[8];
;               const float* sp = MOD + (int)(m >> 11) * 6144 + 3072 + 16 * lane;
; #pragma unroll
;               for (int q = 0; q < 8; ++q) { const f32x2 sh = *(const f32x2*)(sp + 2 * q); hh[q] = pk2(bflo(rr[q]) * xr_ + sh[0], bfhi(rr[q]) * xr_ + sh[1]); }
;               xpa[tk] = (u32x4){hh[0], hh[1], hh[2], hh[3]}; xpb[tk] = (u32x4){hh[4], hh[5], hh[6], hh[7]}; }
	v_fma_f32 v208, v208, v216, v202
	v_fma_f32 v209, v209, v216, v203
	v_cvt_pk_bf16_f32 v210, v208, v209
	v_lshlrev_b32_e32 v42, 16, v210
	v_and_b32_e32 v43, 0xffff0000, v210
	v_lshlrev_b32_e32 v208, 16, v182
	v_and_b32_e32 v209, 0xffff0000, v182
	v_fma_f32 v208, v208, v216, v204
	v_fma_f32 v209, v209, v216, v205
	v_cvt_pk_bf16_f32 v210, v208, v209
	v_lshlrev_b32_e32 v44, 16, v210
	v_and_b32_e32 v45, 0xffff0000, v210
	v_lshlrev_b32_e32 v208, 16, v183
	v_and_b32_e32 v209, 0xffff0000, v183
	v_fma_f32 v208, v208, v216, v206
	v_fma_f32 v209, v209, v216, v207
	v_cvt_pk_bf16_f32 v210, v208, v209
	v_lshlrev_b32_e32 v46, 16, v210
	v_and_b32_e32 v47, 0xffff0000, v210
	v_lshlrev_b32_e32 v208, 16, v184
	v_and_b32_e32 v209, 0xffff0000, v184
	v_fma_f32 v208, v208, v232, v192
	v_fma_f32 v209, v209, v232, v193
	v_cvt_pk_bf16_f32 v210, v208, v209
	v_lshlrev_b32_e32 v48, 16, v210
	v_and_b32_e32 v49, 0xffff0000, v210
	v_lshlrev_b32_e32 v208, 16, v185
	v_and_b32_e32 v209, 0xffff0000, v185
	v_fma_f32 v208, v208, v232, v194
	v_fma_f32 v209, v209, v232, v195
	v_cvt_pk_bf16_f32 v210, v208, v209
	v_lshlrev_b32_e32 v50, 16, v210
	v_and_b32_e32 v51, 0xffff0000, v210
	v_lshlrev_b32_e32 v208, 16, v186
	v_and_b32_e32 v209, 0xffff0000, v186
	v_fma_f32 v208, v208, v232, v196
	v_fma_f32 v209, v209, v232, v197
	v_cvt_pk_bf16_f32 v210, v208, v209
	v_lshlrev_b32_e32 v52, 16, v210
	v_and_b32_e32 v53, 0xffff0000, v210
	v_lshlrev_b32_e32 v208, 16, v187
	v_and_b32_e32 v209, 0xffff0000, v187
	v_fma_f32 v208, v208, v232, v198
	v_fma_f32 v209, v209, v232, v199
	v_cvt_pk_bf16_f32 v210, v208, v209
	v_lshlrev_b32_e32 v54, 16, v210
	v_and_b32_e32 v55, 0xffff0000, v210
	v_lshlrev_b32_e32 v208, 16, v188
	v_and_b32_e32 v209, 0xffff0000, v188
	v_fma_f32 v208, v208, v232, v200
	v_fma_f32 v209, v209, v232, v201
	v_cvt_pk_bf16_f32 v210, v208, v209
	v_lshlrev_b32_e32 v56, 16, v210
	v_and_b32_e32 v57, 0xffff0000, v210
	v_lshlrev_b32_e32 v208, 16, v189
	v_and_b32_e32 v209, 0xffff0000, v189
	v_fma_f32 v208, v208, v232, v202
	v_fma_f32 v209, v209, v232, v203
	v_cvt_pk_bf16_f32 v210, v208, v209
	v_lshlrev_b32_e32 v58, 16, v210
	v_and_b32_e32 v59, 0xffff0000, v210
	v_lshlrev_b32_e32 v208, 16, v190
	v_and_b32_e32 v209, 0xffff0000, v190
	v_fma_f32 v208, v208, v232, v204
	v_fma_f32 v209, v209, v232, v205
	v_cvt_pk_bf16_f32 v210, v208, v209
	v_lshlrev_b32_e32 v60, 16, v210
	v_and_b32_e32 v61, 0xffff0000, v210
	v_lshlrev_b32_e32 v208, 16, v191
	v_and_b32_e32 v209, 0xffff0000, v191
	v_fma_f32 v208, v208, v232, v206
	v_fma_f32 v209, v209, v232, v207
	v_cvt_pk_bf16_f32 v210, v208, v209
	v_lshlrev_b32_e32 v62, 16, v210
	v_and_b32_e32 v63, 0xffff0000, v210
	s_nop 0
	s_add_i32 s0, s77, 6
	s_lshl_b32 s1, s0, 11
	s_add_u32 s78, s12, s1
	s_addc_u32 s79, s13, 0
	global_load_dwordx4 v[176:179], v245, s[78:79]
	global_load_dwordx4 v[180:183], v245, s[78:79] offset:16
	global_load_dwordx4 v[184:187], v245, s[78:79] offset:2048
	global_load_dwordx4 v[188:191], v245, s[78:79] offset:2064
	s_lshl_b32 s1, s0, 6
	s_add_u32 s78, s14, s1
	s_addc_u32 s79, s15, 0
	global_load_dwordx4 v[216:219], v244, s[78:79] offset:0
	global_load_dwordx4 v[220:223], v244, s[78:79] offset:16
	global_load_dwordx4 v[224:227], v244, s[78:79] offset:32
	global_load_dwordx4 v[228:231], v244, s[78:79] offset:48
	global_load_dwordx4 v[232:235], v244, s[78:79] offset:64
	global_load_dwordx4 v[236:239], v244, s[78:79] offset:80
	global_load_dwordx4 v[248:251], v244, s[78:79] offset:96
	global_load_dwordx4 v[252:255], v244, s[78:79] offset:112
	s_waitcnt vmcnt(12)
	v_pk_add_f32 v[144:145], v[144:145], v[148:149]
	v_pk_add_f32 v[146:147], v[146:147], v[150:151]
	v_pk_add_f32 v[152:153], v[152:153], v[156:157]
	v_pk_add_f32 v[154:155], v[154:155], v[158:159]
	v_pk_add_f32 v[144:145], v[144:145], v[152:153]
	v_pk_add_f32 v[146:147], v[146:147], v[154:155]
	v_add_f32_e32 v144, v144, v145
	v_add_f32_e32 v146, v146, v147
	v_add_f32_e32 v144, v144, v146
	v_fmamk_f32 v144, v144, 0x3a800000, v243
	v_rsq_f32_e32 v144, v144
	v_pk_add_f32 v[160:161], v[160:161], v[164:165]
	v_pk_add_f32 v[162:163], v[162:163], v[166:167]
	v_pk_add_f32 v[168:169], v[168:169], v[172:173]
	v_pk_add_f32 v[170:171], v[170:171], v[174:175]
	v_pk_add_f32 v[160:161], v[160:161], v[168:169]
	v_pk_add_f32 v[162:163], v[162:163], v[170:171]
	v_add_f32_e32 v160, v160, v161
	v_add_f32_e32 v162, v162, v163
	v_add_f32_e32 v160, v160, v162
	v_fmamk_f32 v160, v160, 0x3a800000, v243
	v_rsq_f32_e32 v160, v160
	v_lshlrev_b32_e32 v208, 16, v128
	v_and_b32_e32 v209, 0xffff0000, v128
	v_fma_f32 v208, v208, v144, v192
	v_fma_f32 v209, v209, v144, v193
	v_cvt_pk_bf16_f32 v210, v208, v209
	v_lshlrev_b32_e32 v64, 16, v210
	v_and_b32_e32 v65, 0xffff0000, v210
	v_lshlrev_b32_e32 v208, 16, v129
	v_and_b32_e32 v209, 0xffff0000, v129
	v_fma_f32 v208, v208, v144, v194
	v_fma_f32 v209, v209, v144, v195
	v_cvt_pk_bf16_f32 v210, v208, v209
	v_lshlrev_b32_e32 v66, 16, v210
	v_and_b32_e32 v67, 0xffff0000, v210
	v_lshlrev_b32_e32 v208, 16, v130
	v_and_b32_e32 v209, 0xffff0000, v130
	v_fma_f32 v208, v208, v144, v196
	v_fma_f32 v209, v209, v144, v197
	v_cvt_pk_bf16_f32 v210, v208, v209
	v_lshlrev_b32_e32 v68, 16, v210
	v_and_b32_e32 v69, 0xffff0000, v210
	v_lshlrev_b32_e32 v208, 16, v131
	v_and_b32_e32 v209, 0xffff0000, v131
	v_fma_f32 v208, v208, v144, v198
	v_fma_f32 v209, v209, v144, v199
	v_cvt_pk_bf16_f32 v210, v208, v209
	v_lshlrev_b32_e32 v70, 16, v210
	v_and_b32_e32 v71, 0xffff0000, v210
	v_lshlrev_b32_e32 v208, 16, v132
	v_and_b32_e32 v209, 0xffff0000, v132
	v_fma_f32 v208, v208, v144, v200
	v_fma_f32 v209, v209, v144, v201
	v_cvt_pk_bf16_f32 v210, v208, v209
	v_lshlrev_b32_e32 v72, 16, v210
; __device__ __forceinline__ unsigned pk2(float lo, float hi) { const f32x2 v = {lo, hi}; const bf16x2_t b = __builtin_convertvector(v, bf16x2_t); return __builtin_bit_cast(unsigned, b); }
; __device__ __forceinline__ float bflo(unsigned u) { return __uint_as_float(u << 16); }
; __device__ __forceinline__ float bfhi(unsigned u) { return __uint_as_float(u & 0xffff0000u); }
; __device__ __forceinline__ void peer_tile(const Args& A, LAS unsigned char* lds, int tile) {
;     ...
;         for (int tk = 0; tk < 4; ++tk) { const size_t m = (size_t)tile * 64 + tb + tk;
;             { const u32x4 ra = *(const u32x4*)(A3 + m * 1024 + 16 * lane), rb = *(const u32x4*)(A3 + m * 1024 + 16 * lane + 8);
;               float xr_; { const f32x4 p0 = *(const f32x4*)(RSq + m * 16), p1 = *(const f32x4*)(RSq + m * 16 + 4), p2 = *(const f32x4*)(RSq + m * 16 + 8), p3 = *(const f32x4*)(RSq + m * 16 + 12);
;                 const f32x4 ps = (p0 + p1) + (p2 + p3); xr_ = rsqrtf(((ps[0] + ps[1]) + (ps[2] + ps[3])) * (1.f / 1024.f) + 1e-6f); }
;               const unsigned rr[8] = {ra.x, ra.y, ra.z, ra.w, rb.x, rb.y, rb.z, rb.w}; unsigned hh[8];
;               const float* sp = MOD + (int)(m >> 11) * 6144 + 3072 + 16 * lane;
; #pragma unroll
;               for (int q = 0; q < 8; ++q) { const f32x2 sh = *(const f32x2*)(sp + 2 * q); hh[q] = pk2(bflo(rr[q]) * xr_ + sh[0], bfhi(rr[q]) * xr_ + sh[1]); }
;               xpa[tk] = (u32x4){hh[0], hh[1], hh[2], hh[3]}; xpb[tk] = (u32x4){hh[4], hh[5], hh[6], hh[7]}; }
	v_and_b32_e32 v73, 0xffff0000, v210
	v_lshlrev_b32_e32 v208, 16, v133
	v_and_b32_e32 v209, 0xffff0000, v133
	v_fma_f32 v208, v208, v144, v202
	v_fma_f32 v209, v209, v144, v203
	v_cvt_pk_bf16_f32 v210, v208, v209
	v_lshlrev_b32_e32 v74, 16, v210
	v_and_b32_e32 v75, 0xffff0000, v210
	v_lshlrev_b32_e32 v208, 16, v134
	v_and_b32_e32 v209, 0xffff0000, v134
	v_fma_f32 v208, v208, v144, v204
	v_fma_f32 v209, v209, v144, v205
	v_cvt_pk_bf16_f32 v210, v208, v209
	v_lshlrev_b32_e32 v76, 16, v210
	v_and_b32_e32 v77, 0xffff0000, v210
	v_lshlrev_b32_e32 v208, 16, v135
	v_and_b32_e32 v209, 0xffff0000, v135
	v_fma_f32 v208, v208, v144, v206
	v_fma_f32 v209, v209, v144, v207
	v_cvt_pk_bf16_f32 v210, v208, v209
	v_lshlrev_b32_e32 v78, 16, v210
	v_and_b32_e32 v79, 0xffff0000, v210
	v_lshlrev_b32_e32 v208, 16, v136
	v_and_b32_e32 v209, 0xffff0000, v136
	v_fma_f32 v208, v208, v160, v192
	v_fma_f32 v209, v209, v160, v193
	v_cvt_pk_bf16_f32 v210, v208, v209
	v_lshlrev_b32_e32 v80, 16, v210
	v_and_b32_e32 v81, 0xffff0000, v210
	v_lshlrev_b32_e32 v208, 16, v137
	v_and_b32_e32 v209, 0xffff0000, v137
	v_fma_f32 v208, v208, v160, v194
	v_fma_f32 v209, v209, v160, v195
	v_cvt_pk_bf16_f32 v210, v208, v209
	v_lshlrev_b32_e32 v82, 16, v210
	v_and_b32_e32 v83, 0xffff0000, v210
	v_lshlrev_b32_e32 v208, 16, v138
	v_and_b32_e32 v209, 0xffff0000, v138
	v_fma_f32 v208, v208, v160, v196
	v_fma_f32 v209, v209, v160, v197
	v_cvt_pk_bf16_f32 v210, v208, v209
	v_lshlrev_b32_e32 v84, 16, v210
	v_and_b32_e32 v85, 0xffff0000, v210
	v_lshlrev_b32_e32 v208, 16, v139
	v_and_b32_e32 v209, 0xffff0000, v139
	v_fma_f32 v208, v208, v160, v198
	v_fma_f32 v209, v209, v160, v199
	v_cvt_pk_bf16_f32 v210, v208, v209
	v_lshlrev_b32_e32 v86, 16, v210
	v_and_b32_e32 v87, 0xffff0000, v210
	v_lshlrev_b32_e32 v208, 16, v140
	v_and_b32_e32 v209, 0xffff0000, v140
	v_fma_f32 v208, v208, v160, v200
	v_fma_f32 v209, v209, v160, v201
	v_cvt_pk_bf16_f32 v210, v208, v209
	v_lshlrev_b32_e32 v88, 16, v210
	v_and_b32_e32 v89, 0xffff0000, v210
	v_lshlrev_b32_e32 v208, 16, v141
	v_and_b32_e32 v209, 0xffff0000, v141
	v_fma_f32 v208, v208, v160, v202
	v_fma_f32 v209, v209, v160, v203
	v_cvt_pk_bf16_f32 v210, v208, v209
	v_lshlrev_b32_e32 v90, 16, v210
	v_and_b32_e32 v91, 0xffff0000, v210
	v_lshlrev_b32_e32 v208, 16, v142
	v_and_b32_e32 v209, 0xffff0000, v142
	v_fma_f32 v208, v208, v160, v204
	v_fma_f32 v209, v209, v160, v205
	v_cvt_pk_bf16_f32 v210, v208, v209
	v_lshlrev_b32_e32 v92, 16, v210
	v_and_b32_e32 v93, 0xffff0000, v210
	v_lshlrev_b32_e32 v208, 16, v143
	v_and_b32_e32 v209, 0xffff0000, v143
	v_fma_f32 v208, v208, v160, v206
	v_fma_f32 v209, v209, v160, v207
	v_cvt_pk_bf16_f32 v210, v208, v209
	v_lshlrev_b32_e32 v94, 16, v210
	v_and_b32_e32 v95, 0xffff0000, v210
	s_nop 0
	s_waitcnt vmcnt(0)
	v_pk_add_f32 v[216:217], v[216:217], v[220:221]
	v_pk_add_f32 v[218:219], v[218:219], v[222:223]
	v_pk_add_f32 v[224:225], v[224:225], v[228:229]
	v_pk_add_f32 v[226:227], v[226:227], v[230:231]
	v_pk_add_f32 v[216:217], v[216:217], v[224:225]
	v_pk_add_f32 v[218:219], v[218:219], v[226:227]
	v_add_f32_e32 v216, v216, v217
	v_add_f32_e32 v218, v218, v219
	v_add_f32_e32 v216, v216, v218
	v_fmamk_f32 v216, v216, 0x3a800000, v243
	v_rsq_f32_e32 v216, v216
	v_pk_add_f32 v[232:233], v[232:233], v[236:237]
	v_pk_add_f32 v[234:235], v[234:235], v[238:239]
	v_pk_add_f32 v[248:249], v[248:249], v[252:253]
	v_pk_add_f32 v[250:251], v[250:251], v[254:255]
	v_pk_add_f32 v[232:233], v[232:233], v[248:249]
	v_pk_add_f32 v[234:235], v[234:235], v[250:251]
	v_add_f32_e32 v232, v232, v233
	v_add_f32_e32 v234, v234, v235
	v_add_f32_e32 v232, v232, v234
	v_fmamk_f32 v232, v232, 0x3a800000, v243
	v_rsq_f32_e32 v232, v232
	v_lshlrev_b32_e32 v208, 16, v176
	v_and_b32_e32 v209, 0xffff0000, v176
	v_fma_f32 v208, v208, v216, v192
	v_fma_f32 v209, v209, v216, v193
	v_cvt_pk_bf16_f32 v210, v208, v209
	v_lshlrev_b32_e32 v96, 16, v210
	v_and_b32_e32 v97, 0xffff0000, v210
	v_lshlrev_b32_e32 v208, 16, v177
	v_and_b32_e32 v209, 0xffff0000, v177
	v_fma_f32 v208, v208, v216, v194
	v_fma_f32 v209, v209, v216, v195
	v_cvt_pk_bf16_f32 v210, v208, v209
	v_lshlrev_b32_e32 v98, 16, v210
	v_and_b32_e32 v99, 0xffff0000, v210
	v_lshlrev_b32_e32 v208, 16, v178
	v_and_b32_e32 v209, 0xffff0000, v178
	v_fma_f32 v208, v208, v216, v196
	v_fma_f32 v209, v209, v216, v197
	v_cvt_pk_bf16_f32 v210, v208, v209
	v_lshlrev_b32_e32 v100, 16, v210
	v_and_b32_e32 v101, 0xffff0000, v210
	v_lshlrev_b32_e32 v208, 16, v179
	v_and_b32_e32 v209, 0xffff0000, v179
	v_fma_f32 v208, v208, v216, v198
	v_fma_f32 v209, v209, v216, v199
	v_cvt_pk_bf16_f32 v210, v208, v209
	v_lshlrev_b32_e32 v102, 16, v210
	v_and_b32_e32 v103, 0xffff0000, v210
	v_lshlrev_b32_e32 v208, 16, v180
	v_and_b32_e32 v209, 0xffff0000, v180
	v_fma_f32 v208, v208, v216, v200
	v_fma_f32 v209, v209, v216, v201
	v_cvt_pk_bf16_f32 v210, v208, v209
	v_lshlrev_b32_e32 v104, 16, v210
	v_and_b32_e32 v105, 0xffff0000, v210
	v_lshlrev_b32_e32 v208, 16, v181
	v_and_b32_e32 v209, 0xffff0000, v181
	v_fma_f32 v208, v208, v216, v202
	v_fma_f32 v209, v209, v216, v203
	v_cvt_pk_bf16_f32 v210, v208, v209
	v_lshlrev_b32_e32 v106, 16, v210
	v_and_b32_e32 v107, 0xffff0000, v210
	v_lshlrev_b32_e32 v208, 16, v182
	v_and_b32_e32 v209, 0xffff0000, v182
	v_fma_f32 v208, v208, v216, v204
	v_fma_f32 v209, v209, v216, v205
	v_cvt_pk_bf16_f32 v210, v208, v209
	v_lshlrev_b32_e32 v108, 16, v210
	v_and_b32_e32 v109, 0xffff0000, v210
	v_lshlrev_b32_e32 v208, 16, v183
	v_and_b32_e32 v209, 0xffff0000, v183
	v_fma_f32 v208, v208, v216, v206
	v_fma_f32 v209, v209, v216, v207
	v_cvt_pk_bf16_f32 v210, v208, v209
	v_lshlrev_b32_e32 v110, 16, v210
; __device__ __forceinline__ unsigned pk2(float lo, float hi) { const f32x2 v = {lo, hi}; const bf16x2_t b = __builtin_convertvector(v, bf16x2_t); return __builtin_bit_cast(unsigned, b); }
; __device__ __forceinline__ float bflo(unsigned u) { return __uint_as_float(u << 16); }
; __device__ __forceinline__ float bfhi(unsigned u) { return __uint_as_float(u & 0xffff0000u); }
; __device__ __forceinline__ void peer_tile(const Args& A, LAS unsigned char* lds, int tile) {
;     ...
;     for (int ti = 0; ti < 8; ++ti) {
;         const int tl = 8 * w + ti;
;         const u32x2 e0 = SEL[tl * 128 + lane], e1 = SEL[tl * 128 + 64 + lane];
;         const int p0 = (int)(e0.x >> 10), p1 = (int)(e1.x >> 10);
;         int off = 0;
;         for (int p = 0; p < 16; ++p) {
;             const unsigned long long m0 = __ballot(p0 == p), m1 = __ballot(p1 == p);
;             const int c0 = __popcll(m0), c1 = __popcll(m1);
;             const int r0 = __builtin_amdgcn_mbcnt_hi((unsigned)(m0 >> 32), __builtin_amdgcn_mbcnt_lo((unsigned)m0, 0u));
;             const int r1 = __builtin_amdgcn_mbcnt_hi((unsigned)(m1 >> 32), __builtin_amdgcn_mbcnt_lo((unsigned)m1, 0u));
;             if (p0 == p) SORT[tl * 128 + off + r0] = e0;
;             if (p1 == p) SORT[tl * 128 + off + c0 + r1] = e1;
;             if (lane == 0) OFFS[tl * 17 + p] = off;
;             off += c0 + c1;
;     ...
;         for (int tk = 0; tk < 4; ++tk) { const size_t m = (size_t)tile * 64 + tb + tk;
;             { const u32x4 ra = *(const u32x4*)(A3 + m * 1024 + 16 * lane), rb = *(const u32x4*)(A3 + m * 1024 + 16 * lane + 8);
;               float xr_; { const f32x4 p0 = *(const f32x4*)(RSq + m * 16), p1 = *(const f32x4*)(RSq + m * 16 + 4), p2 = *(const f32x4*)(RSq + m * 16 + 8), p3 = *(const f32x4*)(RSq + m * 16 + 12);
;                 const f32x4 ps = (p0 + p1) + (p2 + p3); xr_ = rsqrtf(((ps[0] + ps[1]) + (ps[2] + ps[3])) * (1.f / 1024.f) + 1e-6f); }
;               const unsigned rr[8] = {ra.x, ra.y, ra.z, ra.w, rb.x, rb.y, rb.z, rb.w}; unsigned hh[8];
;               const float* sp = MOD + (int)(m >> 11) * 6144 + 3072 + 16 * lane;
; #pragma unroll
;               for (int q = 0; q < 8; ++q) { const f32x2 sh = *(const f32x2*)(sp + 2 * q); hh[q] = pk2(bflo(rr[q]) * xr_ + sh[0], bfhi(rr[q]) * xr_ + sh[1]); }
;               xpa[tk] = (u32x4){hh[0], hh[1], hh[2], hh[3]}; xpb[tk] = (u32x4){hh[4], hh[5], hh[6], hh[7]}; }
	v_and_b32_e32 v111, 0xffff0000, v210
	v_lshlrev_b32_e32 v208, 16, v184
	v_and_b32_e32 v209, 0xffff0000, v184
	v_fma_f32 v208, v208, v232, v192
	v_fma_f32 v209, v209, v232, v193
	v_cvt_pk_bf16_f32 v210, v208, v209
	v_lshlrev_b32_e32 v112, 16, v210
	v_and_b32_e32 v113, 0xffff0000, v210
	v_lshlrev_b32_e32 v208, 16, v185
	v_and_b32_e32 v209, 0xffff0000, v185
	v_fma_f32 v208, v208, v232, v194
	v_fma_f32 v209, v209, v232, v195
	v_cvt_pk_bf16_f32 v210, v208, v209
	v_lshlrev_b32_e32 v114, 16, v210
	v_and_b32_e32 v115, 0xffff0000, v210
	v_lshlrev_b32_e32 v208, 16, v186
	v_and_b32_e32 v209, 0xffff0000, v186
	v_fma_f32 v208, v208, v232, v196
	v_fma_f32 v209, v209, v232, v197
	v_cvt_pk_bf16_f32 v210, v208, v209
	v_lshlrev_b32_e32 v116, 16, v210
	v_and_b32_e32 v117, 0xffff0000, v210
	v_lshlrev_b32_e32 v208, 16, v187
	v_and_b32_e32 v209, 0xffff0000, v187
	v_fma_f32 v208, v208, v232, v198
	v_fma_f32 v209, v209, v232, v199
	v_cvt_pk_bf16_f32 v210, v208, v209
	v_lshlrev_b32_e32 v118, 16, v210
	v_and_b32_e32 v119, 0xffff0000, v210
	v_lshlrev_b32_e32 v208, 16, v188
	v_and_b32_e32 v209, 0xffff0000, v188
	v_fma_f32 v208, v208, v232, v200
	v_fma_f32 v209, v209, v232, v201
	v_cvt_pk_bf16_f32 v210, v208, v209
	v_lshlrev_b32_e32 v120, 16, v210
	v_and_b32_e32 v121, 0xffff0000, v210
	v_lshlrev_b32_e32 v208, 16, v189
	v_and_b32_e32 v209, 0xffff0000, v189
	v_fma_f32 v208, v208, v232, v202
	v_fma_f32 v209, v209, v232, v203
	v_cvt_pk_bf16_f32 v210, v208, v209
	v_lshlrev_b32_e32 v122, 16, v210
	v_and_b32_e32 v123, 0xffff0000, v210
	v_lshlrev_b32_e32 v208, 16, v190
	v_and_b32_e32 v209, 0xffff0000, v190
	v_fma_f32 v208, v208, v232, v204
	v_fma_f32 v209, v209, v232, v205
	v_cvt_pk_bf16_f32 v210, v208, v209
	v_lshlrev_b32_e32 v124, 16, v210
	v_and_b32_e32 v125, 0xffff0000, v210
	v_lshlrev_b32_e32 v208, 16, v191
	v_and_b32_e32 v209, 0xffff0000, v191
	v_fma_f32 v208, v208, v232, v206
	v_fma_f32 v209, v209, v232, v207
	v_cvt_pk_bf16_f32 v210, v208, v209
	v_lshlrev_b32_e32 v126, 16, v210
	v_and_b32_e32 v127, 0xffff0000, v210
	s_nop 0
	s_mov_b32 s24, s8
	s_and_b32 s25, s9, 0xffff
	s_mov_b32 s26, 0x20000
	s_mov_b32 s27, 0x00027000
	s_lshl_b32 s0, s76, 10
	s_add_i32 s0, s0, 0x11000
	s_sub_i32 s85, s0, s22
	v_mov_b32_e32 v224, 0x7fffffff
	v_mov_b32_e32 v225, 0x7fffffff
	v_mov_b32_e32 v226, 0x7fffffff
	v_mov_b32_e32 v227, 0x7fffffff
	v_mov_b32_e32 v228, 0
	v_mov_b32_e32 v229, 0
	v_mov_b32_e32 v230, 0
	v_mov_b32_e32 v231, 0
	v_add_u32_e32 v232, s22, v240
	ds_write_b128 v232, v[224:227] offset:0
	ds_write_b128 v232, v[228:231] offset:4992
	ds_write_b128 v232, v[224:227] offset:1024
	ds_write_b128 v232, v[228:231] offset:6016
	ds_write_b128 v232, v[224:227] offset:2048
	ds_write_b128 v232, v[228:231] offset:7040
	ds_write_b128 v232, v[224:227] offset:3072
	ds_write_b128 v232, v[228:231] offset:8064
	s_mov_b32 exec_hi, 0x00ffffff
	ds_write_b128 v232, v[224:227] offset:4096
	s_mov_b32 exec_hi, 0x000fffff
	ds_write_b128 v232, v[228:231] offset:9088
	s_mov_b64 exec, -1
	v_lshrrev_b32_e32 v221, 2, v240
	v_add_u32_e32 v221, s22, v221
	ds_write_b32 v221, v228 offset:4224
	v_lshrrev_b32_e32 v233, 1, v240
	s_lshl_b32 s0, s76, 10
	s_add_i32 s0, s0, 0x11000
	v_add_u32_e32 v233, s0, v233
	ds_read_b64 v[128:129], v233 offset:0
	ds_read_b64 v[130:131], v233 offset:512
	ds_read_b64 v[132:133], v233 offset:1024
	ds_read_b64 v[134:135], v233 offset:1536
	ds_read_b64 v[136:137], v233 offset:2048
	ds_read_b64 v[138:139], v233 offset:2560
	ds_read_b64 v[140:141], v233 offset:3072
	ds_read_b64 v[142:143], v233 offset:3584
	ds_read_b64 v[144:145], v233 offset:4096
	ds_read_b64 v[146:147], v233 offset:4608
	ds_read_b64 v[148:149], v233 offset:5120
	ds_read_b64 v[150:151], v233 offset:5632
	ds_read_b64 v[152:153], v233 offset:6144
	ds_read_b64 v[154:155], v233 offset:6656
	ds_read_b64 v[156:157], v233 offset:7168
	ds_read_b64 v[158:159], v233 offset:7680
	v_mov_b32_e32 v220, 1
	v_lshrrev_b32_e32 v200, 4, v240
	v_lshrrev_b32_e32 v201, 3, v200
	v_and_b32_e32 v200, 7, v200
	s_add_i32 s3, s22, 4224
	s_and_b32 s1, s32, 7
	s_waitcnt lgkmcnt(0)
	v_lshrrev_b32_e32 v160, 11, v128
	v_subrev_u32_e32 v160, s1, v160
	v_and_b32_e32 v160, 7, v160
	v_lshl_add_u32 v176, v160, 2, s3
	v_lshrrev_b32_e32 v161, 11, v130
	v_subrev_u32_e32 v161, s1, v161
	v_and_b32_e32 v161, 7, v161
	v_lshl_add_u32 v177, v161, 2, s3
	v_lshrrev_b32_e32 v162, 11, v132
	v_subrev_u32_e32 v162, s1, v162
	v_and_b32_e32 v162, 7, v162
	v_lshl_add_u32 v178, v162, 2, s3
	v_lshrrev_b32_e32 v163, 11, v134
	v_subrev_u32_e32 v163, s1, v163
	v_and_b32_e32 v163, 7, v163
	v_lshl_add_u32 v179, v163, 2, s3
	v_lshrrev_b32_e32 v164, 11, v136
	v_subrev_u32_e32 v164, s1, v164
	v_and_b32_e32 v164, 7, v164
	v_lshl_add_u32 v180, v164, 2, s3
	v_lshrrev_b32_e32 v165, 11, v138
	v_subrev_u32_e32 v165, s1, v165
	v_and_b32_e32 v165, 7, v165
	v_lshl_add_u32 v181, v165, 2, s3
	v_lshrrev_b32_e32 v166, 11, v140
	v_subrev_u32_e32 v166, s1, v166
	v_and_b32_e32 v166, 7, v166
	v_lshl_add_u32 v182, v166, 2, s3
	v_lshrrev_b32_e32 v167, 11, v142
	v_subrev_u32_e32 v167, s1, v167
	v_and_b32_e32 v167, 7, v167
	v_lshl_add_u32 v183, v167, 2, s3
	v_lshrrev_b32_e32 v168, 11, v144
	v_subrev_u32_e32 v168, s1, v168
	v_and_b32_e32 v168, 7, v168
	v_lshl_add_u32 v184, v168, 2, s3
	v_lshrrev_b32_e32 v169, 11, v146
	v_subrev_u32_e32 v169, s1, v169
	v_and_b32_e32 v169, 7, v169
	v_lshl_add_u32 v185, v169, 2, s3
	v_lshrrev_b32_e32 v170, 11, v148
	v_subrev_u32_e32 v170, s1, v170
	v_and_b32_e32 v170, 7, v170
	v_lshl_add_u32 v186, v170, 2, s3
	v_lshrrev_b32_e32 v171, 11, v150
	v_subrev_u32_e32 v171, s1, v171
	v_and_b32_e32 v171, 7, v171
	v_lshl_add_u32 v187, v171, 2, s3
	v_lshrrev_b32_e32 v172, 11, v152
; __device__ __forceinline__ void peer_tile(const Args& A, LAS unsigned char* lds, int tile) {
;     ...
;     for (int ti = 0; ti < 8; ++ti) {
;         const int tl = 8 * w + ti;
;         const u32x2 e0 = SEL[tl * 128 + lane], e1 = SEL[tl * 128 + 64 + lane];
;         const int p0 = (int)(e0.x >> 10), p1 = (int)(e1.x >> 10);
;         int off = 0;
;         for (int p = 0; p < 16; ++p) {
;             const unsigned long long m0 = __ballot(p0 == p), m1 = __ballot(p1 == p);
;             const int c0 = __popcll(m0), c1 = __popcll(m1);
;             const int r0 = __builtin_amdgcn_mbcnt_hi((unsigned)(m0 >> 32), __builtin_amdgcn_mbcnt_lo((unsigned)m0, 0u));
;             const int r1 = __builtin_amdgcn_mbcnt_hi((unsigned)(m1 >> 32), __builtin_amdgcn_mbcnt_lo((unsigned)m1, 0u));
;             if (p0 == p) SORT[tl * 128 + off + r0] = e0;
;             if (p1 == p) SORT[tl * 128 + off + c0 + r1] = e1;
;             if (lane == 0) OFFS[tl * 17 + p] = off;
;             off += c0 + c1;
;         }
;         if (lane == 0) OFFS[tl * 17 + 16] = off;
	v_subrev_u32_e32 v172, s1, v172
	v_and_b32_e32 v172, 7, v172
	v_lshl_add_u32 v188, v172, 2, s3
	v_lshrrev_b32_e32 v173, 11, v154
	v_subrev_u32_e32 v173, s1, v173
	v_and_b32_e32 v173, 7, v173
	v_lshl_add_u32 v189, v173, 2, s3
	v_lshrrev_b32_e32 v174, 11, v156
	v_subrev_u32_e32 v174, s1, v174
	v_and_b32_e32 v174, 7, v174
	v_lshl_add_u32 v190, v174, 2, s3
	v_lshrrev_b32_e32 v175, 11, v158
	v_subrev_u32_e32 v175, s1, v175
	v_and_b32_e32 v175, 7, v175
	v_lshl_add_u32 v191, v175, 2, s3
	v_lshlrev_b32_e32 v206, 3, v128
	buffer_load_dwordx2 v[224:225], v206, s[24:27], 0 offen
	v_lshlrev_b32_e32 v206, 3, v130
	buffer_load_dwordx2 v[226:227], v206, s[24:27], 0 offen
	v_lshlrev_b32_e32 v206, 3, v132
	buffer_load_dwordx2 v[228:229], v206, s[24:27], 0 offen
	v_lshlrev_b32_e32 v206, 3, v134
	buffer_load_dwordx2 v[230:231], v206, s[24:27], 0 offen
	v_lshlrev_b32_e32 v206, 3, v136
	buffer_load_dwordx2 v[232:233], v206, s[24:27], 0 offen
	v_lshlrev_b32_e32 v206, 3, v138
	buffer_load_dwordx2 v[234:235], v206, s[24:27], 0 offen
	v_lshlrev_b32_e32 v206, 3, v140
	buffer_load_dwordx2 v[236:237], v206, s[24:27], 0 offen
	v_lshlrev_b32_e32 v206, 3, v142
	buffer_load_dwordx2 v[238:239], v206, s[24:27], 0 offen
	v_lshlrev_b32_e32 v206, 3, v144
	buffer_load_dwordx2 v[248:249], v206, s[24:27], 0 offen
	v_lshlrev_b32_e32 v206, 3, v146
	buffer_load_dwordx2 v[250:251], v206, s[24:27], 0 offen
	v_lshlrev_b32_e32 v206, 3, v148
	buffer_load_dwordx2 v[252:253], v206, s[24:27], 0 offen
	v_lshlrev_b32_e32 v206, 3, v150
	buffer_load_dwordx2 v[254:255], v206, s[24:27], 0 offen
	ds_add_rtn_u32 v176, v176, v220 offset:0
	ds_add_rtn_u32 v177, v177, v220 offset:0
	ds_add_rtn_u32 v178, v178, v220 offset:32
	ds_add_rtn_u32 v179, v179, v220 offset:32
	ds_add_rtn_u32 v180, v180, v220 offset:64
	ds_add_rtn_u32 v181, v181, v220 offset:64
	ds_add_rtn_u32 v182, v182, v220 offset:96
	ds_add_rtn_u32 v183, v183, v220 offset:96
	ds_add_rtn_u32 v184, v184, v220 offset:128
	ds_add_rtn_u32 v185, v185, v220 offset:128
	ds_add_rtn_u32 v186, v186, v220 offset:160
	ds_add_rtn_u32 v187, v187, v220 offset:160
	ds_add_rtn_u32 v188, v188, v220 offset:192
	ds_add_rtn_u32 v189, v189, v220 offset:192
	ds_add_rtn_u32 v190, v190, v220 offset:224
	ds_add_rtn_u32 v191, v191, v220 offset:224
	v_lshl_add_u32 v207, v201, 5, s3
	ds_read_b32 v203, v221 offset:4224
	ds_read_b128 v[192:195], v207
	ds_read_b128 v[196:199], v207 offset:16
	v_mov_b32_e32 v202, 0
	s_waitcnt lgkmcnt(0)
	v_cmp_lt_u32_e64 s[38:39], 0, v200
	v_cmp_lt_u32_e64 s[40:41], 1, v200
	v_cmp_lt_u32_e64 s[42:43], 2, v200
	v_cmp_lt_u32_e64 s[44:45], 3, v200
	v_cmp_lt_u32_e64 s[64:65], 4, v200
	v_cmp_lt_u32_e64 s[66:67], 5, v200
	v_cmp_lt_u32_e64 s[94:95], 6, v200
	v_cndmask_b32_e64 v206, 0, v192, s[38:39]
	v_add_u32_e32 v202, v202, v206
	v_cndmask_b32_e64 v206, 0, v193, s[40:41]
	v_add_u32_e32 v202, v202, v206
	v_cndmask_b32_e64 v206, 0, v194, s[42:43]
	v_add_u32_e32 v202, v202, v206
	v_cndmask_b32_e64 v206, 0, v195, s[44:45]
	v_add_u32_e32 v202, v202, v206
	v_cndmask_b32_e64 v206, 0, v196, s[64:65]
	v_add_u32_e32 v202, v202, v206
	v_cndmask_b32_e64 v206, 0, v197, s[66:67]
	v_add_u32_e32 v202, v202, v206
	v_cndmask_b32_e64 v206, 0, v198, s[94:95]
	v_add_u32_e32 v202, v202, v206
	v_add_u32_e32 v204, 3, v202
	v_add3_u32 v212, v202, v203, 3
	v_lshrrev_b32_e32 v204, 2, v204
	v_lshrrev_b32_e32 v212, 2, v212
	v_sub_u32_e32 v212, v212, v204
	v_lshl_add_u32 v207, v200, 3, v201
	v_lshl_add_u32 v207, v207, 2, s3
	ds_write_b32 v207, v212 offset:256
	v_lshl_add_u32 v208, v200, 5, s3
	ds_read_b128 v[192:195], v208 offset:256
	ds_read_b128 v[196:199], v208 offset:272
	v_mov_b32_e32 v205, 0
	s_waitcnt lgkmcnt(0)
	v_cmp_lt_u32_e64 s[38:39], 0, v201
	v_cmp_lt_u32_e64 s[40:41], 1, v201
	v_cmp_lt_u32_e64 s[42:43], 2, v201
	v_cmp_lt_u32_e64 s[44:45], 3, v201
	v_cmp_lt_u32_e64 s[64:65], 4, v201
	v_cmp_lt_u32_e64 s[66:67], 5, v201
	v_cmp_lt_u32_e64 s[94:95], 6, v201
	v_cndmask_b32_e64 v206, 0, v192, s[38:39]
	v_add_u32_e32 v205, v205, v206
	v_cndmask_b32_e64 v206, 0, v193, s[40:41]
	v_add_u32_e32 v205, v205, v206
	v_cndmask_b32_e64 v206, 0, v194, s[42:43]
	v_add_u32_e32 v205, v205, v206
	v_cndmask_b32_e64 v206, 0, v195, s[44:45]
	v_add_u32_e32 v205, v205, v206
	v_cndmask_b32_e64 v206, 0, v196, s[64:65]
	v_add_u32_e32 v205, v205, v206
	v_cndmask_b32_e64 v206, 0, v197, s[66:67]
	v_add_u32_e32 v205, v205, v206
	v_cndmask_b32_e64 v206, 0, v198, s[94:95]
	v_add_u32_e32 v205, v205, v206
	v_add_u32_e32 v206, v192, v193
	v_add_u32_e32 v206, v206, v194
	v_add_u32_e32 v206, v206, v195
	v_add_u32_e32 v206, v206, v196
	v_add_u32_e32 v206, v206, v197
	v_add_u32_e32 v206, v206, v198
	v_add_u32_e32 v206, v206, v199
	v_lshl_add_u32 v207, v200, 2, s3
	ds_write_b32 v207, v206 offset:512
	v_mov_b32_e32 v207, s3
	ds_read_b128 v[192:195], v207 offset:512
	ds_read_b128 v[196:199], v207 offset:528
	ds_write_b32 v221, v202 offset:4224
	s_waitcnt lgkmcnt(0)
	v_cmp_lt_u32_e64 s[38:39], 0, v200
	v_cmp_lt_u32_e64 s[40:41], 1, v200
	v_cmp_lt_u32_e64 s[42:43], 2, v200
	v_cmp_lt_u32_e64 s[44:45], 3, v200
	v_cmp_lt_u32_e64 s[64:65], 4, v200
	v_cmp_lt_u32_e64 s[66:67], 5, v200
	v_cmp_lt_u32_e64 s[94:95], 6, v200
	v_cndmask_b32_e64 v206, 0, v192, s[38:39]
	v_add_u32_e32 v205, v205, v206
	v_cndmask_b32_e64 v206, 0, v193, s[40:41]
	v_add_u32_e32 v205, v205, v206
	v_cndmask_b32_e64 v206, 0, v194, s[42:43]
	v_add_u32_e32 v205, v205, v206
	v_cndmask_b32_e64 v206, 0, v195, s[44:45]
	v_add_u32_e32 v205, v205, v206
	v_cndmask_b32_e64 v206, 0, v196, s[64:65]
	v_add_u32_e32 v205, v205, v206
	v_cndmask_b32_e64 v206, 0, v197, s[66:67]
	v_add_u32_e32 v205, v205, v206
	v_cndmask_b32_e64 v206, 0, v198, s[94:95]
	v_add_u32_e32 v205, v205, v206
	v_sub_u32_e32 v205, v205, v204
	v_lshrrev_b32_e32 v208, 4, v240
	v_and_b32_e32 v222, 31, v208
	v_lshrrev_b32_e32 v208, 5, v208
	v_add_u32_e32 v207, 0, v208
	v_lshl_add_u32 v206, v207, 5, s3
	ds_read_b128 v[192:195], v206
	ds_read_b128 v[196:199], v206 offset:16
	v_lshlrev_b32_e32 v206, 2, v222
	v_lshlrev_b32_e32 v223, 3, v207
	s_waitcnt lgkmcnt(0)
; __device__ __forceinline__ void peer_tile(const Args& A, LAS unsigned char* lds, int tile) {
;     ...
;     for (int ti = 0; ti < 8; ++ti) {
;         const int tl = 8 * w + ti;
;         const u32x2 e0 = SEL[tl * 128 + lane], e1 = SEL[tl * 128 + 64 + lane];
;         const int p0 = (int)(e0.x >> 10), p1 = (int)(e1.x >> 10);
;         int off = 0;
;         for (int p = 0; p < 16; ++p) {
;             const unsigned long long m0 = __ballot(p0 == p), m1 = __ballot(p1 == p);
;             const int c0 = __popcll(m0), c1 = __popcll(m1);
;             const int r0 = __builtin_amdgcn_mbcnt_hi((unsigned)(m0 >> 32), __builtin_amdgcn_mbcnt_lo((unsigned)m0, 0u));
;             const int r1 = __builtin_amdgcn_mbcnt_hi((unsigned)(m1 >> 32), __builtin_amdgcn_mbcnt_lo((unsigned)m1, 0u));
;             if (p0 == p) SORT[tl * 128 + off + r0] = e0;
;             if (p1 == p) SORT[tl * 128 + off + c0 + r1] = e1;
;             if (lane == 0) OFFS[tl * 17 + p] = off;
;             off += c0 + c1;
;         }
;         if (lane == 0) OFFS[tl * 17 + 16] = off;
	v_cmp_le_u32_e64 s[38:39], v193, v206
	v_cmp_le_u32_e64 s[40:41], v194, v206
	v_cmp_le_u32_e64 s[42:43], v195, v206
	v_cmp_le_u32_e64 s[44:45], v196, v206
	v_cmp_le_u32_e64 s[64:65], v197, v206
	v_cmp_le_u32_e64 s[66:67], v198, v206
	v_cmp_le_u32_e64 s[94:95], v199, v206
	v_addc_co_u32_e64 v223, s[92:93], 0, v223, s[38:39]
	v_addc_co_u32_e64 v223, s[92:93], 0, v223, s[40:41]
	v_addc_co_u32_e64 v223, s[92:93], 0, v223, s[42:43]
	v_addc_co_u32_e64 v223, s[92:93], 0, v223, s[44:45]
	v_addc_co_u32_e64 v223, s[92:93], 0, v223, s[64:65]
	v_addc_co_u32_e64 v223, s[92:93], 0, v223, s[66:67]
	v_addc_co_u32_e64 v223, s[92:93], 0, v223, s[94:95]
	v_lshlrev_b32_e32 v223, 2, v223
	ds_bpermute_b32 v216, v223, v205
	v_add_u32_e32 v207, 2, v208
	v_lshl_add_u32 v206, v207, 5, s3
	ds_read_b128 v[192:195], v206
	ds_read_b128 v[196:199], v206 offset:16
	v_lshlrev_b32_e32 v206, 2, v222
	v_lshlrev_b32_e32 v223, 3, v207
	s_waitcnt lgkmcnt(0)
	v_cmp_le_u32_e64 s[38:39], v193, v206
	v_cmp_le_u32_e64 s[40:41], v194, v206
	v_cmp_le_u32_e64 s[42:43], v195, v206
	v_cmp_le_u32_e64 s[44:45], v196, v206
	v_cmp_le_u32_e64 s[64:65], v197, v206
	v_cmp_le_u32_e64 s[66:67], v198, v206
	v_cmp_le_u32_e64 s[94:95], v199, v206
	v_addc_co_u32_e64 v223, s[92:93], 0, v223, s[38:39]
	v_addc_co_u32_e64 v223, s[92:93], 0, v223, s[40:41]
	v_addc_co_u32_e64 v223, s[92:93], 0, v223, s[42:43]
	v_addc_co_u32_e64 v223, s[92:93], 0, v223, s[44:45]
	v_addc_co_u32_e64 v223, s[92:93], 0, v223, s[64:65]
	v_addc_co_u32_e64 v223, s[92:93], 0, v223, s[66:67]
	v_addc_co_u32_e64 v223, s[92:93], 0, v223, s[94:95]
	v_lshlrev_b32_e32 v223, 2, v223
	ds_bpermute_b32 v217, v223, v205
	v_add_u32_e32 v207, 4, v208
	v_lshl_add_u32 v206, v207, 5, s3
	ds_read_b128 v[192:195], v206
	ds_read_b128 v[196:199], v206 offset:16
	v_lshlrev_b32_e32 v206, 2, v222
	v_lshlrev_b32_e32 v223, 3, v207
	s_waitcnt lgkmcnt(0)
	v_cmp_le_u32_e64 s[38:39], v193, v206
	v_cmp_le_u32_e64 s[40:41], v194, v206
	v_cmp_le_u32_e64 s[42:43], v195, v206
	v_cmp_le_u32_e64 s[44:45], v196, v206
	v_cmp_le_u32_e64 s[64:65], v197, v206
	v_cmp_le_u32_e64 s[66:67], v198, v206
	v_cmp_le_u32_e64 s[94:95], v199, v206
	v_addc_co_u32_e64 v223, s[92:93], 0, v223, s[38:39]
	v_addc_co_u32_e64 v223, s[92:93], 0, v223, s[40:41]
	v_addc_co_u32_e64 v223, s[92:93], 0, v223, s[42:43]
	v_addc_co_u32_e64 v223, s[92:93], 0, v223, s[44:45]
	v_addc_co_u32_e64 v223, s[92:93], 0, v223, s[64:65]
	v_addc_co_u32_e64 v223, s[92:93], 0, v223, s[66:67]
	v_addc_co_u32_e64 v223, s[92:93], 0, v223, s[94:95]
	v_lshlrev_b32_e32 v223, 2, v223
	ds_bpermute_b32 v218, v223, v205
	v_add_u32_e32 v207, 6, v208
	v_lshl_add_u32 v206, v207, 5, s3
	ds_read_b128 v[192:195], v206
	ds_read_b128 v[196:199], v206 offset:16
	v_lshlrev_b32_e32 v206, 2, v222
	v_lshlrev_b32_e32 v223, 3, v207
	s_waitcnt lgkmcnt(0)
	v_cmp_le_u32_e64 s[38:39], v193, v206
	v_cmp_le_u32_e64 s[40:41], v194, v206
	v_cmp_le_u32_e64 s[42:43], v195, v206
	v_cmp_le_u32_e64 s[44:45], v196, v206
	v_cmp_le_u32_e64 s[64:65], v197, v206
	v_cmp_le_u32_e64 s[66:67], v198, v206
	v_cmp_le_u32_e64 s[94:95], v199, v206
	v_addc_co_u32_e64 v223, s[92:93], 0, v223, s[38:39]
	v_addc_co_u32_e64 v223, s[92:93], 0, v223, s[40:41]
	v_addc_co_u32_e64 v223, s[92:93], 0, v223, s[42:43]
	v_addc_co_u32_e64 v223, s[92:93], 0, v223, s[44:45]
	v_addc_co_u32_e64 v223, s[92:93], 0, v223, s[64:65]
	v_addc_co_u32_e64 v223, s[92:93], 0, v223, s[66:67]
	v_addc_co_u32_e64 v223, s[92:93], 0, v223, s[94:95]
	v_lshlrev_b32_e32 v223, 2, v223
	ds_bpermute_b32 v219, v223, v205
	s_waitcnt lgkmcnt(0)
	v_add_u32_e32 v216, v216, v222
	v_add_u32_e32 v217, v217, v222
	v_add_u32_e32 v218, v218, v222
	v_add_u32_e32 v219, v219, v222
	v_lshlrev_b32_e32 v206, 3, v152
	buffer_load_dwordx2 v[192:193], v206, s[24:27], 0 offen
	v_lshlrev_b32_e32 v206, 3, v154
	buffer_load_dwordx2 v[194:195], v206, s[24:27], 0 offen
	v_lshlrev_b32_e32 v206, 3, v156
	buffer_load_dwordx2 v[196:197], v206, s[24:27], 0 offen
	v_lshlrev_b32_e32 v206, 3, v158
	buffer_load_dwordx2 v[198:199], v206, s[24:27], 0 offen
	v_lshlrev_b32_e32 v160, 2, v160
	ds_bpermute_b32 v160, v160, v202
	v_lshlrev_b32_e32 v161, 2, v161
	ds_bpermute_b32 v161, v161, v202
	v_lshlrev_b32_e32 v162, 2, v162
	v_add_u32_e32 v162, 32, v162
	ds_bpermute_b32 v162, v162, v202
	v_lshlrev_b32_e32 v163, 2, v163
	v_add_u32_e32 v163, 32, v163
	ds_bpermute_b32 v163, v163, v202
	v_lshlrev_b32_e32 v164, 2, v164
	v_add_u32_e32 v164, 64, v164
	ds_bpermute_b32 v164, v164, v202
	v_lshlrev_b32_e32 v165, 2, v165
	v_add_u32_e32 v165, 64, v165
	ds_bpermute_b32 v165, v165, v202
	v_lshlrev_b32_e32 v166, 2, v166
	v_add_u32_e32 v166, 96, v166
	ds_bpermute_b32 v166, v166, v202
	v_lshlrev_b32_e32 v167, 2, v167
	v_add_u32_e32 v167, 96, v167
	ds_bpermute_b32 v167, v167, v202
	v_lshlrev_b32_e32 v168, 2, v168
	v_add_u32_e32 v168, 128, v168
	ds_bpermute_b32 v168, v168, v202
	v_lshlrev_b32_e32 v169, 2, v169
	v_add_u32_e32 v169, 128, v169
	ds_bpermute_b32 v169, v169, v202
	v_lshlrev_b32_e32 v170, 2, v170
	v_add_u32_e32 v170, 160, v170
	ds_bpermute_b32 v170, v170, v202
	v_lshlrev_b32_e32 v171, 2, v171
	v_add_u32_e32 v171, 160, v171
	ds_bpermute_b32 v171, v171, v202
	v_lshlrev_b32_e32 v172, 2, v172
	v_add_u32_e32 v172, 192, v172
	ds_bpermute_b32 v172, v172, v202
	v_lshlrev_b32_e32 v173, 2, v173
	v_add_u32_e32 v173, 192, v173
	ds_bpermute_b32 v173, v173, v202
	v_lshlrev_b32_e32 v174, 2, v174
	v_add_u32_e32 v174, 224, v174
	ds_bpermute_b32 v174, v174, v202
	v_lshlrev_b32_e32 v175, 2, v175
	v_add_u32_e32 v175, 224, v175
	ds_bpermute_b32 v175, v175, v202
	s_waitcnt lgkmcnt(0)
; __device__ __forceinline__ void peer_tile(const Args& A, LAS unsigned char* lds, int tile) {
;     ...
;     for (int ti = 0; ti < 8; ++ti) {
;         const int tl = 8 * w + ti;
;         const u32x2 e0 = SEL[tl * 128 + lane], e1 = SEL[tl * 128 + 64 + lane];
;         const int p0 = (int)(e0.x >> 10), p1 = (int)(e1.x >> 10);
;         int off = 0;
;         for (int p = 0; p < 16; ++p) {
;             const unsigned long long m0 = __ballot(p0 == p), m1 = __ballot(p1 == p);
;             const int c0 = __popcll(m0), c1 = __popcll(m1);
;             const int r0 = __builtin_amdgcn_mbcnt_hi((unsigned)(m0 >> 32), __builtin_amdgcn_mbcnt_lo((unsigned)m0, 0u));
;             const int r1 = __builtin_amdgcn_mbcnt_hi((unsigned)(m1 >> 32), __builtin_amdgcn_mbcnt_lo((unsigned)m1, 0u));
;             if (p0 == p) SORT[tl * 128 + off + r0] = e0;
;             if (p1 == p) SORT[tl * 128 + off + c0 + r1] = e1;
;             if (lane == 0) OFFS[tl * 17 + p] = off;
;             off += c0 + c1;
;         }
;         if (lane == 0) OFFS[tl * 17 + 16] = off;
;     }
	v_add_u32_e32 v176, v176, v160
	v_lshrrev_b32_e32 v160, 2, v176
	v_and_b32_e32 v176, 3, v176
	v_lshlrev_b32_e32 v160, 2, v160
	ds_bpermute_b32 v160, v160, v216
	v_add_u32_e32 v177, v177, v161
	v_lshrrev_b32_e32 v161, 2, v177
	v_and_b32_e32 v177, 3, v177
	v_lshlrev_b32_e32 v161, 2, v161
	ds_bpermute_b32 v161, v161, v216
	v_add_u32_e32 v178, v178, v162
	v_lshrrev_b32_e32 v162, 2, v178
	v_and_b32_e32 v178, 3, v178
	v_lshlrev_b32_e32 v162, 2, v162
	v_add_u32_e32 v162, 128, v162
	ds_bpermute_b32 v162, v162, v216
	v_add_u32_e32 v179, v179, v163
	v_lshrrev_b32_e32 v163, 2, v179
	v_and_b32_e32 v179, 3, v179
	v_lshlrev_b32_e32 v163, 2, v163
	v_add_u32_e32 v163, 128, v163
	ds_bpermute_b32 v163, v163, v216
	v_add_u32_e32 v180, v180, v164
	v_lshrrev_b32_e32 v164, 2, v180
	v_and_b32_e32 v180, 3, v180
	v_lshlrev_b32_e32 v164, 2, v164
	ds_bpermute_b32 v164, v164, v217
	v_add_u32_e32 v181, v181, v165
	v_lshrrev_b32_e32 v165, 2, v181
	v_and_b32_e32 v181, 3, v181
	v_lshlrev_b32_e32 v165, 2, v165
	ds_bpermute_b32 v165, v165, v217
	v_add_u32_e32 v182, v182, v166
	v_lshrrev_b32_e32 v166, 2, v182
	v_and_b32_e32 v182, 3, v182
	v_lshlrev_b32_e32 v166, 2, v166
	v_add_u32_e32 v166, 128, v166
	ds_bpermute_b32 v166, v166, v217
	v_add_u32_e32 v183, v183, v167
	v_lshrrev_b32_e32 v167, 2, v183
	v_and_b32_e32 v183, 3, v183
	v_lshlrev_b32_e32 v167, 2, v167
	v_add_u32_e32 v167, 128, v167
	ds_bpermute_b32 v167, v167, v217
	v_add_u32_e32 v184, v184, v168
	v_lshrrev_b32_e32 v168, 2, v184
	v_and_b32_e32 v184, 3, v184
	v_lshlrev_b32_e32 v168, 2, v168
	ds_bpermute_b32 v168, v168, v218
	v_add_u32_e32 v185, v185, v169
	v_lshrrev_b32_e32 v169, 2, v185
	v_and_b32_e32 v185, 3, v185
	v_lshlrev_b32_e32 v169, 2, v169
	ds_bpermute_b32 v169, v169, v218
	v_add_u32_e32 v186, v186, v170
	v_lshrrev_b32_e32 v170, 2, v186
	v_and_b32_e32 v186, 3, v186
	v_lshlrev_b32_e32 v170, 2, v170
	v_add_u32_e32 v170, 128, v170
	ds_bpermute_b32 v170, v170, v218
	v_add_u32_e32 v187, v187, v171
	v_lshrrev_b32_e32 v171, 2, v187
	v_and_b32_e32 v187, 3, v187
	v_lshlrev_b32_e32 v171, 2, v171
	v_add_u32_e32 v171, 128, v171
	ds_bpermute_b32 v171, v171, v218
	v_add_u32_e32 v188, v188, v172
	v_lshrrev_b32_e32 v172, 2, v188
	v_and_b32_e32 v188, 3, v188
	v_lshlrev_b32_e32 v172, 2, v172
	ds_bpermute_b32 v172, v172, v219
	v_add_u32_e32 v189, v189, v173
	v_lshrrev_b32_e32 v173, 2, v189
	v_and_b32_e32 v189, 3, v189
	v_lshlrev_b32_e32 v173, 2, v173
	ds_bpermute_b32 v173, v173, v219
	v_add_u32_e32 v190, v190, v174
	v_lshrrev_b32_e32 v174, 2, v190
	v_and_b32_e32 v190, 3, v190
	v_lshlrev_b32_e32 v174, 2, v174
	v_add_u32_e32 v174, 128, v174
	ds_bpermute_b32 v174, v174, v219
	v_add_u32_e32 v191, v191, v175
	v_lshrrev_b32_e32 v175, 2, v191
	v_and_b32_e32 v191, 3, v191
	v_lshlrev_b32_e32 v175, 2, v175
	v_add_u32_e32 v175, 128, v175
	ds_bpermute_b32 v175, v175, v219
	s_waitcnt lgkmcnt(0)
	v_lshl_add_u32 v160, v160, 4, s22
	v_lshl_add_u32 v160, v176, 2, v160
	ds_write_b32 v160, v128
	ds_write_b32 v160, v129 offset:4992
	v_lshl_add_u32 v161, v161, 4, s22
	v_lshl_add_u32 v161, v177, 2, v161
	ds_write_b32 v161, v130
	ds_write_b32 v161, v131 offset:4992
	v_lshl_add_u32 v162, v162, 4, s22
	v_lshl_add_u32 v162, v178, 2, v162
	ds_write_b32 v162, v132
	ds_write_b32 v162, v133 offset:4992
	v_lshl_add_u32 v163, v163, 4, s22
	v_lshl_add_u32 v163, v179, 2, v163
	ds_write_b32 v163, v134
	ds_write_b32 v163, v135 offset:4992
	v_lshl_add_u32 v164, v164, 4, s22
	v_lshl_add_u32 v164, v180, 2, v164
	ds_write_b32 v164, v136
	ds_write_b32 v164, v137 offset:4992
	v_lshl_add_u32 v165, v165, 4, s22
	v_lshl_add_u32 v165, v181, 2, v165
	ds_write_b32 v165, v138
	ds_write_b32 v165, v139 offset:4992
	v_lshl_add_u32 v166, v166, 4, s22
	v_lshl_add_u32 v166, v182, 2, v166
	ds_write_b32 v166, v140
	ds_write_b32 v166, v141 offset:4992
	v_lshl_add_u32 v167, v167, 4, s22
	v_lshl_add_u32 v167, v183, 2, v167
	ds_write_b32 v167, v142
	ds_write_b32 v167, v143 offset:4992
	v_lshl_add_u32 v168, v168, 4, s22
	v_lshl_add_u32 v168, v184, 2, v168
	ds_write_b32 v168, v144
	ds_write_b32 v168, v145 offset:4992
	v_lshl_add_u32 v169, v169, 4, s22
	v_lshl_add_u32 v169, v185, 2, v169
	ds_write_b32 v169, v146
	ds_write_b32 v169, v147 offset:4992
	v_lshl_add_u32 v170, v170, 4, s22
	v_lshl_add_u32 v170, v186, 2, v170
	ds_write_b32 v170, v148
	ds_write_b32 v170, v149 offset:4992
	v_lshl_add_u32 v171, v171, 4, s22
	v_lshl_add_u32 v171, v187, 2, v171
	ds_write_b32 v171, v150
	ds_write_b32 v171, v151 offset:4992
	v_lshl_add_u32 v172, v172, 4, s22
	v_lshl_add_u32 v172, v188, 2, v172
	ds_write_b32 v172, v152
	ds_write_b32 v172, v153 offset:4992
	v_lshl_add_u32 v173, v173, 4, s22
	v_lshl_add_u32 v173, v189, 2, v173
	ds_write_b32 v173, v154
	ds_write_b32 v173, v155 offset:4992
	v_lshl_add_u32 v174, v174, 4, s22
	v_lshl_add_u32 v174, v190, 2, v174
	ds_write_b32 v174, v156
	ds_write_b32 v174, v157 offset:4992
	v_lshl_add_u32 v175, v175, 4, s22
	v_lshl_add_u32 v175, v191, 2, v175
	ds_write_b32 v175, v158
	ds_write_b32 v175, v159 offset:4992
	s_waitcnt vmcnt(0)
; #define IT_ADVANCE() do { it_j += 4; while (it_j >= it_end) { if (it_done) break; ++it_tk; if (it_tk == 4) { it_tk = 0; ++it_p; if (it_p == 16) { it_done = true; it_p = 15; it_j = 0; it_end = 1; break; } } \
;             it_j = __builtin_amdgcn_readfirstlane(OFFS[(tb + it_tk) * 17 + it_p]); it_end = __builtin_amdgcn_readfirstlane(OFFS[(tb + it_tk) * 17 + it_p + 1]); } } while (0)
; __device__ __forceinline__ void peer_tile(const Args& A, LAS unsigned char* lds, int tile) {
;     ...
;         int it_p = 0, it_tk = -1, it_j = 0, it_end = 0; bool it_done = false;
;     ...
;         u32x4 uA[4], vA[4], uB[4], vB[4]; float cgA = 0.f, suA = 0.f, svA = 0.f, cgB = 0.f, suB = 0.f, svB = 0.f;
; #pragma unroll
;         for (int k = 0; k < 4; ++k) { uA[k] = (u32x4){0u, 0u, 0u, 0u}; vA[k] = uA[k]; uB[k] = uA[k]; vB[k] = uA[k]; }
;         IT_ADVANCE();
;         LOAD_SET(uA, vA, cgA, suA, svA);
	v_add_u32_e32 v160, s85, v160
	ds_write_b32 v160, v224
	ds_write_b32 v160, v225 offset:4096
	v_add_u32_e32 v161, s85, v161
	ds_write_b32 v161, v226
	ds_write_b32 v161, v227 offset:4096
	v_add_u32_e32 v162, s85, v162
	ds_write_b32 v162, v228
	ds_write_b32 v162, v229 offset:4096
	v_add_u32_e32 v163, s85, v163
	ds_write_b32 v163, v230
	ds_write_b32 v163, v231 offset:4096
	v_add_u32_e32 v164, s85, v164
	ds_write_b32 v164, v232
	ds_write_b32 v164, v233 offset:4096
	v_add_u32_e32 v165, s85, v165
	ds_write_b32 v165, v234
	ds_write_b32 v165, v235 offset:4096
	v_add_u32_e32 v166, s85, v166
	ds_write_b32 v166, v236
	ds_write_b32 v166, v237 offset:4096
	v_add_u32_e32 v167, s85, v167
	ds_write_b32 v167, v238
	ds_write_b32 v167, v239 offset:4096
	v_add_u32_e32 v168, s85, v168
	ds_write_b32 v168, v248
	ds_write_b32 v168, v249 offset:4096
	v_add_u32_e32 v169, s85, v169
	ds_write_b32 v169, v250
	ds_write_b32 v169, v251 offset:4096
	v_add_u32_e32 v170, s85, v170
	ds_write_b32 v170, v252
	ds_write_b32 v170, v253 offset:4096
	v_add_u32_e32 v171, s85, v171
	ds_write_b32 v171, v254
	ds_write_b32 v171, v255 offset:4096
	v_add_u32_e32 v172, s85, v172
	ds_write_b32 v172, v192
	ds_write_b32 v172, v193 offset:4096
	v_add_u32_e32 v173, s85, v173
	ds_write_b32 v173, v194
	ds_write_b32 v173, v195 offset:4096
	v_add_u32_e32 v174, s85, v174
	ds_write_b32 v174, v196
	ds_write_b32 v174, v197 offset:4096
	v_add_u32_e32 v175, s85, v175
	ds_write_b32 v175, v198
	ds_write_b32 v175, v199 offset:4096
	v_mov_b32_e32 v206, 0x7fffffff
	ds_write_b32 v221, v206 offset:4224
	ds_write_b32 v221, v206 offset:4480
	ds_write_b32 v221, v206 offset:4736
	s_mov_b64 exec, 0xfff
	ds_read_b32 v206, v221
	s_waitcnt lgkmcnt(0)
	v_add_u32_e32 v206, 0x4000, v206
	ds_write_b32 v221, v206 offset:4096
	s_mov_b64 exec, -1
	s_mov_b32 s91, 256
	s_add_i32 s20, s91, 3
	s_and_b32 s20, s20, -4
	s_mov_b32 s24, s8
	s_and_b32 s25, s9, 0xffff
	s_mov_b32 s26, 0x20000
	s_mov_b32 s27, 0x00027000
	s_mov_b32 s28, s52
	s_and_b32 s29, s53, 0xffff
	s_mov_b32 s30, 0x20000
	s_mov_b32 s31, 0x00027000
	s_waitcnt vmcnt(0) lgkmcnt(0)
	v_mov_b32_e32 v213, s22
	v_mov_b32_e32 v233, v240
	v_mov_b32_e32 v235, v240
	v_mov_b32_e32 v237, v240
	v_mov_b32_e32 v239, v240
	ds_read_b32 v232, v213 offset:0
	ds_read_b32 v234, v213 offset:4
	ds_read_b32 v236, v213 offset:8
	ds_read_b32 v238, v213 offset:12
	s_waitcnt lgkmcnt(0)
	buffer_load_dwordx4 v[128:131], v[232:233], s[56:59], 0 idxen offen
	buffer_load_dwordx4 v[132:135], v[234:235], s[56:59], 0 idxen offen
	buffer_load_dwordx4 v[136:139], v[236:237], s[56:59], 0 idxen offen
	buffer_load_dwordx4 v[140:143], v[238:239], s[56:59], 0 idxen offen
	ds_read_b32 v232, v213 offset:16
	ds_read_b32 v234, v213 offset:20
	ds_read_b32 v236, v213 offset:24
	ds_read_b32 v238, v213 offset:28
	s_waitcnt lgkmcnt(0)
	buffer_load_dwordx4 v[144:147], v[232:233], s[56:59], 0 idxen offen
	buffer_load_dwordx4 v[148:151], v[234:235], s[56:59], 0 idxen offen
	buffer_load_dwordx4 v[152:155], v[236:237], s[56:59], 0 idxen offen
	buffer_load_dwordx4 v[156:159], v[238:239], s[56:59], 0 idxen offen
	ds_read_b32 v232, v213 offset:32
	ds_read_b32 v234, v213 offset:36
	ds_read_b32 v236, v213 offset:40
	ds_read_b32 v238, v213 offset:44
	s_waitcnt lgkmcnt(0)
	buffer_load_dwordx4 v[160:163], v[232:233], s[56:59], 0 idxen offen
	buffer_load_dwordx4 v[164:167], v[234:235], s[56:59], 0 idxen offen
	buffer_load_dwordx4 v[168:171], v[236:237], s[56:59], 0 idxen offen
	buffer_load_dwordx4 v[172:175], v[238:239], s[56:59], 0 idxen offen
	ds_read_b32 v232, v213 offset:48
	ds_read_b32 v234, v213 offset:52
	ds_read_b32 v236, v213 offset:56
	ds_read_b32 v238, v213 offset:60
	s_mov_b32 s21, 0
	s_mov_b32 s89, -1
	s_mov_b32 s86, 0
	v_lshrrev_b32_e32 v208, 6, v240
	v_and_b32_e32 v208, 3, v208
	v_lshrrev_b32_e32 v209, 1, v208
	v_lshlrev_b32_e32 v208, 1, v208
	v_and_b32_e32 v208, 2, v208
	v_or_b32_e32 v208, v208, v209
	v_lshlrev_b32_e32 v208, 2, v208
	v_add3_u32 v211, v208, v247, s22
	v_add_u32_e32 v250, s85, v211
	ds_read_b32 v252, v250
	ds_read_b32 v253, v250 offset:4096
	ds_read_b32 v249, v211 offset:4992
	s_branch .LU_sw0

; #define IT_ADVANCE() do { it_j += 4; while (it_j >= it_end) { if (it_done) break; ++it_tk; if (it_tk == 4) { it_tk = 0; ++it_p; if (it_p == 16) { it_done = true; it_p = 15; it_j = 0; it_end = 1; break; } } \
;             it_j = __builtin_amdgcn_readfirstlane(OFFS[(tb + it_tk) * 17 + it_p]); it_end = __builtin_amdgcn_readfirstlane(OFFS[(tb + it_tk) * 17 + it_p + 1]); } } while (0)
; __device__ __forceinline__ void peer_tile(const Args& A, LAS unsigned char* lds, int tile) {
;     ...
;             for (int q = 0; q < 8; ++q) oacc[tk][q] = (f32x2){0.f, 0.f}; }
;         int it_p = 0, it_tk = -1, it_j = 0, it_end = 0; bool it_done = false;
;     ...
;         u32x4 uA[4], vA[4], uB[4], vB[4]; float cgA = 0.f, suA = 0.f, svA = 0.f, cgB = 0.f, suB = 0.f, svB = 0.f;
; #pragma unroll
;         for (int k = 0; k < 4; ++k) { uA[k] = (u32x4){0u, 0u, 0u, 0u}; vA[k] = uA[k]; uB[k] = uA[k]; vB[k] = uA[k]; }
;         IT_ADVANCE();
;         LOAD_SET(uA, vA, cgA, suA, svA);
.LU_done:
	s_waitcnt lgkmcnt(0)
	s_add_i32 s20, s91, 3
	s_and_b32 s20, s20, -4
	s_waitcnt lgkmcnt(0)
	v_mov_b32_e32 v213, s22
	v_mov_b32_e32 v233, v240
	v_mov_b32_e32 v235, v240
	v_mov_b32_e32 v237, v240
	v_mov_b32_e32 v239, v240
	ds_read_b32 v232, v213 offset:48
	ds_read_b32 v234, v213 offset:52
	ds_read_b32 v236, v213 offset:56
	ds_read_b32 v238, v213 offset:60
	s_waitcnt lgkmcnt(0)
	buffer_load_dwordx4 v[176:179], v[232:233], s[60:63], 0 idxen offen
	buffer_load_dwordx4 v[180:183], v[234:235], s[60:63], 0 idxen offen
	buffer_load_dwordx4 v[184:187], v[236:237], s[60:63], 0 idxen offen
	buffer_load_dwordx4 v[188:191], v[238:239], s[60:63], 0 idxen offen
	ds_read_b128 v[248:251], v213 offset:4992
	ds_read_b32 v232, v213 offset:64
	ds_read_b32 v234, v213 offset:68
	ds_read_b32 v236, v213 offset:72
	ds_read_b32 v238, v213 offset:76
	s_mov_b32 s21, 0
	s_mov_b32 s89, -1
	s_mov_b32 s86, 0
	s_mov_b32 s20, 260
	v_mov_b64_e32 v[0:1], 0
	v_mov_b64_e32 v[2:3], 0
	v_mov_b64_e32 v[4:5], 0
	v_mov_b64_e32 v[6:7], 0
	v_mov_b64_e32 v[8:9], 0
	v_mov_b64_e32 v[10:11], 0
	v_mov_b64_e32 v[12:13], 0
	v_mov_b64_e32 v[14:15], 0
	v_mov_b64_e32 v[16:17], 0
	v_mov_b64_e32 v[18:19], 0
	v_mov_b64_e32 v[20:21], 0
	v_mov_b64_e32 v[22:23], 0
	v_mov_b64_e32 v[24:25], 0
	v_mov_b64_e32 v[26:27], 0
	v_mov_b64_e32 v[28:29], 0
	v_mov_b64_e32 v[30:31], 0
	v_mov_b64_e32 v[32:33], 0
	v_mov_b64_e32 v[34:35], 0
	v_mov_b64_e32 v[36:37], 0
	v_mov_b64_e32 v[38:39], 0
	v_mov_b64_e32 v[40:41], 0
	v_mov_b64_e32 v[42:43], 0
	v_mov_b64_e32 v[44:45], 0
	v_mov_b64_e32 v[46:47], 0
	v_mov_b64_e32 v[48:49], 0
	v_mov_b64_e32 v[50:51], 0
	v_mov_b64_e32 v[52:53], 0
	v_mov_b64_e32 v[54:55], 0
	v_mov_b64_e32 v[56:57], 0
	v_mov_b64_e32 v[58:59], 0
	v_mov_b64_e32 v[60:61], 0
	v_mov_b64_e32 v[62:63], 0
	v_mov_b64_e32 v[64:65], 0
	v_mov_b64_e32 v[66:67], 0
	v_mov_b64_e32 v[68:69], 0
	v_mov_b64_e32 v[70:71], 0
	v_mov_b64_e32 v[72:73], 0
	v_mov_b64_e32 v[74:75], 0
	v_mov_b64_e32 v[76:77], 0
	v_mov_b64_e32 v[78:79], 0
	v_mov_b64_e32 v[80:81], 0
	v_mov_b64_e32 v[82:83], 0
	v_mov_b64_e32 v[84:85], 0
	v_mov_b64_e32 v[86:87], 0
	v_mov_b64_e32 v[88:89], 0
	v_mov_b64_e32 v[90:91], 0
	v_mov_b64_e32 v[92:93], 0
	v_mov_b64_e32 v[94:95], 0
	v_mov_b64_e32 v[96:97], 0
	v_mov_b64_e32 v[98:99], 0
	v_mov_b64_e32 v[100:101], 0
	v_mov_b64_e32 v[102:103], 0
	v_mov_b64_e32 v[104:105], 0
	v_mov_b64_e32 v[106:107], 0
	v_mov_b64_e32 v[108:109], 0
	v_mov_b64_e32 v[110:111], 0
	v_mov_b64_e32 v[112:113], 0
	v_mov_b64_e32 v[114:115], 0
	v_mov_b64_e32 v[116:117], 0
	v_mov_b64_e32 v[118:119], 0
	v_mov_b64_e32 v[120:121], 0
	v_mov_b64_e32 v[122:123], 0
	v_mov_b64_e32 v[124:125], 0
	v_mov_b64_e32 v[126:127], 0
	s_branch .LV_sw0
